# v30 plus non-temporal (nt) cache hint on once-touched streams: row loads and all stores of the four residual/norm row loops, the first pre-norm loop, and the f32 weight loads / bf16 weight stores of t
# baseline (speedup 1.0000x reference)
.LBB0_69:
	ds_write2_b32 v78, v24, v25 offset1:1
	ds_write2_b32 v78, v26, v27 offset0:2 offset1:3
	ds_write2_b32 v79, v28, v29 offset1:1
	ds_write2_b32 v80, v30, v31 offset1:1
	ds_write2_b32 v81, v32, v33 offset1:1
	ds_write2_b32 v82, v34, v35 offset1:1
	ds_write2_b32 v83, v36, v37 offset1:1
	ds_write2_b32 v84, v38, v39 offset1:1
	ds_write2_b32 v85, v48, v49 offset1:1
	ds_write2_b32 v86, v50, v51 offset1:1
	ds_write2_b32 v87, v52, v53 offset1:1
	ds_write2_b32 v88, v54, v55 offset1:1
	ds_write2_b32 v89, v56, v57 offset1:1
	ds_write2_b32 v90, v58, v59 offset1:1
	ds_write2_b32 v91, v60, v61 offset1:1
	ds_write2_b32 v92, v62, v63 offset1:1
	s_waitcnt lgkmcnt(0)
	ds_read2_b32 v[66:67], v77 offset1:8
	ds_read2_b32 v[84:85], v77 offset0:33 offset1:41
	ds_read2_b32 v[86:87], v77 offset0:66 offset1:74
	ds_read2_b32 v[88:89], v77 offset0:99 offset1:107
	ds_read2_b32 v[90:91], v77 offset0:132 offset1:140
	s_waitcnt lgkmcnt(0)
	v_bfe_u32 v79, v66, 16, 1
	v_add3_u32 v66, v66, v79, s33
	v_bfe_u32 v79, v84, 16, 1
	v_lshrrev_b32_e32 v66, 16, v66
	v_add3_u32 v79, v84, v79, s33
	ds_read2_b32 v[92:93], v77 offset0:165 offset1:173
	v_and_or_b32 v80, v79, s34, v66
	v_bfe_u32 v66, v86, 16, 1
	v_add3_u32 v66, v86, v66, s33
	v_bfe_u32 v79, v88, 16, 1
	ds_read2_b32 v[94:95], v77 offset0:198 offset1:206
	v_lshrrev_b32_e32 v66, 16, v66
	v_add3_u32 v79, v88, v79, s33
	ds_read2_b32 v[96:97], v77 offset0:231 offset1:239
	v_and_or_b32 v81, v79, s34, v66
	v_bfe_u32 v66, v90, 16, 1
	v_add3_u32 v66, v90, v66, s33
	s_waitcnt lgkmcnt(2)
	v_bfe_u32 v79, v92, 16, 1
	v_lshrrev_b32_e32 v66, 16, v66
	v_add3_u32 v79, v92, v79, s33
	v_and_or_b32 v82, v79, s34, v66
	s_waitcnt lgkmcnt(1)
	v_bfe_u32 v66, v94, 16, 1
	v_add_u32_e32 v98, s18, v68
	v_add3_u32 v66, v94, v66, s33
	s_waitcnt lgkmcnt(0)
	v_bfe_u32 v79, v96, 16, 1
	v_ashrrev_i32_e32 v99, 31, v98
	v_lshrrev_b32_e32 v66, 16, v66
	v_add3_u32 v79, v96, v79, s33
	v_lshlrev_b64 v[98:99], 13, v[98:99]
	s_ashr_i32 s15, s14, 31
	v_and_or_b32 v83, v79, s34, v66
	v_lshl_add_u64 v[98:99], s[12:13], 0, v[98:99]
	s_lshl_b64 s[14:15], s[14:15], 1
	v_bfe_u32 v66, v67, 16, 1
	v_lshl_add_u64 v[98:99], v[98:99], 0, s[14:15]
	v_add3_u32 v66, v67, v66, s33
	v_bfe_u32 v67, v85, 16, 1
	v_lshl_add_u64 v[98:99], v[98:99], 0, v[64:65]
	v_lshrrev_b32_e32 v66, 16, v66
	v_add3_u32 v67, v85, v67, s33
	global_store_dwordx4 v[98:99], v[80:83], off nt
	ds_read2_b32 v[84:85], v77 offset0:16 offset1:24
	v_add_u32_e32 v98, s18, v71
	v_and_or_b32 v80, v67, s34, v66
	v_bfe_u32 v66, v87, 16, 1
	v_add3_u32 v66, v87, v66, s33
	v_bfe_u32 v67, v89, 16, 1
	v_lshrrev_b32_e32 v66, 16, v66
	v_add3_u32 v67, v89, v67, s33
	v_and_or_b32 v81, v67, s34, v66
	v_bfe_u32 v66, v91, 16, 1
	v_add3_u32 v66, v91, v66, s33
	v_bfe_u32 v67, v93, 16, 1
	v_lshrrev_b32_e32 v66, 16, v66
	v_add3_u32 v67, v93, v67, s33
	v_and_or_b32 v82, v67, s34, v66
	v_bfe_u32 v66, v95, 16, 1
	v_add3_u32 v66, v95, v66, s33
	v_bfe_u32 v67, v97, 16, 1
	v_lshrrev_b32_e32 v66, 16, v66
	v_add3_u32 v67, v97, v67, s33
	v_and_or_b32 v83, v67, s34, v66
	v_add_u32_e32 v66, s18, v70
	v_ashrrev_i32_e32 v67, 31, v66
	v_lshlrev_b64 v[66:67], 13, v[66:67]
	v_lshl_add_u64 v[66:67], s[12:13], 0, v[66:67]
	v_lshl_add_u64 v[66:67], v[66:67], 0, s[14:15]
	v_lshl_add_u64 v[66:67], v[66:67], 0, v[64:65]
	global_store_dwordx4 v[66:67], v[80:83], off nt
	ds_read2_b32 v[66:67], v77 offset0:49 offset1:57
	ds_read2_b32 v[86:87], v77 offset0:82 offset1:90
	ds_read2_b32 v[88:89], v77 offset0:115 offset1:123
	s_waitcnt lgkmcnt(3)
	v_bfe_u32 v79, v84, 16, 1
	v_add3_u32 v79, v84, v79, s33
	s_waitcnt lgkmcnt(2)
	v_bfe_u32 v80, v66, 16, 1
	ds_read2_b32 v[90:91], v77 offset0:148 offset1:156
	v_lshrrev_b32_e32 v79, 16, v79
	v_add3_u32 v66, v66, v80, s33
	ds_read2_b32 v[92:93], v77 offset0:181 offset1:189
	v_and_or_b32 v80, v66, s34, v79
	s_waitcnt lgkmcnt(3)
	v_bfe_u32 v66, v86, 16, 1
	v_add3_u32 v66, v86, v66, s33
	s_waitcnt lgkmcnt(2)
	v_bfe_u32 v79, v88, 16, 1
	ds_read2_b32 v[94:95], v77 offset0:214 offset1:222
	v_lshrrev_b32_e32 v66, 16, v66
	v_add3_u32 v79, v88, v79, s33
	ds_read2_b32 v[96:97], v77 offset0:247 offset1:255
	v_and_or_b32 v81, v79, s34, v66
	s_waitcnt lgkmcnt(3)
	v_bfe_u32 v66, v90, 16, 1
	v_add3_u32 v66, v90, v66, s33
	s_waitcnt lgkmcnt(2)
	v_bfe_u32 v79, v92, 16, 1
	v_lshrrev_b32_e32 v66, 16, v66
	v_add3_u32 v79, v92, v79, s33
	v_and_or_b32 v82, v79, s34, v66
	s_waitcnt lgkmcnt(1)
	v_bfe_u32 v66, v94, 16, 1
	v_add3_u32 v66, v94, v66, s33
	s_waitcnt lgkmcnt(0)
	v_bfe_u32 v79, v96, 16, 1
	v_ashrrev_i32_e32 v99, 31, v98
	v_lshrrev_b32_e32 v66, 16, v66
	v_add3_u32 v79, v96, v79, s33
	v_lshlrev_b64 v[98:99], 13, v[98:99]
	v_and_or_b32 v83, v79, s34, v66
	v_lshl_add_u64 v[98:99], s[12:13], 0, v[98:99]
	v_bfe_u32 v66, v85, 16, 1
	v_lshl_add_u64 v[98:99], v[98:99], 0, s[14:15]
	v_add3_u32 v66, v85, v66, s33
	v_bfe_u32 v79, v67, 16, 1
	v_lshl_add_u64 v[98:99], v[98:99], 0, v[64:65]
	v_lshrrev_b32_e32 v66, 16, v66
	v_add3_u32 v67, v67, v79, s33
	global_store_dwordx4 v[98:99], v[80:83], off nt
	s_add_i32 s35, s36, s22
	s_add_i32 s23, s23, s24
	v_and_or_b32 v80, v67, s34, v66
	v_bfe_u32 v66, v87, 16, 1
	v_add3_u32 v66, v87, v66, s33
	v_bfe_u32 v67, v89, 16, 1
	v_lshrrev_b32_e32 v66, 16, v66
	v_add3_u32 v67, v89, v67, s33
	v_and_or_b32 v81, v67, s34, v66
	v_bfe_u32 v66, v91, 16, 1
	v_add3_u32 v66, v91, v66, s33
	v_bfe_u32 v67, v93, 16, 1
	v_lshrrev_b32_e32 v66, 16, v66
	v_add3_u32 v67, v93, v67, s33
	v_and_or_b32 v82, v67, s34, v66
	v_bfe_u32 v66, v95, 16, 1
	v_add3_u32 v66, v95, v66, s33
	v_bfe_u32 v67, v97, 16, 1
	v_lshrrev_b32_e32 v66, 16, v66
	v_add3_u32 v67, v97, v67, s33
	v_and_or_b32 v83, v67, s34, v66
	v_add_u32_e32 v66, s18, v72
	v_ashrrev_i32_e32 v67, 31, v66
	v_lshlrev_b64 v[66:67], 13, v[66:67]
	v_lshl_add_u64 v[66:67], s[12:13], 0, v[66:67]
	v_lshl_add_u64 v[66:67], v[66:67], 0, s[14:15]
	v_lshl_add_u64 v[66:67], v[66:67], 0, v[64:65]
	global_store_dwordx4 v[66:67], v[80:83], off nt
	s_waitcnt lgkmcnt(0)
	s_cmp_gt_i32 s35, 0x139ff
	s_cselect_b64 s[12:13], -1, 0

.LBB0_100:
	v_cmp_lt_i32_e32 vcc, -1, v66
	v_mov_b32_e32 v28, 0
	v_mov_b32_e32 v24, 0
	v_mov_b32_e32 v25, 0
	v_mov_b32_e32 v26, 0
	v_mov_b32_e32 v27, 0
	s_and_saveexec_b64 s[18:19], vcc
	s_cbranch_execz .LBB0_102
	v_add_u32_e32 v24, s20, v68
	v_ashrrev_i32_e32 v25, 31, v24
	v_mul_lo_u32 v26, s16, v25
	v_mul_lo_u32 v27, s17, v24
	v_mad_u64_u32 v[24:25], s[38:39], s16, v24, 0
	v_add3_u32 v25, v25, v26, v27
	s_waitcnt lgkmcnt(0)
	v_lshl_add_u64 v[24:25], v[24:25], 2, s[14:15]
	v_mov_b32_e32 v67, v65
	v_lshl_add_u64 v[24:25], v[66:67], 2, v[24:25]
	global_load_dwordx4 v[24:27], v[24:25], off nt
.LBB0_102:
	s_or_b64 exec, exec, s[18:19]
	v_mov_b32_e32 v29, 0
	v_mov_b32_e32 v30, 0
	v_mov_b32_e32 v31, 0
	s_and_saveexec_b64 s[18:19], vcc
	s_cbranch_execz .LBB0_104
	v_add_u32_e32 v28, s20, v70
	v_ashrrev_i32_e32 v29, 31, v28
	v_mul_lo_u32 v30, s16, v29
	v_mul_lo_u32 v31, s17, v28
	v_mad_u64_u32 v[28:29], s[38:39], s16, v28, 0
	v_add3_u32 v29, v29, v30, v31
	s_waitcnt lgkmcnt(0)
	v_lshl_add_u64 v[28:29], v[28:29], 2, s[14:15]
	v_mov_b32_e32 v67, v65
	v_lshl_add_u64 v[28:29], v[66:67], 2, v[28:29]
	global_load_dwordx4 v[28:31], v[28:29], off nt
.LBB0_104:
	s_or_b64 exec, exec, s[18:19]
	v_mov_b32_e32 v36, 0
	v_mov_b32_e32 v32, 0
	v_mov_b32_e32 v33, 0
	v_mov_b32_e32 v34, 0
	v_mov_b32_e32 v35, 0
	s_and_saveexec_b64 s[18:19], vcc
	s_cbranch_execz .LBB0_106
	v_add_u32_e32 v32, s20, v71
	v_ashrrev_i32_e32 v33, 31, v32
	v_mul_lo_u32 v34, s16, v33
	v_mul_lo_u32 v35, s17, v32
	v_mad_u64_u32 v[32:33], s[38:39], s16, v32, 0
	v_add3_u32 v33, v33, v34, v35
	s_waitcnt lgkmcnt(0)
	v_lshl_add_u64 v[32:33], v[32:33], 2, s[14:15]
	v_mov_b32_e32 v67, v65
	v_lshl_add_u64 v[32:33], v[66:67], 2, v[32:33]
	global_load_dwordx4 v[32:35], v[32:33], off nt
.LBB0_106:
	s_or_b64 exec, exec, s[18:19]
	v_mov_b32_e32 v37, 0
	v_mov_b32_e32 v38, 0
	v_mov_b32_e32 v39, 0
	s_and_saveexec_b64 s[18:19], vcc
	s_cbranch_execz .LBB0_108
	v_add_u32_e32 v36, s20, v72
	v_ashrrev_i32_e32 v37, 31, v36
	v_mul_lo_u32 v38, s16, v37
	v_mul_lo_u32 v39, s17, v36
	v_mad_u64_u32 v[36:37], s[38:39], s16, v36, 0
	v_add3_u32 v37, v37, v38, v39
	s_waitcnt lgkmcnt(0)
	v_lshl_add_u64 v[36:37], v[36:37], 2, s[14:15]
	v_mov_b32_e32 v67, v65
	v_lshl_add_u64 v[36:37], v[66:67], 2, v[36:37]
	global_load_dwordx4 v[36:39], v[36:37], off nt
.LBB0_108:
	s_or_b64 exec, exec, s[18:19]
	v_mov_b32_e32 v52, 0
	v_mov_b32_e32 v48, 0
	v_mov_b32_e32 v49, 0
	v_mov_b32_e32 v50, 0
	v_mov_b32_e32 v51, 0
	s_and_saveexec_b64 s[18:19], vcc
	s_cbranch_execz .LBB0_110
	v_add_u32_e32 v48, s20, v74
	v_ashrrev_i32_e32 v49, 31, v48
	v_mul_lo_u32 v50, s16, v49
	v_mul_lo_u32 v51, s17, v48
	v_mad_u64_u32 v[48:49], s[38:39], s16, v48, 0
	v_add3_u32 v49, v49, v50, v51
	s_waitcnt lgkmcnt(0)
	v_lshl_add_u64 v[48:49], v[48:49], 2, s[14:15]
	v_mov_b32_e32 v67, v65
	v_lshl_add_u64 v[48:49], v[66:67], 2, v[48:49]
	global_load_dwordx4 v[48:51], v[48:49], off nt
.LBB0_110:
	s_or_b64 exec, exec, s[18:19]
	v_mov_b32_e32 v53, 0
	v_mov_b32_e32 v54, 0
	v_mov_b32_e32 v55, 0
	s_and_saveexec_b64 s[18:19], vcc
	s_cbranch_execz .LBB0_112
	v_add_u32_e32 v52, s20, v75
	v_ashrrev_i32_e32 v53, 31, v52
	v_mul_lo_u32 v54, s16, v53
	v_mul_lo_u32 v55, s17, v52
	v_mad_u64_u32 v[52:53], s[38:39], s16, v52, 0
	v_add3_u32 v53, v53, v54, v55
	s_waitcnt lgkmcnt(0)
	v_lshl_add_u64 v[52:53], v[52:53], 2, s[14:15]
	v_mov_b32_e32 v67, v65
	v_lshl_add_u64 v[52:53], v[66:67], 2, v[52:53]
	global_load_dwordx4 v[52:55], v[52:53], off nt
.LBB0_112:
	s_or_b64 exec, exec, s[18:19]
	v_mov_b32_e32 v63, 0
	v_mov_b32_e32 v56, 0
	v_mov_b32_e32 v57, 0
	v_mov_b32_e32 v58, 0
	v_mov_b32_e32 v59, 0
	s_and_saveexec_b64 s[18:19], vcc
	s_cbranch_execz .LBB0_114
	v_add_u32_e32 v56, s20, v76
	v_ashrrev_i32_e32 v57, 31, v56
	v_mul_lo_u32 v58, s16, v57
	v_mul_lo_u32 v59, s17, v56
	v_mad_u64_u32 v[56:57], s[38:39], s16, v56, 0
	v_add3_u32 v57, v57, v58, v59
	s_waitcnt lgkmcnt(0)
	v_lshl_add_u64 v[56:57], v[56:57], 2, s[14:15]
	v_mov_b32_e32 v67, v65
	v_lshl_add_u64 v[56:57], v[66:67], 2, v[56:57]
	global_load_dwordx4 v[56:59], v[56:57], off nt
.LBB0_114:
	s_or_b64 exec, exec, s[18:19]
	v_mov_b32_e32 v62, 0
	v_mov_b32_e32 v61, 0
	v_mov_b32_e32 v60, 0
	s_and_saveexec_b64 s[18:19], vcc
	s_cbranch_execz .LBB0_116
	v_add_u32_e32 v60, s20, v69
	v_ashrrev_i32_e32 v61, 31, v60
	v_mul_lo_u32 v62, s16, v61
	v_mul_lo_u32 v63, s17, v60
	v_mad_u64_u32 v[60:61], s[16:17], s16, v60, 0
	v_add3_u32 v61, v61, v62, v63
	s_waitcnt lgkmcnt(0)
	v_lshl_add_u64 v[60:61], v[60:61], 2, s[14:15]
	v_mov_b32_e32 v67, v65
	v_lshl_add_u64 v[60:61], v[66:67], 2, v[60:61]
	global_load_dwordx4 v[60:63], v[60:61], off nt

.LBB0_125:
	v_add_u32_e32 v79, 0x420, v78
	v_add_u32_e32 v80, 0x428, v78
	v_add_u32_e32 v81, 0x840, v78
	v_add_u32_e32 v82, 0x848, v78
	v_add_u32_e32 v83, 0xc60, v78
	v_add_u32_e32 v84, 0xc68, v78
	v_add_u32_e32 v85, 0x1080, v78
	v_add_u32_e32 v86, 0x1088, v78
	v_add_u32_e32 v87, 0x14a0, v78
	v_add_u32_e32 v88, 0x14a8, v78
	v_add_u32_e32 v89, 0x18c0, v78
	v_add_u32_e32 v90, 0x18c8, v78
	v_add_u32_e32 v91, 0x1ce0, v78
	v_add_u32_e32 v92, 0x1ce8, v78
	s_waitcnt vmcnt(0)
	ds_write2_b32 v78, v4, v5 offset1:1
	ds_write2_b32 v78, v6, v7 offset0:2 offset1:3
	ds_write2_b32 v79, v0, v1 offset1:1
	ds_write2_b32 v80, v2, v3 offset1:1
	ds_write2_b32 v81, v12, v13 offset1:1
	ds_write2_b32 v82, v14, v15 offset1:1
	ds_write2_b32 v83, v8, v9 offset1:1
	ds_write2_b32 v84, v10, v11 offset1:1
	ds_write2_b32 v85, v20, v21 offset1:1
	ds_write2_b32 v86, v22, v23 offset1:1
	ds_write2_b32 v87, v16, v17 offset1:1
	ds_write2_b32 v88, v18, v19 offset1:1
	ds_write2_b32 v89, v44, v45 offset1:1
	ds_write2_b32 v90, v46, v47 offset1:1
	ds_write2_b32 v91, v40, v41 offset1:1
	ds_write2_b32 v92, v42, v43 offset1:1
	s_waitcnt lgkmcnt(0)
	ds_read2_b32 v[66:67], v77 offset1:8
	ds_read2_b32 v[98:99], v77 offset0:33 offset1:41
	ds_read2_b32 v[100:101], v77 offset0:66 offset1:74
	ds_read2_b32 v[102:103], v77 offset0:99 offset1:107
	ds_read2_b32 v[104:105], v77 offset0:132 offset1:140
	s_waitcnt lgkmcnt(0)
	v_bfe_u32 v93, v66, 16, 1
	v_add3_u32 v66, v66, v93, s33
	v_bfe_u32 v93, v98, 16, 1
	v_lshrrev_b32_e32 v66, 16, v66
	v_add3_u32 v93, v98, v93, s33
	ds_read2_b32 v[106:107], v77 offset0:165 offset1:173
	v_and_or_b32 v94, v93, s34, v66
	v_bfe_u32 v66, v100, 16, 1
	v_add3_u32 v66, v100, v66, s33
	v_bfe_u32 v93, v102, 16, 1
	ds_read2_b32 v[108:109], v77 offset0:198 offset1:206
	v_lshrrev_b32_e32 v66, 16, v66
	v_add3_u32 v93, v102, v93, s33
	ds_read2_b32 v[110:111], v77 offset0:231 offset1:239
	v_and_or_b32 v95, v93, s34, v66
	v_bfe_u32 v66, v104, 16, 1
	v_add3_u32 v66, v104, v66, s33
	s_waitcnt lgkmcnt(2)
	v_bfe_u32 v93, v106, 16, 1
	v_lshrrev_b32_e32 v66, 16, v66
	v_add3_u32 v93, v106, v93, s33
	v_and_or_b32 v96, v93, s34, v66
	s_waitcnt lgkmcnt(1)
	v_bfe_u32 v66, v108, 16, 1
	v_add_u32_e32 v112, s20, v68
	v_add3_u32 v66, v108, v66, s33
	s_waitcnt lgkmcnt(0)
	v_bfe_u32 v93, v110, 16, 1
	v_ashrrev_i32_e32 v113, 31, v112
	v_lshrrev_b32_e32 v66, 16, v66
	v_add3_u32 v93, v110, v93, s33
	v_lshlrev_b64 v[112:113], 13, v[112:113]
	s_ashr_i32 s17, s16, 31
	v_and_or_b32 v97, v93, s34, v66
	v_lshl_add_u64 v[112:113], s[14:15], 0, v[112:113]
	s_lshl_b64 s[16:17], s[16:17], 1
	v_bfe_u32 v66, v67, 16, 1
	v_lshl_add_u64 v[112:113], v[112:113], 0, s[16:17]
	v_add3_u32 v66, v67, v66, s33
	v_bfe_u32 v67, v99, 16, 1
	v_lshl_add_u64 v[112:113], v[112:113], 0, v[64:65]
	v_lshrrev_b32_e32 v66, 16, v66
	v_add3_u32 v67, v99, v67, s33
	global_store_dwordx4 v[112:113], v[94:97], off nt
	ds_read2_b32 v[98:99], v77 offset0:16 offset1:24
	v_add_u32_e32 v112, s20, v71
	v_and_or_b32 v94, v67, s34, v66
	v_bfe_u32 v66, v101, 16, 1
	v_add3_u32 v66, v101, v66, s33
	v_bfe_u32 v67, v103, 16, 1
	v_lshrrev_b32_e32 v66, 16, v66
	v_add3_u32 v67, v103, v67, s33
	v_and_or_b32 v95, v67, s34, v66
	v_bfe_u32 v66, v105, 16, 1
	v_add3_u32 v66, v105, v66, s33
	v_bfe_u32 v67, v107, 16, 1
	v_lshrrev_b32_e32 v66, 16, v66
	v_add3_u32 v67, v107, v67, s33
	v_and_or_b32 v96, v67, s34, v66
	v_bfe_u32 v66, v109, 16, 1
	v_add3_u32 v66, v109, v66, s33
	v_bfe_u32 v67, v111, 16, 1
	v_lshrrev_b32_e32 v66, 16, v66
	v_add3_u32 v67, v111, v67, s33
	v_and_or_b32 v97, v67, s34, v66
	v_add_u32_e32 v66, s20, v70
	v_ashrrev_i32_e32 v67, 31, v66
	v_lshlrev_b64 v[66:67], 13, v[66:67]
	v_lshl_add_u64 v[66:67], s[14:15], 0, v[66:67]
	v_lshl_add_u64 v[66:67], v[66:67], 0, s[16:17]
	v_lshl_add_u64 v[66:67], v[66:67], 0, v[64:65]
	global_store_dwordx4 v[66:67], v[94:97], off nt
	ds_read2_b32 v[66:67], v77 offset0:49 offset1:57
	ds_read2_b32 v[100:101], v77 offset0:82 offset1:90
	ds_read2_b32 v[102:103], v77 offset0:115 offset1:123
	s_waitcnt lgkmcnt(3)
	v_bfe_u32 v93, v98, 16, 1
	v_add3_u32 v93, v98, v93, s33
	s_waitcnt lgkmcnt(2)
	v_bfe_u32 v94, v66, 16, 1
	ds_read2_b32 v[104:105], v77 offset0:148 offset1:156
	v_lshrrev_b32_e32 v93, 16, v93
	v_add3_u32 v66, v66, v94, s33
	ds_read2_b32 v[106:107], v77 offset0:181 offset1:189
	v_and_or_b32 v94, v66, s34, v93
	s_waitcnt lgkmcnt(3)
	v_bfe_u32 v66, v100, 16, 1
	v_add3_u32 v66, v100, v66, s33
	s_waitcnt lgkmcnt(2)
	v_bfe_u32 v93, v102, 16, 1
	ds_read2_b32 v[108:109], v77 offset0:214 offset1:222
	v_lshrrev_b32_e32 v66, 16, v66
	v_add3_u32 v93, v102, v93, s33
	ds_read2_b32 v[110:111], v77 offset0:247 offset1:255
	v_and_or_b32 v95, v93, s34, v66
	s_waitcnt lgkmcnt(3)
	v_bfe_u32 v66, v104, 16, 1
	v_add3_u32 v66, v104, v66, s33
	s_waitcnt lgkmcnt(2)
	v_bfe_u32 v93, v106, 16, 1
	v_lshrrev_b32_e32 v66, 16, v66
	v_add3_u32 v93, v106, v93, s33
	v_and_or_b32 v96, v93, s34, v66
	s_waitcnt lgkmcnt(1)
	v_bfe_u32 v66, v108, 16, 1
	v_add3_u32 v66, v108, v66, s33
	s_waitcnt lgkmcnt(0)
	v_bfe_u32 v93, v110, 16, 1
	v_ashrrev_i32_e32 v113, 31, v112
	v_lshrrev_b32_e32 v66, 16, v66
	v_add3_u32 v93, v110, v93, s33
	v_lshlrev_b64 v[112:113], 13, v[112:113]
	v_and_or_b32 v97, v93, s34, v66
	v_lshl_add_u64 v[112:113], s[14:15], 0, v[112:113]
	v_bfe_u32 v66, v99, 16, 1
	v_lshl_add_u64 v[112:113], v[112:113], 0, s[16:17]
	v_add3_u32 v66, v99, v66, s33
	v_bfe_u32 v93, v67, 16, 1
	v_lshl_add_u64 v[112:113], v[112:113], 0, v[64:65]
	v_lshrrev_b32_e32 v66, 16, v66
	v_add3_u32 v67, v67, v93, s33
	global_store_dwordx4 v[112:113], v[94:97], off nt
	s_andn2_b64 vcc, exec, s[12:13]
	s_mov_b64 s[12:13], -1
	v_and_or_b32 v94, v67, s34, v66
	v_bfe_u32 v66, v101, 16, 1
	v_add3_u32 v66, v101, v66, s33
	v_bfe_u32 v67, v103, 16, 1
	v_lshrrev_b32_e32 v66, 16, v66
	v_add3_u32 v67, v103, v67, s33
	v_and_or_b32 v95, v67, s34, v66
	v_bfe_u32 v66, v105, 16, 1
	v_add3_u32 v66, v105, v66, s33
	v_bfe_u32 v67, v107, 16, 1
	v_lshrrev_b32_e32 v66, 16, v66
	v_add3_u32 v67, v107, v67, s33
	v_and_or_b32 v96, v67, s34, v66
	v_bfe_u32 v66, v109, 16, 1
	v_add3_u32 v66, v109, v66, s33
	v_bfe_u32 v67, v111, 16, 1
	v_lshrrev_b32_e32 v66, 16, v66
	v_add3_u32 v67, v111, v67, s33
	v_and_or_b32 v97, v67, s34, v66
	v_add_u32_e32 v66, s20, v72
	v_ashrrev_i32_e32 v67, 31, v66
	v_lshlrev_b64 v[66:67], 13, v[66:67]
	v_lshl_add_u64 v[66:67], s[14:15], 0, v[66:67]
	v_lshl_add_u64 v[66:67], v[66:67], 0, s[16:17]
	v_lshl_add_u64 v[66:67], v[66:67], 0, v[64:65]
	global_store_dwordx4 v[66:67], v[94:97], off nt
	s_waitcnt lgkmcnt(0)
	s_cbranch_vccnz .LBB0_70
	s_add_i32 s19, s26, s35
	s_cmp_gt_i32 s19, 0x139ff
	s_cbranch_scc1 .LBB0_172
	s_cmpk_gt_i32 s19, 0x6dff
	s_cbranch_scc0 .LBB0_130
	s_cmpk_gt_u32 s19, 0x8dff
	s_cbranch_scc0 .LBB0_131
	s_add_i32 s12, s19, 0x7200
	s_and_b32 s13, s12, 0xffff
	s_mul_i32 s13, s13, 0xbe83
	s_lshr_b32 s14, s13, 25
	s_mul_i32 s13, s14, 0x2b0
	s_sub_i32 s12, s12, s13
	s_and_b32 s15, s12, 0xffff
	s_lshl_b32 s16, s15, 5
	s_bitcmp0_b32 s12, 2
	s_cselect_b32 s12, s27, 0x70
	s_add_u32 s12, s2, s12
	s_addc_u32 s13, s3, 0
	s_load_dwordx2 s[12:13], s[12:13], 0x0
	s_lshl_b32 s15, s15, 4
	s_and_b32 s15, s15, 0x3f80
	s_and_b32 s16, s16, 0x60
	s_or_b32 s15, s15, s16
	v_or_b32_e32 v66, s15, v73
	s_lshl_b32 s18, s14, 6
	s_mov_b64 s[14:15], 0x2b00
	s_cbranch_execz .LBB0_132
	s_branch .LBB0_133

.LBB0_155:
	v_cmp_lt_i32_e32 vcc, -1, v66
	v_mov_b32_e32 v0, 0
	v_mov_b32_e32 v4, 0
	v_mov_b32_e32 v5, 0
	v_mov_b32_e32 v6, 0
	v_mov_b32_e32 v7, 0
	s_and_saveexec_b64 s[16:17], vcc
	s_cbranch_execz .LBB0_157
	v_add_u32_e32 v1, s18, v68
	v_ashrrev_i32_e32 v2, 31, v1
	v_mul_lo_u32 v4, s14, v2
	v_mul_lo_u32 v5, s15, v1
	v_mad_u64_u32 v[2:3], s[20:21], s14, v1, 0
	v_add3_u32 v3, v3, v4, v5
	s_waitcnt lgkmcnt(0)
	v_lshl_add_u64 v[2:3], v[2:3], 2, s[12:13]
	v_mov_b32_e32 v67, v65
	v_lshl_add_u64 v[2:3], v[66:67], 2, v[2:3]
	global_load_dwordx4 v[4:7], v[2:3], off nt
.LBB0_157:
	s_or_b64 exec, exec, s[16:17]
	v_mov_b32_e32 v1, 0
	v_mov_b32_e32 v2, 0
	v_mov_b32_e32 v3, 0
	s_and_saveexec_b64 s[16:17], vcc
	s_cbranch_execz .LBB0_159
	v_add_u32_e32 v0, s18, v70
	v_ashrrev_i32_e32 v1, 31, v0
	v_mul_lo_u32 v2, s14, v1
	v_mul_lo_u32 v3, s15, v0
	v_mad_u64_u32 v[0:1], s[20:21], s14, v0, 0
	v_add3_u32 v1, v1, v2, v3
	s_waitcnt lgkmcnt(0)
	v_lshl_add_u64 v[0:1], v[0:1], 2, s[12:13]
	v_mov_b32_e32 v67, v65
	v_lshl_add_u64 v[0:1], v[66:67], 2, v[0:1]
	global_load_dwordx4 v[0:3], v[0:1], off nt
.LBB0_159:
	s_or_b64 exec, exec, s[16:17]
	v_mov_b32_e32 v8, 0
	v_mov_b32_e32 v12, 0
	v_mov_b32_e32 v13, 0
	v_mov_b32_e32 v14, 0
	v_mov_b32_e32 v15, 0
	s_and_saveexec_b64 s[16:17], vcc
	s_cbranch_execz .LBB0_161
	v_add_u32_e32 v9, s18, v71
	v_ashrrev_i32_e32 v10, 31, v9
	v_mul_lo_u32 v12, s14, v10
	v_mul_lo_u32 v13, s15, v9
	v_mad_u64_u32 v[10:11], s[20:21], s14, v9, 0
	v_add3_u32 v11, v11, v12, v13
	s_waitcnt lgkmcnt(0)
	v_lshl_add_u64 v[10:11], v[10:11], 2, s[12:13]
	v_mov_b32_e32 v67, v65
	v_lshl_add_u64 v[10:11], v[66:67], 2, v[10:11]
	global_load_dwordx4 v[12:15], v[10:11], off nt
.LBB0_161:
	s_or_b64 exec, exec, s[16:17]
	v_mov_b32_e32 v9, 0
	v_mov_b32_e32 v10, 0
	v_mov_b32_e32 v11, 0
	s_and_saveexec_b64 s[16:17], vcc
	s_cbranch_execz .LBB0_163
	v_add_u32_e32 v8, s18, v72
	v_ashrrev_i32_e32 v9, 31, v8
	v_mul_lo_u32 v10, s14, v9
	v_mul_lo_u32 v11, s15, v8
	v_mad_u64_u32 v[8:9], s[20:21], s14, v8, 0
	v_add3_u32 v9, v9, v10, v11
	s_waitcnt lgkmcnt(0)
	v_lshl_add_u64 v[8:9], v[8:9], 2, s[12:13]
	v_mov_b32_e32 v67, v65
	v_lshl_add_u64 v[8:9], v[66:67], 2, v[8:9]
	global_load_dwordx4 v[8:11], v[8:9], off nt
.LBB0_163:
	s_or_b64 exec, exec, s[16:17]
	v_mov_b32_e32 v16, 0
	v_mov_b32_e32 v20, 0
	v_mov_b32_e32 v21, 0
	v_mov_b32_e32 v22, 0
	v_mov_b32_e32 v23, 0
	s_and_saveexec_b64 s[16:17], vcc
	s_cbranch_execz .LBB0_165
	v_add_u32_e32 v17, s18, v74
	v_ashrrev_i32_e32 v18, 31, v17
	v_mul_lo_u32 v20, s14, v18
	v_mul_lo_u32 v21, s15, v17
	v_mad_u64_u32 v[18:19], s[20:21], s14, v17, 0
	v_add3_u32 v19, v19, v20, v21
	s_waitcnt lgkmcnt(0)
	v_lshl_add_u64 v[18:19], v[18:19], 2, s[12:13]
	v_mov_b32_e32 v67, v65
	v_lshl_add_u64 v[18:19], v[66:67], 2, v[18:19]
	global_load_dwordx4 v[20:23], v[18:19], off nt
.LBB0_165:
	s_or_b64 exec, exec, s[16:17]
	v_mov_b32_e32 v17, 0
	v_mov_b32_e32 v18, 0
	v_mov_b32_e32 v19, 0
	s_and_saveexec_b64 s[16:17], vcc
	s_cbranch_execz .LBB0_167
	v_add_u32_e32 v16, s18, v75
	v_ashrrev_i32_e32 v17, 31, v16
	v_mul_lo_u32 v18, s14, v17
	v_mul_lo_u32 v19, s15, v16
	v_mad_u64_u32 v[16:17], s[20:21], s14, v16, 0
	v_add3_u32 v17, v17, v18, v19
	s_waitcnt lgkmcnt(0)
	v_lshl_add_u64 v[16:17], v[16:17], 2, s[12:13]
	v_mov_b32_e32 v67, v65
	v_lshl_add_u64 v[16:17], v[66:67], 2, v[16:17]
	global_load_dwordx4 v[16:19], v[16:17], off nt
.LBB0_167:
	s_or_b64 exec, exec, s[16:17]
	v_mov_b32_e32 v43, 0
	v_mov_b32_e32 v44, 0
	v_mov_b32_e32 v45, 0
	v_mov_b32_e32 v46, 0
	v_mov_b32_e32 v47, 0
	s_and_saveexec_b64 s[16:17], vcc
	s_cbranch_execz .LBB0_169
	v_add_u32_e32 v40, s18, v76
	v_ashrrev_i32_e32 v41, 31, v40
	v_mul_lo_u32 v42, s14, v41
	v_mul_lo_u32 v44, s15, v40
	v_mad_u64_u32 v[40:41], s[20:21], s14, v40, 0
	v_add3_u32 v41, v41, v42, v44
	s_waitcnt lgkmcnt(0)
	v_lshl_add_u64 v[40:41], v[40:41], 2, s[12:13]
	v_mov_b32_e32 v67, v65
	v_lshl_add_u64 v[40:41], v[66:67], 2, v[40:41]
	global_load_dwordx4 v[44:47], v[40:41], off nt
.LBB0_169:
	s_or_b64 exec, exec, s[16:17]
	v_mov_b32_e32 v42, 0
	v_mov_b32_e32 v41, 0
	v_mov_b32_e32 v40, 0
	s_and_saveexec_b64 s[16:17], vcc
	s_cbranch_execz .LBB0_171
	v_add_u32_e32 v40, s18, v69
	v_ashrrev_i32_e32 v41, 31, v40
	v_mul_lo_u32 v42, s14, v41
	v_mul_lo_u32 v43, s15, v40
	v_mad_u64_u32 v[40:41], s[14:15], s14, v40, 0
	v_add3_u32 v41, v41, v42, v43
	s_waitcnt lgkmcnt(0)
	v_lshl_add_u64 v[40:41], v[40:41], 2, s[12:13]
	v_mov_b32_e32 v67, v65
	v_lshl_add_u64 v[40:41], v[66:67], 2, v[40:41]
	global_load_dwordx4 v[40:43], v[40:41], off nt

.LBB0_238:
	ds_write2_b32 v78, v24, v25 offset1:1
	ds_write2_b32 v78, v26, v27 offset0:2 offset1:3
	ds_write2_b32 v79, v28, v29 offset1:1
	ds_write2_b32 v80, v30, v31 offset1:1
	ds_write2_b32 v81, v32, v33 offset1:1
	ds_write2_b32 v82, v34, v35 offset1:1
	ds_write2_b32 v83, v36, v37 offset1:1
	ds_write2_b32 v84, v38, v39 offset1:1
	ds_write2_b32 v85, v48, v49 offset1:1
	ds_write2_b32 v86, v50, v51 offset1:1
	ds_write2_b32 v87, v52, v53 offset1:1
	ds_write2_b32 v88, v54, v55 offset1:1
	ds_write2_b32 v89, v56, v57 offset1:1
	ds_write2_b32 v90, v58, v59 offset1:1
	ds_write2_b32 v91, v60, v61 offset1:1
	ds_write2_b32 v92, v62, v63 offset1:1
	s_waitcnt lgkmcnt(0)
	ds_read2_b32 v[66:67], v77 offset1:8
	ds_read2_b32 v[84:85], v77 offset0:33 offset1:41
	ds_read2_b32 v[86:87], v77 offset0:66 offset1:74
	ds_read2_b32 v[88:89], v77 offset0:99 offset1:107
	ds_read2_b32 v[90:91], v77 offset0:132 offset1:140
	s_waitcnt lgkmcnt(0)
	v_bfe_u32 v79, v66, 16, 1
	v_add3_u32 v66, v66, v79, s35
	v_bfe_u32 v79, v84, 16, 1
	v_lshrrev_b32_e32 v66, 16, v66
	v_add3_u32 v79, v84, v79, s35
	ds_read2_b32 v[92:93], v77 offset0:165 offset1:173
	v_and_or_b32 v80, v79, s36, v66
	v_bfe_u32 v66, v86, 16, 1
	v_add3_u32 v66, v86, v66, s35
	v_bfe_u32 v79, v88, 16, 1
	ds_read2_b32 v[94:95], v77 offset0:198 offset1:206
	v_lshrrev_b32_e32 v66, 16, v66
	v_add3_u32 v79, v88, v79, s35
	ds_read2_b32 v[96:97], v77 offset0:231 offset1:239
	v_and_or_b32 v81, v79, s36, v66
	v_bfe_u32 v66, v90, 16, 1
	v_add3_u32 v66, v90, v66, s35
	s_waitcnt lgkmcnt(2)
	v_bfe_u32 v79, v92, 16, 1
	v_lshrrev_b32_e32 v66, 16, v66
	v_add3_u32 v79, v92, v79, s35
	v_and_or_b32 v82, v79, s36, v66
	s_waitcnt lgkmcnt(1)
	v_bfe_u32 v66, v94, 16, 1
	v_add3_u32 v66, v94, v66, s35
	s_waitcnt lgkmcnt(0)
	v_bfe_u32 v79, v96, 16, 1
	v_lshrrev_b32_e32 v66, 16, v66
	v_add3_u32 v79, v96, v79, s35
	v_and_or_b32 v83, v79, s36, v66
	v_add_u32_e32 v66, s22, v68
	v_ashrrev_i32_e32 v79, 31, v66
	v_mul_lo_u32 v79, s14, v79
	v_mul_lo_u32 v84, s15, v66
	v_mad_u64_u32 v[98:99], s[20:21], s14, v66, 0
	v_add3_u32 v99, v99, v79, v84
	s_ashr_i32 s19, s18, 31
	v_lshl_add_u64 v[98:99], v[98:99], 1, s[16:17]
	s_lshl_b64 s[18:19], s[18:19], 1
	v_bfe_u32 v66, v67, 16, 1
	v_lshl_add_u64 v[98:99], v[98:99], 0, s[18:19]
	v_add3_u32 v66, v67, v66, s35
	v_bfe_u32 v67, v85, 16, 1
	v_lshl_add_u64 v[98:99], v[98:99], 0, v[64:65]
	v_lshrrev_b32_e32 v66, 16, v66
	v_add3_u32 v67, v85, v67, s35
	global_store_dwordx4 v[98:99], v[80:83], off nt
	s_add_i32 s37, s38, s24
	s_add_i32 s25, s25, s26
	v_and_or_b32 v80, v67, s36, v66
	v_bfe_u32 v66, v87, 16, 1
	v_add3_u32 v66, v87, v66, s35
	v_bfe_u32 v67, v89, 16, 1
	v_lshrrev_b32_e32 v66, 16, v66
	v_add3_u32 v67, v89, v67, s35
	v_and_or_b32 v81, v67, s36, v66
	v_bfe_u32 v66, v91, 16, 1
	v_add3_u32 v66, v91, v66, s35
	v_bfe_u32 v67, v93, 16, 1
	v_lshrrev_b32_e32 v66, 16, v66
	v_add3_u32 v67, v93, v67, s35
	v_and_or_b32 v82, v67, s36, v66
	v_bfe_u32 v66, v95, 16, 1
	v_add3_u32 v66, v95, v66, s35
	v_bfe_u32 v67, v97, 16, 1
	v_lshrrev_b32_e32 v66, 16, v66
	v_add3_u32 v67, v97, v67, s35
	v_and_or_b32 v83, v67, s36, v66
	v_add_u32_e32 v66, s22, v70
	v_ashrrev_i32_e32 v67, 31, v66
	v_mul_lo_u32 v79, s14, v67
	v_mul_lo_u32 v84, s15, v66
	v_mad_u64_u32 v[66:67], s[20:21], s14, v66, 0
	v_add3_u32 v67, v67, v79, v84
	v_lshl_add_u64 v[66:67], v[66:67], 1, s[16:17]
	v_lshl_add_u64 v[66:67], v[66:67], 0, s[18:19]
	ds_read2_b32 v[84:85], v77 offset0:16 offset1:24
	v_lshl_add_u64 v[66:67], v[66:67], 0, v[64:65]
	global_store_dwordx4 v[66:67], v[80:83], off nt
	ds_read2_b32 v[66:67], v77 offset0:49 offset1:57
	ds_read2_b32 v[86:87], v77 offset0:82 offset1:90
	ds_read2_b32 v[88:89], v77 offset0:115 offset1:123
	s_waitcnt lgkmcnt(3)
	v_bfe_u32 v79, v84, 16, 1
	v_add3_u32 v79, v84, v79, s35
	s_waitcnt lgkmcnt(2)
	v_bfe_u32 v80, v66, 16, 1
	ds_read2_b32 v[90:91], v77 offset0:148 offset1:156
	v_lshrrev_b32_e32 v79, 16, v79
	v_add3_u32 v66, v66, v80, s35
	ds_read2_b32 v[92:93], v77 offset0:181 offset1:189
	v_and_or_b32 v80, v66, s36, v79
	s_waitcnt lgkmcnt(3)
	v_bfe_u32 v66, v86, 16, 1
	v_add3_u32 v66, v86, v66, s35
	s_waitcnt lgkmcnt(2)
	v_bfe_u32 v79, v88, 16, 1
	ds_read2_b32 v[94:95], v77 offset0:214 offset1:222
	v_lshrrev_b32_e32 v66, 16, v66
	v_add3_u32 v79, v88, v79, s35
	ds_read2_b32 v[96:97], v77 offset0:247 offset1:255
	v_and_or_b32 v81, v79, s36, v66
	s_waitcnt lgkmcnt(3)
	v_bfe_u32 v66, v90, 16, 1
	v_add3_u32 v66, v90, v66, s35
	s_waitcnt lgkmcnt(2)
	v_bfe_u32 v79, v92, 16, 1
	v_lshrrev_b32_e32 v66, 16, v66
	v_add3_u32 v79, v92, v79, s35
	v_and_or_b32 v82, v79, s36, v66
	s_waitcnt lgkmcnt(1)
	v_bfe_u32 v66, v94, 16, 1
	v_add3_u32 v66, v94, v66, s35
	s_waitcnt lgkmcnt(0)
	v_bfe_u32 v79, v96, 16, 1
	v_lshrrev_b32_e32 v66, 16, v66
	v_add3_u32 v79, v96, v79, s35
	v_and_or_b32 v83, v79, s36, v66
	v_add_u32_e32 v66, s22, v71
	v_ashrrev_i32_e32 v79, 31, v66
	v_mul_lo_u32 v79, s14, v79
	v_mul_lo_u32 v84, s15, v66
	v_mad_u64_u32 v[98:99], s[20:21], s14, v66, 0
	v_add3_u32 v99, v99, v79, v84
	v_lshl_add_u64 v[98:99], v[98:99], 1, s[16:17]
	v_bfe_u32 v66, v85, 16, 1
	v_lshl_add_u64 v[98:99], v[98:99], 0, s[18:19]
	v_add3_u32 v66, v85, v66, s35
	v_bfe_u32 v79, v67, 16, 1
	v_lshl_add_u64 v[98:99], v[98:99], 0, v[64:65]
	v_lshrrev_b32_e32 v66, 16, v66
	v_add3_u32 v67, v67, v79, s35
	global_store_dwordx4 v[98:99], v[80:83], off nt
	s_cmp_gt_i32 s37, 0x18fff
	s_nop 0
	v_and_or_b32 v80, v67, s36, v66
	v_bfe_u32 v66, v87, 16, 1
	v_add3_u32 v66, v87, v66, s35
	v_bfe_u32 v67, v89, 16, 1
	v_lshrrev_b32_e32 v66, 16, v66
	v_add3_u32 v67, v89, v67, s35
	v_and_or_b32 v81, v67, s36, v66
	v_bfe_u32 v66, v91, 16, 1
	v_add3_u32 v66, v91, v66, s35
	v_bfe_u32 v67, v93, 16, 1
	v_lshrrev_b32_e32 v66, 16, v66
	v_add3_u32 v67, v93, v67, s35
	v_and_or_b32 v82, v67, s36, v66
	v_bfe_u32 v66, v95, 16, 1
	v_add3_u32 v66, v95, v66, s35
	v_bfe_u32 v67, v97, 16, 1
	v_lshrrev_b32_e32 v66, 16, v66
	v_add3_u32 v67, v97, v67, s35
	v_and_or_b32 v83, v67, s36, v66
	v_add_u32_e32 v66, s22, v72
	v_ashrrev_i32_e32 v67, 31, v66
	v_mul_lo_u32 v79, s14, v67
	v_mul_lo_u32 v84, s15, v66
	v_mad_u64_u32 v[66:67], s[14:15], s14, v66, 0
	v_add3_u32 v67, v67, v79, v84
	v_lshl_add_u64 v[66:67], v[66:67], 1, s[16:17]
	v_lshl_add_u64 v[66:67], v[66:67], 0, s[18:19]
	v_lshl_add_u64 v[66:67], v[66:67], 0, v[64:65]
	global_store_dwordx4 v[66:67], v[80:83], off nt
	s_waitcnt lgkmcnt(0)
	s_cselect_b64 s[14:15], -1, 0

.LBB0_273:
	v_cmp_lt_i32_e32 vcc, -1, v66
	v_mov_b32_e32 v28, 0
	v_mov_b32_e32 v24, 0
	v_mov_b32_e32 v25, 0
	v_mov_b32_e32 v26, 0
	v_mov_b32_e32 v27, 0
	s_and_saveexec_b64 s[20:21], vcc
	s_cbranch_execz .LBB0_275
	v_add_u32_e32 v24, s22, v68
	v_ashrrev_i32_e32 v25, 31, v24
	v_mul_lo_u32 v26, s18, v25
	v_mul_lo_u32 v27, s19, v24
	v_mad_u64_u32 v[24:25], s[40:41], s18, v24, 0
	v_add3_u32 v25, v25, v26, v27
	s_waitcnt lgkmcnt(0)
	v_lshl_add_u64 v[24:25], v[24:25], 2, s[16:17]
	v_mov_b32_e32 v67, v65
	v_lshl_add_u64 v[24:25], v[66:67], 2, v[24:25]
	global_load_dwordx4 v[24:27], v[24:25], off nt
.LBB0_275:
	s_or_b64 exec, exec, s[20:21]
	v_mov_b32_e32 v29, 0
	v_mov_b32_e32 v30, 0
	v_mov_b32_e32 v31, 0
	s_and_saveexec_b64 s[20:21], vcc
	s_cbranch_execz .LBB0_277
	v_add_u32_e32 v28, s22, v70
	v_ashrrev_i32_e32 v29, 31, v28
	v_mul_lo_u32 v30, s18, v29
	v_mul_lo_u32 v31, s19, v28
	v_mad_u64_u32 v[28:29], s[40:41], s18, v28, 0
	v_add3_u32 v29, v29, v30, v31
	s_waitcnt lgkmcnt(0)
	v_lshl_add_u64 v[28:29], v[28:29], 2, s[16:17]
	v_mov_b32_e32 v67, v65
	v_lshl_add_u64 v[28:29], v[66:67], 2, v[28:29]
	global_load_dwordx4 v[28:31], v[28:29], off nt
.LBB0_277:
	s_or_b64 exec, exec, s[20:21]
	v_mov_b32_e32 v36, 0
	v_mov_b32_e32 v32, 0
	v_mov_b32_e32 v33, 0
	v_mov_b32_e32 v34, 0
	v_mov_b32_e32 v35, 0
	s_and_saveexec_b64 s[20:21], vcc
	s_cbranch_execz .LBB0_279
	v_add_u32_e32 v32, s22, v71
	v_ashrrev_i32_e32 v33, 31, v32
	v_mul_lo_u32 v34, s18, v33
	v_mul_lo_u32 v35, s19, v32
	v_mad_u64_u32 v[32:33], s[40:41], s18, v32, 0
	v_add3_u32 v33, v33, v34, v35
	s_waitcnt lgkmcnt(0)
	v_lshl_add_u64 v[32:33], v[32:33], 2, s[16:17]
	v_mov_b32_e32 v67, v65
	v_lshl_add_u64 v[32:33], v[66:67], 2, v[32:33]
	global_load_dwordx4 v[32:35], v[32:33], off nt
.LBB0_279:
	s_or_b64 exec, exec, s[20:21]
	v_mov_b32_e32 v37, 0
	v_mov_b32_e32 v38, 0
	v_mov_b32_e32 v39, 0
	s_and_saveexec_b64 s[20:21], vcc
	s_cbranch_execz .LBB0_281
	v_add_u32_e32 v36, s22, v72
	v_ashrrev_i32_e32 v37, 31, v36
	v_mul_lo_u32 v38, s18, v37
	v_mul_lo_u32 v39, s19, v36
	v_mad_u64_u32 v[36:37], s[40:41], s18, v36, 0
	v_add3_u32 v37, v37, v38, v39
	s_waitcnt lgkmcnt(0)
	v_lshl_add_u64 v[36:37], v[36:37], 2, s[16:17]
	v_mov_b32_e32 v67, v65
	v_lshl_add_u64 v[36:37], v[66:67], 2, v[36:37]
	global_load_dwordx4 v[36:39], v[36:37], off nt
.LBB0_281:
	s_or_b64 exec, exec, s[20:21]
	v_mov_b32_e32 v52, 0
	v_mov_b32_e32 v48, 0
	v_mov_b32_e32 v49, 0
	v_mov_b32_e32 v50, 0
	v_mov_b32_e32 v51, 0
	s_and_saveexec_b64 s[20:21], vcc
	s_cbranch_execz .LBB0_283
	v_add_u32_e32 v48, s22, v74
	v_ashrrev_i32_e32 v49, 31, v48
	v_mul_lo_u32 v50, s18, v49
	v_mul_lo_u32 v51, s19, v48
	v_mad_u64_u32 v[48:49], s[40:41], s18, v48, 0
	v_add3_u32 v49, v49, v50, v51
	s_waitcnt lgkmcnt(0)
	v_lshl_add_u64 v[48:49], v[48:49], 2, s[16:17]
	v_mov_b32_e32 v67, v65
	v_lshl_add_u64 v[48:49], v[66:67], 2, v[48:49]
	global_load_dwordx4 v[48:51], v[48:49], off nt
.LBB0_283:
	s_or_b64 exec, exec, s[20:21]
	v_mov_b32_e32 v53, 0
	v_mov_b32_e32 v54, 0
	v_mov_b32_e32 v55, 0
	s_and_saveexec_b64 s[20:21], vcc
	s_cbranch_execz .LBB0_285
	v_add_u32_e32 v52, s22, v75
	v_ashrrev_i32_e32 v53, 31, v52
	v_mul_lo_u32 v54, s18, v53
	v_mul_lo_u32 v55, s19, v52
	v_mad_u64_u32 v[52:53], s[40:41], s18, v52, 0
	v_add3_u32 v53, v53, v54, v55
	s_waitcnt lgkmcnt(0)
	v_lshl_add_u64 v[52:53], v[52:53], 2, s[16:17]
	v_mov_b32_e32 v67, v65
	v_lshl_add_u64 v[52:53], v[66:67], 2, v[52:53]
	global_load_dwordx4 v[52:55], v[52:53], off nt
.LBB0_285:
	s_or_b64 exec, exec, s[20:21]
	v_mov_b32_e32 v63, 0
	v_mov_b32_e32 v56, 0
	v_mov_b32_e32 v57, 0
	v_mov_b32_e32 v58, 0
	v_mov_b32_e32 v59, 0
	s_and_saveexec_b64 s[20:21], vcc
	s_cbranch_execz .LBB0_287
	v_add_u32_e32 v56, s22, v76
	v_ashrrev_i32_e32 v57, 31, v56
	v_mul_lo_u32 v58, s18, v57
	v_mul_lo_u32 v59, s19, v56
	v_mad_u64_u32 v[56:57], s[40:41], s18, v56, 0
	v_add3_u32 v57, v57, v58, v59
	s_waitcnt lgkmcnt(0)
	v_lshl_add_u64 v[56:57], v[56:57], 2, s[16:17]
	v_mov_b32_e32 v67, v65
	v_lshl_add_u64 v[56:57], v[66:67], 2, v[56:57]
	global_load_dwordx4 v[56:59], v[56:57], off nt
.LBB0_287:
	s_or_b64 exec, exec, s[20:21]
	v_mov_b32_e32 v62, 0
	v_mov_b32_e32 v61, 0
	v_mov_b32_e32 v60, 0
	s_and_saveexec_b64 s[20:21], vcc
	s_cbranch_execz .LBB0_289
	v_add_u32_e32 v60, s22, v69
	v_ashrrev_i32_e32 v61, 31, v60
	v_mul_lo_u32 v62, s18, v61
	v_mul_lo_u32 v63, s19, v60
	v_mad_u64_u32 v[60:61], s[18:19], s18, v60, 0
	v_add3_u32 v61, v61, v62, v63
	s_waitcnt lgkmcnt(0)
	v_lshl_add_u64 v[60:61], v[60:61], 2, s[16:17]
	v_mov_b32_e32 v67, v65
	v_lshl_add_u64 v[60:61], v[66:67], 2, v[60:61]
	global_load_dwordx4 v[60:63], v[60:61], off nt

.LBB0_302:
	v_add_u32_e32 v79, 0x420, v78
	v_add_u32_e32 v80, 0x428, v78
	v_add_u32_e32 v81, 0x840, v78
	v_add_u32_e32 v82, 0x848, v78
	v_add_u32_e32 v83, 0xc60, v78
	v_add_u32_e32 v84, 0xc68, v78
	v_add_u32_e32 v85, 0x1080, v78
	v_add_u32_e32 v86, 0x1088, v78
	v_add_u32_e32 v87, 0x14a0, v78
	v_add_u32_e32 v88, 0x14a8, v78
	v_add_u32_e32 v89, 0x18c0, v78
	v_add_u32_e32 v90, 0x18c8, v78
	v_add_u32_e32 v91, 0x1ce0, v78
	v_add_u32_e32 v92, 0x1ce8, v78
	s_waitcnt vmcnt(0)
	ds_write2_b32 v78, v4, v5 offset1:1
	ds_write2_b32 v78, v6, v7 offset0:2 offset1:3
	ds_write2_b32 v79, v0, v1 offset1:1
	ds_write2_b32 v80, v2, v3 offset1:1
	ds_write2_b32 v81, v12, v13 offset1:1
	ds_write2_b32 v82, v14, v15 offset1:1
	ds_write2_b32 v83, v8, v9 offset1:1
	ds_write2_b32 v84, v10, v11 offset1:1
	ds_write2_b32 v85, v20, v21 offset1:1
	ds_write2_b32 v86, v22, v23 offset1:1
	ds_write2_b32 v87, v16, v17 offset1:1
	ds_write2_b32 v88, v18, v19 offset1:1
	ds_write2_b32 v89, v44, v45 offset1:1
	ds_write2_b32 v90, v46, v47 offset1:1
	ds_write2_b32 v91, v40, v41 offset1:1
	ds_write2_b32 v92, v42, v43 offset1:1
	s_waitcnt lgkmcnt(0)
	ds_read2_b32 v[66:67], v77 offset1:8
	ds_read2_b32 v[98:99], v77 offset0:33 offset1:41
	ds_read2_b32 v[100:101], v77 offset0:66 offset1:74
	ds_read2_b32 v[102:103], v77 offset0:99 offset1:107
	ds_read2_b32 v[104:105], v77 offset0:132 offset1:140
	s_waitcnt lgkmcnt(0)
	v_bfe_u32 v93, v66, 16, 1
	v_add3_u32 v66, v66, v93, s35
	v_bfe_u32 v93, v98, 16, 1
	v_lshrrev_b32_e32 v66, 16, v66
	v_add3_u32 v93, v98, v93, s35
	ds_read2_b32 v[106:107], v77 offset0:165 offset1:173
	v_and_or_b32 v94, v93, s36, v66
	v_bfe_u32 v66, v100, 16, 1
	v_add3_u32 v66, v100, v66, s35
	v_bfe_u32 v93, v102, 16, 1
	ds_read2_b32 v[108:109], v77 offset0:198 offset1:206
	v_lshrrev_b32_e32 v66, 16, v66
	v_add3_u32 v93, v102, v93, s35
	ds_read2_b32 v[110:111], v77 offset0:231 offset1:239
	v_and_or_b32 v95, v93, s36, v66
	v_bfe_u32 v66, v104, 16, 1
	v_add3_u32 v66, v104, v66, s35
	s_waitcnt lgkmcnt(2)
	v_bfe_u32 v93, v106, 16, 1
	v_lshrrev_b32_e32 v66, 16, v66
	v_add3_u32 v93, v106, v93, s35
	v_and_or_b32 v96, v93, s36, v66
	s_waitcnt lgkmcnt(1)
	v_bfe_u32 v66, v108, 16, 1
	v_add3_u32 v66, v108, v66, s35
	s_waitcnt lgkmcnt(0)
	v_bfe_u32 v93, v110, 16, 1
	v_lshrrev_b32_e32 v66, 16, v66
	v_add3_u32 v93, v110, v93, s35
	v_and_or_b32 v97, v93, s36, v66
	v_add_u32_e32 v66, s39, v68
	v_ashrrev_i32_e32 v93, 31, v66
	v_mul_lo_u32 v93, s16, v93
	v_mul_lo_u32 v98, s17, v66
	v_mad_u64_u32 v[112:113], s[22:23], s16, v66, 0
	v_add3_u32 v113, v113, v93, v98
	s_ashr_i32 s21, s20, 31
	v_lshl_add_u64 v[112:113], v[112:113], 1, s[18:19]
	s_lshl_b64 s[20:21], s[20:21], 1
	v_bfe_u32 v66, v67, 16, 1
	v_lshl_add_u64 v[112:113], v[112:113], 0, s[20:21]
	v_add3_u32 v66, v67, v66, s35
	v_bfe_u32 v67, v99, 16, 1
	v_lshl_add_u64 v[112:113], v[112:113], 0, v[64:65]
	v_lshrrev_b32_e32 v66, 16, v66
	v_add3_u32 v67, v99, v67, s35
	global_store_dwordx4 v[112:113], v[94:97], off nt
	s_andn2_b64 vcc, exec, s[14:15]
	s_mov_b64 s[14:15], -1
	v_and_or_b32 v94, v67, s36, v66
	v_bfe_u32 v66, v101, 16, 1
	v_add3_u32 v66, v101, v66, s35
	v_bfe_u32 v67, v103, 16, 1
	v_lshrrev_b32_e32 v66, 16, v66
	v_add3_u32 v67, v103, v67, s35
	v_and_or_b32 v95, v67, s36, v66
	v_bfe_u32 v66, v105, 16, 1
	v_add3_u32 v66, v105, v66, s35
	v_bfe_u32 v67, v107, 16, 1
	v_lshrrev_b32_e32 v66, 16, v66
	v_add3_u32 v67, v107, v67, s35
	v_and_or_b32 v96, v67, s36, v66
	v_bfe_u32 v66, v109, 16, 1
	v_add3_u32 v66, v109, v66, s35
	v_bfe_u32 v67, v111, 16, 1
	v_lshrrev_b32_e32 v66, 16, v66
	v_add3_u32 v67, v111, v67, s35
	v_and_or_b32 v97, v67, s36, v66
	v_add_u32_e32 v66, s39, v70
	v_ashrrev_i32_e32 v67, 31, v66
	v_mul_lo_u32 v93, s16, v67
	v_mul_lo_u32 v98, s17, v66
	v_mad_u64_u32 v[66:67], s[22:23], s16, v66, 0
	v_add3_u32 v67, v67, v93, v98
	v_lshl_add_u64 v[66:67], v[66:67], 1, s[18:19]
	v_lshl_add_u64 v[66:67], v[66:67], 0, s[20:21]
	ds_read2_b32 v[98:99], v77 offset0:16 offset1:24
	v_lshl_add_u64 v[66:67], v[66:67], 0, v[64:65]
	global_store_dwordx4 v[66:67], v[94:97], off nt
	ds_read2_b32 v[66:67], v77 offset0:49 offset1:57
	ds_read2_b32 v[100:101], v77 offset0:82 offset1:90
	ds_read2_b32 v[102:103], v77 offset0:115 offset1:123
	s_waitcnt lgkmcnt(3)
	v_bfe_u32 v93, v98, 16, 1
	v_add3_u32 v93, v98, v93, s35
	s_waitcnt lgkmcnt(2)
	v_bfe_u32 v94, v66, 16, 1
	ds_read2_b32 v[104:105], v77 offset0:148 offset1:156
	v_lshrrev_b32_e32 v93, 16, v93
	v_add3_u32 v66, v66, v94, s35
	ds_read2_b32 v[106:107], v77 offset0:181 offset1:189
	v_and_or_b32 v94, v66, s36, v93
	s_waitcnt lgkmcnt(3)
	v_bfe_u32 v66, v100, 16, 1
	v_add3_u32 v66, v100, v66, s35
	s_waitcnt lgkmcnt(2)
	v_bfe_u32 v93, v102, 16, 1
	ds_read2_b32 v[108:109], v77 offset0:214 offset1:222
	v_lshrrev_b32_e32 v66, 16, v66
	v_add3_u32 v93, v102, v93, s35
	ds_read2_b32 v[110:111], v77 offset0:247 offset1:255
	v_and_or_b32 v95, v93, s36, v66
	s_waitcnt lgkmcnt(3)
	v_bfe_u32 v66, v104, 16, 1
	v_add3_u32 v66, v104, v66, s35
	s_waitcnt lgkmcnt(2)
	v_bfe_u32 v93, v106, 16, 1
	v_lshrrev_b32_e32 v66, 16, v66
	v_add3_u32 v93, v106, v93, s35
	v_and_or_b32 v96, v93, s36, v66
	s_waitcnt lgkmcnt(1)
	v_bfe_u32 v66, v108, 16, 1
	v_add3_u32 v66, v108, v66, s35
	s_waitcnt lgkmcnt(0)
	v_bfe_u32 v93, v110, 16, 1
	v_lshrrev_b32_e32 v66, 16, v66
	v_add3_u32 v93, v110, v93, s35
	v_and_or_b32 v97, v93, s36, v66
	v_add_u32_e32 v66, s39, v71
	v_ashrrev_i32_e32 v93, 31, v66
	v_mul_lo_u32 v93, s16, v93
	v_mul_lo_u32 v98, s17, v66
	v_mad_u64_u32 v[112:113], s[22:23], s16, v66, 0
	v_add3_u32 v113, v113, v93, v98
	v_lshl_add_u64 v[112:113], v[112:113], 1, s[18:19]
	v_bfe_u32 v66, v99, 16, 1
	v_lshl_add_u64 v[112:113], v[112:113], 0, s[20:21]
	v_add3_u32 v66, v99, v66, s35
	v_bfe_u32 v93, v67, 16, 1
	v_lshl_add_u64 v[112:113], v[112:113], 0, v[64:65]
	v_lshrrev_b32_e32 v66, 16, v66
	v_add3_u32 v67, v67, v93, s35
	global_store_dwordx4 v[112:113], v[94:97], off nt
	s_nop 1
	v_and_or_b32 v94, v67, s36, v66
	v_bfe_u32 v66, v101, 16, 1
	v_add3_u32 v66, v101, v66, s35
	v_bfe_u32 v67, v103, 16, 1
	v_lshrrev_b32_e32 v66, 16, v66
	v_add3_u32 v67, v103, v67, s35
	v_and_or_b32 v95, v67, s36, v66
	v_bfe_u32 v66, v105, 16, 1
	v_add3_u32 v66, v105, v66, s35
	v_bfe_u32 v67, v107, 16, 1
	v_lshrrev_b32_e32 v66, 16, v66
	v_add3_u32 v67, v107, v67, s35
	v_and_or_b32 v96, v67, s36, v66
	v_bfe_u32 v66, v109, 16, 1
	v_add3_u32 v66, v109, v66, s35
	v_bfe_u32 v67, v111, 16, 1
	v_lshrrev_b32_e32 v66, 16, v66
	v_add3_u32 v67, v111, v67, s35
	v_and_or_b32 v97, v67, s36, v66
	v_add_u32_e32 v66, s39, v72
	v_ashrrev_i32_e32 v67, 31, v66
	v_mul_lo_u32 v93, s16, v67
	v_mul_lo_u32 v98, s17, v66
	v_mad_u64_u32 v[66:67], s[16:17], s16, v66, 0
	v_add3_u32 v67, v67, v93, v98
	v_lshl_add_u64 v[66:67], v[66:67], 1, s[18:19]
	v_lshl_add_u64 v[66:67], v[66:67], 0, s[20:21]
	v_lshl_add_u64 v[66:67], v[66:67], 0, v[64:65]
	global_store_dwordx4 v[66:67], v[94:97], off nt
	s_waitcnt lgkmcnt(0)
	s_cbranch_vccnz .LBB0_239
	s_add_i32 s21, s28, s37
	s_cmp_gt_i32 s21, 0x18fff
	s_cbranch_scc1 .LBB0_353
	s_cmpk_gt_i32 s21, 0x6dff
	s_cbranch_scc0 .LBB0_308
	s_cmpk_gt_u32 s21, 0x8dff
	s_cbranch_scc0 .LBB0_309
	s_cmp_gt_u32 s21, 0x139ff
	s_cbranch_scc0 .LBB0_310
	s_load_dwordx2 s[14:15], s[2:3], 0x78
	s_add_i32 s16, s21, 0xfffec600
	s_add_i32 s17, s26, s25
	s_and_b32 s17, s17, 0xfe0
	s_lshr_b32 s16, s16, 1
	v_or_b32_e32 v66, s17, v73
	s_and_b32 s20, s16, 0x7fffffc0
	s_mov_b64 s[16:17], 0x1000
	s_cbranch_execz .LBB0_311
	s_branch .LBB0_312

.LBB0_336:
	v_cmp_lt_i32_e32 vcc, -1, v66
	v_mov_b32_e32 v0, 0
	v_mov_b32_e32 v4, 0
	v_mov_b32_e32 v5, 0
	v_mov_b32_e32 v6, 0
	v_mov_b32_e32 v7, 0
	s_and_saveexec_b64 s[18:19], vcc
	s_cbranch_execz .LBB0_338
	v_add_u32_e32 v1, s20, v68
	v_ashrrev_i32_e32 v2, 31, v1
	v_mul_lo_u32 v4, s16, v2
	v_mul_lo_u32 v5, s17, v1
	v_mad_u64_u32 v[2:3], s[22:23], s16, v1, 0
	v_add3_u32 v3, v3, v4, v5
	s_waitcnt lgkmcnt(0)
	v_lshl_add_u64 v[2:3], v[2:3], 2, s[14:15]
	v_mov_b32_e32 v67, v65
	v_lshl_add_u64 v[2:3], v[66:67], 2, v[2:3]
	global_load_dwordx4 v[4:7], v[2:3], off nt
.LBB0_338:
	s_or_b64 exec, exec, s[18:19]
	v_mov_b32_e32 v1, 0
	v_mov_b32_e32 v2, 0
	v_mov_b32_e32 v3, 0
	s_and_saveexec_b64 s[18:19], vcc
	s_cbranch_execz .LBB0_340
	v_add_u32_e32 v0, s20, v70
	v_ashrrev_i32_e32 v1, 31, v0
	v_mul_lo_u32 v2, s16, v1
	v_mul_lo_u32 v3, s17, v0
	v_mad_u64_u32 v[0:1], s[22:23], s16, v0, 0
	v_add3_u32 v1, v1, v2, v3
	s_waitcnt lgkmcnt(0)
	v_lshl_add_u64 v[0:1], v[0:1], 2, s[14:15]
	v_mov_b32_e32 v67, v65
	v_lshl_add_u64 v[0:1], v[66:67], 2, v[0:1]
	global_load_dwordx4 v[0:3], v[0:1], off nt
.LBB0_340:
	s_or_b64 exec, exec, s[18:19]
	v_mov_b32_e32 v8, 0
	v_mov_b32_e32 v12, 0
	v_mov_b32_e32 v13, 0
	v_mov_b32_e32 v14, 0
	v_mov_b32_e32 v15, 0
	s_and_saveexec_b64 s[18:19], vcc
	s_cbranch_execz .LBB0_342
	v_add_u32_e32 v9, s20, v71
	v_ashrrev_i32_e32 v10, 31, v9
	v_mul_lo_u32 v12, s16, v10
	v_mul_lo_u32 v13, s17, v9
	v_mad_u64_u32 v[10:11], s[22:23], s16, v9, 0
	v_add3_u32 v11, v11, v12, v13
	s_waitcnt lgkmcnt(0)
	v_lshl_add_u64 v[10:11], v[10:11], 2, s[14:15]
	v_mov_b32_e32 v67, v65
	v_lshl_add_u64 v[10:11], v[66:67], 2, v[10:11]
	global_load_dwordx4 v[12:15], v[10:11], off nt
.LBB0_342:
	s_or_b64 exec, exec, s[18:19]
	v_mov_b32_e32 v9, 0
	v_mov_b32_e32 v10, 0
	v_mov_b32_e32 v11, 0
	s_and_saveexec_b64 s[18:19], vcc
	s_cbranch_execz .LBB0_344
	v_add_u32_e32 v8, s20, v72
	v_ashrrev_i32_e32 v9, 31, v8
	v_mul_lo_u32 v10, s16, v9
	v_mul_lo_u32 v11, s17, v8
	v_mad_u64_u32 v[8:9], s[22:23], s16, v8, 0
	v_add3_u32 v9, v9, v10, v11
	s_waitcnt lgkmcnt(0)
	v_lshl_add_u64 v[8:9], v[8:9], 2, s[14:15]
	v_mov_b32_e32 v67, v65
	v_lshl_add_u64 v[8:9], v[66:67], 2, v[8:9]
	global_load_dwordx4 v[8:11], v[8:9], off nt
.LBB0_344:
	s_or_b64 exec, exec, s[18:19]
	v_mov_b32_e32 v16, 0
	v_mov_b32_e32 v20, 0
	v_mov_b32_e32 v21, 0
	v_mov_b32_e32 v22, 0
	v_mov_b32_e32 v23, 0
	s_and_saveexec_b64 s[18:19], vcc
	s_cbranch_execz .LBB0_346
	v_add_u32_e32 v17, s20, v74
	v_ashrrev_i32_e32 v18, 31, v17
	v_mul_lo_u32 v20, s16, v18
	v_mul_lo_u32 v21, s17, v17
	v_mad_u64_u32 v[18:19], s[22:23], s16, v17, 0
	v_add3_u32 v19, v19, v20, v21
	s_waitcnt lgkmcnt(0)
	v_lshl_add_u64 v[18:19], v[18:19], 2, s[14:15]
	v_mov_b32_e32 v67, v65
	v_lshl_add_u64 v[18:19], v[66:67], 2, v[18:19]
	global_load_dwordx4 v[20:23], v[18:19], off nt
.LBB0_346:
	s_or_b64 exec, exec, s[18:19]
	v_mov_b32_e32 v17, 0
	v_mov_b32_e32 v18, 0
	v_mov_b32_e32 v19, 0
	s_and_saveexec_b64 s[18:19], vcc
	s_cbranch_execz .LBB0_348
	v_add_u32_e32 v16, s20, v75
	v_ashrrev_i32_e32 v17, 31, v16
	v_mul_lo_u32 v18, s16, v17
	v_mul_lo_u32 v19, s17, v16
	v_mad_u64_u32 v[16:17], s[22:23], s16, v16, 0
	v_add3_u32 v17, v17, v18, v19
	s_waitcnt lgkmcnt(0)
	v_lshl_add_u64 v[16:17], v[16:17], 2, s[14:15]
	v_mov_b32_e32 v67, v65
	v_lshl_add_u64 v[16:17], v[66:67], 2, v[16:17]
	global_load_dwordx4 v[16:19], v[16:17], off nt
.LBB0_348:
	s_or_b64 exec, exec, s[18:19]
	v_mov_b32_e32 v43, 0
	v_mov_b32_e32 v44, 0
	v_mov_b32_e32 v45, 0
	v_mov_b32_e32 v46, 0
	v_mov_b32_e32 v47, 0
	s_and_saveexec_b64 s[18:19], vcc
	s_cbranch_execz .LBB0_350
	v_add_u32_e32 v40, s20, v76
	v_ashrrev_i32_e32 v41, 31, v40
	v_mul_lo_u32 v42, s16, v41
	v_mul_lo_u32 v44, s17, v40
	v_mad_u64_u32 v[40:41], s[22:23], s16, v40, 0
	v_add3_u32 v41, v41, v42, v44
	s_waitcnt lgkmcnt(0)
	v_lshl_add_u64 v[40:41], v[40:41], 2, s[14:15]
	v_mov_b32_e32 v67, v65
	v_lshl_add_u64 v[40:41], v[66:67], 2, v[40:41]
	global_load_dwordx4 v[44:47], v[40:41], off nt
.LBB0_350:
	s_or_b64 exec, exec, s[18:19]
	v_mov_b32_e32 v42, 0
	v_mov_b32_e32 v41, 0
	v_mov_b32_e32 v40, 0
	s_and_saveexec_b64 s[18:19], vcc
	s_cbranch_execz .LBB0_352
	v_add_u32_e32 v40, s20, v69
	v_ashrrev_i32_e32 v41, 31, v40
	v_mul_lo_u32 v42, s16, v41
	v_mul_lo_u32 v43, s17, v40
	v_mad_u64_u32 v[40:41], s[16:17], s16, v40, 0
	v_add3_u32 v41, v41, v42, v43
	s_waitcnt lgkmcnt(0)
	v_lshl_add_u64 v[40:41], v[40:41], 2, s[14:15]
	v_mov_b32_e32 v67, v65
	v_lshl_add_u64 v[40:41], v[66:67], 2, v[40:41]
	global_load_dwordx4 v[40:43], v[40:41], off nt

.LBB0_367:
	v_add_co_u32_e64 v52, s[2:3], s11, v96
	v_add_co_u32_e32 v100, vcc, 0xffffd000, v96
	s_nop 0
	v_addc_co_u32_e64 v53, s[2:3], -1, v97, s[2:3]
	v_add_co_u32_e64 v54, s[2:3], s13, v96
	v_addc_co_u32_e32 v101, vcc, -1, v97, vcc
	s_nop 0
	v_addc_co_u32_e64 v55, s[2:3], -1, v97, s[2:3]
	global_load_dwordx4 v[12:15], v[96:97], off offset:-3072 nt
	global_load_dwordx4 v[8:11], v[96:97], off offset:-2048 nt
	global_load_dwordx4 v[4:7], v[96:97], off offset:-1024 nt
	global_load_dwordx4 v[0:3], v[96:97], off nt
	global_load_dwordx4 v[28:31], v[68:69], off
	global_load_dwordx4 v[44:47], v[52:53], off offset:-3072 nt
	global_load_dwordx4 v[32:35], v[52:53], off offset:-1024 nt
	global_load_dwordx4 v[48:51], v[52:53], off offset:-2048 nt
	global_load_dwordx4 v[36:39], v[52:53], off nt
	global_load_dwordx4 v[24:27], v[54:55], off offset:-2048 nt
	global_load_dwordx4 v[40:43], v[54:55], off offset:-3072 nt
	global_load_dwordx4 v[20:23], v[54:55], off offset:-1024 nt
	global_load_dwordx4 v[16:19], v[96:97], off offset:-4096 nt
	global_load_dwordx4 v[64:67], v[100:101], off offset:-3072 nt
	global_load_dwordx4 v[56:59], v[100:101], off offset:-2048 nt
	s_nop 0
	global_load_dwordx4 v[52:55], v[100:101], off nt
	global_load_dwordx4 v[60:63], v[100:101], off offset:-1024 nt
	v_add_co_u32_e64 v98, s[2:3], s13, v94
	s_add_i32 s10, s10, s12
	s_nop 0
	v_addc_co_u32_e64 v99, s[2:3], -1, v95, s[2:3]
	v_lshl_add_u64 v[96:97], v[96:97], 0, s[4:5]
	s_cmpk_lt_i32 s10, 0x4000
	s_waitcnt vmcnt(11)
	v_pk_mul_f32 v[112:113], v[46:47], v[46:47]
	s_waitcnt vmcnt(10)
	v_mul_f32_e32 v142, v32, v32
	v_mul_f32_e32 v145, v33, v33
	s_waitcnt vmcnt(8)
	v_pk_mul_f32 v[114:115], v[38:39], v[38:39]
	v_pk_mul_f32 v[102:103], v[36:37], v[36:37]
	s_waitcnt vmcnt(7)
	v_mul_f32_e32 v144, v24, v24
	v_mul_f32_e32 v148, v25, v25
	v_mul_f32_e32 v151, v26, v26
	s_waitcnt vmcnt(6)
	v_mul_f32_e32 v122, v41, v41
	v_mul_f32_e32 v124, v43, v43
	v_mov_b32_e32 v156, v24
	v_mov_b32_e32 v157, v26
	v_mov_b32_e32 v26, v25
	s_waitcnt vmcnt(3)
	v_pk_mul_f32 v[24:25], v[66:67], v[66:67]
	v_pk_mul_f32 v[158:159], v[64:65], v[64:65]
	s_waitcnt vmcnt(2)
	v_pk_mul_f32 v[160:161], v[58:59], v[58:59]
	v_pk_mul_f32 v[162:163], v[56:57], v[56:57]
	v_pk_mul_f32 v[106:107], v[10:11], v[10:11]
	v_pk_mul_f32 v[108:109], v[8:9], v[8:9]
	v_mul_f32_e32 v110, v5, v5
	v_mul_f32_e32 v132, v7, v7
	v_mul_f32_e32 v149, v34, v34
	v_mov_b32_e32 v134, v32
	v_mov_b32_e32 v135, v34
	v_mov_b32_e32 v34, v33
	v_mov_b32_e32 v32, v36
	v_mov_b32_e32 v33, v38
	v_mov_b32_e32 v38, v37
	v_mov_b32_e32 v36, v40
	v_mov_b32_e32 v37, v42
	v_pk_mov_b32 v[172:173], v[102:103], v[114:115] op_sel:[1,0]
	v_mov_b32_e32 v103, v115
	v_pk_fma_f32 v[114:115], v[40:41], v[40:41], v[122:123] op_sel_hi:[1,1,0]
	v_pk_fma_f32 v[174:175], v[42:43], v[42:43], v[124:125] op_sel_hi:[1,1,0]
	v_mov_b32_e32 v42, v41
	v_pk_mov_b32 v[40:41], v[158:159], v[24:25] op_sel:[1,0]
	v_mov_b32_e32 v159, v25
	v_pk_mov_b32 v[24:25], v[162:163], v[160:161] op_sel:[1,0]
	v_mov_b32_e32 v163, v161
	v_mul_f32_e32 v154, v3, v3
	v_mov_b32_e32 v100, v28
	v_mov_b32_e32 v101, v30
	v_mov_b32_e32 v30, v29
	v_pk_mul_f32 v[28:29], v[44:45], v[44:45]
	v_mul_f32_e32 v116, v49, v49
	v_mul_f32_e32 v118, v51, v51
	v_pk_mov_b32 v[130:131], v[108:109], v[106:107] op_sel:[1,0]
	v_mov_b32_e32 v109, v107
	v_pk_fma_f32 v[106:107], v[4:5], v[4:5], v[110:111] op_sel_hi:[1,1,0]
	v_pk_fma_f32 v[110:111], v[6:7], v[6:7], v[132:133] op_sel_hi:[1,1,0]
	s_waitcnt vmcnt(1)
	v_mul_f32_e32 v165, v52, v52
	v_mul_f32_e32 v167, v53, v53
	s_waitcnt vmcnt(0)
	v_mul_f32_e32 v164, v61, v61
	v_mul_f32_e32 v166, v63, v63
	v_pk_add_f32 v[40:41], v[40:41], v[158:159]
	v_pk_add_f32 v[24:25], v[24:25], v[162:163]
	v_mov_b32_e32 v132, v44
	v_mov_b32_e32 v133, v46
	v_mov_b32_e32 v46, v45
	v_mov_b32_e32 v44, v48
	v_mov_b32_e32 v45, v50
	v_mul_f32_e32 v180, v54, v54
	v_mul_f32_e32 v181, v55, v55
	v_pk_mov_b32 v[168:169], v[28:29], v[112:113] op_sel:[1,0]
	v_mov_b32_e32 v29, v113
	v_pk_fma_f32 v[112:113], v[48:49], v[48:49], v[116:117] op_sel_hi:[1,1,0]
	v_pk_fma_f32 v[170:171], v[50:51], v[50:51], v[118:119] op_sel_hi:[1,1,0]
	v_mov_b32_e32 v111, v154
	v_mov_b32_e32 v154, v52
	v_mov_b32_e32 v155, v54
	v_mov_b32_e32 v54, v53
	v_mov_b32_e32 v50, v49
	v_pk_fma_f32 v[48:49], v[60:61], v[60:61], v[164:165] op_sel_hi:[1,1,0]
	v_pk_fma_f32 v[52:53], v[62:63], v[62:63], v[166:167] op_sel_hi:[1,1,0]
	v_pk_add_f32 v[40:41], v[40:41], v[40:41] op_sel:[0,1] op_sel_hi:[1,0]
	v_pk_add_f32 v[24:25], v[24:25], v[24:25] op_sel:[0,1] op_sel_hi:[1,0]
	v_mov_b32_e32 v49, v180
	v_mov_b32_e32 v53, v181
	v_mov_b32_e32 v41, v165
	v_mov_b32_e32 v25, v167
	v_pk_add_f32 v[48:49], v[48:49], v[52:53]
	v_pk_add_f32 v[24:25], v[40:41], v[24:25]
	v_pk_add_f32 v[28:29], v[168:169], v[28:29]
	v_pk_add_f32 v[24:25], v[24:25], v[48:49]
	v_mul_f32_e32 v150, v35, v35
	v_pk_add_f32 v[28:29], v[28:29], v[28:29] op_sel:[0,1] op_sel_hi:[1,0]
	v_pk_add_f32 v[24:25], v[24:25], v[24:25] op_sel:[0,1] op_sel_hi:[1,0]
	v_mov_b32_e32 v113, v149
	v_mov_b32_e32 v171, v150
	v_mov_b32_e32 v29, v145
	v_mov_b32_e32 v25, v142
	v_pk_add_f32 v[108:109], v[130:131], v[108:109]
	v_mov_b32_e32 v130, v64
	v_mov_b32_e32 v131, v66
	v_mov_b32_e32 v66, v65
	v_mov_b32_e32 v64, v56
	v_mov_b32_e32 v65, v58
	v_mov_b32_e32 v58, v57
	v_mov_b32_e32 v56, v60
	v_mov_b32_e32 v57, v62
	v_mov_b32_e32 v62, v61
	v_pk_add_f32 v[60:61], v[112:113], v[170:171]
	v_pk_add_f32 v[24:25], v[24:25], v[28:29]
	v_pk_add_f32 v[102:103], v[172:173], v[102:103]
	v_pk_add_f32 v[24:25], v[24:25], v[60:61]
	v_mul_f32_e32 v153, v2, v2
	v_mul_f32_e32 v152, v27, v27
	v_pk_add_f32 v[102:103], v[102:103], v[102:103] op_sel:[0,1] op_sel_hi:[1,0]
	v_pk_add_f32 v[24:25], v[24:25], v[24:25] op_sel:[0,1] op_sel_hi:[1,0]
	v_pk_mul_f32 v[120:121], v[22:23], v[22:23]
	v_pk_mul_f32 v[104:105], v[20:21], v[20:21]
	v_mov_b32_e32 v107, v153
	v_mov_b32_e32 v115, v151
	v_mov_b32_e32 v175, v152
	v_mov_b32_e32 v103, v148
	v_mov_b32_e32 v25, v144
	v_pk_mov_b32 v[176:177], v[104:105], v[120:121] op_sel:[1,0]
	v_mov_b32_e32 v105, v121
	v_pk_add_f32 v[106:107], v[106:107], v[110:111]
	v_pk_add_f32 v[110:111], v[114:115], v[174:175]
	v_pk_add_f32 v[24:25], v[24:25], v[102:103]
	v_mul_f32_e32 v126, v17, v17
	v_mul_f32_e32 v128, v19, v19
	v_pk_add_f32 v[104:105], v[176:177], v[104:105]
	v_pk_add_f32 v[24:25], v[24:25], v[110:111]
	v_mul_f32_e32 v139, v12, v12
	v_mul_f32_e32 v141, v13, v13
	v_mul_f32_e32 v146, v14, v14
	v_mul_f32_e32 v147, v15, v15
	v_pk_fma_f32 v[120:121], v[16:17], v[16:17], v[126:127] op_sel_hi:[1,1,0]
	v_pk_fma_f32 v[178:179], v[18:19], v[18:19], v[128:129] op_sel_hi:[1,1,0]
	v_pk_add_f32 v[104:105], v[104:105], v[104:105] op_sel:[0,1] op_sel_hi:[1,0]
	v_pk_add_f32 v[24:25], v[24:25], v[24:25] op_sel:[0,1] op_sel_hi:[1,0]
	v_mov_b32_e32 v121, v146
	v_mov_b32_e32 v179, v147
	v_mov_b32_e32 v105, v141
	v_mov_b32_e32 v25, v139
	v_pk_add_f32 v[112:113], v[120:121], v[178:179]
	v_pk_add_f32 v[24:25], v[24:25], v[104:105]
	v_mul_f32_e32 v140, v0, v0
	v_pk_add_f32 v[24:25], v[24:25], v[112:113]
	v_mul_f32_e32 v143, v1, v1
	v_pk_add_f32 v[108:109], v[108:109], v[108:109] op_sel:[0,1] op_sel_hi:[1,0]
	v_pk_add_f32 v[24:25], v[24:25], v[24:25] op_sel:[0,1] op_sel_hi:[1,0]
	v_mov_b32_e32 v109, v143
	v_mov_b32_e32 v25, v140
	v_pk_add_f32 v[24:25], v[24:25], v[108:109]
	s_nop 0
	v_pk_add_f32 v[24:25], v[24:25], v[106:107]
	s_nop 0
	v_add_f32_e32 v24, v24, v25
	ds_bpermute_b32 v25, v117, v24
	s_waitcnt lgkmcnt(0)
	v_add_f32_e32 v24, v24, v25
	ds_bpermute_b32 v25, v119, v24
	s_waitcnt lgkmcnt(0)
	v_add_f32_e32 v24, v24, v25
	ds_bpermute_b32 v25, v123, v24
	s_waitcnt lgkmcnt(0)
	v_add_f32_e32 v24, v24, v25
	ds_bpermute_b32 v25, v125, v24
	s_waitcnt lgkmcnt(0)
	v_add_f32_e32 v24, v24, v25
	ds_bpermute_b32 v25, v127, v24
	s_waitcnt lgkmcnt(0)
	v_add_f32_e32 v24, v24, v25
	ds_bpermute_b32 v25, v129, v24
	s_waitcnt lgkmcnt(0)
	v_add_f32_e32 v24, v24, v25
	v_fmamk_f32 v24, v24, 0x39800000, v136
	v_mul_f32_e32 v25, 0x4f800000, v24
	v_cmp_gt_f32_e32 vcc, s14, v24
	s_nop 1
	v_cndmask_b32_e32 v24, v24, v25, vcc
	v_sqrt_f32_e32 v25, v24
	s_nop 0
	v_add_u32_e32 v28, -1, v25
	v_add_u32_e32 v29, 1, v25
	v_fma_f32 v40, -v28, v25, v24
	v_fma_f32 v41, -v29, v25, v24
	v_cmp_ge_f32_e64 s[2:3], 0, v40
	s_nop 1
	v_cndmask_b32_e64 v25, v25, v28, s[2:3]
	v_cmp_lt_f32_e64 s[2:3], 0, v41
	s_nop 1
	v_cndmask_b32_e64 v25, v25, v29, s[2:3]
	v_mul_f32_e32 v28, 0x37800000, v25
	v_cndmask_b32_e32 v25, v25, v28, vcc
	v_cmp_class_f32_e32 vcc, v24, v137
	s_nop 1
	v_cndmask_b32_e32 v24, v25, v24, vcc
	v_div_scale_f32 v25, s[2:3], v24, v24, 1.0
	v_rcp_f32_e32 v29, v25
	v_div_scale_f32 v28, vcc, 1.0, v24, 1.0
	v_fma_f32 v40, -v25, v29, 1.0
	v_fmac_f32_e32 v29, v40, v29
	v_mul_f32_e32 v40, v28, v29
	v_fma_f32 v41, -v25, v40, v28
	v_fmac_f32_e32 v40, v41, v29
	v_fma_f32 v25, -v25, v40, v28
	v_div_fmas_f32 v25, v25, v29, v40
	v_div_fixup_f32 v24, v25, v24, 1.0
	v_pk_mul_f32 v[48:49], v[66:67], v[24:25] op_sel_hi:[1,0]
	v_pk_mul_f32 v[40:41], v[130:131], v[24:25] op_sel_hi:[1,0]
	v_pk_mul_f32 v[30:31], v[30:31], v[48:49]
	v_pk_mul_f32 v[102:103], v[32:33], v[24:25] op_sel_hi:[1,0]
	v_pk_mul_f32 v[32:33], v[100:101], v[40:41]
	v_and_b32_sdwa v41, v31, v138 dst_sel:DWORD dst_unused:UNUSED_PAD src0_sel:WORD_1 src1_sel:DWORD
	v_and_b32_sdwa v48, v30, v138 dst_sel:DWORD dst_unused:UNUSED_PAD src0_sel:WORD_1 src1_sel:DWORD
	v_pk_mul_f32 v[52:53], v[64:65], v[24:25] op_sel_hi:[1,0]
	v_pk_mul_f32 v[58:59], v[58:59], v[24:25] op_sel_hi:[1,0]
	v_pk_mul_f32 v[56:57], v[56:57], v[24:25] op_sel_hi:[1,0]
	v_pk_mul_f32 v[60:61], v[62:63], v[24:25] op_sel_hi:[1,0]
	v_pk_mul_f32 v[62:63], v[154:155], v[24:25] op_sel_hi:[1,0]
	v_pk_mul_f32 v[54:55], v[54:55], v[24:25] op_sel_hi:[1,0]
	v_pk_mul_f32 v[64:65], v[132:133], v[24:25] op_sel_hi:[1,0]
	v_pk_mul_f32 v[46:47], v[46:47], v[24:25] op_sel_hi:[1,0]
	v_pk_mul_f32 v[44:45], v[44:45], v[24:25] op_sel_hi:[1,0]
	v_pk_mul_f32 v[50:51], v[50:51], v[24:25] op_sel_hi:[1,0]
	v_pk_mul_f32 v[66:67], v[134:135], v[24:25] op_sel_hi:[1,0]
	v_pk_mul_f32 v[34:35], v[34:35], v[24:25] op_sel_hi:[1,0]
	v_pk_mul_f32 v[38:39], v[38:39], v[24:25] op_sel_hi:[1,0]
	v_pk_mul_f32 v[36:37], v[36:37], v[24:25] op_sel_hi:[1,0]
	v_pk_mul_f32 v[42:43], v[42:43], v[24:25] op_sel_hi:[1,0]
	v_pk_mul_f32 v[28:29], v[156:157], v[24:25] op_sel_hi:[1,0]
	v_and_b32_sdwa v25, v33, v138 dst_sel:DWORD dst_unused:UNUSED_PAD src0_sel:WORD_1 src1_sel:DWORD
	v_and_b32_sdwa v40, v32, v138 dst_sel:DWORD dst_unused:UNUSED_PAD src0_sel:WORD_1 src1_sel:DWORD
	v_add3_u32 v31, v31, v41, s15
	v_add3_u32 v30, v30, v48, s15
	v_add3_u32 v32, v32, v40, s15
	v_add3_u32 v25, v33, v25, s15
	v_and_b32_e32 v31, 0xffff0000, v31
	v_and_b32_e32 v30, 0xffff0000, v30
	v_or_b32_sdwa v31, v31, v25 dst_sel:DWORD dst_unused:UNUSED_PAD src0_sel:DWORD src1_sel:WORD_1
	v_or_b32_sdwa v30, v30, v32 dst_sel:DWORD dst_unused:UNUSED_PAD src0_sel:DWORD src1_sel:WORD_1
	global_store_dwordx2 v[98:99], v[30:31], off offset:-3584 nt
	global_load_dwordx4 v[30:33], v[68:69], off offset:1024
	s_waitcnt vmcnt(0)
	v_mov_b32_e32 v40, v30
	v_mov_b32_e32 v41, v32
	v_mov_b32_e32 v32, v31
	v_pk_mul_f32 v[30:31], v[40:41], v[52:53]
	v_pk_mul_f32 v[32:33], v[32:33], v[58:59]
	v_and_b32_sdwa v25, v31, v138 dst_sel:DWORD dst_unused:UNUSED_PAD src0_sel:WORD_1 src1_sel:DWORD
	v_and_b32_sdwa v41, v33, v138 dst_sel:DWORD dst_unused:UNUSED_PAD src0_sel:WORD_1 src1_sel:DWORD
	v_and_b32_sdwa v48, v32, v138 dst_sel:DWORD dst_unused:UNUSED_PAD src0_sel:WORD_1 src1_sel:DWORD
	v_and_b32_sdwa v40, v30, v138 dst_sel:DWORD dst_unused:UNUSED_PAD src0_sel:WORD_1 src1_sel:DWORD
	v_add3_u32 v25, v31, v25, s15
	v_add3_u32 v31, v33, v41, s15
	v_add3_u32 v32, v32, v48, s15
	v_add3_u32 v30, v30, v40, s15
	v_and_b32_e32 v31, 0xffff0000, v31
	v_and_b32_e32 v32, 0xffff0000, v32
	v_or_b32_sdwa v31, v31, v25 dst_sel:DWORD dst_unused:UNUSED_PAD src0_sel:DWORD src1_sel:WORD_1
	v_or_b32_sdwa v30, v32, v30 dst_sel:DWORD dst_unused:UNUSED_PAD src0_sel:DWORD src1_sel:WORD_1
	global_store_dwordx2 v[98:99], v[30:31], off offset:-3072 nt
	global_load_dwordx4 v[30:33], v[68:69], off offset:2048
	s_waitcnt vmcnt(0)
	v_mov_b32_e32 v40, v30
	v_mov_b32_e32 v41, v32
	v_mov_b32_e32 v32, v31
	v_pk_mul_f32 v[30:31], v[40:41], v[56:57]
	v_pk_mul_f32 v[32:33], v[32:33], v[60:61]
	v_and_b32_sdwa v25, v31, v138 dst_sel:DWORD dst_unused:UNUSED_PAD src0_sel:WORD_1 src1_sel:DWORD
	v_and_b32_sdwa v41, v33, v138 dst_sel:DWORD dst_unused:UNUSED_PAD src0_sel:WORD_1 src1_sel:DWORD
	v_and_b32_sdwa v48, v32, v138 dst_sel:DWORD dst_unused:UNUSED_PAD src0_sel:WORD_1 src1_sel:DWORD
	v_and_b32_sdwa v40, v30, v138 dst_sel:DWORD dst_unused:UNUSED_PAD src0_sel:WORD_1 src1_sel:DWORD
	v_add3_u32 v25, v31, v25, s15
	v_add3_u32 v31, v33, v41, s15
	v_add3_u32 v32, v32, v48, s15
	v_add3_u32 v30, v30, v40, s15
	v_and_b32_e32 v31, 0xffff0000, v31
	v_and_b32_e32 v32, 0xffff0000, v32
	v_or_b32_sdwa v31, v31, v25 dst_sel:DWORD dst_unused:UNUSED_PAD src0_sel:DWORD src1_sel:WORD_1
	v_or_b32_sdwa v30, v32, v30 dst_sel:DWORD dst_unused:UNUSED_PAD src0_sel:DWORD src1_sel:WORD_1
	global_store_dwordx2 v[98:99], v[30:31], off offset:-2560 nt
	global_load_dwordx4 v[30:33], v[68:69], off offset:3072
	s_waitcnt vmcnt(0)
	v_mov_b32_e32 v40, v30
	v_mov_b32_e32 v41, v32
	v_mov_b32_e32 v32, v31
	v_pk_mul_f32 v[30:31], v[40:41], v[62:63]
	v_pk_mul_f32 v[32:33], v[32:33], v[54:55]
	v_and_b32_sdwa v25, v31, v138 dst_sel:DWORD dst_unused:UNUSED_PAD src0_sel:WORD_1 src1_sel:DWORD
	v_and_b32_sdwa v41, v33, v138 dst_sel:DWORD dst_unused:UNUSED_PAD src0_sel:WORD_1 src1_sel:DWORD
	v_and_b32_sdwa v48, v32, v138 dst_sel:DWORD dst_unused:UNUSED_PAD src0_sel:WORD_1 src1_sel:DWORD
	v_and_b32_sdwa v40, v30, v138 dst_sel:DWORD dst_unused:UNUSED_PAD src0_sel:WORD_1 src1_sel:DWORD
	v_add3_u32 v25, v31, v25, s15
	v_add3_u32 v31, v33, v41, s15
	v_add3_u32 v32, v32, v48, s15
	v_add3_u32 v30, v30, v40, s15
	v_and_b32_e32 v31, 0xffff0000, v31
	v_and_b32_e32 v32, 0xffff0000, v32
	v_or_b32_sdwa v31, v31, v25 dst_sel:DWORD dst_unused:UNUSED_PAD src0_sel:DWORD src1_sel:WORD_1
	v_or_b32_sdwa v30, v32, v30 dst_sel:DWORD dst_unused:UNUSED_PAD src0_sel:DWORD src1_sel:WORD_1
	global_store_dwordx2 v[98:99], v[30:31], off offset:-2048 nt
	global_load_dwordx4 v[30:33], v[70:71], off
	s_waitcnt vmcnt(0)
	v_mov_b32_e32 v40, v30
	v_mov_b32_e32 v41, v32
	v_mov_b32_e32 v32, v31
	v_pk_mul_f32 v[30:31], v[64:65], v[40:41]
	v_pk_mul_f32 v[32:33], v[46:47], v[32:33]
	v_and_b32_sdwa v25, v31, v138 dst_sel:DWORD dst_unused:UNUSED_PAD src0_sel:WORD_1 src1_sel:DWORD
	v_and_b32_sdwa v41, v33, v138 dst_sel:DWORD dst_unused:UNUSED_PAD src0_sel:WORD_1 src1_sel:DWORD
	v_and_b32_sdwa v46, v32, v138 dst_sel:DWORD dst_unused:UNUSED_PAD src0_sel:WORD_1 src1_sel:DWORD
	v_and_b32_sdwa v40, v30, v138 dst_sel:DWORD dst_unused:UNUSED_PAD src0_sel:WORD_1 src1_sel:DWORD
	v_add3_u32 v25, v31, v25, s15
	v_add3_u32 v31, v33, v41, s15
	v_add3_u32 v32, v32, v46, s15
	v_add3_u32 v30, v30, v40, s15
	v_and_b32_e32 v31, 0xffff0000, v31
	v_and_b32_e32 v32, 0xffff0000, v32
	v_or_b32_sdwa v31, v31, v25 dst_sel:DWORD dst_unused:UNUSED_PAD src0_sel:DWORD src1_sel:WORD_1
	v_or_b32_sdwa v30, v32, v30 dst_sel:DWORD dst_unused:UNUSED_PAD src0_sel:DWORD src1_sel:WORD_1
	global_store_dwordx2 v[98:99], v[30:31], off offset:-1536 nt
	global_load_dwordx4 v[30:33], v[72:73], off
	s_waitcnt vmcnt(0)
	v_mov_b32_e32 v40, v30
	v_mov_b32_e32 v41, v32
	v_mov_b32_e32 v32, v31
	v_pk_mul_f32 v[30:31], v[44:45], v[40:41]
	v_pk_mul_f32 v[32:33], v[50:51], v[32:33]
	v_and_b32_sdwa v25, v31, v138 dst_sel:DWORD dst_unused:UNUSED_PAD src0_sel:WORD_1 src1_sel:DWORD
	v_and_b32_sdwa v41, v33, v138 dst_sel:DWORD dst_unused:UNUSED_PAD src0_sel:WORD_1 src1_sel:DWORD
	v_and_b32_sdwa v44, v32, v138 dst_sel:DWORD dst_unused:UNUSED_PAD src0_sel:WORD_1 src1_sel:DWORD
	v_and_b32_sdwa v40, v30, v138 dst_sel:DWORD dst_unused:UNUSED_PAD src0_sel:WORD_1 src1_sel:DWORD
	v_add3_u32 v25, v31, v25, s15
	v_add3_u32 v31, v33, v41, s15
	v_add3_u32 v32, v32, v44, s15
	v_add3_u32 v30, v30, v40, s15
	v_and_b32_e32 v31, 0xffff0000, v31
	v_and_b32_e32 v32, 0xffff0000, v32
	v_or_b32_sdwa v31, v31, v25 dst_sel:DWORD dst_unused:UNUSED_PAD src0_sel:DWORD src1_sel:WORD_1
	v_or_b32_sdwa v30, v32, v30 dst_sel:DWORD dst_unused:UNUSED_PAD src0_sel:DWORD src1_sel:WORD_1
	global_store_dwordx2 v[98:99], v[30:31], off offset:-1024 nt
	global_load_dwordx4 v[30:33], v[74:75], off
	s_waitcnt vmcnt(0)
	v_mov_b32_e32 v40, v30
	v_mov_b32_e32 v41, v32
	v_mov_b32_e32 v32, v31
	v_pk_mul_f32 v[30:31], v[66:67], v[40:41]
	v_pk_mul_f32 v[32:33], v[34:35], v[32:33]
	v_and_b32_sdwa v25, v31, v138 dst_sel:DWORD dst_unused:UNUSED_PAD src0_sel:WORD_1 src1_sel:DWORD
	v_and_b32_sdwa v35, v33, v138 dst_sel:DWORD dst_unused:UNUSED_PAD src0_sel:WORD_1 src1_sel:DWORD
	v_and_b32_sdwa v40, v32, v138 dst_sel:DWORD dst_unused:UNUSED_PAD src0_sel:WORD_1 src1_sel:DWORD
	v_and_b32_sdwa v34, v30, v138 dst_sel:DWORD dst_unused:UNUSED_PAD src0_sel:WORD_1 src1_sel:DWORD
	v_add3_u32 v25, v31, v25, s15
	v_add3_u32 v31, v33, v35, s15
	v_add3_u32 v32, v32, v40, s15
	v_add3_u32 v30, v30, v34, s15
	v_and_b32_e32 v31, 0xffff0000, v31
	v_and_b32_e32 v32, 0xffff0000, v32
	v_or_b32_sdwa v31, v31, v25 dst_sel:DWORD dst_unused:UNUSED_PAD src0_sel:DWORD src1_sel:WORD_1
	v_or_b32_sdwa v30, v32, v30 dst_sel:DWORD dst_unused:UNUSED_PAD src0_sel:DWORD src1_sel:WORD_1
	global_store_dwordx2 v[98:99], v[30:31], off offset:-512 nt
	global_load_dwordx4 v[30:33], v[76:77], off
	s_waitcnt vmcnt(0)
	v_mov_b32_e32 v34, v30
	v_mov_b32_e32 v35, v32
	v_mov_b32_e32 v32, v31
	v_pk_mul_f32 v[30:31], v[102:103], v[34:35]
	v_pk_mul_f32 v[32:33], v[38:39], v[32:33]
	v_and_b32_sdwa v25, v31, v138 dst_sel:DWORD dst_unused:UNUSED_PAD src0_sel:WORD_1 src1_sel:DWORD
	v_and_b32_sdwa v35, v33, v138 dst_sel:DWORD dst_unused:UNUSED_PAD src0_sel:WORD_1 src1_sel:DWORD
	v_and_b32_sdwa v38, v32, v138 dst_sel:DWORD dst_unused:UNUSED_PAD src0_sel:WORD_1 src1_sel:DWORD
	v_and_b32_sdwa v34, v30, v138 dst_sel:DWORD dst_unused:UNUSED_PAD src0_sel:WORD_1 src1_sel:DWORD
	v_add3_u32 v25, v31, v25, s15
	v_add3_u32 v31, v33, v35, s15
	v_add3_u32 v32, v32, v38, s15
	v_add3_u32 v30, v30, v34, s15
	v_and_b32_e32 v31, 0xffff0000, v31
	v_and_b32_e32 v32, 0xffff0000, v32
	v_or_b32_sdwa v31, v31, v25 dst_sel:DWORD dst_unused:UNUSED_PAD src0_sel:DWORD src1_sel:WORD_1
	v_or_b32_sdwa v30, v32, v30 dst_sel:DWORD dst_unused:UNUSED_PAD src0_sel:DWORD src1_sel:WORD_1
	global_store_dwordx2 v[94:95], v[30:31], off offset:-4096 nt
	global_load_dwordx4 v[30:33], v[78:79], off
	s_waitcnt vmcnt(0)
	v_mov_b32_e32 v34, v30
	v_mov_b32_e32 v35, v32
	v_mov_b32_e32 v32, v31
	v_pk_mul_f32 v[30:31], v[36:37], v[34:35]
	v_pk_mul_f32 v[32:33], v[42:43], v[32:33]
	v_and_b32_sdwa v25, v31, v138 dst_sel:DWORD dst_unused:UNUSED_PAD src0_sel:WORD_1 src1_sel:DWORD
	v_and_b32_sdwa v35, v33, v138 dst_sel:DWORD dst_unused:UNUSED_PAD src0_sel:WORD_1 src1_sel:DWORD
	v_and_b32_sdwa v36, v32, v138 dst_sel:DWORD dst_unused:UNUSED_PAD src0_sel:WORD_1 src1_sel:DWORD
	v_and_b32_sdwa v34, v30, v138 dst_sel:DWORD dst_unused:UNUSED_PAD src0_sel:WORD_1 src1_sel:DWORD
	v_add3_u32 v25, v31, v25, s15
	v_add3_u32 v31, v33, v35, s15
	v_add3_u32 v32, v32, v36, s15
	v_add3_u32 v30, v30, v34, s15
	v_and_b32_e32 v31, 0xffff0000, v31
	v_and_b32_e32 v32, 0xffff0000, v32
	v_or_b32_sdwa v31, v31, v25 dst_sel:DWORD dst_unused:UNUSED_PAD src0_sel:DWORD src1_sel:WORD_1
	v_or_b32_sdwa v30, v32, v30 dst_sel:DWORD dst_unused:UNUSED_PAD src0_sel:DWORD src1_sel:WORD_1
	global_store_dwordx2 v[94:95], v[30:31], off offset:-3584 nt
	global_load_dwordx4 v[30:33], v[80:81], off
	v_pk_mul_f32 v[26:27], v[26:27], v[24:25] op_sel_hi:[1,0]
	s_waitcnt vmcnt(0)
	v_mov_b32_e32 v35, v32
	v_mov_b32_e32 v32, v31
	v_mov_b32_e32 v34, v30
	v_pk_mul_f32 v[26:27], v[26:27], v[32:33]
	v_pk_mul_f32 v[28:29], v[28:29], v[34:35]
	v_and_b32_sdwa v31, v27, v138 dst_sel:DWORD dst_unused:UNUSED_PAD src0_sel:WORD_1 src1_sel:DWORD
	v_and_b32_sdwa v32, v26, v138 dst_sel:DWORD dst_unused:UNUSED_PAD src0_sel:WORD_1 src1_sel:DWORD
	v_and_b32_sdwa v25, v29, v138 dst_sel:DWORD dst_unused:UNUSED_PAD src0_sel:WORD_1 src1_sel:DWORD
	v_and_b32_sdwa v30, v28, v138 dst_sel:DWORD dst_unused:UNUSED_PAD src0_sel:WORD_1 src1_sel:DWORD
	v_add3_u32 v27, v27, v31, s15
	v_add3_u32 v26, v26, v32, s15
	v_add3_u32 v28, v28, v30, s15
	v_add3_u32 v25, v29, v25, s15
	v_and_b32_e32 v27, 0xffff0000, v27
	v_and_b32_e32 v26, 0xffff0000, v26
	v_or_b32_sdwa v27, v27, v25 dst_sel:DWORD dst_unused:UNUSED_PAD src0_sel:DWORD src1_sel:WORD_1
	v_or_b32_sdwa v26, v26, v28 dst_sel:DWORD dst_unused:UNUSED_PAD src0_sel:DWORD src1_sel:WORD_1
	global_store_dwordx2 v[94:95], v[26:27], off offset:-3072 nt
	global_load_dwordx4 v[26:29], v[82:83], off
	v_mov_b32_e32 v30, v20
	v_mov_b32_e32 v31, v22
	v_mov_b32_e32 v22, v21
	v_pk_mul_f32 v[20:21], v[30:31], v[24:25] op_sel_hi:[1,0]
	v_pk_mul_f32 v[22:23], v[22:23], v[24:25] op_sel_hi:[1,0]
	s_waitcnt vmcnt(0)
	v_mov_b32_e32 v31, v28
	v_mov_b32_e32 v28, v27
	v_mov_b32_e32 v30, v26
	v_pk_mul_f32 v[22:23], v[22:23], v[28:29]
	v_pk_mul_f32 v[20:21], v[20:21], v[30:31]
	v_and_b32_sdwa v27, v23, v138 dst_sel:DWORD dst_unused:UNUSED_PAD src0_sel:WORD_1 src1_sel:DWORD
	v_and_b32_sdwa v28, v22, v138 dst_sel:DWORD dst_unused:UNUSED_PAD src0_sel:WORD_1 src1_sel:DWORD
	v_and_b32_sdwa v25, v21, v138 dst_sel:DWORD dst_unused:UNUSED_PAD src0_sel:WORD_1 src1_sel:DWORD
	v_and_b32_sdwa v26, v20, v138 dst_sel:DWORD dst_unused:UNUSED_PAD src0_sel:WORD_1 src1_sel:DWORD
	v_add3_u32 v23, v23, v27, s15
	v_add3_u32 v22, v22, v28, s15
	v_add3_u32 v20, v20, v26, s15
	v_add3_u32 v21, v21, v25, s15
	v_and_b32_e32 v23, 0xffff0000, v23
	v_and_b32_e32 v22, 0xffff0000, v22
	v_or_b32_sdwa v21, v23, v21 dst_sel:DWORD dst_unused:UNUSED_PAD src0_sel:DWORD src1_sel:WORD_1
	v_or_b32_sdwa v20, v22, v20 dst_sel:DWORD dst_unused:UNUSED_PAD src0_sel:DWORD src1_sel:WORD_1
	global_store_dwordx2 v[94:95], v[20:21], off offset:-2560 nt
	global_load_dwordx4 v[20:23], v[84:85], off
	v_mov_b32_e32 v26, v16
	v_mov_b32_e32 v27, v18
	v_mov_b32_e32 v18, v17
	v_pk_mul_f32 v[16:17], v[26:27], v[24:25] op_sel_hi:[1,0]
	v_pk_mul_f32 v[18:19], v[18:19], v[24:25] op_sel_hi:[1,0]
	s_waitcnt vmcnt(0)
	v_mov_b32_e32 v27, v22
	v_mov_b32_e32 v22, v21
	v_mov_b32_e32 v26, v20
	v_pk_mul_f32 v[18:19], v[18:19], v[22:23]
	v_pk_mul_f32 v[16:17], v[16:17], v[26:27]
	v_and_b32_sdwa v22, v19, v138 dst_sel:DWORD dst_unused:UNUSED_PAD src0_sel:WORD_1 src1_sel:DWORD
	v_and_b32_sdwa v23, v18, v138 dst_sel:DWORD dst_unused:UNUSED_PAD src0_sel:WORD_1 src1_sel:DWORD
	v_and_b32_sdwa v20, v17, v138 dst_sel:DWORD dst_unused:UNUSED_PAD src0_sel:WORD_1 src1_sel:DWORD
	v_and_b32_sdwa v21, v16, v138 dst_sel:DWORD dst_unused:UNUSED_PAD src0_sel:WORD_1 src1_sel:DWORD
	v_add3_u32 v19, v19, v22, s15
	v_add3_u32 v18, v18, v23, s15
	v_add3_u32 v16, v16, v21, s15
	v_add3_u32 v17, v17, v20, s15
	v_and_b32_e32 v19, 0xffff0000, v19
	v_and_b32_e32 v18, 0xffff0000, v18
	v_or_b32_sdwa v17, v19, v17 dst_sel:DWORD dst_unused:UNUSED_PAD src0_sel:DWORD src1_sel:WORD_1
	v_or_b32_sdwa v16, v18, v16 dst_sel:DWORD dst_unused:UNUSED_PAD src0_sel:DWORD src1_sel:WORD_1
	global_store_dwordx2 v[94:95], v[16:17], off offset:-2048 nt
	global_load_dwordx4 v[16:19], v[86:87], off
	v_mov_b32_e32 v20, v12
	v_mov_b32_e32 v21, v14
	v_mov_b32_e32 v14, v13
	v_pk_mul_f32 v[12:13], v[20:21], v[24:25] op_sel_hi:[1,0]
	v_pk_mul_f32 v[14:15], v[14:15], v[24:25] op_sel_hi:[1,0]
	s_waitcnt vmcnt(0)
	v_mov_b32_e32 v21, v18
	v_mov_b32_e32 v18, v17
	v_mov_b32_e32 v20, v16
	v_pk_mul_f32 v[14:15], v[14:15], v[18:19]
	v_pk_mul_f32 v[12:13], v[12:13], v[20:21]
	v_and_b32_sdwa v18, v15, v138 dst_sel:DWORD dst_unused:UNUSED_PAD src0_sel:WORD_1 src1_sel:DWORD
	v_and_b32_sdwa v19, v14, v138 dst_sel:DWORD dst_unused:UNUSED_PAD src0_sel:WORD_1 src1_sel:DWORD
	v_and_b32_sdwa v16, v13, v138 dst_sel:DWORD dst_unused:UNUSED_PAD src0_sel:WORD_1 src1_sel:DWORD
	v_and_b32_sdwa v17, v12, v138 dst_sel:DWORD dst_unused:UNUSED_PAD src0_sel:WORD_1 src1_sel:DWORD
	v_add3_u32 v15, v15, v18, s15
	v_add3_u32 v14, v14, v19, s15
	v_add3_u32 v12, v12, v17, s15
	v_add3_u32 v13, v13, v16, s15
	v_and_b32_e32 v15, 0xffff0000, v15
	v_and_b32_e32 v14, 0xffff0000, v14
	v_or_b32_sdwa v13, v15, v13 dst_sel:DWORD dst_unused:UNUSED_PAD src0_sel:DWORD src1_sel:WORD_1
	v_or_b32_sdwa v12, v14, v12 dst_sel:DWORD dst_unused:UNUSED_PAD src0_sel:DWORD src1_sel:WORD_1
	global_store_dwordx2 v[94:95], v[12:13], off offset:-1536 nt
	global_load_dwordx4 v[12:15], v[88:89], off
	v_mov_b32_e32 v16, v8
	v_mov_b32_e32 v17, v10
	v_mov_b32_e32 v10, v9
	v_pk_mul_f32 v[8:9], v[16:17], v[24:25] op_sel_hi:[1,0]
	v_pk_mul_f32 v[10:11], v[10:11], v[24:25] op_sel_hi:[1,0]
	s_waitcnt vmcnt(0)
	v_mov_b32_e32 v17, v14
	v_mov_b32_e32 v14, v13
	v_mov_b32_e32 v16, v12
	v_pk_mul_f32 v[10:11], v[10:11], v[14:15]
	v_pk_mul_f32 v[8:9], v[8:9], v[16:17]
	v_and_b32_sdwa v14, v11, v138 dst_sel:DWORD dst_unused:UNUSED_PAD src0_sel:WORD_1 src1_sel:DWORD
	v_and_b32_sdwa v15, v10, v138 dst_sel:DWORD dst_unused:UNUSED_PAD src0_sel:WORD_1 src1_sel:DWORD
	v_and_b32_sdwa v12, v9, v138 dst_sel:DWORD dst_unused:UNUSED_PAD src0_sel:WORD_1 src1_sel:DWORD
	v_and_b32_sdwa v13, v8, v138 dst_sel:DWORD dst_unused:UNUSED_PAD src0_sel:WORD_1 src1_sel:DWORD
	v_add3_u32 v11, v11, v14, s15
	v_add3_u32 v10, v10, v15, s15
	v_add3_u32 v8, v8, v13, s15
	v_add3_u32 v9, v9, v12, s15
	v_and_b32_e32 v11, 0xffff0000, v11
	v_and_b32_e32 v10, 0xffff0000, v10
	v_or_b32_sdwa v9, v11, v9 dst_sel:DWORD dst_unused:UNUSED_PAD src0_sel:DWORD src1_sel:WORD_1
	v_or_b32_sdwa v8, v10, v8 dst_sel:DWORD dst_unused:UNUSED_PAD src0_sel:DWORD src1_sel:WORD_1
	global_store_dwordx2 v[94:95], v[8:9], off offset:-1024 nt
	global_load_dwordx4 v[8:11], v[90:91], off
	v_mov_b32_e32 v12, v4
	v_mov_b32_e32 v13, v6
	v_mov_b32_e32 v6, v5
	v_pk_mul_f32 v[4:5], v[12:13], v[24:25] op_sel_hi:[1,0]
	v_pk_mul_f32 v[6:7], v[6:7], v[24:25] op_sel_hi:[1,0]
	s_waitcnt vmcnt(0)
	v_mov_b32_e32 v13, v10
	v_mov_b32_e32 v10, v9
	v_mov_b32_e32 v12, v8
	v_pk_mul_f32 v[6:7], v[6:7], v[10:11]
	v_pk_mul_f32 v[4:5], v[4:5], v[12:13]
	v_and_b32_sdwa v10, v7, v138 dst_sel:DWORD dst_unused:UNUSED_PAD src0_sel:WORD_1 src1_sel:DWORD
	v_and_b32_sdwa v11, v6, v138 dst_sel:DWORD dst_unused:UNUSED_PAD src0_sel:WORD_1 src1_sel:DWORD
	v_and_b32_sdwa v8, v5, v138 dst_sel:DWORD dst_unused:UNUSED_PAD src0_sel:WORD_1 src1_sel:DWORD
	v_and_b32_sdwa v9, v4, v138 dst_sel:DWORD dst_unused:UNUSED_PAD src0_sel:WORD_1 src1_sel:DWORD
	v_add3_u32 v7, v7, v10, s15
	v_add3_u32 v6, v6, v11, s15
	v_add3_u32 v4, v4, v9, s15
	v_add3_u32 v5, v5, v8, s15
	v_and_b32_e32 v7, 0xffff0000, v7
	v_and_b32_e32 v6, 0xffff0000, v6
	v_or_b32_sdwa v5, v7, v5 dst_sel:DWORD dst_unused:UNUSED_PAD src0_sel:DWORD src1_sel:WORD_1
	v_or_b32_sdwa v4, v6, v4 dst_sel:DWORD dst_unused:UNUSED_PAD src0_sel:DWORD src1_sel:WORD_1
	global_store_dwordx2 v[94:95], v[4:5], off offset:-512 nt
	global_load_dwordx4 v[4:7], v[92:93], off
	v_mov_b32_e32 v8, v0
	v_mov_b32_e32 v9, v2
	v_mov_b32_e32 v2, v1
	v_pk_mul_f32 v[0:1], v[8:9], v[24:25] op_sel_hi:[1,0]
	v_pk_mul_f32 v[2:3], v[2:3], v[24:25] op_sel_hi:[1,0]
	s_waitcnt vmcnt(0)
	v_mov_b32_e32 v9, v6
	v_mov_b32_e32 v6, v5
	v_mov_b32_e32 v8, v4
	v_pk_mul_f32 v[2:3], v[2:3], v[6:7]
	v_pk_mul_f32 v[0:1], v[0:1], v[8:9]
	v_and_b32_sdwa v6, v3, v138 dst_sel:DWORD dst_unused:UNUSED_PAD src0_sel:WORD_1 src1_sel:DWORD
	v_and_b32_sdwa v7, v2, v138 dst_sel:DWORD dst_unused:UNUSED_PAD src0_sel:WORD_1 src1_sel:DWORD
	v_and_b32_sdwa v4, v1, v138 dst_sel:DWORD dst_unused:UNUSED_PAD src0_sel:WORD_1 src1_sel:DWORD
	v_and_b32_sdwa v5, v0, v138 dst_sel:DWORD dst_unused:UNUSED_PAD src0_sel:WORD_1 src1_sel:DWORD
	v_add3_u32 v3, v3, v6, s15
	v_add3_u32 v2, v2, v7, s15
	v_add3_u32 v0, v0, v5, s15
	v_add3_u32 v1, v1, v4, s15
	v_and_b32_e32 v3, 0xffff0000, v3
	v_and_b32_e32 v2, 0xffff0000, v2
	v_or_b32_sdwa v1, v3, v1 dst_sel:DWORD dst_unused:UNUSED_PAD src0_sel:DWORD src1_sel:WORD_1
	v_or_b32_sdwa v0, v2, v0 dst_sel:DWORD dst_unused:UNUSED_PAD src0_sel:DWORD src1_sel:WORD_1
	global_store_dwordx2 v[94:95], v[0:1], off nt
	v_lshl_add_u64 v[94:95], v[94:95], 0, s[6:7]
	s_cbranch_scc1 .LBB0_367

.LBB0_1692:
	s_waitcnt lgkmcnt(0)
	v_lshl_add_u64 v[4:5], s[16:17], 0, v[68:69]
	global_load_dword v8, v[4:5], off nt
	global_load_dwordx4 v[0:3], v[16:17], off
	v_lshl_add_u64 v[12:13], s[12:13], 0, v[72:73]
	global_load_dwordx4 v[4:7], v[12:13], off nt
	v_lshl_add_u64 v[74:75], s[16:17], 0, v[70:71]
	v_add_co_u32_e32 v120, vcc, s28, v74
	s_waitcnt vmcnt(2)
	ds_bpermute_b32 v9, v126, v8
	v_addc_co_u32_e32 v121, vcc, 0, v75, vcc
	global_load_dwordx2 v[76:77], v[120:121], off offset:-4096 nt
	v_add_co_u32_e32 v14, vcc, s15, v74
	s_waitcnt lgkmcnt(0)
	v_add_f32_e32 v8, v8, v9
	ds_bpermute_b32 v9, v127, v8
	v_addc_co_u32_e32 v15, vcc, 0, v75, vcc
	s_waitcnt vmcnt(2)
	v_mov_b32_e32 v78, v0
	s_waitcnt vmcnt(1)
	v_mov_b32_e32 v0, v4
	s_waitcnt lgkmcnt(0)
	v_add_f32_e32 v10, v8, v9
	ds_bpermute_b32 v11, v128, v10
	v_lshl_add_u64 v[8:9], s[16:17], 0, v[72:73]
	v_mov_b32_e32 v79, v2
	v_mov_b32_e32 v2, v1
	v_mov_b32_e32 v1, v6
	s_waitcnt lgkmcnt(0)
	v_add_f32_e32 v10, v10, v11
	ds_bpermute_b32 v11, v129, v10
	v_mov_b32_e32 v6, v5
	s_waitcnt lgkmcnt(0)
	v_add_f32_e32 v80, v10, v11
	ds_bpermute_b32 v81, v130, v80
	v_add_co_u32_e32 v10, vcc, s27, v8
	s_waitcnt lgkmcnt(0)
	v_add_f32_e32 v80, v80, v81
	ds_bpermute_b32 v81, v131, v80
	v_addc_co_u32_e32 v11, vcc, 0, v9, vcc
	s_waitcnt lgkmcnt(0)
	v_add_f32_e32 v4, v80, v81
	v_fmamk_f32 v4, v4, 0x39800000, v132
	v_mul_f32_e32 v5, 0x4f800000, v4
	v_cmp_gt_f32_e32 vcc, s11, v4
	s_nop 1
	v_cndmask_b32_e32 v80, v4, v5, vcc
	v_sqrt_f32_e32 v81, v80
	s_waitcnt vmcnt(0)
	v_lshlrev_b32_e32 v4, 16, v76
	v_add_u32_e32 v82, -1, v81
	v_add_u32_e32 v83, 1, v81
	v_fma_f32 v84, -v82, v81, v80
	v_fma_f32 v85, -v83, v81, v80
	v_cmp_ge_f32_e64 s[2:3], 0, v84
	v_and_b32_e32 v76, 0xffff0000, v76
	v_lshlrev_b32_e32 v5, 16, v77
	v_cndmask_b32_e64 v81, v81, v82, s[2:3]
	v_cmp_lt_f32_e64 s[2:3], 0, v85
	v_and_b32_e32 v77, 0xffff0000, v77
	s_nop 0
	v_cndmask_b32_e64 v81, v81, v83, s[2:3]
	v_mul_f32_e32 v82, 0x37800000, v81
	v_cndmask_b32_e32 v81, v81, v82, vcc
	v_cmp_class_f32_e32 vcc, v80, v133
	s_nop 1
	v_cndmask_b32_e32 v80, v81, v80, vcc
	v_div_scale_f32 v81, s[2:3], v80, v80, 1.0
	v_rcp_f32_e32 v82, v81
	v_div_scale_f32 v83, vcc, 1.0, v80, 1.0
	v_fma_f32 v84, -v81, v82, 1.0
	v_fmac_f32_e32 v82, v84, v82
	v_mul_f32_e32 v84, v83, v82
	v_fma_f32 v85, -v81, v84, v83
	v_fmac_f32_e32 v84, v85, v82
	v_fma_f32 v81, -v81, v84, v83
	v_div_fmas_f32 v81, v81, v82, v84
	v_div_fixup_f32 v122, v81, v80, 1.0
	v_pk_mul_f32 v[4:5], v[122:123], v[4:5] op_sel_hi:[0,1]
	v_pk_mul_f32 v[76:77], v[122:123], v[76:77] op_sel_hi:[0,1]
	v_pk_fma_f32 v[82:83], v[78:79], v[4:5], v[0:1]
	v_pk_fma_f32 v[76:77], v[2:3], v[76:77], v[6:7]
	v_mov_b32_e32 v0, v82
	v_mov_b32_e32 v1, v76
	v_mov_b32_e32 v2, v83
	v_mov_b32_e32 v3, v77
	global_store_dwordx4 v[10:11], v[0:3], off offset:-4096 nt
	global_load_dwordx2 v[78:79], v[14:15], off offset:512 nt
	s_nop 0
	global_load_dwordx4 v[0:3], v[16:17], off offset:1024
	global_load_dwordx4 v[4:7], v[12:13], off offset:1024 nt
	v_add_co_u32_e32 v92, vcc, s26, v8
	s_waitcnt vmcnt(2)
	v_lshlrev_b32_e32 v81, 16, v79
	v_lshlrev_b32_e32 v80, 16, v78
	v_and_b32_e32 v79, 0xffff0000, v79
	v_and_b32_e32 v78, 0xffff0000, v78
	s_waitcnt vmcnt(1)
	v_mov_b32_e32 v84, v0
	v_mov_b32_e32 v85, v2
	s_waitcnt vmcnt(0)
	v_mov_b32_e32 v86, v4
	v_mov_b32_e32 v87, v6
	v_mov_b32_e32 v2, v1
	v_mov_b32_e32 v6, v5
	v_pk_mul_f32 v[0:1], v[122:123], v[80:81] op_sel_hi:[0,1]
	v_pk_mul_f32 v[4:5], v[122:123], v[78:79] op_sel_hi:[0,1]
	v_pk_fma_f32 v[86:87], v[84:85], v[0:1], v[86:87]
	v_pk_fma_f32 v[84:85], v[2:3], v[4:5], v[6:7]
	v_addc_co_u32_e32 v93, vcc, 0, v9, vcc
	v_mov_b32_e32 v0, v86
	v_mov_b32_e32 v1, v84
	v_mov_b32_e32 v2, v87
	v_mov_b32_e32 v3, v85
	global_store_dwordx4 v[92:93], v[0:3], off offset:1024 nt
	global_load_dwordx2 v[78:79], v[14:15], off offset:1024 nt
	s_nop 0
	global_load_dwordx4 v[0:3], v[12:13], off offset:2048 nt
	global_load_dwordx4 v[4:7], v[16:17], off offset:2048
	v_add_co_u32_e32 v104, vcc, s24, v12
	s_waitcnt vmcnt(2)
	v_lshlrev_b32_e32 v80, 16, v78
	v_and_b32_e32 v81, 0xffff0000, v78
	v_lshlrev_b32_e32 v78, 16, v79
	v_and_b32_e32 v79, 0xffff0000, v79
	v_pk_mul_f32 v[80:81], v[122:123], v[80:81] op_sel_hi:[0,1]
	v_pk_mul_f32 v[78:79], v[122:123], v[78:79] op_sel_hi:[0,1]
	s_waitcnt vmcnt(0)
	v_pk_fma_f32 v[0:1], v[4:5], v[80:81], v[0:1]
	v_pk_fma_f32 v[2:3], v[6:7], v[78:79], v[2:3]
	global_store_dwordx4 v[92:93], v[0:3], off offset:2048 nt
	global_load_dwordx2 v[78:79], v[14:15], off offset:1536 nt
	global_load_dwordx4 v[4:7], v[16:17], off offset:3072
	global_load_dwordx4 v[88:91], v[12:13], off offset:3072 nt
	v_addc_co_u32_e32 v105, vcc, 0, v13, vcc
	v_add_co_u32_e32 v110, vcc, s23, v12
	s_waitcnt vmcnt(2)
	v_lshlrev_b32_e32 v80, 16, v78
	v_and_b32_e32 v78, 0xffff0000, v78
	v_lshlrev_b32_e32 v81, 16, v79
	v_and_b32_e32 v79, 0xffff0000, v79
	s_waitcnt vmcnt(1)
	v_mov_b32_e32 v94, v4
	v_mov_b32_e32 v95, v6
	s_waitcnt vmcnt(0)
	v_mov_b32_e32 v96, v88
	v_mov_b32_e32 v97, v90
	v_mov_b32_e32 v6, v5
	v_mov_b32_e32 v90, v89
	v_pk_mul_f32 v[4:5], v[122:123], v[80:81] op_sel_hi:[0,1]
	v_pk_mul_f32 v[78:79], v[122:123], v[78:79] op_sel_hi:[0,1]
	v_pk_fma_f32 v[80:81], v[94:95], v[4:5], v[96:97]
	v_pk_fma_f32 v[78:79], v[6:7], v[78:79], v[90:91]
	v_mov_b32_e32 v4, v80
	v_mov_b32_e32 v5, v78
	v_mov_b32_e32 v6, v81
	v_mov_b32_e32 v7, v79
	global_store_dwordx4 v[92:93], v[4:7], off offset:3072 nt
	global_load_dwordx2 v[88:89], v[14:15], off offset:2048 nt
	s_nop 0
	global_load_dwordx4 v[4:7], v[18:19], off
	global_load_dwordx4 v[90:93], v[104:105], off offset:-4096 nt
	v_addc_co_u32_e32 v111, vcc, 0, v13, vcc
	v_add_co_u32_e32 v124, vcc, s30, v8
	s_waitcnt vmcnt(2)
	v_lshlrev_b32_e32 v95, 16, v89
	v_lshlrev_b32_e32 v94, 16, v88
	v_and_b32_e32 v89, 0xffff0000, v89
	v_and_b32_e32 v88, 0xffff0000, v88
	s_waitcnt vmcnt(1)
	v_mov_b32_e32 v96, v4
	v_mov_b32_e32 v97, v6
	s_waitcnt vmcnt(0)
	v_mov_b32_e32 v98, v90
	v_mov_b32_e32 v99, v92
	v_mov_b32_e32 v6, v5
	v_mov_b32_e32 v92, v91
	v_pk_mul_f32 v[4:5], v[122:123], v[94:95] op_sel_hi:[0,1]
	v_pk_mul_f32 v[88:89], v[122:123], v[88:89] op_sel_hi:[0,1]
	v_pk_fma_f32 v[90:91], v[96:97], v[4:5], v[98:99]
	v_pk_fma_f32 v[88:89], v[6:7], v[88:89], v[92:93]
	v_mov_b32_e32 v4, v90
	v_mov_b32_e32 v5, v88
	v_mov_b32_e32 v6, v91
	v_mov_b32_e32 v7, v89
	global_store_dwordx4 v[10:11], v[4:7], off nt
	global_load_dwordx2 v[96:97], v[14:15], off offset:2560 nt
	s_nop 0
	global_load_dwordx4 v[4:7], v[20:21], off
	global_load_dwordx4 v[92:95], v[110:111], off offset:1024 nt
	v_addc_co_u32_e32 v125, vcc, 0, v9, vcc
	s_waitcnt vmcnt(2)
	v_lshlrev_b32_e32 v99, 16, v97
	v_lshlrev_b32_e32 v98, 16, v96
	v_and_b32_e32 v97, 0xffff0000, v97
	v_and_b32_e32 v96, 0xffff0000, v96
	s_waitcnt vmcnt(1)
	v_mov_b32_e32 v100, v4
	v_mov_b32_e32 v101, v6
	s_waitcnt vmcnt(0)
	v_mov_b32_e32 v102, v92
	v_mov_b32_e32 v103, v94
	v_mov_b32_e32 v6, v5
	v_mov_b32_e32 v94, v93
	v_pk_mul_f32 v[4:5], v[122:123], v[98:99] op_sel_hi:[0,1]
	v_pk_mul_f32 v[92:93], v[122:123], v[96:97] op_sel_hi:[0,1]
	v_pk_fma_f32 v[98:99], v[100:101], v[4:5], v[102:103]
	v_pk_fma_f32 v[94:95], v[6:7], v[92:93], v[94:95]
	v_mov_b32_e32 v4, v98
	v_mov_b32_e32 v5, v94
	v_mov_b32_e32 v6, v99
	v_mov_b32_e32 v7, v95
	global_store_dwordx4 v[10:11], v[4:7], off offset:1024 nt
	global_load_dwordx2 v[92:93], v[14:15], off offset:3072 nt
	s_nop 0
	global_load_dwordx4 v[4:7], v[110:111], off offset:2048 nt
	global_load_dwordx4 v[100:103], v[22:23], off
	s_waitcnt vmcnt(2)
	v_lshlrev_b32_e32 v96, 16, v92
	v_and_b32_e32 v97, 0xffff0000, v92
	v_lshlrev_b32_e32 v92, 16, v93
	v_and_b32_e32 v93, 0xffff0000, v93
	v_pk_mul_f32 v[96:97], v[122:123], v[96:97] op_sel_hi:[0,1]
	v_pk_mul_f32 v[92:93], v[122:123], v[92:93] op_sel_hi:[0,1]
	s_waitcnt vmcnt(0)
	v_pk_fma_f32 v[4:5], v[100:101], v[96:97], v[4:5]
	v_pk_fma_f32 v[6:7], v[102:103], v[92:93], v[6:7]
	global_store_dwordx4 v[10:11], v[4:7], off offset:2048 nt
	global_load_dwordx2 v[92:93], v[14:15], off offset:3584 nt
	global_load_dwordx4 v[100:103], v[24:25], off
	global_load_dwordx4 v[106:109], v[110:111], off offset:3072 nt
	s_waitcnt vmcnt(2)
	v_lshlrev_b32_e32 v14, 16, v92
	v_and_b32_e32 v92, 0xffff0000, v92
	v_lshlrev_b32_e32 v15, 16, v93
	v_and_b32_e32 v93, 0xffff0000, v93
	s_waitcnt vmcnt(1)
	v_mov_b32_e32 v96, v100
	v_mov_b32_e32 v97, v102
	s_waitcnt vmcnt(0)
	v_mov_b32_e32 v110, v106
	v_mov_b32_e32 v111, v108
	v_mov_b32_e32 v102, v101
	v_mov_b32_e32 v108, v107
	v_pk_mul_f32 v[14:15], v[122:123], v[14:15] op_sel_hi:[0,1]
	v_pk_mul_f32 v[92:93], v[122:123], v[92:93] op_sel_hi:[0,1]
	v_pk_fma_f32 v[96:97], v[96:97], v[14:15], v[110:111]
	v_pk_fma_f32 v[92:93], v[102:103], v[92:93], v[108:109]
	v_mov_b32_e32 v100, v96
	v_mov_b32_e32 v101, v92
	v_mov_b32_e32 v102, v97
	v_mov_b32_e32 v103, v93
	global_store_dwordx4 v[10:11], v[100:103], off offset:3072 nt
	global_load_dwordx2 v[10:11], v[120:121], off nt
	s_nop 0
	global_load_dwordx4 v[106:109], v[26:27], off
	global_load_dwordx4 v[110:113], v[104:105], off nt
	s_waitcnt vmcnt(2)
	v_lshlrev_b32_e32 v15, 16, v11
	v_lshlrev_b32_e32 v14, 16, v10
	v_and_b32_e32 v11, 0xffff0000, v11
	v_and_b32_e32 v10, 0xffff0000, v10
	s_waitcnt vmcnt(1)
	v_mov_b32_e32 v100, v106
	v_mov_b32_e32 v101, v108
	s_waitcnt vmcnt(0)
	v_mov_b32_e32 v102, v110
	v_mov_b32_e32 v103, v112
	v_mov_b32_e32 v108, v107
	v_mov_b32_e32 v112, v111
	v_pk_mul_f32 v[14:15], v[122:123], v[14:15] op_sel_hi:[0,1]
	v_pk_mul_f32 v[10:11], v[122:123], v[10:11] op_sel_hi:[0,1]
	v_pk_fma_f32 v[102:103], v[100:101], v[14:15], v[102:103]
	v_pk_fma_f32 v[100:101], v[108:109], v[10:11], v[112:113]
	v_mov_b32_e32 v106, v102
	v_mov_b32_e32 v107, v100
	v_mov_b32_e32 v108, v103
	v_mov_b32_e32 v109, v101
	global_store_dwordx4 v[124:125], v[106:109], off offset:-4096 nt
	global_load_dwordx2 v[10:11], v[120:121], off offset:512 nt
	s_nop 0
	global_load_dwordx4 v[106:109], v[28:29], off
	global_load_dwordx4 v[110:113], v[104:105], off offset:1024 nt
	v_add_co_u32_e32 v14, vcc, s29, v8
	s_waitcnt vmcnt(2)
	v_lshlrev_b32_e32 v8, 16, v10
	v_addc_co_u32_e32 v15, vcc, 0, v9, vcc
	v_lshlrev_b32_e32 v9, 16, v11
	v_and_b32_e32 v11, 0xffff0000, v11
	v_and_b32_e32 v10, 0xffff0000, v10
	s_waitcnt vmcnt(1)
	v_mov_b32_e32 v114, v106
	v_mov_b32_e32 v115, v108
	s_waitcnt vmcnt(0)
	v_mov_b32_e32 v116, v110
	v_mov_b32_e32 v117, v112
	v_mov_b32_e32 v108, v107
	v_mov_b32_e32 v112, v111
	v_pk_mul_f32 v[8:9], v[122:123], v[8:9] op_sel_hi:[0,1]
	v_pk_mul_f32 v[10:11], v[122:123], v[10:11] op_sel_hi:[0,1]
	v_pk_fma_f32 v[110:111], v[114:115], v[8:9], v[116:117]
	v_pk_fma_f32 v[108:109], v[108:109], v[10:11], v[112:113]
	v_mov_b32_e32 v8, v110
	v_mov_b32_e32 v9, v108
	v_mov_b32_e32 v10, v111
	v_mov_b32_e32 v11, v109
	global_store_dwordx4 v[14:15], v[8:11], off offset:1024 nt
	global_load_dwordx2 v[106:107], v[120:121], off offset:1024 nt
	s_nop 0
	global_load_dwordx4 v[8:11], v[104:105], off offset:2048 nt
	global_load_dwordx4 v[112:115], v[30:31], off
	v_add_co_u32_e32 v140, vcc, s25, v12
	s_waitcnt vmcnt(2)
	v_lshlrev_b32_e32 v116, 16, v106
	v_and_b32_e32 v117, 0xffff0000, v106
	v_lshlrev_b32_e32 v106, 16, v107
	v_and_b32_e32 v107, 0xffff0000, v107
	v_pk_mul_f32 v[116:117], v[122:123], v[116:117] op_sel_hi:[0,1]
	v_pk_mul_f32 v[106:107], v[122:123], v[106:107] op_sel_hi:[0,1]
	s_waitcnt vmcnt(0)
	v_pk_fma_f32 v[8:9], v[112:113], v[116:117], v[8:9]
	v_pk_fma_f32 v[10:11], v[114:115], v[106:107], v[10:11]
	global_store_dwordx4 v[14:15], v[8:11], off offset:2048 nt
	global_load_dwordx2 v[106:107], v[120:121], off offset:1536 nt
	global_load_dwordx4 v[112:115], v[32:33], off
	global_load_dwordx4 v[116:119], v[104:105], off offset:3072 nt
	v_addc_co_u32_e32 v141, vcc, 0, v13, vcc
	s_andn2_b64 vcc, exec, s[4:5]
	s_waitcnt vmcnt(2)
	v_lshlrev_b32_e32 v104, 16, v106
	v_and_b32_e32 v106, 0xffff0000, v106
	v_lshlrev_b32_e32 v105, 16, v107
	v_and_b32_e32 v107, 0xffff0000, v107
	s_waitcnt vmcnt(1)
	v_mov_b32_e32 v136, v112
	v_mov_b32_e32 v137, v114
	s_waitcnt vmcnt(0)
	v_mov_b32_e32 v138, v116
	v_mov_b32_e32 v139, v118
	v_mov_b32_e32 v114, v113
	v_mov_b32_e32 v118, v117
	v_pk_mul_f32 v[104:105], v[122:123], v[104:105] op_sel_hi:[0,1]
	v_pk_mul_f32 v[112:113], v[122:123], v[106:107] op_sel_hi:[0,1]
	v_pk_fma_f32 v[106:107], v[136:137], v[104:105], v[138:139]
	v_pk_fma_f32 v[104:105], v[114:115], v[112:113], v[118:119]
	v_mov_b32_e32 v112, v106
	v_mov_b32_e32 v113, v104
	v_mov_b32_e32 v114, v107
	v_mov_b32_e32 v115, v105
	global_store_dwordx4 v[14:15], v[112:115], off offset:3072 nt
	global_load_dwordx2 v[112:113], v[120:121], off offset:2048 nt
	s_nop 0
	global_load_dwordx4 v[114:117], v[34:35], off
	global_load_dwordx4 v[12:15], v[140:141], off nt
	s_waitcnt vmcnt(2)
	v_lshlrev_b32_e32 v119, 16, v113
	v_lshlrev_b32_e32 v118, 16, v112
	v_and_b32_e32 v113, 0xffff0000, v113
	v_and_b32_e32 v112, 0xffff0000, v112
	s_waitcnt vmcnt(1)
	v_mov_b32_e32 v136, v114
	v_mov_b32_e32 v137, v116
	s_waitcnt vmcnt(0)
	v_mov_b32_e32 v138, v12
	v_mov_b32_e32 v139, v14
	v_mov_b32_e32 v116, v115
	v_mov_b32_e32 v14, v13
	v_pk_mul_f32 v[12:13], v[122:123], v[118:119] op_sel_hi:[0,1]
	v_pk_mul_f32 v[112:113], v[122:123], v[112:113] op_sel_hi:[0,1]
	v_pk_fma_f32 v[114:115], v[136:137], v[12:13], v[138:139]
	v_pk_fma_f32 v[112:113], v[116:117], v[112:113], v[14:15]
	v_mov_b32_e32 v12, v114
	v_mov_b32_e32 v13, v112
	v_mov_b32_e32 v14, v115
	v_mov_b32_e32 v15, v113
	global_store_dwordx4 v[124:125], v[12:15], off nt
	global_load_dwordx2 v[116:117], v[120:121], off offset:2560 nt
	s_nop 0
	global_load_dwordx4 v[12:15], v[36:37], off
	global_load_dwordx4 v[136:139], v[140:141], off offset:1024 nt
	s_waitcnt vmcnt(2)
	v_lshlrev_b32_e32 v119, 16, v117
	v_lshlrev_b32_e32 v118, 16, v116
	v_and_b32_e32 v117, 0xffff0000, v117
	v_and_b32_e32 v116, 0xffff0000, v116
	s_waitcnt vmcnt(1)
	v_mov_b32_e32 v142, v12
	v_mov_b32_e32 v143, v14
	s_waitcnt vmcnt(0)
	v_mov_b32_e32 v144, v136
	v_mov_b32_e32 v145, v138
	v_mov_b32_e32 v14, v13
	v_mov_b32_e32 v138, v137
	v_pk_mul_f32 v[12:13], v[122:123], v[118:119] op_sel_hi:[0,1]
	v_pk_mul_f32 v[116:117], v[122:123], v[116:117] op_sel_hi:[0,1]
	v_pk_fma_f32 v[118:119], v[142:143], v[12:13], v[144:145]
	v_pk_fma_f32 v[116:117], v[14:15], v[116:117], v[138:139]
	v_mov_b32_e32 v12, v118
	v_mov_b32_e32 v13, v116
	v_mov_b32_e32 v14, v119
	v_mov_b32_e32 v15, v117
	global_store_dwordx4 v[124:125], v[12:15], off offset:1024 nt
	global_load_dwordx2 v[142:143], v[120:121], off offset:3072 nt
	s_nop 0
	global_load_dwordx4 v[12:15], v[140:141], off offset:2048 nt
	global_load_dwordx4 v[136:139], v[38:39], off
	s_waitcnt vmcnt(2)
	v_lshlrev_b32_e32 v144, 16, v142
	v_and_b32_e32 v145, 0xffff0000, v142
	v_lshlrev_b32_e32 v142, 16, v143
	v_and_b32_e32 v143, 0xffff0000, v143
	v_pk_mul_f32 v[144:145], v[122:123], v[144:145] op_sel_hi:[0,1]
	v_pk_mul_f32 v[142:143], v[122:123], v[142:143] op_sel_hi:[0,1]
	s_waitcnt vmcnt(0)
	v_pk_fma_f32 v[12:13], v[136:137], v[144:145], v[12:13]
	v_pk_fma_f32 v[14:15], v[138:139], v[142:143], v[14:15]
	global_store_dwordx4 v[124:125], v[12:15], off offset:2048 nt
	global_load_dwordx2 v[120:121], v[120:121], off offset:3584 nt
	s_nop 0
	global_load_dwordx4 v[136:139], v[40:41], off
	s_nop 0
	global_load_dwordx4 v[140:143], v[140:141], off offset:3072 nt
	s_waitcnt vmcnt(2)
	v_lshlrev_b32_e32 v144, 16, v120
	v_and_b32_e32 v120, 0xffff0000, v120
	v_lshlrev_b32_e32 v145, 16, v121
	v_and_b32_e32 v121, 0xffff0000, v121
	s_waitcnt vmcnt(1)
	v_mov_b32_e32 v146, v136
	v_mov_b32_e32 v147, v138
	s_waitcnt vmcnt(0)
	v_mov_b32_e32 v148, v140
	v_mov_b32_e32 v149, v142
	v_mov_b32_e32 v138, v137
	v_mov_b32_e32 v142, v141
	v_pk_mul_f32 v[136:137], v[122:123], v[144:145] op_sel_hi:[0,1]
	v_pk_mul_f32 v[120:121], v[122:123], v[120:121] op_sel_hi:[0,1]
	v_pk_fma_f32 v[122:123], v[146:147], v[136:137], v[148:149]
	v_pk_fma_f32 v[120:121], v[138:139], v[120:121], v[142:143]
	v_mov_b32_e32 v136, v122
	v_mov_b32_e32 v137, v120
	v_mov_b32_e32 v138, v123
	v_mov_b32_e32 v139, v121
	global_store_dwordx4 v[124:125], v[136:139], off offset:3072 nt
	s_cbranch_vccnz .LBB0_1691
	v_mov_b32_e32 v124, v82
	v_mov_b32_e32 v125, v76
	v_mul_f32_e32 v136, v76, v76
	v_pk_fma_f32 v[124:125], v[124:125], v[124:125], v[136:137] op_sel_hi:[1,1,0]
	v_mov_b32_e32 v136, v83
	v_mov_b32_e32 v137, v77
	v_mul_f32_e32 v138, v77, v77
	v_pk_fma_f32 v[136:137], v[136:137], v[136:137], v[138:139] op_sel_hi:[1,1,0]
	v_pk_mul_f32 v[138:139], v[84:85], v[84:85]
	v_mul_f32_e32 v140, v1, v1
	v_pk_fma_f32 v[138:139], v[86:87], v[86:87], v[138:139]
	v_mul_f32_e32 v142, v3, v3
	v_pk_add_f32 v[138:139], v[138:139], v[138:139] op_sel:[0,1] op_sel_hi:[1,0]
	v_pk_fma_f32 v[140:141], v[0:1], v[0:1], v[140:141] op_sel_hi:[1,1,0]
	v_pk_fma_f32 v[142:143], v[2:3], v[2:3], v[142:143] op_sel_hi:[1,1,0]
	v_pk_mul_f32 v[144:145], v[78:79], v[78:79]
	v_pk_mul_f32 v[146:147], v[80:81], v[80:81]
	v_pk_add_f32 v[124:125], v[124:125], v[136:137]
	v_mov_b32_e32 v139, v144
	v_mov_b32_e32 v125, v146
	v_mov_b32_e32 v141, v147
	v_mov_b32_e32 v143, v145
	v_pk_add_f32 v[124:125], v[124:125], v[138:139]
	v_pk_add_f32 v[136:137], v[140:141], v[142:143]
	v_pk_mul_f32 v[138:139], v[94:95], v[94:95]
	v_pk_add_f32 v[124:125], v[124:125], v[136:137]
	v_pk_mul_f32 v[136:137], v[88:89], v[88:89]
	v_pk_add_f32 v[124:125], v[124:125], v[124:125] op_sel:[0,1] op_sel_hi:[1,0]
	v_pk_fma_f32 v[136:137], v[90:91], v[90:91], v[136:137]
	v_pk_fma_f32 v[138:139], v[98:99], v[98:99], v[138:139]
	v_pk_add_f32 v[136:137], v[136:137], v[136:137] op_sel:[0,1] op_sel_hi:[1,0]
	v_mul_f32_e32 v140, v5, v5
	v_mul_f32_e32 v142, v7, v7
	v_pk_add_f32 v[138:139], v[138:139], v[138:139] op_sel:[0,1] op_sel_hi:[1,0]
	v_pk_fma_f32 v[140:141], v[4:5], v[4:5], v[140:141] op_sel_hi:[1,1,0]
	v_pk_fma_f32 v[142:143], v[6:7], v[6:7], v[142:143] op_sel_hi:[1,1,0]
	v_pk_mul_f32 v[144:145], v[92:93], v[92:93]
	v_pk_mul_f32 v[146:147], v[96:97], v[96:97]
	v_pk_add_f32 v[124:125], v[124:125], v[136:137]
	v_mov_b32_e32 v139, v144
	v_mov_b32_e32 v125, v146
	v_mov_b32_e32 v141, v147
	v_mov_b32_e32 v143, v145
	v_pk_add_f32 v[124:125], v[124:125], v[138:139]
	v_pk_add_f32 v[136:137], v[140:141], v[142:143]
	v_pk_mul_f32 v[138:139], v[108:109], v[108:109]
	v_pk_add_f32 v[124:125], v[124:125], v[136:137]
	v_pk_mul_f32 v[136:137], v[100:101], v[100:101]
	v_pk_add_f32 v[124:125], v[124:125], v[124:125] op_sel:[0,1] op_sel_hi:[1,0]
	v_pk_fma_f32 v[136:137], v[102:103], v[102:103], v[136:137]
	v_pk_fma_f32 v[138:139], v[110:111], v[110:111], v[138:139]
	v_pk_add_f32 v[136:137], v[136:137], v[136:137] op_sel:[0,1] op_sel_hi:[1,0]
	v_mul_f32_e32 v140, v9, v9
	v_mul_f32_e32 v142, v11, v11
	v_pk_add_f32 v[138:139], v[138:139], v[138:139] op_sel:[0,1] op_sel_hi:[1,0]
	v_pk_fma_f32 v[140:141], v[8:9], v[8:9], v[140:141] op_sel_hi:[1,1,0]
	v_pk_fma_f32 v[142:143], v[10:11], v[10:11], v[142:143] op_sel_hi:[1,1,0]
	v_pk_mul_f32 v[144:145], v[104:105], v[104:105]
	v_pk_mul_f32 v[146:147], v[106:107], v[106:107]
	v_pk_add_f32 v[124:125], v[124:125], v[136:137]
	v_mov_b32_e32 v139, v144
	v_mov_b32_e32 v125, v146
	v_mov_b32_e32 v141, v147
	v_mov_b32_e32 v143, v145
	v_pk_add_f32 v[124:125], v[124:125], v[138:139]
	v_pk_add_f32 v[136:137], v[140:141], v[142:143]
	v_pk_mul_f32 v[138:139], v[116:117], v[116:117]
	v_pk_add_f32 v[124:125], v[124:125], v[136:137]
	v_pk_mul_f32 v[136:137], v[112:113], v[112:113]
	v_pk_add_f32 v[124:125], v[124:125], v[124:125] op_sel:[0,1] op_sel_hi:[1,0]
	v_pk_fma_f32 v[136:137], v[114:115], v[114:115], v[136:137]
	v_pk_fma_f32 v[138:139], v[118:119], v[118:119], v[138:139]
	v_pk_add_f32 v[136:137], v[136:137], v[136:137] op_sel:[0,1] op_sel_hi:[1,0]
	v_pk_add_f32 v[138:139], v[138:139], v[138:139] op_sel:[0,1] op_sel_hi:[1,0]
	v_pk_mul_f32 v[144:145], v[120:121], v[120:121]
	v_pk_mul_f32 v[146:147], v[122:123], v[122:123]
	v_pk_add_f32 v[124:125], v[124:125], v[136:137]
	v_mov_b32_e32 v139, v144
	v_mov_b32_e32 v125, v146
	v_pk_add_f32 v[124:125], v[124:125], v[138:139]
	global_load_dwordx4 v[136:139], v[42:43], off
	v_mul_f32_e32 v140, v13, v13
	v_mul_f32_e32 v142, v15, v15
	v_pk_fma_f32 v[140:141], v[12:13], v[12:13], v[140:141] op_sel_hi:[1,1,0]
	v_pk_fma_f32 v[142:143], v[14:15], v[14:15], v[142:143] op_sel_hi:[1,1,0]
	v_mov_b32_e32 v141, v147
	v_mov_b32_e32 v143, v145
	v_pk_add_f32 v[140:141], v[140:141], v[142:143]
	s_nop 0
	v_pk_add_f32 v[124:125], v[124:125], v[140:141]
	s_nop 0
	v_add_f32_e32 v124, v124, v125
	ds_bpermute_b32 v125, v126, v124
	s_waitcnt lgkmcnt(0)
	v_add_f32_e32 v124, v124, v125
	ds_bpermute_b32 v125, v127, v124
	s_waitcnt lgkmcnt(0)
	v_add_f32_e32 v124, v124, v125
	ds_bpermute_b32 v125, v128, v124
	s_waitcnt lgkmcnt(0)
	v_add_f32_e32 v124, v124, v125
	ds_bpermute_b32 v125, v129, v124
	s_waitcnt lgkmcnt(0)
	v_add_f32_e32 v124, v124, v125
	ds_bpermute_b32 v125, v130, v124
	s_waitcnt lgkmcnt(0)
	v_add_f32_e32 v124, v124, v125
	ds_bpermute_b32 v125, v131, v124
	s_waitcnt lgkmcnt(0)
	v_add_f32_e32 v124, v124, v125
	v_fmamk_f32 v124, v124, 0x39800000, v132
	v_mul_f32_e32 v125, 0x4f800000, v124
	v_cmp_gt_f32_e32 vcc, s11, v124
	s_nop 1
	v_cndmask_b32_e32 v124, v124, v125, vcc
	v_sqrt_f32_e32 v125, v124
	s_nop 0
	v_add_u32_e32 v135, -1, v125
	v_fma_f32 v140, -v135, v125, v124
	v_cmp_ge_f32_e64 s[2:3], 0, v140
	v_add_u32_e32 v140, 1, v125
	s_nop 0
	v_cndmask_b32_e64 v135, v125, v135, s[2:3]
	v_fma_f32 v125, -v140, v125, v124
	v_cmp_lt_f32_e64 s[2:3], 0, v125
	s_nop 1
	v_cndmask_b32_e64 v125, v135, v140, s[2:3]
	v_mul_f32_e32 v135, 0x37800000, v125
	v_cndmask_b32_e32 v125, v125, v135, vcc
	v_cmp_class_f32_e32 vcc, v124, v133
	s_nop 1
	v_cndmask_b32_e32 v124, v125, v124, vcc
	v_div_scale_f32 v125, s[2:3], v124, v124, 1.0
	v_rcp_f32_e32 v135, v125
	s_nop 0
	v_fma_f32 v140, -v125, v135, 1.0
	v_fmac_f32_e32 v135, v140, v135
	v_div_scale_f32 v140, vcc, 1.0, v124, 1.0
	v_mul_f32_e32 v141, v140, v135
	v_fma_f32 v142, -v125, v141, v140
	v_fmac_f32_e32 v141, v142, v135
	v_fma_f32 v125, -v125, v141, v140
	v_div_fmas_f32 v125, v125, v135, v141
	v_div_fixup_f32 v124, v125, v124, 1.0
	v_pk_mul_f32 v[82:83], v[82:83], v[124:125] op_sel_hi:[1,0]
	s_waitcnt vmcnt(0)
	v_mov_b32_e32 v140, v136
	v_mov_b32_e32 v141, v138
	v_pk_mul_f32 v[82:83], v[140:141], v[82:83]
	v_pk_mul_f32 v[76:77], v[76:77], v[124:125] op_sel_hi:[1,0]
	v_mov_b32_e32 v138, v137
	v_pk_mul_f32 v[76:77], v[138:139], v[76:77]
	v_and_b32_sdwa v135, v82, v134 dst_sel:DWORD dst_unused:UNUSED_PAD src0_sel:WORD_1 src1_sel:DWORD
	v_and_b32_sdwa v125, v83, v134 dst_sel:DWORD dst_unused:UNUSED_PAD src0_sel:WORD_1 src1_sel:DWORD
	v_add3_u32 v82, v82, v135, s31
	v_and_b32_sdwa v135, v76, v134 dst_sel:DWORD dst_unused:UNUSED_PAD src0_sel:WORD_1 src1_sel:DWORD
	v_add3_u32 v83, v83, v125, s31
	v_and_b32_sdwa v125, v77, v134 dst_sel:DWORD dst_unused:UNUSED_PAD src0_sel:WORD_1 src1_sel:DWORD
	v_add3_u32 v76, v76, v135, s31
	v_add3_u32 v77, v77, v125, s31
	v_and_b32_e32 v76, 0xffff0000, v76
	v_and_b32_e32 v77, 0xffff0000, v77
	v_or_b32_sdwa v82, v76, v82 dst_sel:DWORD dst_unused:UNUSED_PAD src0_sel:DWORD src1_sel:WORD_1
	v_add_co_u32_e32 v76, vcc, s34, v74
	v_or_b32_sdwa v83, v77, v83 dst_sel:DWORD dst_unused:UNUSED_PAD src0_sel:DWORD src1_sel:WORD_1
	s_nop 0
	v_addc_co_u32_e32 v77, vcc, 0, v75, vcc
	global_store_dwordx2 v[76:77], v[82:83], off offset:-4096 nt
	global_load_dwordx4 v[136:139], v[42:43], off offset:1024
	v_pk_mul_f32 v[82:83], v[86:87], v[124:125] op_sel_hi:[1,0]
	v_pk_mul_f32 v[84:85], v[84:85], v[124:125] op_sel_hi:[1,0]
	v_add_co_u32_e32 v74, vcc, s33, v74
	s_waitcnt vmcnt(0)
	v_mov_b32_e32 v87, v138
	v_mov_b32_e32 v138, v137
	v_mov_b32_e32 v86, v136
	v_pk_mul_f32 v[84:85], v[138:139], v[84:85]
	v_pk_mul_f32 v[82:83], v[86:87], v[82:83]
	v_and_b32_sdwa v125, v85, v134 dst_sel:DWORD dst_unused:UNUSED_PAD src0_sel:WORD_1 src1_sel:DWORD
	v_and_b32_sdwa v135, v84, v134 dst_sel:DWORD dst_unused:UNUSED_PAD src0_sel:WORD_1 src1_sel:DWORD
	v_and_b32_sdwa v86, v83, v134 dst_sel:DWORD dst_unused:UNUSED_PAD src0_sel:WORD_1 src1_sel:DWORD
	v_and_b32_sdwa v87, v82, v134 dst_sel:DWORD dst_unused:UNUSED_PAD src0_sel:WORD_1 src1_sel:DWORD
	v_add3_u32 v85, v85, v125, s31
	v_add3_u32 v84, v84, v135, s31
	v_add3_u32 v82, v82, v87, s31
	v_add3_u32 v83, v83, v86, s31
	v_and_b32_e32 v85, 0xffff0000, v85
	v_and_b32_e32 v84, 0xffff0000, v84
	v_addc_co_u32_e32 v75, vcc, 0, v75, vcc
	v_or_b32_sdwa v83, v85, v83 dst_sel:DWORD dst_unused:UNUSED_PAD src0_sel:DWORD src1_sel:WORD_1
	v_or_b32_sdwa v82, v84, v82 dst_sel:DWORD dst_unused:UNUSED_PAD src0_sel:DWORD src1_sel:WORD_1
	global_store_dwordx2 v[74:75], v[82:83], off offset:512 nt
	global_load_dwordx4 v[82:85], v[42:43], off offset:2048
	v_mov_b32_e32 v86, v0
	v_mov_b32_e32 v87, v2
	v_mov_b32_e32 v2, v1
	v_pk_mul_f32 v[0:1], v[86:87], v[124:125] op_sel_hi:[1,0]
	v_pk_mul_f32 v[2:3], v[2:3], v[124:125] op_sel_hi:[1,0]
	v_pk_mul_f32 v[78:79], v[78:79], v[124:125] op_sel_hi:[1,0]
	v_pk_mul_f32 v[80:81], v[80:81], v[124:125] op_sel_hi:[1,0]
	s_waitcnt vmcnt(0)
	v_mov_b32_e32 v87, v84
	v_mov_b32_e32 v84, v83
	v_mov_b32_e32 v86, v82
	v_pk_mul_f32 v[2:3], v[84:85], v[2:3]
	v_pk_mul_f32 v[0:1], v[86:87], v[0:1]
	v_and_b32_sdwa v84, v3, v134 dst_sel:DWORD dst_unused:UNUSED_PAD src0_sel:WORD_1 src1_sel:DWORD
	v_and_b32_sdwa v85, v2, v134 dst_sel:DWORD dst_unused:UNUSED_PAD src0_sel:WORD_1 src1_sel:DWORD
	v_and_b32_sdwa v82, v1, v134 dst_sel:DWORD dst_unused:UNUSED_PAD src0_sel:WORD_1 src1_sel:DWORD
	v_and_b32_sdwa v83, v0, v134 dst_sel:DWORD dst_unused:UNUSED_PAD src0_sel:WORD_1 src1_sel:DWORD
	v_add3_u32 v3, v3, v84, s31
	v_add3_u32 v2, v2, v85, s31
	v_add3_u32 v0, v0, v83, s31
	v_add3_u32 v1, v1, v82, s31
	v_and_b32_e32 v3, 0xffff0000, v3
	v_and_b32_e32 v2, 0xffff0000, v2
	v_or_b32_sdwa v1, v3, v1 dst_sel:DWORD dst_unused:UNUSED_PAD src0_sel:DWORD src1_sel:WORD_1
	v_or_b32_sdwa v0, v2, v0 dst_sel:DWORD dst_unused:UNUSED_PAD src0_sel:DWORD src1_sel:WORD_1
	global_store_dwordx2 v[74:75], v[0:1], off offset:1024 nt
	global_load_dwordx4 v[0:3], v[42:43], off offset:3072
	s_waitcnt vmcnt(0)
	v_mov_b32_e32 v83, v2
	v_mov_b32_e32 v2, v1
	v_mov_b32_e32 v82, v0
	v_pk_mul_f32 v[2:3], v[78:79], v[2:3]
	v_pk_mul_f32 v[0:1], v[80:81], v[82:83]
	v_and_b32_sdwa v80, v3, v134 dst_sel:DWORD dst_unused:UNUSED_PAD src0_sel:WORD_1 src1_sel:DWORD
	v_and_b32_sdwa v81, v2, v134 dst_sel:DWORD dst_unused:UNUSED_PAD src0_sel:WORD_1 src1_sel:DWORD
	v_and_b32_sdwa v78, v1, v134 dst_sel:DWORD dst_unused:UNUSED_PAD src0_sel:WORD_1 src1_sel:DWORD
	v_and_b32_sdwa v79, v0, v134 dst_sel:DWORD dst_unused:UNUSED_PAD src0_sel:WORD_1 src1_sel:DWORD
	v_add3_u32 v3, v3, v80, s31
	v_add3_u32 v2, v2, v81, s31
	v_add3_u32 v0, v0, v79, s31
	v_add3_u32 v1, v1, v78, s31
	v_and_b32_e32 v3, 0xffff0000, v3
	v_and_b32_e32 v2, 0xffff0000, v2
	v_or_b32_sdwa v1, v3, v1 dst_sel:DWORD dst_unused:UNUSED_PAD src0_sel:DWORD src1_sel:WORD_1
	v_or_b32_sdwa v0, v2, v0 dst_sel:DWORD dst_unused:UNUSED_PAD src0_sel:DWORD src1_sel:WORD_1
	global_store_dwordx2 v[74:75], v[0:1], off offset:1536 nt
	global_load_dwordx4 v[0:3], v[44:45], off
	v_pk_mul_f32 v[80:81], v[88:89], v[124:125] op_sel_hi:[1,0]
	v_pk_mul_f32 v[78:79], v[90:91], v[124:125] op_sel_hi:[1,0]
	s_waitcnt vmcnt(0)
	v_mov_b32_e32 v83, v2
	v_mov_b32_e32 v2, v1
	v_mov_b32_e32 v82, v0
	v_pk_mul_f32 v[2:3], v[80:81], v[2:3]
	v_pk_mul_f32 v[0:1], v[78:79], v[82:83]
	v_and_b32_sdwa v80, v3, v134 dst_sel:DWORD dst_unused:UNUSED_PAD src0_sel:WORD_1 src1_sel:DWORD
	v_and_b32_sdwa v81, v2, v134 dst_sel:DWORD dst_unused:UNUSED_PAD src0_sel:WORD_1 src1_sel:DWORD
	v_and_b32_sdwa v78, v1, v134 dst_sel:DWORD dst_unused:UNUSED_PAD src0_sel:WORD_1 src1_sel:DWORD
	v_and_b32_sdwa v79, v0, v134 dst_sel:DWORD dst_unused:UNUSED_PAD src0_sel:WORD_1 src1_sel:DWORD
	v_add3_u32 v3, v3, v80, s31
	v_add3_u32 v2, v2, v81, s31
	v_add3_u32 v0, v0, v79, s31
	v_add3_u32 v1, v1, v78, s31
	v_and_b32_e32 v3, 0xffff0000, v3
	v_and_b32_e32 v2, 0xffff0000, v2
	v_or_b32_sdwa v1, v3, v1 dst_sel:DWORD dst_unused:UNUSED_PAD src0_sel:DWORD src1_sel:WORD_1
	v_or_b32_sdwa v0, v2, v0 dst_sel:DWORD dst_unused:UNUSED_PAD src0_sel:DWORD src1_sel:WORD_1
	global_store_dwordx2 v[74:75], v[0:1], off offset:2048 nt
	global_load_dwordx4 v[0:3], v[46:47], off
	v_pk_mul_f32 v[80:81], v[94:95], v[124:125] op_sel_hi:[1,0]
	v_pk_mul_f32 v[78:79], v[98:99], v[124:125] op_sel_hi:[1,0]
	s_waitcnt vmcnt(0)
	v_mov_b32_e32 v83, v2
	v_mov_b32_e32 v2, v1
	v_mov_b32_e32 v82, v0
	v_pk_mul_f32 v[2:3], v[80:81], v[2:3]
	v_pk_mul_f32 v[0:1], v[78:79], v[82:83]
	v_and_b32_sdwa v80, v3, v134 dst_sel:DWORD dst_unused:UNUSED_PAD src0_sel:WORD_1 src1_sel:DWORD
	v_and_b32_sdwa v81, v2, v134 dst_sel:DWORD dst_unused:UNUSED_PAD src0_sel:WORD_1 src1_sel:DWORD
	v_and_b32_sdwa v78, v1, v134 dst_sel:DWORD dst_unused:UNUSED_PAD src0_sel:WORD_1 src1_sel:DWORD
	v_and_b32_sdwa v79, v0, v134 dst_sel:DWORD dst_unused:UNUSED_PAD src0_sel:WORD_1 src1_sel:DWORD
	v_add3_u32 v3, v3, v80, s31
	v_add3_u32 v2, v2, v81, s31
	v_add3_u32 v0, v0, v79, s31
	v_add3_u32 v1, v1, v78, s31
	v_and_b32_e32 v3, 0xffff0000, v3
	v_and_b32_e32 v2, 0xffff0000, v2
	v_or_b32_sdwa v1, v3, v1 dst_sel:DWORD dst_unused:UNUSED_PAD src0_sel:DWORD src1_sel:WORD_1
	v_or_b32_sdwa v0, v2, v0 dst_sel:DWORD dst_unused:UNUSED_PAD src0_sel:DWORD src1_sel:WORD_1
	global_store_dwordx2 v[74:75], v[0:1], off offset:2560 nt
	global_load_dwordx4 v[0:3], v[48:49], off
	v_mov_b32_e32 v78, v4
	v_mov_b32_e32 v79, v6
	v_mov_b32_e32 v6, v5
	v_pk_mul_f32 v[4:5], v[78:79], v[124:125] op_sel_hi:[1,0]
	v_pk_mul_f32 v[6:7], v[6:7], v[124:125] op_sel_hi:[1,0]
	s_waitcnt vmcnt(0)
	v_mov_b32_e32 v79, v2
	v_mov_b32_e32 v2, v1
	v_mov_b32_e32 v78, v0
	v_pk_mul_f32 v[2:3], v[6:7], v[2:3]
	v_pk_mul_f32 v[0:1], v[4:5], v[78:79]
	v_and_b32_sdwa v6, v3, v134 dst_sel:DWORD dst_unused:UNUSED_PAD src0_sel:WORD_1 src1_sel:DWORD
	v_and_b32_sdwa v7, v2, v134 dst_sel:DWORD dst_unused:UNUSED_PAD src0_sel:WORD_1 src1_sel:DWORD
	v_and_b32_sdwa v4, v1, v134 dst_sel:DWORD dst_unused:UNUSED_PAD src0_sel:WORD_1 src1_sel:DWORD
	v_and_b32_sdwa v5, v0, v134 dst_sel:DWORD dst_unused:UNUSED_PAD src0_sel:WORD_1 src1_sel:DWORD
	v_add3_u32 v3, v3, v6, s31
	v_add3_u32 v2, v2, v7, s31
	v_add3_u32 v0, v0, v5, s31
	v_add3_u32 v1, v1, v4, s31
	v_and_b32_e32 v3, 0xffff0000, v3
	v_and_b32_e32 v2, 0xffff0000, v2
	v_or_b32_sdwa v1, v3, v1 dst_sel:DWORD dst_unused:UNUSED_PAD src0_sel:DWORD src1_sel:WORD_1
	v_or_b32_sdwa v0, v2, v0 dst_sel:DWORD dst_unused:UNUSED_PAD src0_sel:DWORD src1_sel:WORD_1
	global_store_dwordx2 v[74:75], v[0:1], off offset:3072 nt
	global_load_dwordx4 v[0:3], v[50:51], off
	v_pk_mul_f32 v[6:7], v[92:93], v[124:125] op_sel_hi:[1,0]
	v_pk_mul_f32 v[4:5], v[96:97], v[124:125] op_sel_hi:[1,0]
	s_waitcnt vmcnt(0)
	v_mov_b32_e32 v79, v2
	v_mov_b32_e32 v2, v1
	v_mov_b32_e32 v78, v0
	v_pk_mul_f32 v[2:3], v[6:7], v[2:3]
	v_pk_mul_f32 v[0:1], v[4:5], v[78:79]
	v_and_b32_sdwa v6, v3, v134 dst_sel:DWORD dst_unused:UNUSED_PAD src0_sel:WORD_1 src1_sel:DWORD
	v_and_b32_sdwa v7, v2, v134 dst_sel:DWORD dst_unused:UNUSED_PAD src0_sel:WORD_1 src1_sel:DWORD
	v_and_b32_sdwa v4, v1, v134 dst_sel:DWORD dst_unused:UNUSED_PAD src0_sel:WORD_1 src1_sel:DWORD
	v_and_b32_sdwa v5, v0, v134 dst_sel:DWORD dst_unused:UNUSED_PAD src0_sel:WORD_1 src1_sel:DWORD
	v_add3_u32 v3, v3, v6, s31
	v_add3_u32 v2, v2, v7, s31
	v_add3_u32 v0, v0, v5, s31
	v_add3_u32 v1, v1, v4, s31
	v_and_b32_e32 v3, 0xffff0000, v3
	v_and_b32_e32 v2, 0xffff0000, v2
	v_or_b32_sdwa v1, v3, v1 dst_sel:DWORD dst_unused:UNUSED_PAD src0_sel:DWORD src1_sel:WORD_1
	v_or_b32_sdwa v0, v2, v0 dst_sel:DWORD dst_unused:UNUSED_PAD src0_sel:DWORD src1_sel:WORD_1
	global_store_dwordx2 v[74:75], v[0:1], off offset:3584 nt
	global_load_dwordx4 v[0:3], v[52:53], off
	v_pk_mul_f32 v[6:7], v[100:101], v[124:125] op_sel_hi:[1,0]
	v_pk_mul_f32 v[4:5], v[102:103], v[124:125] op_sel_hi:[1,0]
	s_waitcnt vmcnt(0)
	v_mov_b32_e32 v75, v2
	v_mov_b32_e32 v2, v1
	v_mov_b32_e32 v74, v0
	v_pk_mul_f32 v[2:3], v[6:7], v[2:3]
	v_pk_mul_f32 v[0:1], v[4:5], v[74:75]
	v_and_b32_sdwa v6, v3, v134 dst_sel:DWORD dst_unused:UNUSED_PAD src0_sel:WORD_1 src1_sel:DWORD
	v_and_b32_sdwa v7, v2, v134 dst_sel:DWORD dst_unused:UNUSED_PAD src0_sel:WORD_1 src1_sel:DWORD
	v_and_b32_sdwa v4, v1, v134 dst_sel:DWORD dst_unused:UNUSED_PAD src0_sel:WORD_1 src1_sel:DWORD
	v_and_b32_sdwa v5, v0, v134 dst_sel:DWORD dst_unused:UNUSED_PAD src0_sel:WORD_1 src1_sel:DWORD
	v_add3_u32 v3, v3, v6, s31
	v_add3_u32 v2, v2, v7, s31
	v_add3_u32 v0, v0, v5, s31
	v_add3_u32 v1, v1, v4, s31
	v_and_b32_e32 v3, 0xffff0000, v3
	v_and_b32_e32 v2, 0xffff0000, v2
	v_or_b32_sdwa v1, v3, v1 dst_sel:DWORD dst_unused:UNUSED_PAD src0_sel:DWORD src1_sel:WORD_1
	v_or_b32_sdwa v0, v2, v0 dst_sel:DWORD dst_unused:UNUSED_PAD src0_sel:DWORD src1_sel:WORD_1
	global_store_dwordx2 v[76:77], v[0:1], off nt
	global_load_dwordx4 v[0:3], v[54:55], off
	v_pk_mul_f32 v[6:7], v[108:109], v[124:125] op_sel_hi:[1,0]
	v_pk_mul_f32 v[4:5], v[110:111], v[124:125] op_sel_hi:[1,0]
	s_waitcnt vmcnt(0)
	v_mov_b32_e32 v75, v2
	v_mov_b32_e32 v2, v1
	v_mov_b32_e32 v74, v0
	v_pk_mul_f32 v[2:3], v[6:7], v[2:3]
	v_pk_mul_f32 v[0:1], v[4:5], v[74:75]
	v_and_b32_sdwa v6, v3, v134 dst_sel:DWORD dst_unused:UNUSED_PAD src0_sel:WORD_1 src1_sel:DWORD
	v_and_b32_sdwa v7, v2, v134 dst_sel:DWORD dst_unused:UNUSED_PAD src0_sel:WORD_1 src1_sel:DWORD
	v_and_b32_sdwa v4, v1, v134 dst_sel:DWORD dst_unused:UNUSED_PAD src0_sel:WORD_1 src1_sel:DWORD
	v_and_b32_sdwa v5, v0, v134 dst_sel:DWORD dst_unused:UNUSED_PAD src0_sel:WORD_1 src1_sel:DWORD
	v_add3_u32 v3, v3, v6, s31
	v_add3_u32 v2, v2, v7, s31
	v_add3_u32 v0, v0, v5, s31
	v_add3_u32 v1, v1, v4, s31
	v_and_b32_e32 v3, 0xffff0000, v3
	v_and_b32_e32 v2, 0xffff0000, v2
	v_or_b32_sdwa v1, v3, v1 dst_sel:DWORD dst_unused:UNUSED_PAD src0_sel:DWORD src1_sel:WORD_1
	v_or_b32_sdwa v0, v2, v0 dst_sel:DWORD dst_unused:UNUSED_PAD src0_sel:DWORD src1_sel:WORD_1
	global_store_dwordx2 v[76:77], v[0:1], off offset:512 nt
	global_load_dwordx4 v[0:3], v[56:57], off
	v_mov_b32_e32 v5, v10
	v_mov_b32_e32 v10, v9
	v_mov_b32_e32 v4, v8
	v_pk_mul_f32 v[6:7], v[10:11], v[124:125] op_sel_hi:[1,0]
	v_pk_mul_f32 v[4:5], v[4:5], v[124:125] op_sel_hi:[1,0]
	s_waitcnt vmcnt(0)
	v_mov_b32_e32 v9, v2
	v_mov_b32_e32 v2, v1
	v_mov_b32_e32 v8, v0
	v_pk_mul_f32 v[2:3], v[6:7], v[2:3]
	v_pk_mul_f32 v[0:1], v[4:5], v[8:9]
	v_and_b32_sdwa v6, v3, v134 dst_sel:DWORD dst_unused:UNUSED_PAD src0_sel:WORD_1 src1_sel:DWORD
	v_and_b32_sdwa v7, v2, v134 dst_sel:DWORD dst_unused:UNUSED_PAD src0_sel:WORD_1 src1_sel:DWORD
	v_and_b32_sdwa v4, v1, v134 dst_sel:DWORD dst_unused:UNUSED_PAD src0_sel:WORD_1 src1_sel:DWORD
	v_and_b32_sdwa v5, v0, v134 dst_sel:DWORD dst_unused:UNUSED_PAD src0_sel:WORD_1 src1_sel:DWORD
	v_add3_u32 v3, v3, v6, s31
	v_add3_u32 v2, v2, v7, s31
	v_add3_u32 v0, v0, v5, s31
	v_add3_u32 v1, v1, v4, s31
	v_and_b32_e32 v3, 0xffff0000, v3
	v_and_b32_e32 v2, 0xffff0000, v2
	v_or_b32_sdwa v1, v3, v1 dst_sel:DWORD dst_unused:UNUSED_PAD src0_sel:DWORD src1_sel:WORD_1
	v_or_b32_sdwa v0, v2, v0 dst_sel:DWORD dst_unused:UNUSED_PAD src0_sel:DWORD src1_sel:WORD_1
	global_store_dwordx2 v[76:77], v[0:1], off offset:1024 nt
	global_load_dwordx4 v[0:3], v[58:59], off
	v_pk_mul_f32 v[6:7], v[104:105], v[124:125] op_sel_hi:[1,0]
	v_pk_mul_f32 v[4:5], v[106:107], v[124:125] op_sel_hi:[1,0]
	s_waitcnt vmcnt(0)
	v_mov_b32_e32 v9, v2
	v_mov_b32_e32 v2, v1
	v_mov_b32_e32 v8, v0
	v_pk_mul_f32 v[2:3], v[6:7], v[2:3]
	v_pk_mul_f32 v[0:1], v[4:5], v[8:9]
	v_and_b32_sdwa v6, v3, v134 dst_sel:DWORD dst_unused:UNUSED_PAD src0_sel:WORD_1 src1_sel:DWORD
	v_and_b32_sdwa v7, v2, v134 dst_sel:DWORD dst_unused:UNUSED_PAD src0_sel:WORD_1 src1_sel:DWORD
	v_and_b32_sdwa v4, v1, v134 dst_sel:DWORD dst_unused:UNUSED_PAD src0_sel:WORD_1 src1_sel:DWORD
	v_and_b32_sdwa v5, v0, v134 dst_sel:DWORD dst_unused:UNUSED_PAD src0_sel:WORD_1 src1_sel:DWORD
	v_add3_u32 v3, v3, v6, s31
	v_add3_u32 v2, v2, v7, s31
	v_add3_u32 v0, v0, v5, s31
	v_add3_u32 v1, v1, v4, s31
	v_and_b32_e32 v3, 0xffff0000, v3
	v_and_b32_e32 v2, 0xffff0000, v2
	v_or_b32_sdwa v1, v3, v1 dst_sel:DWORD dst_unused:UNUSED_PAD src0_sel:DWORD src1_sel:WORD_1
	v_or_b32_sdwa v0, v2, v0 dst_sel:DWORD dst_unused:UNUSED_PAD src0_sel:DWORD src1_sel:WORD_1
	global_store_dwordx2 v[76:77], v[0:1], off offset:1536 nt
	global_load_dwordx4 v[0:3], v[60:61], off
	v_pk_mul_f32 v[6:7], v[112:113], v[124:125] op_sel_hi:[1,0]
	v_pk_mul_f32 v[4:5], v[114:115], v[124:125] op_sel_hi:[1,0]
	s_waitcnt vmcnt(0)
	v_mov_b32_e32 v9, v2
	v_mov_b32_e32 v2, v1
	v_mov_b32_e32 v8, v0
	v_pk_mul_f32 v[2:3], v[6:7], v[2:3]
	v_pk_mul_f32 v[0:1], v[4:5], v[8:9]
	v_and_b32_sdwa v6, v3, v134 dst_sel:DWORD dst_unused:UNUSED_PAD src0_sel:WORD_1 src1_sel:DWORD
	v_and_b32_sdwa v7, v2, v134 dst_sel:DWORD dst_unused:UNUSED_PAD src0_sel:WORD_1 src1_sel:DWORD
	v_and_b32_sdwa v4, v1, v134 dst_sel:DWORD dst_unused:UNUSED_PAD src0_sel:WORD_1 src1_sel:DWORD
	v_and_b32_sdwa v5, v0, v134 dst_sel:DWORD dst_unused:UNUSED_PAD src0_sel:WORD_1 src1_sel:DWORD
	v_add3_u32 v3, v3, v6, s31
	v_add3_u32 v2, v2, v7, s31
	v_add3_u32 v0, v0, v5, s31
	v_add3_u32 v1, v1, v4, s31
	v_and_b32_e32 v3, 0xffff0000, v3
	v_and_b32_e32 v2, 0xffff0000, v2
	v_or_b32_sdwa v1, v3, v1 dst_sel:DWORD dst_unused:UNUSED_PAD src0_sel:DWORD src1_sel:WORD_1
	v_or_b32_sdwa v0, v2, v0 dst_sel:DWORD dst_unused:UNUSED_PAD src0_sel:DWORD src1_sel:WORD_1
	global_store_dwordx2 v[76:77], v[0:1], off offset:2048 nt
	global_load_dwordx4 v[0:3], v[62:63], off
	v_pk_mul_f32 v[6:7], v[116:117], v[124:125] op_sel_hi:[1,0]
	v_pk_mul_f32 v[4:5], v[118:119], v[124:125] op_sel_hi:[1,0]
	s_waitcnt vmcnt(0)
	v_mov_b32_e32 v9, v2
	v_mov_b32_e32 v2, v1
	v_mov_b32_e32 v8, v0
	v_pk_mul_f32 v[2:3], v[6:7], v[2:3]
	v_pk_mul_f32 v[0:1], v[4:5], v[8:9]
	v_and_b32_sdwa v6, v3, v134 dst_sel:DWORD dst_unused:UNUSED_PAD src0_sel:WORD_1 src1_sel:DWORD
	v_and_b32_sdwa v7, v2, v134 dst_sel:DWORD dst_unused:UNUSED_PAD src0_sel:WORD_1 src1_sel:DWORD
	v_and_b32_sdwa v4, v1, v134 dst_sel:DWORD dst_unused:UNUSED_PAD src0_sel:WORD_1 src1_sel:DWORD
	v_and_b32_sdwa v5, v0, v134 dst_sel:DWORD dst_unused:UNUSED_PAD src0_sel:WORD_1 src1_sel:DWORD
	v_add3_u32 v3, v3, v6, s31
	v_add3_u32 v2, v2, v7, s31
	v_add3_u32 v0, v0, v5, s31
	v_add3_u32 v1, v1, v4, s31
	v_and_b32_e32 v3, 0xffff0000, v3
	v_and_b32_e32 v2, 0xffff0000, v2
	v_or_b32_sdwa v1, v3, v1 dst_sel:DWORD dst_unused:UNUSED_PAD src0_sel:DWORD src1_sel:WORD_1
	v_or_b32_sdwa v0, v2, v0 dst_sel:DWORD dst_unused:UNUSED_PAD src0_sel:DWORD src1_sel:WORD_1
	global_store_dwordx2 v[76:77], v[0:1], off offset:2560 nt
	global_load_dwordx4 v[0:3], v[64:65], off
	v_mov_b32_e32 v5, v14
	v_mov_b32_e32 v14, v13
	v_mov_b32_e32 v4, v12
	v_pk_mul_f32 v[6:7], v[14:15], v[124:125] op_sel_hi:[1,0]
	v_pk_mul_f32 v[4:5], v[4:5], v[124:125] op_sel_hi:[1,0]
	s_waitcnt vmcnt(0)
	v_mov_b32_e32 v9, v2
	v_mov_b32_e32 v2, v1
	v_mov_b32_e32 v8, v0
	v_pk_mul_f32 v[2:3], v[6:7], v[2:3]
	v_pk_mul_f32 v[0:1], v[4:5], v[8:9]
	v_and_b32_sdwa v6, v3, v134 dst_sel:DWORD dst_unused:UNUSED_PAD src0_sel:WORD_1 src1_sel:DWORD
	v_and_b32_sdwa v7, v2, v134 dst_sel:DWORD dst_unused:UNUSED_PAD src0_sel:WORD_1 src1_sel:DWORD
	v_and_b32_sdwa v4, v1, v134 dst_sel:DWORD dst_unused:UNUSED_PAD src0_sel:WORD_1 src1_sel:DWORD
	v_and_b32_sdwa v5, v0, v134 dst_sel:DWORD dst_unused:UNUSED_PAD src0_sel:WORD_1 src1_sel:DWORD
	v_add3_u32 v3, v3, v6, s31
	v_add3_u32 v2, v2, v7, s31
	v_add3_u32 v0, v0, v5, s31
	v_add3_u32 v1, v1, v4, s31
	v_and_b32_e32 v3, 0xffff0000, v3
	v_and_b32_e32 v2, 0xffff0000, v2
	v_or_b32_sdwa v1, v3, v1 dst_sel:DWORD dst_unused:UNUSED_PAD src0_sel:DWORD src1_sel:WORD_1
	v_or_b32_sdwa v0, v2, v0 dst_sel:DWORD dst_unused:UNUSED_PAD src0_sel:DWORD src1_sel:WORD_1
	global_store_dwordx2 v[76:77], v[0:1], off offset:3072 nt
	global_load_dwordx4 v[0:3], v[66:67], off
	v_pk_mul_f32 v[6:7], v[120:121], v[124:125] op_sel_hi:[1,0]
	v_pk_mul_f32 v[4:5], v[122:123], v[124:125] op_sel_hi:[1,0]
	s_waitcnt vmcnt(0)
	v_mov_b32_e32 v9, v2
	v_mov_b32_e32 v2, v1
	v_mov_b32_e32 v8, v0
	v_pk_mul_f32 v[2:3], v[6:7], v[2:3]
	v_pk_mul_f32 v[0:1], v[4:5], v[8:9]
	v_and_b32_sdwa v6, v3, v134 dst_sel:DWORD dst_unused:UNUSED_PAD src0_sel:WORD_1 src1_sel:DWORD
	v_and_b32_sdwa v7, v2, v134 dst_sel:DWORD dst_unused:UNUSED_PAD src0_sel:WORD_1 src1_sel:DWORD
	v_and_b32_sdwa v4, v1, v134 dst_sel:DWORD dst_unused:UNUSED_PAD src0_sel:WORD_1 src1_sel:DWORD
	v_and_b32_sdwa v5, v0, v134 dst_sel:DWORD dst_unused:UNUSED_PAD src0_sel:WORD_1 src1_sel:DWORD
	v_add3_u32 v3, v3, v6, s31
	v_add3_u32 v2, v2, v7, s31
	v_add3_u32 v0, v0, v5, s31
	v_add3_u32 v1, v1, v4, s31
	v_and_b32_e32 v3, 0xffff0000, v3
	v_and_b32_e32 v2, 0xffff0000, v2
	v_or_b32_sdwa v1, v3, v1 dst_sel:DWORD dst_unused:UNUSED_PAD src0_sel:DWORD src1_sel:WORD_1
	v_or_b32_sdwa v0, v2, v0 dst_sel:DWORD dst_unused:UNUSED_PAD src0_sel:DWORD src1_sel:WORD_1
	global_store_dwordx2 v[76:77], v[0:1], off offset:3584 nt
	s_branch .LBB0_1691

.LBB0_2076:
	s_waitcnt lgkmcnt(0)
	v_lshl_add_u64 v[6:7], s[14:15], 0, v[108:109]
	v_add_co_u32_e32 v28, vcc, s13, v6
	v_lshl_add_u64 v[8:9], s[14:15], 0, v[110:111]
	s_nop 0
	v_addc_co_u32_e32 v29, vcc, 0, v7, vcc
	v_add_co_u32_e32 v16, vcc, s25, v6
	v_lshl_add_u64 v[18:19], s[6:7], 0, v[110:111]
	s_nop 0
	v_addc_co_u32_e32 v17, vcc, 0, v7, vcc
	v_add_co_u32_e32 v12, vcc, s23, v8
	v_lshl_add_u64 v[4:5], s[14:15], 0, v[106:107]
	s_nop 0
	v_addc_co_u32_e32 v13, vcc, 0, v9, vcc
	v_add_co_u32_e32 v30, vcc, s24, v8
	global_load_dwordx4 v[0:3], v[54:55], off
	s_nop 0
	v_addc_co_u32_e32 v31, vcc, 0, v9, vcc
	v_add_co_u32_e32 v34, vcc, s20, v18
	s_add_i32 s12, s12, s10
	s_nop 0
	v_addc_co_u32_e32 v35, vcc, 0, v19, vcc
	v_add_co_u32_e32 v22, vcc, s21, v18
	v_lshl_add_u64 v[106:107], v[106:107], 0, s[4:5]
	s_nop 0
	v_addc_co_u32_e32 v23, vcc, 0, v19, vcc
	v_add_co_u32_e32 v32, vcc, s27, v8
	v_lshl_add_u64 v[108:109], v[108:109], 0, s[16:17]
	s_nop 0
	v_addc_co_u32_e32 v33, vcc, 0, v9, vcc
	v_add_co_u32_e32 v114, vcc, s28, v8
	v_lshl_add_u64 v[110:111], v[110:111], 0, s[18:19]
	s_nop 0
	v_addc_co_u32_e32 v115, vcc, 0, v9, vcc
	v_add_co_u32_e32 v116, vcc, s22, v18
	s_cmpk_gt_i32 s12, 0x3fff
	s_nop 0
	v_addc_co_u32_e32 v117, vcc, 0, v19, vcc
	v_add_co_u32_e32 v118, vcc, s30, v6
	s_nop 1
	v_addc_co_u32_e32 v119, vcc, 0, v7, vcc
	v_add_co_u32_e32 v112, vcc, s31, v6
	s_nop 1
	v_addc_co_u32_e32 v113, vcc, 0, v7, vcc
	global_load_dword v14, v[4:5], off nt
	global_load_dwordx2 v[10:11], v[16:17], off offset:-4096 nt
	global_load_dwordx4 v[6:9], v[30:31], off offset:-4096 nt
	s_waitcnt vmcnt(2)
	ds_bpermute_b32 v15, v123, v14
	s_waitcnt vmcnt(1)
	v_lshlrev_b32_e32 v4, 16, v10
	v_and_b32_e32 v5, 0xffff0000, v10
	v_lshlrev_b32_e32 v10, 16, v11
	v_and_b32_e32 v11, 0xffff0000, v11
	s_waitcnt lgkmcnt(0)
	v_add_f32_e32 v14, v14, v15
	ds_bpermute_b32 v15, v132, v14
	s_waitcnt lgkmcnt(0)
	v_add_f32_e32 v14, v14, v15
	ds_bpermute_b32 v15, v133, v14
	s_waitcnt lgkmcnt(0)
	v_add_f32_e32 v14, v14, v15
	ds_bpermute_b32 v15, v134, v14
	s_waitcnt lgkmcnt(0)
	v_add_f32_e32 v14, v14, v15
	ds_bpermute_b32 v15, v135, v14
	s_waitcnt lgkmcnt(0)
	v_add_f32_e32 v14, v14, v15
	ds_bpermute_b32 v15, v136, v14
	s_waitcnt lgkmcnt(0)
	v_add_f32_e32 v14, v14, v15
	v_fmamk_f32 v14, v14, 0x39800000, v137
	v_mul_f32_e32 v15, 0x4f800000, v14
	v_cmp_gt_f32_e32 vcc, s11, v14
	s_nop 1
	v_cndmask_b32_e32 v14, v14, v15, vcc
	v_sqrt_f32_e32 v15, v14
	s_nop 0
	v_add_u32_e32 v20, -1, v15
	v_add_u32_e32 v21, 1, v15
	v_fma_f32 v24, -v20, v15, v14
	v_fma_f32 v25, -v21, v15, v14
	v_cmp_ge_f32_e64 s[2:3], 0, v24
	s_nop 1
	v_cndmask_b32_e64 v15, v15, v20, s[2:3]
	v_cmp_lt_f32_e64 s[2:3], 0, v25
	s_nop 1
	v_cndmask_b32_e64 v15, v15, v21, s[2:3]
	v_mul_f32_e32 v20, 0x37800000, v15
	v_cndmask_b32_e32 v15, v15, v20, vcc
	v_cmp_class_f32_e32 vcc, v14, v138
	s_nop 1
	v_cndmask_b32_e32 v14, v15, v14, vcc
	v_div_scale_f32 v15, s[2:3], v14, v14, 1.0
	v_rcp_f32_e32 v21, v15
	v_div_scale_f32 v20, vcc, 1.0, v14, 1.0
	v_fma_f32 v24, -v15, v21, 1.0
	v_fmac_f32_e32 v21, v24, v21
	v_mul_f32_e32 v24, v20, v21
	v_fma_f32 v25, -v15, v24, v20
	v_fmac_f32_e32 v24, v25, v21
	v_fma_f32 v15, -v15, v24, v20
	v_div_fmas_f32 v15, v15, v21, v24
	v_div_fixup_f32 v122, v15, v14, 1.0
	v_pk_mul_f32 v[4:5], v[122:123], v[4:5] op_sel_hi:[0,1]
	v_pk_mul_f32 v[10:11], v[122:123], v[10:11] op_sel_hi:[0,1]
	s_waitcnt vmcnt(0)
	v_pk_fma_f32 v[0:1], v[0:1], v[4:5], v[6:7]
	v_pk_fma_f32 v[2:3], v[2:3], v[10:11], v[8:9]
	global_store_dwordx4 v[18:19], v[0:3], off nt
	v_mov_b32_e32 v120, v0
	v_mov_b32_e32 v121, v2
	v_mov_b32_e32 v2, v1
	global_load_dwordx2 v[0:1], v[28:29], off offset:512 nt
	global_load_dwordx4 v[4:7], v[12:13], off offset:1024 nt
	global_load_dwordx4 v[8:11], v[54:55], off offset:1024
	v_pk_mul_f32 v[14:15], v[2:3], v[2:3]
	s_nop 0
	v_pk_fma_f32 v[14:15], v[120:121], v[120:121], v[14:15]
	s_nop 0
	v_pk_add_f32 v[40:41], v[14:15], v[14:15] op_sel:[0,1] op_sel_hi:[1,0]
	s_waitcnt vmcnt(2)
	v_lshlrev_b32_e32 v14, 16, v0
	v_and_b32_e32 v15, 0xffff0000, v0
	v_lshlrev_b32_e32 v0, 16, v1
	v_and_b32_e32 v1, 0xffff0000, v1
	v_pk_mul_f32 v[14:15], v[122:123], v[14:15] op_sel_hi:[0,1]
	v_pk_mul_f32 v[0:1], v[122:123], v[0:1] op_sel_hi:[0,1]
	s_waitcnt vmcnt(0)
	v_pk_fma_f32 v[4:5], v[8:9], v[14:15], v[4:5]
	v_pk_fma_f32 v[6:7], v[10:11], v[0:1], v[6:7]
	global_store_dwordx4 v[18:19], v[4:7], off offset:1024 nt
	v_mov_b32_e32 v0, v4
	v_mov_b32_e32 v1, v6
	v_mov_b32_e32 v6, v5
	global_load_dwordx2 v[4:5], v[28:29], off offset:1024 nt
	global_load_dwordx4 v[8:11], v[12:13], off offset:2048 nt
	global_load_dwordx4 v[24:27], v[54:55], off offset:2048
	v_pk_mul_f32 v[14:15], v[6:7], v[6:7]
	s_nop 0
	v_pk_fma_f32 v[14:15], v[0:1], v[0:1], v[14:15]
	s_nop 0
	v_pk_add_f32 v[42:43], v[14:15], v[14:15] op_sel:[0,1] op_sel_hi:[1,0]
	s_waitcnt vmcnt(2)
	v_lshlrev_b32_e32 v14, 16, v4
	v_and_b32_e32 v15, 0xffff0000, v4
	v_lshlrev_b32_e32 v4, 16, v5
	v_and_b32_e32 v5, 0xffff0000, v5
	v_pk_mul_f32 v[14:15], v[122:123], v[14:15] op_sel_hi:[0,1]
	v_pk_mul_f32 v[4:5], v[122:123], v[4:5] op_sel_hi:[0,1]
	s_waitcnt vmcnt(0)
	v_pk_fma_f32 v[8:9], v[24:25], v[14:15], v[8:9]
	v_pk_fma_f32 v[10:11], v[26:27], v[4:5], v[10:11]
	global_store_dwordx4 v[18:19], v[8:11], off offset:2048 nt
	global_load_dwordx2 v[44:45], v[28:29], off offset:1536 nt
	global_load_dwordx4 v[24:27], v[12:13], off offset:3072 nt
	global_load_dwordx4 v[36:39], v[54:55], off offset:3072
	v_mul_f32_e32 v14, v9, v9
	v_mul_f32_e32 v20, v11, v11
	v_mov_b32_e32 v4, v8
	v_mov_b32_e32 v5, v10
	v_pk_fma_f32 v[46:47], v[8:9], v[8:9], v[14:15] op_sel_hi:[1,1,0]
	v_pk_fma_f32 v[48:49], v[10:11], v[10:11], v[20:21] op_sel_hi:[1,1,0]
	v_mov_b32_e32 v10, v9
	s_waitcnt vmcnt(2)
	v_lshlrev_b32_e32 v8, 16, v44
	v_and_b32_e32 v9, 0xffff0000, v44
	v_lshlrev_b32_e32 v12, 16, v45
	v_and_b32_e32 v13, 0xffff0000, v45
	v_pk_mul_f32 v[8:9], v[122:123], v[8:9] op_sel_hi:[0,1]
	v_pk_mul_f32 v[14:15], v[122:123], v[12:13] op_sel_hi:[0,1]
	s_waitcnt vmcnt(0)
	v_pk_fma_f32 v[12:13], v[36:37], v[8:9], v[24:25]
	v_pk_fma_f32 v[14:15], v[38:39], v[14:15], v[26:27]
	global_store_dwordx4 v[18:19], v[12:15], off offset:3072 nt
	v_pk_mul_f32 v[36:37], v[12:13], v[12:13]
	v_pk_mul_f32 v[38:39], v[14:15], v[14:15]
	v_mov_b32_e32 v8, v12
	v_mov_b32_e32 v9, v14
	v_mov_b32_e32 v14, v13
	global_load_dwordx2 v[12:13], v[28:29], off offset:2048 nt
	global_load_dwordx4 v[18:21], v[30:31], off nt
	global_load_dwordx4 v[24:27], v[56:57], off
	v_mov_b32_e32 v41, v36
	v_mov_b32_e32 v43, v37
	v_mov_b32_e32 v47, v38
	v_mov_b32_e32 v49, v39
	v_pk_add_f32 v[36:37], v[40:41], v[42:43]
	v_pk_add_f32 v[38:39], v[46:47], v[48:49]
	s_nop 0
	v_pk_add_f32 v[36:37], v[36:37], v[38:39]
	s_nop 0
	v_pk_add_f32 v[40:41], v[36:37], v[36:37] op_sel:[0,1] op_sel_hi:[1,0]
	s_waitcnt vmcnt(2)
	v_lshlrev_b32_e32 v36, 16, v12
	v_and_b32_e32 v37, 0xffff0000, v12
	v_lshlrev_b32_e32 v12, 16, v13
	v_and_b32_e32 v13, 0xffff0000, v13
	v_pk_mul_f32 v[36:37], v[122:123], v[36:37] op_sel_hi:[0,1]
	v_pk_mul_f32 v[12:13], v[122:123], v[12:13] op_sel_hi:[0,1]
	s_waitcnt vmcnt(0)
	v_pk_fma_f32 v[18:19], v[24:25], v[36:37], v[18:19]
	v_pk_fma_f32 v[20:21], v[26:27], v[12:13], v[20:21]
	global_store_dwordx4 v[22:23], v[18:21], off offset:-4096 nt
	v_mov_b32_e32 v12, v18
	v_mov_b32_e32 v13, v20
	v_mov_b32_e32 v20, v19
	global_load_dwordx2 v[18:19], v[28:29], off offset:2560 nt
	global_load_dwordx4 v[24:27], v[30:31], off offset:1024 nt
	global_load_dwordx4 v[36:39], v[58:59], off
	v_pk_mul_f32 v[42:43], v[20:21], v[20:21]
	s_nop 0
	v_pk_fma_f32 v[42:43], v[12:13], v[12:13], v[42:43]
	s_nop 0
	v_pk_add_f32 v[46:47], v[42:43], v[42:43] op_sel:[0,1] op_sel_hi:[1,0]
	s_waitcnt vmcnt(2)
	v_lshlrev_b32_e32 v42, 16, v18
	v_and_b32_e32 v43, 0xffff0000, v18
	v_lshlrev_b32_e32 v18, 16, v19
	v_and_b32_e32 v19, 0xffff0000, v19
	v_pk_mul_f32 v[42:43], v[122:123], v[42:43] op_sel_hi:[0,1]
	v_pk_mul_f32 v[18:19], v[122:123], v[18:19] op_sel_hi:[0,1]
	s_waitcnt vmcnt(0)
	v_pk_fma_f32 v[24:25], v[36:37], v[42:43], v[24:25]
	v_pk_fma_f32 v[26:27], v[38:39], v[18:19], v[26:27]
	global_store_dwordx4 v[34:35], v[24:27], off offset:1024 nt
	global_load_dwordx2 v[50:51], v[28:29], off offset:3072 nt
	global_load_dwordx4 v[36:39], v[30:31], off offset:2048 nt
	global_load_dwordx4 v[42:45], v[60:61], off
	v_mul_f32_e32 v18, v25, v25
	v_mul_f32_e32 v48, v27, v27
	v_mov_b32_e32 v124, v24
	v_mov_b32_e32 v125, v26
	v_pk_fma_f32 v[18:19], v[24:25], v[24:25], v[18:19] op_sel_hi:[1,1,0]
	v_pk_fma_f32 v[48:49], v[26:27], v[26:27], v[48:49] op_sel_hi:[1,1,0]
	v_mov_b32_e32 v26, v25
	s_waitcnt vmcnt(2)
	v_lshlrev_b32_e32 v24, 16, v50
	v_and_b32_e32 v25, 0xffff0000, v50
	v_lshlrev_b32_e32 v50, 16, v51
	v_and_b32_e32 v51, 0xffff0000, v51
	v_pk_mul_f32 v[24:25], v[122:123], v[24:25] op_sel_hi:[0,1]
	v_pk_mul_f32 v[50:51], v[122:123], v[50:51] op_sel_hi:[0,1]
	s_waitcnt vmcnt(0)
	v_pk_fma_f32 v[42:43], v[42:43], v[24:25], v[36:37]
	v_pk_fma_f32 v[44:45], v[44:45], v[50:51], v[38:39]
	global_store_dwordx4 v[34:35], v[42:45], off offset:2048 nt
	v_pk_mul_f32 v[24:25], v[42:43], v[42:43]
	v_pk_mul_f32 v[50:51], v[44:45], v[44:45]
	v_mov_b32_e32 v128, v42
	v_mov_b32_e32 v129, v44
	v_mov_b32_e32 v44, v43
	global_load_dwordx2 v[42:43], v[28:29], off offset:3584 nt
	s_nop 0
	global_load_dwordx4 v[28:31], v[30:31], off offset:3072 nt
	s_nop 0
	global_load_dwordx4 v[36:39], v[62:63], off
	v_mov_b32_e32 v41, v24
	v_mov_b32_e32 v47, v25
	v_mov_b32_e32 v19, v50
	v_mov_b32_e32 v49, v51
	v_pk_add_f32 v[24:25], v[40:41], v[46:47]
	v_pk_add_f32 v[18:19], v[18:19], v[48:49]
	s_waitcnt vmcnt(2)
	v_lshlrev_b32_e32 v40, 16, v43
	v_pk_add_f32 v[18:19], v[24:25], v[18:19]
	v_lshlrev_b32_e32 v24, 16, v42
	v_and_b32_e32 v25, 0xffff0000, v42
	v_and_b32_e32 v41, 0xffff0000, v43
	v_pk_mul_f32 v[24:25], v[122:123], v[24:25] op_sel_hi:[0,1]
	v_pk_mul_f32 v[40:41], v[122:123], v[40:41] op_sel_hi:[0,1]
	s_waitcnt vmcnt(0)
	v_pk_fma_f32 v[46:47], v[36:37], v[24:25], v[28:29]
	v_pk_fma_f32 v[48:49], v[38:39], v[40:41], v[30:31]
	global_store_dwordx4 v[34:35], v[46:49], off offset:3072 nt
	global_load_dwordx2 v[24:25], v[16:17], off nt
	global_load_dwordx4 v[28:31], v[114:115], off offset:-4096 nt
	s_nop 0
	global_load_dwordx4 v[34:37], v[64:65], off
	v_mov_b32_e32 v130, v46
	v_mov_b32_e32 v131, v48
	v_mov_b32_e32 v48, v47
	v_pk_mul_f32 v[38:39], v[48:49], v[48:49]
	v_pk_add_f32 v[18:19], v[18:19], v[18:19] op_sel:[0,1] op_sel_hi:[1,0]
	v_pk_fma_f32 v[38:39], v[130:131], v[130:131], v[38:39]
	s_waitcnt vmcnt(2)
	v_lshlrev_b32_e32 v40, 16, v24
	v_and_b32_e32 v41, 0xffff0000, v24
	v_lshlrev_b32_e32 v24, 16, v25
	v_and_b32_e32 v25, 0xffff0000, v25
	v_pk_mul_f32 v[40:41], v[122:123], v[40:41] op_sel_hi:[0,1]
	v_pk_mul_f32 v[24:25], v[122:123], v[24:25] op_sel_hi:[0,1]
	s_waitcnt vmcnt(0)
	v_pk_fma_f32 v[50:51], v[34:35], v[40:41], v[28:29]
	v_pk_fma_f32 v[52:53], v[36:37], v[24:25], v[30:31]
	global_store_dwordx4 v[22:23], v[50:53], off nt
	global_load_dwordx2 v[42:43], v[16:17], off offset:512 nt
	global_load_dwordx4 v[28:31], v[32:33], off offset:1024 nt
	global_load_dwordx4 v[34:37], v[66:67], off
	v_mul_f32_e32 v40, v53, v53
	v_pk_fma_f32 v[46:47], v[52:53], v[52:53], v[40:41] op_sel_hi:[1,1,0]
	v_mul_f32_e32 v24, v51, v51
	v_mov_b32_e32 v144, v50
	v_mov_b32_e32 v145, v52
	v_pk_fma_f32 v[24:25], v[50:51], v[50:51], v[24:25] op_sel_hi:[1,1,0]
	v_mov_b32_e32 v52, v51
	v_pk_add_f32 v[38:39], v[38:39], v[38:39] op_sel:[0,1] op_sel_hi:[1,0]
	s_waitcnt vmcnt(2)
	v_lshlrev_b32_e32 v40, 16, v42
	v_and_b32_e32 v41, 0xffff0000, v42
	v_lshlrev_b32_e32 v42, 16, v43
	v_and_b32_e32 v43, 0xffff0000, v43
	v_pk_mul_f32 v[40:41], v[122:123], v[40:41] op_sel_hi:[0,1]
	v_pk_mul_f32 v[42:43], v[122:123], v[42:43] op_sel_hi:[0,1]
	s_waitcnt vmcnt(0)
	v_pk_fma_f32 v[34:35], v[34:35], v[40:41], v[28:29]
	v_pk_fma_f32 v[36:37], v[36:37], v[42:43], v[30:31]
	global_store_dwordx4 v[22:23], v[34:37], off offset:1024 nt
	v_pk_mul_f32 v[126:127], v[34:35], v[34:35]
	v_pk_mul_f32 v[140:141], v[36:37], v[36:37]
	v_mov_b32_e32 v50, v34
	v_mov_b32_e32 v51, v36
	v_mov_b32_e32 v36, v35
	global_load_dwordx2 v[34:35], v[16:17], off offset:1024 nt
	global_load_dwordx4 v[28:31], v[32:33], off offset:2048 nt
	global_load_dwordx4 v[40:43], v[68:69], off
	v_mov_b32_e32 v19, v126
	v_mov_b32_e32 v39, v127
	v_mov_b32_e32 v25, v140
	v_mov_b32_e32 v47, v141
	v_pk_add_f32 v[18:19], v[18:19], v[38:39]
	v_pk_add_f32 v[24:25], v[24:25], v[46:47]
	s_nop 0
	v_pk_add_f32 v[18:19], v[18:19], v[24:25]
	s_waitcnt vmcnt(2)
	v_lshlrev_b32_e32 v24, 16, v34
	v_and_b32_e32 v25, 0xffff0000, v34
	v_lshlrev_b32_e32 v34, 16, v35
	v_and_b32_e32 v35, 0xffff0000, v35
	v_pk_mul_f32 v[24:25], v[122:123], v[24:25] op_sel_hi:[0,1]
	v_pk_mul_f32 v[34:35], v[122:123], v[34:35] op_sel_hi:[0,1]
	s_waitcnt vmcnt(0)
	v_pk_fma_f32 v[40:41], v[40:41], v[24:25], v[28:29]
	v_pk_fma_f32 v[42:43], v[42:43], v[34:35], v[30:31]
	global_store_dwordx4 v[22:23], v[40:43], off offset:2048 nt
	global_load_dwordx2 v[24:25], v[16:17], off offset:1536 nt
	global_load_dwordx4 v[28:31], v[32:33], off offset:3072 nt
	s_nop 0
	global_load_dwordx4 v[32:35], v[70:71], off
	v_mov_b32_e32 v127, v42
	v_mov_b32_e32 v42, v41
	v_mov_b32_e32 v126, v40
	v_pk_mul_f32 v[38:39], v[42:43], v[42:43]
	v_pk_add_f32 v[18:19], v[18:19], v[18:19] op_sel:[0,1] op_sel_hi:[1,0]
	v_pk_fma_f32 v[38:39], v[126:127], v[126:127], v[38:39]
	s_nop 0
	v_pk_add_f32 v[46:47], v[38:39], v[38:39] op_sel:[0,1] op_sel_hi:[1,0]
	s_waitcnt vmcnt(2)
	v_lshlrev_b32_e32 v38, 16, v24
	v_and_b32_e32 v39, 0xffff0000, v24
	v_lshlrev_b32_e32 v24, 16, v25
	v_and_b32_e32 v25, 0xffff0000, v25
	v_pk_mul_f32 v[38:39], v[122:123], v[38:39] op_sel_hi:[0,1]
	v_pk_mul_f32 v[24:25], v[122:123], v[24:25] op_sel_hi:[0,1]
	s_waitcnt vmcnt(0)
	v_pk_fma_f32 v[38:39], v[32:33], v[38:39], v[28:29]
	v_pk_fma_f32 v[40:41], v[34:35], v[24:25], v[30:31]
	global_store_dwordx4 v[22:23], v[38:41], off offset:3072 nt
	global_load_dwordx2 v[140:141], v[16:17], off offset:2048 nt
	s_nop 0
	global_load_dwordx4 v[22:25], v[114:115], off nt
	global_load_dwordx4 v[28:31], v[72:73], off
	v_mul_f32_e32 v32, v39, v39
	v_mul_f32_e32 v34, v41, v41
	v_pk_fma_f32 v[142:143], v[38:39], v[38:39], v[32:33] op_sel_hi:[1,1,0]
	v_pk_fma_f32 v[146:147], v[40:41], v[40:41], v[34:35] op_sel_hi:[1,1,0]
	s_waitcnt vmcnt(2)
	v_lshlrev_b32_e32 v32, 16, v140
	v_and_b32_e32 v33, 0xffff0000, v140
	v_lshlrev_b32_e32 v34, 16, v141
	v_and_b32_e32 v35, 0xffff0000, v141
	v_pk_mul_f32 v[32:33], v[122:123], v[32:33] op_sel_hi:[0,1]
	v_pk_mul_f32 v[34:35], v[122:123], v[34:35] op_sel_hi:[0,1]
	s_waitcnt vmcnt(0)
	v_pk_fma_f32 v[32:33], v[28:29], v[32:33], v[22:23]
	v_pk_fma_f32 v[34:35], v[30:31], v[34:35], v[24:25]
	global_store_dwordx4 v[116:117], v[32:35], off nt
	global_load_dwordx2 v[150:151], v[16:17], off offset:2560 nt
	global_load_dwordx4 v[22:25], v[114:115], off offset:1024 nt
	global_load_dwordx4 v[28:31], v[74:75], off
	v_pk_mul_f32 v[140:141], v[32:33], v[32:33]
	v_pk_mul_f32 v[148:149], v[34:35], v[34:35]
	v_mov_b32_e32 v19, v140
	v_mov_b32_e32 v47, v141
	v_mov_b32_e32 v143, v148
	v_mov_b32_e32 v147, v149
	v_pk_add_f32 v[18:19], v[18:19], v[46:47]
	v_pk_add_f32 v[46:47], v[142:143], v[146:147]
	s_nop 0
	v_pk_add_f32 v[18:19], v[18:19], v[46:47]
	s_waitcnt vmcnt(2)
	v_lshlrev_b32_e32 v46, 16, v151
	v_pk_add_f32 v[146:147], v[18:19], v[18:19] op_sel:[0,1] op_sel_hi:[1,0]
	v_lshlrev_b32_e32 v18, 16, v150
	v_and_b32_e32 v19, 0xffff0000, v150
	v_and_b32_e32 v47, 0xffff0000, v151
	v_pk_mul_f32 v[18:19], v[122:123], v[18:19] op_sel_hi:[0,1]
	v_pk_mul_f32 v[46:47], v[122:123], v[46:47] op_sel_hi:[0,1]
	s_waitcnt vmcnt(0)
	v_pk_fma_f32 v[28:29], v[28:29], v[18:19], v[22:23]
	v_pk_fma_f32 v[30:31], v[30:31], v[46:47], v[24:25]
	global_store_dwordx4 v[116:117], v[28:31], off offset:1024 nt
	global_load_dwordx2 v[18:19], v[16:17], off offset:3072 nt
	global_load_dwordx4 v[22:25], v[114:115], off offset:2048 nt
	global_load_dwordx4 v[140:143], v[76:77], off
	v_mov_b32_e32 v47, v30
	v_mov_b32_e32 v30, v29
	v_mov_b32_e32 v46, v28
	v_pk_mul_f32 v[28:29], v[30:31], v[30:31]
	s_waitcnt vmcnt(2)
	v_lshlrev_b32_e32 v148, 16, v18
	v_and_b32_e32 v149, 0xffff0000, v18
	v_lshlrev_b32_e32 v18, 16, v19
	v_and_b32_e32 v19, 0xffff0000, v19
	v_pk_mul_f32 v[148:149], v[122:123], v[148:149] op_sel_hi:[0,1]
	v_pk_mul_f32 v[18:19], v[122:123], v[18:19] op_sel_hi:[0,1]
	s_waitcnt vmcnt(0)
	v_pk_fma_f32 v[22:23], v[140:141], v[148:149], v[22:23]
	v_pk_fma_f32 v[24:25], v[142:143], v[18:19], v[24:25]
	global_store_dwordx4 v[116:117], v[22:25], off offset:2048 nt
	global_load_dwordx2 v[152:153], v[16:17], off offset:3584 nt
	s_nop 0
	global_load_dwordx4 v[16:19], v[114:115], off offset:3072 nt
	global_load_dwordx4 v[140:143], v[78:79], off
	v_pk_fma_f32 v[28:29], v[46:47], v[46:47], v[28:29]
	v_mul_f32_e32 v148, v23, v23
	v_mul_f32_e32 v150, v25, v25
	v_pk_add_f32 v[28:29], v[28:29], v[28:29] op_sel:[0,1] op_sel_hi:[1,0]
	v_pk_fma_f32 v[148:149], v[22:23], v[22:23], v[148:149] op_sel_hi:[1,1,0]
	v_pk_fma_f32 v[150:151], v[24:25], v[24:25], v[150:151] op_sel_hi:[1,1,0]
	s_waitcnt vmcnt(2)
	v_lshlrev_b32_e32 v114, 16, v152
	v_and_b32_e32 v115, 0xffff0000, v152
	v_lshlrev_b32_e32 v152, 16, v153
	v_and_b32_e32 v153, 0xffff0000, v153
	v_pk_mul_f32 v[114:115], v[122:123], v[114:115] op_sel_hi:[0,1]
	v_pk_mul_f32 v[152:153], v[122:123], v[152:153] op_sel_hi:[0,1]
	s_waitcnt vmcnt(0)
	v_pk_fma_f32 v[16:17], v[140:141], v[114:115], v[16:17]
	v_pk_fma_f32 v[18:19], v[142:143], v[152:153], v[18:19]
	global_store_dwordx4 v[116:117], v[16:19], off offset:3072 nt
	v_pk_mul_f32 v[114:115], v[16:17], v[16:17]
	v_pk_mul_f32 v[116:117], v[18:19], v[18:19]
	v_mov_b32_e32 v147, v114
	v_mov_b32_e32 v29, v115
	v_mov_b32_e32 v149, v116
	v_mov_b32_e32 v151, v117
	global_load_dwordx4 v[114:117], v[80:81], off
	v_pk_add_f32 v[28:29], v[146:147], v[28:29]
	v_pk_add_f32 v[140:141], v[148:149], v[150:151]
	s_nop 0
	v_pk_add_f32 v[28:29], v[28:29], v[140:141]
	s_nop 0
	v_add_f32_e32 v28, v28, v29
	ds_bpermute_b32 v29, v123, v28
	s_waitcnt lgkmcnt(0)
	v_add_f32_e32 v28, v28, v29
	ds_bpermute_b32 v29, v132, v28
	s_waitcnt lgkmcnt(0)
	v_add_f32_e32 v28, v28, v29
	ds_bpermute_b32 v29, v133, v28
	s_waitcnt lgkmcnt(0)
	v_add_f32_e32 v28, v28, v29
	ds_bpermute_b32 v29, v134, v28
	s_waitcnt lgkmcnt(0)
	v_add_f32_e32 v28, v28, v29
	ds_bpermute_b32 v29, v135, v28
	s_waitcnt lgkmcnt(0)
	v_add_f32_e32 v28, v28, v29
	ds_bpermute_b32 v29, v136, v28
	s_waitcnt lgkmcnt(0)
	v_add_f32_e32 v28, v28, v29
	v_fmamk_f32 v28, v28, 0x39800000, v137
	v_mul_f32_e32 v29, 0x4f800000, v28
	v_cmp_gt_f32_e32 vcc, s11, v28
	s_nop 1
	v_cndmask_b32_e32 v28, v28, v29, vcc
	v_sqrt_f32_e32 v29, v28
	s_nop 0
	v_add_u32_e32 v122, -1, v29
	v_add_u32_e32 v140, 1, v29
	v_fma_f32 v141, -v122, v29, v28
	v_fma_f32 v142, -v140, v29, v28
	v_cmp_ge_f32_e64 s[2:3], 0, v141
	s_nop 1
	v_cndmask_b32_e64 v29, v29, v122, s[2:3]
	v_cmp_lt_f32_e64 s[2:3], 0, v142
	s_nop 1
	v_cndmask_b32_e64 v29, v29, v140, s[2:3]
	v_mul_f32_e32 v122, 0x37800000, v29
	v_cndmask_b32_e32 v29, v29, v122, vcc
	v_cmp_class_f32_e32 vcc, v28, v138
	s_nop 1
	v_cndmask_b32_e32 v28, v29, v28, vcc
	v_div_scale_f32 v29, s[2:3], v28, v28, 1.0
	v_rcp_f32_e32 v140, v29
	v_div_scale_f32 v122, vcc, 1.0, v28, 1.0
	v_fma_f32 v141, -v29, v140, 1.0
	v_fmac_f32_e32 v140, v141, v140
	v_mul_f32_e32 v141, v122, v140
	v_fma_f32 v142, -v29, v141, v122
	v_fmac_f32_e32 v141, v142, v140
	v_fma_f32 v29, -v29, v141, v122
	v_div_fmas_f32 v29, v29, v140, v141
	v_div_fixup_f32 v28, v29, v28, 1.0
	v_pk_mul_f32 v[2:3], v[2:3], v[28:29] op_sel_hi:[1,0]
	v_pk_mul_f32 v[140:141], v[0:1], v[28:29] op_sel_hi:[1,0]
	s_waitcnt vmcnt(0)
	v_mov_b32_e32 v1, v116
	v_mov_b32_e32 v116, v115
	v_pk_mul_f32 v[120:121], v[120:121], v[28:29] op_sel_hi:[1,0]
	v_mov_b32_e32 v0, v114
	v_pk_mul_f32 v[2:3], v[116:117], v[2:3]
	v_pk_mul_f32 v[0:1], v[0:1], v[120:121]
	v_and_b32_sdwa v115, v3, v139 dst_sel:DWORD dst_unused:UNUSED_PAD src0_sel:WORD_1 src1_sel:DWORD
	v_and_b32_sdwa v116, v2, v139 dst_sel:DWORD dst_unused:UNUSED_PAD src0_sel:WORD_1 src1_sel:DWORD
	v_pk_mul_f32 v[6:7], v[6:7], v[28:29] op_sel_hi:[1,0]
	v_pk_mul_f32 v[4:5], v[4:5], v[28:29] op_sel_hi:[1,0]
	v_pk_mul_f32 v[10:11], v[10:11], v[28:29] op_sel_hi:[1,0]
	v_pk_mul_f32 v[8:9], v[8:9], v[28:29] op_sel_hi:[1,0]
	v_pk_mul_f32 v[14:15], v[14:15], v[28:29] op_sel_hi:[1,0]
	v_pk_mul_f32 v[12:13], v[12:13], v[28:29] op_sel_hi:[1,0]
	v_pk_mul_f32 v[20:21], v[20:21], v[28:29] op_sel_hi:[1,0]
	v_pk_mul_f32 v[124:125], v[124:125], v[28:29] op_sel_hi:[1,0]
	v_pk_mul_f32 v[26:27], v[26:27], v[28:29] op_sel_hi:[1,0]
	v_pk_mul_f32 v[128:129], v[128:129], v[28:29] op_sel_hi:[1,0]
	v_pk_mul_f32 v[44:45], v[44:45], v[28:29] op_sel_hi:[1,0]
	v_pk_mul_f32 v[130:131], v[130:131], v[28:29] op_sel_hi:[1,0]
	v_pk_mul_f32 v[48:49], v[48:49], v[28:29] op_sel_hi:[1,0]
	v_pk_mul_f32 v[142:143], v[144:145], v[28:29] op_sel_hi:[1,0]
	v_pk_mul_f32 v[52:53], v[52:53], v[28:29] op_sel_hi:[1,0]
	v_and_b32_sdwa v29, v1, v139 dst_sel:DWORD dst_unused:UNUSED_PAD src0_sel:WORD_1 src1_sel:DWORD
	v_and_b32_sdwa v114, v0, v139 dst_sel:DWORD dst_unused:UNUSED_PAD src0_sel:WORD_1 src1_sel:DWORD
	v_add3_u32 v3, v3, v115, s29
	v_add3_u32 v2, v2, v116, s29
	v_add3_u32 v0, v0, v114, s29
	v_add3_u32 v1, v1, v29, s29
	v_and_b32_e32 v3, 0xffff0000, v3
	v_and_b32_e32 v2, 0xffff0000, v2
	v_or_b32_sdwa v1, v3, v1 dst_sel:DWORD dst_unused:UNUSED_PAD src0_sel:DWORD src1_sel:WORD_1
	v_or_b32_sdwa v0, v2, v0 dst_sel:DWORD dst_unused:UNUSED_PAD src0_sel:DWORD src1_sel:WORD_1
	global_store_dwordx2 v[112:113], v[0:1], off offset:-4096 nt
	global_load_dwordx4 v[0:3], v[80:81], off offset:1024
	s_waitcnt vmcnt(0)
	v_mov_b32_e32 v115, v2
	v_mov_b32_e32 v2, v1
	v_mov_b32_e32 v114, v0
	v_pk_mul_f32 v[2:3], v[2:3], v[6:7]
	v_pk_mul_f32 v[0:1], v[114:115], v[140:141]
	v_and_b32_sdwa v29, v3, v139 dst_sel:DWORD dst_unused:UNUSED_PAD src0_sel:WORD_1 src1_sel:DWORD
	v_and_b32_sdwa v114, v2, v139 dst_sel:DWORD dst_unused:UNUSED_PAD src0_sel:WORD_1 src1_sel:DWORD
	v_and_b32_sdwa v6, v1, v139 dst_sel:DWORD dst_unused:UNUSED_PAD src0_sel:WORD_1 src1_sel:DWORD
	v_and_b32_sdwa v7, v0, v139 dst_sel:DWORD dst_unused:UNUSED_PAD src0_sel:WORD_1 src1_sel:DWORD
	v_add3_u32 v3, v3, v29, s29
	v_add3_u32 v2, v2, v114, s29
	v_add3_u32 v0, v0, v7, s29
	v_add3_u32 v1, v1, v6, s29
	v_and_b32_e32 v3, 0xffff0000, v3
	v_and_b32_e32 v2, 0xffff0000, v2
	v_or_b32_sdwa v1, v3, v1 dst_sel:DWORD dst_unused:UNUSED_PAD src0_sel:DWORD src1_sel:WORD_1
	v_or_b32_sdwa v0, v2, v0 dst_sel:DWORD dst_unused:UNUSED_PAD src0_sel:DWORD src1_sel:WORD_1
	global_store_dwordx2 v[118:119], v[0:1], off offset:512 nt
	global_load_dwordx4 v[0:3], v[80:81], off offset:2048
	s_waitcnt vmcnt(0)
	v_mov_b32_e32 v7, v2
	v_mov_b32_e32 v2, v1
	v_mov_b32_e32 v6, v0
	v_pk_mul_f32 v[2:3], v[2:3], v[10:11]
	v_pk_mul_f32 v[0:1], v[6:7], v[4:5]
	v_and_b32_sdwa v6, v3, v139 dst_sel:DWORD dst_unused:UNUSED_PAD src0_sel:WORD_1 src1_sel:DWORD
	v_and_b32_sdwa v7, v2, v139 dst_sel:DWORD dst_unused:UNUSED_PAD src0_sel:WORD_1 src1_sel:DWORD
	v_and_b32_sdwa v4, v1, v139 dst_sel:DWORD dst_unused:UNUSED_PAD src0_sel:WORD_1 src1_sel:DWORD
	v_and_b32_sdwa v5, v0, v139 dst_sel:DWORD dst_unused:UNUSED_PAD src0_sel:WORD_1 src1_sel:DWORD
	v_add3_u32 v3, v3, v6, s29
	v_add3_u32 v2, v2, v7, s29
	v_add3_u32 v0, v0, v5, s29
	v_add3_u32 v1, v1, v4, s29
	v_and_b32_e32 v3, 0xffff0000, v3
	v_and_b32_e32 v2, 0xffff0000, v2
	v_or_b32_sdwa v1, v3, v1 dst_sel:DWORD dst_unused:UNUSED_PAD src0_sel:DWORD src1_sel:WORD_1
	v_or_b32_sdwa v0, v2, v0 dst_sel:DWORD dst_unused:UNUSED_PAD src0_sel:DWORD src1_sel:WORD_1
	global_store_dwordx2 v[118:119], v[0:1], off offset:1024 nt
	global_load_dwordx4 v[0:3], v[80:81], off offset:3072
	s_waitcnt vmcnt(0)
	v_mov_b32_e32 v5, v2
	v_mov_b32_e32 v2, v1
	v_mov_b32_e32 v4, v0
	v_pk_mul_f32 v[2:3], v[2:3], v[14:15]
	v_pk_mul_f32 v[0:1], v[4:5], v[8:9]
	v_and_b32_sdwa v6, v3, v139 dst_sel:DWORD dst_unused:UNUSED_PAD src0_sel:WORD_1 src1_sel:DWORD
	v_and_b32_sdwa v7, v2, v139 dst_sel:DWORD dst_unused:UNUSED_PAD src0_sel:WORD_1 src1_sel:DWORD
	v_and_b32_sdwa v4, v1, v139 dst_sel:DWORD dst_unused:UNUSED_PAD src0_sel:WORD_1 src1_sel:DWORD
	v_and_b32_sdwa v5, v0, v139 dst_sel:DWORD dst_unused:UNUSED_PAD src0_sel:WORD_1 src1_sel:DWORD
	v_add3_u32 v3, v3, v6, s29
	v_add3_u32 v2, v2, v7, s29
	v_add3_u32 v0, v0, v5, s29
	v_add3_u32 v1, v1, v4, s29
	v_and_b32_e32 v3, 0xffff0000, v3
	v_and_b32_e32 v2, 0xffff0000, v2
	v_or_b32_sdwa v1, v3, v1 dst_sel:DWORD dst_unused:UNUSED_PAD src0_sel:DWORD src1_sel:WORD_1
	v_or_b32_sdwa v0, v2, v0 dst_sel:DWORD dst_unused:UNUSED_PAD src0_sel:DWORD src1_sel:WORD_1
	global_store_dwordx2 v[118:119], v[0:1], off offset:1536 nt
	global_load_dwordx4 v[0:3], v[82:83], off
	s_waitcnt vmcnt(0)
	v_mov_b32_e32 v5, v2
	v_mov_b32_e32 v2, v1
	v_mov_b32_e32 v4, v0
	v_pk_mul_f32 v[2:3], v[2:3], v[20:21]
	v_pk_mul_f32 v[0:1], v[4:5], v[12:13]
	v_and_b32_sdwa v6, v3, v139 dst_sel:DWORD dst_unused:UNUSED_PAD src0_sel:WORD_1 src1_sel:DWORD
	v_and_b32_sdwa v7, v2, v139 dst_sel:DWORD dst_unused:UNUSED_PAD src0_sel:WORD_1 src1_sel:DWORD
	v_and_b32_sdwa v4, v1, v139 dst_sel:DWORD dst_unused:UNUSED_PAD src0_sel:WORD_1 src1_sel:DWORD
	v_and_b32_sdwa v5, v0, v139 dst_sel:DWORD dst_unused:UNUSED_PAD src0_sel:WORD_1 src1_sel:DWORD
	v_add3_u32 v3, v3, v6, s29
	v_add3_u32 v2, v2, v7, s29
	v_add3_u32 v0, v0, v5, s29
	v_add3_u32 v1, v1, v4, s29
	v_and_b32_e32 v3, 0xffff0000, v3
	v_and_b32_e32 v2, 0xffff0000, v2
	v_or_b32_sdwa v1, v3, v1 dst_sel:DWORD dst_unused:UNUSED_PAD src0_sel:DWORD src1_sel:WORD_1
	v_or_b32_sdwa v0, v2, v0 dst_sel:DWORD dst_unused:UNUSED_PAD src0_sel:DWORD src1_sel:WORD_1
	global_store_dwordx2 v[118:119], v[0:1], off offset:2048 nt
	global_load_dwordx4 v[0:3], v[84:85], off
	s_waitcnt vmcnt(0)
	v_mov_b32_e32 v5, v2
	v_mov_b32_e32 v2, v1
	v_mov_b32_e32 v4, v0
	v_pk_mul_f32 v[2:3], v[2:3], v[26:27]
	v_pk_mul_f32 v[0:1], v[4:5], v[124:125]
	v_and_b32_sdwa v6, v3, v139 dst_sel:DWORD dst_unused:UNUSED_PAD src0_sel:WORD_1 src1_sel:DWORD
	v_and_b32_sdwa v7, v2, v139 dst_sel:DWORD dst_unused:UNUSED_PAD src0_sel:WORD_1 src1_sel:DWORD
	v_and_b32_sdwa v4, v1, v139 dst_sel:DWORD dst_unused:UNUSED_PAD src0_sel:WORD_1 src1_sel:DWORD
	v_and_b32_sdwa v5, v0, v139 dst_sel:DWORD dst_unused:UNUSED_PAD src0_sel:WORD_1 src1_sel:DWORD
	v_add3_u32 v3, v3, v6, s29
	v_add3_u32 v2, v2, v7, s29
	v_add3_u32 v0, v0, v5, s29
	v_add3_u32 v1, v1, v4, s29
	v_and_b32_e32 v3, 0xffff0000, v3
	v_and_b32_e32 v2, 0xffff0000, v2
	v_or_b32_sdwa v1, v3, v1 dst_sel:DWORD dst_unused:UNUSED_PAD src0_sel:DWORD src1_sel:WORD_1
	v_or_b32_sdwa v0, v2, v0 dst_sel:DWORD dst_unused:UNUSED_PAD src0_sel:DWORD src1_sel:WORD_1
	global_store_dwordx2 v[118:119], v[0:1], off offset:2560 nt
	global_load_dwordx4 v[0:3], v[86:87], off
	s_waitcnt vmcnt(0)
	v_mov_b32_e32 v5, v2
	v_mov_b32_e32 v2, v1
	v_mov_b32_e32 v4, v0
	v_pk_mul_f32 v[2:3], v[44:45], v[2:3]
	v_pk_mul_f32 v[0:1], v[128:129], v[4:5]
	v_and_b32_sdwa v6, v3, v139 dst_sel:DWORD dst_unused:UNUSED_PAD src0_sel:WORD_1 src1_sel:DWORD
	v_and_b32_sdwa v7, v2, v139 dst_sel:DWORD dst_unused:UNUSED_PAD src0_sel:WORD_1 src1_sel:DWORD
	v_and_b32_sdwa v4, v1, v139 dst_sel:DWORD dst_unused:UNUSED_PAD src0_sel:WORD_1 src1_sel:DWORD
	v_and_b32_sdwa v5, v0, v139 dst_sel:DWORD dst_unused:UNUSED_PAD src0_sel:WORD_1 src1_sel:DWORD
	v_add3_u32 v3, v3, v6, s29
	v_add3_u32 v2, v2, v7, s29
	v_add3_u32 v0, v0, v5, s29
	v_add3_u32 v1, v1, v4, s29
	v_and_b32_e32 v3, 0xffff0000, v3
	v_and_b32_e32 v2, 0xffff0000, v2
	v_or_b32_sdwa v1, v3, v1 dst_sel:DWORD dst_unused:UNUSED_PAD src0_sel:DWORD src1_sel:WORD_1
	v_or_b32_sdwa v0, v2, v0 dst_sel:DWORD dst_unused:UNUSED_PAD src0_sel:DWORD src1_sel:WORD_1
	global_store_dwordx2 v[118:119], v[0:1], off offset:3072 nt
	global_load_dwordx4 v[0:3], v[88:89], off
	s_waitcnt vmcnt(0)
	v_mov_b32_e32 v5, v2
	v_mov_b32_e32 v2, v1
	v_mov_b32_e32 v4, v0
	v_pk_mul_f32 v[2:3], v[48:49], v[2:3]
	v_pk_mul_f32 v[0:1], v[130:131], v[4:5]
	v_and_b32_sdwa v6, v3, v139 dst_sel:DWORD dst_unused:UNUSED_PAD src0_sel:WORD_1 src1_sel:DWORD
	v_and_b32_sdwa v7, v2, v139 dst_sel:DWORD dst_unused:UNUSED_PAD src0_sel:WORD_1 src1_sel:DWORD
	v_and_b32_sdwa v4, v1, v139 dst_sel:DWORD dst_unused:UNUSED_PAD src0_sel:WORD_1 src1_sel:DWORD
	v_and_b32_sdwa v5, v0, v139 dst_sel:DWORD dst_unused:UNUSED_PAD src0_sel:WORD_1 src1_sel:DWORD
	v_add3_u32 v3, v3, v6, s29
	v_add3_u32 v2, v2, v7, s29
	v_add3_u32 v0, v0, v5, s29
	v_add3_u32 v1, v1, v4, s29
	v_and_b32_e32 v3, 0xffff0000, v3
	v_and_b32_e32 v2, 0xffff0000, v2
	v_or_b32_sdwa v1, v3, v1 dst_sel:DWORD dst_unused:UNUSED_PAD src0_sel:DWORD src1_sel:WORD_1
	v_or_b32_sdwa v0, v2, v0 dst_sel:DWORD dst_unused:UNUSED_PAD src0_sel:DWORD src1_sel:WORD_1
	global_store_dwordx2 v[118:119], v[0:1], off offset:3584 nt
	global_load_dwordx4 v[0:3], v[90:91], off
	s_waitcnt vmcnt(0)
	v_mov_b32_e32 v5, v2
	v_mov_b32_e32 v2, v1
	v_mov_b32_e32 v4, v0
	v_pk_mul_f32 v[2:3], v[52:53], v[2:3]
	v_pk_mul_f32 v[0:1], v[142:143], v[4:5]
	v_and_b32_sdwa v6, v3, v139 dst_sel:DWORD dst_unused:UNUSED_PAD src0_sel:WORD_1 src1_sel:DWORD
	v_and_b32_sdwa v7, v2, v139 dst_sel:DWORD dst_unused:UNUSED_PAD src0_sel:WORD_1 src1_sel:DWORD
	v_and_b32_sdwa v4, v1, v139 dst_sel:DWORD dst_unused:UNUSED_PAD src0_sel:WORD_1 src1_sel:DWORD
	v_and_b32_sdwa v5, v0, v139 dst_sel:DWORD dst_unused:UNUSED_PAD src0_sel:WORD_1 src1_sel:DWORD
	v_add3_u32 v3, v3, v6, s29
	v_add3_u32 v2, v2, v7, s29
	v_add3_u32 v0, v0, v5, s29
	v_add3_u32 v1, v1, v4, s29
	v_and_b32_e32 v3, 0xffff0000, v3
	v_and_b32_e32 v2, 0xffff0000, v2
	v_or_b32_sdwa v1, v3, v1 dst_sel:DWORD dst_unused:UNUSED_PAD src0_sel:DWORD src1_sel:WORD_1
	v_or_b32_sdwa v0, v2, v0 dst_sel:DWORD dst_unused:UNUSED_PAD src0_sel:DWORD src1_sel:WORD_1
	global_store_dwordx2 v[112:113], v[0:1], off nt
	global_load_dwordx4 v[0:3], v[92:93], off
	v_pk_mul_f32 v[6:7], v[36:37], v[28:29] op_sel_hi:[1,0]
	v_pk_mul_f32 v[4:5], v[50:51], v[28:29] op_sel_hi:[1,0]
	s_waitcnt vmcnt(0)
	v_mov_b32_e32 v9, v2
	v_mov_b32_e32 v2, v1
	v_mov_b32_e32 v8, v0
	v_pk_mul_f32 v[2:3], v[6:7], v[2:3]
	v_pk_mul_f32 v[0:1], v[4:5], v[8:9]
	v_and_b32_sdwa v6, v3, v139 dst_sel:DWORD dst_unused:UNUSED_PAD src0_sel:WORD_1 src1_sel:DWORD
	v_and_b32_sdwa v7, v2, v139 dst_sel:DWORD dst_unused:UNUSED_PAD src0_sel:WORD_1 src1_sel:DWORD
	v_and_b32_sdwa v4, v1, v139 dst_sel:DWORD dst_unused:UNUSED_PAD src0_sel:WORD_1 src1_sel:DWORD
	v_and_b32_sdwa v5, v0, v139 dst_sel:DWORD dst_unused:UNUSED_PAD src0_sel:WORD_1 src1_sel:DWORD
	v_add3_u32 v3, v3, v6, s29
	v_add3_u32 v2, v2, v7, s29
	v_add3_u32 v0, v0, v5, s29
	v_add3_u32 v1, v1, v4, s29
	v_and_b32_e32 v3, 0xffff0000, v3
	v_and_b32_e32 v2, 0xffff0000, v2
	v_or_b32_sdwa v1, v3, v1 dst_sel:DWORD dst_unused:UNUSED_PAD src0_sel:DWORD src1_sel:WORD_1
	v_or_b32_sdwa v0, v2, v0 dst_sel:DWORD dst_unused:UNUSED_PAD src0_sel:DWORD src1_sel:WORD_1
	global_store_dwordx2 v[112:113], v[0:1], off offset:512 nt
	global_load_dwordx4 v[0:3], v[94:95], off
	v_pk_mul_f32 v[6:7], v[42:43], v[28:29] op_sel_hi:[1,0]
	v_pk_mul_f32 v[4:5], v[126:127], v[28:29] op_sel_hi:[1,0]
	s_waitcnt vmcnt(0)
	v_mov_b32_e32 v9, v2
	v_mov_b32_e32 v2, v1
	v_mov_b32_e32 v8, v0
	v_pk_mul_f32 v[2:3], v[6:7], v[2:3]
	v_pk_mul_f32 v[0:1], v[4:5], v[8:9]
	v_and_b32_sdwa v6, v3, v139 dst_sel:DWORD dst_unused:UNUSED_PAD src0_sel:WORD_1 src1_sel:DWORD
	v_and_b32_sdwa v7, v2, v139 dst_sel:DWORD dst_unused:UNUSED_PAD src0_sel:WORD_1 src1_sel:DWORD
	v_and_b32_sdwa v4, v1, v139 dst_sel:DWORD dst_unused:UNUSED_PAD src0_sel:WORD_1 src1_sel:DWORD
	v_and_b32_sdwa v5, v0, v139 dst_sel:DWORD dst_unused:UNUSED_PAD src0_sel:WORD_1 src1_sel:DWORD
	v_add3_u32 v3, v3, v6, s29
	v_add3_u32 v2, v2, v7, s29
	v_add3_u32 v0, v0, v5, s29
	v_add3_u32 v1, v1, v4, s29
	v_and_b32_e32 v3, 0xffff0000, v3
	v_and_b32_e32 v2, 0xffff0000, v2
	v_or_b32_sdwa v1, v3, v1 dst_sel:DWORD dst_unused:UNUSED_PAD src0_sel:DWORD src1_sel:WORD_1
	v_or_b32_sdwa v0, v2, v0 dst_sel:DWORD dst_unused:UNUSED_PAD src0_sel:DWORD src1_sel:WORD_1
	global_store_dwordx2 v[112:113], v[0:1], off offset:1024 nt
	global_load_dwordx4 v[0:3], v[96:97], off
	v_mov_b32_e32 v5, v40
	v_mov_b32_e32 v40, v39
	v_mov_b32_e32 v4, v38
	v_pk_mul_f32 v[6:7], v[40:41], v[28:29] op_sel_hi:[1,0]
	v_pk_mul_f32 v[4:5], v[4:5], v[28:29] op_sel_hi:[1,0]
	s_waitcnt vmcnt(0)
	v_mov_b32_e32 v9, v2
	v_mov_b32_e32 v2, v1
	v_mov_b32_e32 v8, v0
	v_pk_mul_f32 v[2:3], v[6:7], v[2:3]
	v_pk_mul_f32 v[0:1], v[4:5], v[8:9]
	v_and_b32_sdwa v6, v3, v139 dst_sel:DWORD dst_unused:UNUSED_PAD src0_sel:WORD_1 src1_sel:DWORD
	v_and_b32_sdwa v7, v2, v139 dst_sel:DWORD dst_unused:UNUSED_PAD src0_sel:WORD_1 src1_sel:DWORD
	v_and_b32_sdwa v4, v1, v139 dst_sel:DWORD dst_unused:UNUSED_PAD src0_sel:WORD_1 src1_sel:DWORD
	v_and_b32_sdwa v5, v0, v139 dst_sel:DWORD dst_unused:UNUSED_PAD src0_sel:WORD_1 src1_sel:DWORD
	v_add3_u32 v3, v3, v6, s29
	v_add3_u32 v2, v2, v7, s29
	v_add3_u32 v0, v0, v5, s29
	v_add3_u32 v1, v1, v4, s29
	v_and_b32_e32 v3, 0xffff0000, v3
	v_and_b32_e32 v2, 0xffff0000, v2
	v_or_b32_sdwa v1, v3, v1 dst_sel:DWORD dst_unused:UNUSED_PAD src0_sel:DWORD src1_sel:WORD_1
	v_or_b32_sdwa v0, v2, v0 dst_sel:DWORD dst_unused:UNUSED_PAD src0_sel:DWORD src1_sel:WORD_1
	global_store_dwordx2 v[112:113], v[0:1], off offset:1536 nt
	global_load_dwordx4 v[0:3], v[98:99], off
	v_mov_b32_e32 v5, v34
	v_mov_b32_e32 v34, v33
	v_mov_b32_e32 v4, v32
	v_pk_mul_f32 v[6:7], v[34:35], v[28:29] op_sel_hi:[1,0]
	v_pk_mul_f32 v[4:5], v[4:5], v[28:29] op_sel_hi:[1,0]
	s_waitcnt vmcnt(0)
	v_mov_b32_e32 v9, v2
	v_mov_b32_e32 v2, v1
	v_mov_b32_e32 v8, v0
	v_pk_mul_f32 v[2:3], v[6:7], v[2:3]
	v_pk_mul_f32 v[0:1], v[4:5], v[8:9]
	v_and_b32_sdwa v6, v3, v139 dst_sel:DWORD dst_unused:UNUSED_PAD src0_sel:WORD_1 src1_sel:DWORD
	v_and_b32_sdwa v7, v2, v139 dst_sel:DWORD dst_unused:UNUSED_PAD src0_sel:WORD_1 src1_sel:DWORD
	v_and_b32_sdwa v4, v1, v139 dst_sel:DWORD dst_unused:UNUSED_PAD src0_sel:WORD_1 src1_sel:DWORD
	v_and_b32_sdwa v5, v0, v139 dst_sel:DWORD dst_unused:UNUSED_PAD src0_sel:WORD_1 src1_sel:DWORD
	v_add3_u32 v3, v3, v6, s29
	v_add3_u32 v2, v2, v7, s29
	v_add3_u32 v0, v0, v5, s29
	v_add3_u32 v1, v1, v4, s29
	v_and_b32_e32 v3, 0xffff0000, v3
	v_and_b32_e32 v2, 0xffff0000, v2
	v_or_b32_sdwa v1, v3, v1 dst_sel:DWORD dst_unused:UNUSED_PAD src0_sel:DWORD src1_sel:WORD_1
	v_or_b32_sdwa v0, v2, v0 dst_sel:DWORD dst_unused:UNUSED_PAD src0_sel:DWORD src1_sel:WORD_1
	global_store_dwordx2 v[112:113], v[0:1], off offset:2048 nt
	global_load_dwordx4 v[0:3], v[100:101], off
	v_pk_mul_f32 v[6:7], v[30:31], v[28:29] op_sel_hi:[1,0]
	v_pk_mul_f32 v[4:5], v[46:47], v[28:29] op_sel_hi:[1,0]
	s_waitcnt vmcnt(0)
	v_mov_b32_e32 v9, v2
	v_mov_b32_e32 v2, v1
	v_mov_b32_e32 v8, v0
	v_pk_mul_f32 v[2:3], v[6:7], v[2:3]
	v_pk_mul_f32 v[0:1], v[4:5], v[8:9]
	v_and_b32_sdwa v6, v3, v139 dst_sel:DWORD dst_unused:UNUSED_PAD src0_sel:WORD_1 src1_sel:DWORD
	v_and_b32_sdwa v7, v2, v139 dst_sel:DWORD dst_unused:UNUSED_PAD src0_sel:WORD_1 src1_sel:DWORD
	v_and_b32_sdwa v4, v1, v139 dst_sel:DWORD dst_unused:UNUSED_PAD src0_sel:WORD_1 src1_sel:DWORD
	v_and_b32_sdwa v5, v0, v139 dst_sel:DWORD dst_unused:UNUSED_PAD src0_sel:WORD_1 src1_sel:DWORD
	v_add3_u32 v3, v3, v6, s29
	v_add3_u32 v2, v2, v7, s29
	v_add3_u32 v0, v0, v5, s29
	v_add3_u32 v1, v1, v4, s29
	v_and_b32_e32 v3, 0xffff0000, v3
	v_and_b32_e32 v2, 0xffff0000, v2
	v_or_b32_sdwa v1, v3, v1 dst_sel:DWORD dst_unused:UNUSED_PAD src0_sel:DWORD src1_sel:WORD_1
	v_or_b32_sdwa v0, v2, v0 dst_sel:DWORD dst_unused:UNUSED_PAD src0_sel:DWORD src1_sel:WORD_1
	global_store_dwordx2 v[112:113], v[0:1], off offset:2560 nt
	global_load_dwordx4 v[0:3], v[102:103], off
	v_mov_b32_e32 v5, v24
	v_mov_b32_e32 v24, v23
	v_mov_b32_e32 v4, v22
	v_pk_mul_f32 v[6:7], v[24:25], v[28:29] op_sel_hi:[1,0]
	v_pk_mul_f32 v[4:5], v[4:5], v[28:29] op_sel_hi:[1,0]
	s_waitcnt vmcnt(0)
	v_mov_b32_e32 v9, v2
	v_mov_b32_e32 v2, v1
	v_mov_b32_e32 v8, v0
	v_pk_mul_f32 v[2:3], v[6:7], v[2:3]
	v_pk_mul_f32 v[0:1], v[4:5], v[8:9]
	v_and_b32_sdwa v6, v3, v139 dst_sel:DWORD dst_unused:UNUSED_PAD src0_sel:WORD_1 src1_sel:DWORD
	v_and_b32_sdwa v7, v2, v139 dst_sel:DWORD dst_unused:UNUSED_PAD src0_sel:WORD_1 src1_sel:DWORD
	v_and_b32_sdwa v4, v1, v139 dst_sel:DWORD dst_unused:UNUSED_PAD src0_sel:WORD_1 src1_sel:DWORD
	v_and_b32_sdwa v5, v0, v139 dst_sel:DWORD dst_unused:UNUSED_PAD src0_sel:WORD_1 src1_sel:DWORD
	v_add3_u32 v3, v3, v6, s29
	v_add3_u32 v2, v2, v7, s29
	v_add3_u32 v0, v0, v5, s29
	v_add3_u32 v1, v1, v4, s29
	v_and_b32_e32 v3, 0xffff0000, v3
	v_and_b32_e32 v2, 0xffff0000, v2
	v_or_b32_sdwa v1, v3, v1 dst_sel:DWORD dst_unused:UNUSED_PAD src0_sel:DWORD src1_sel:WORD_1
	v_or_b32_sdwa v0, v2, v0 dst_sel:DWORD dst_unused:UNUSED_PAD src0_sel:DWORD src1_sel:WORD_1
	global_store_dwordx2 v[112:113], v[0:1], off offset:3072 nt
	global_load_dwordx4 v[0:3], v[104:105], off
	v_mov_b32_e32 v5, v18
	v_mov_b32_e32 v18, v17
	v_mov_b32_e32 v4, v16
	v_pk_mul_f32 v[6:7], v[18:19], v[28:29] op_sel_hi:[1,0]
	v_pk_mul_f32 v[4:5], v[4:5], v[28:29] op_sel_hi:[1,0]
	s_waitcnt vmcnt(0)
	v_mov_b32_e32 v9, v2
	v_mov_b32_e32 v2, v1
	v_mov_b32_e32 v8, v0
	v_pk_mul_f32 v[2:3], v[6:7], v[2:3]
	v_pk_mul_f32 v[0:1], v[4:5], v[8:9]
	v_and_b32_sdwa v6, v3, v139 dst_sel:DWORD dst_unused:UNUSED_PAD src0_sel:WORD_1 src1_sel:DWORD
	v_and_b32_sdwa v7, v2, v139 dst_sel:DWORD dst_unused:UNUSED_PAD src0_sel:WORD_1 src1_sel:DWORD
	v_and_b32_sdwa v4, v1, v139 dst_sel:DWORD dst_unused:UNUSED_PAD src0_sel:WORD_1 src1_sel:DWORD
	v_and_b32_sdwa v5, v0, v139 dst_sel:DWORD dst_unused:UNUSED_PAD src0_sel:WORD_1 src1_sel:DWORD
	v_add3_u32 v3, v3, v6, s29
	v_add3_u32 v2, v2, v7, s29
	v_add3_u32 v0, v0, v5, s29
	v_add3_u32 v1, v1, v4, s29
	v_and_b32_e32 v3, 0xffff0000, v3
	v_and_b32_e32 v2, 0xffff0000, v2
	v_or_b32_sdwa v1, v3, v1 dst_sel:DWORD dst_unused:UNUSED_PAD src0_sel:DWORD src1_sel:WORD_1
	v_or_b32_sdwa v0, v2, v0 dst_sel:DWORD dst_unused:UNUSED_PAD src0_sel:DWORD src1_sel:WORD_1
	global_store_dwordx2 v[112:113], v[0:1], off offset:3584 nt
	s_cbranch_scc0 .LBB0_2076

.LBB0_2130:
	ds_write2_b32 v78, v24, v25 offset1:1
	ds_write2_b32 v78, v26, v27 offset0:2 offset1:3
	ds_write2_b32 v79, v28, v29 offset1:1
	ds_write2_b32 v80, v30, v31 offset1:1
	ds_write2_b32 v81, v32, v33 offset1:1
	ds_write2_b32 v82, v34, v35 offset1:1
	ds_write2_b32 v83, v36, v37 offset1:1
	ds_write2_b32 v84, v38, v39 offset1:1
	ds_write2_b32 v85, v48, v49 offset1:1
	ds_write2_b32 v86, v50, v51 offset1:1
	ds_write2_b32 v87, v52, v53 offset1:1
	ds_write2_b32 v88, v54, v55 offset1:1
	ds_write2_b32 v89, v56, v57 offset1:1
	ds_write2_b32 v90, v58, v59 offset1:1
	ds_write2_b32 v91, v60, v61 offset1:1
	ds_write2_b32 v92, v62, v63 offset1:1
	s_waitcnt lgkmcnt(0)
	ds_read2_b32 v[66:67], v77 offset1:8
	ds_read2_b32 v[84:85], v77 offset0:33 offset1:41
	ds_read2_b32 v[86:87], v77 offset0:66 offset1:74
	ds_read2_b32 v[88:89], v77 offset0:99 offset1:107
	ds_read2_b32 v[90:91], v77 offset0:132 offset1:140
	s_waitcnt lgkmcnt(4)
	v_bfe_u32 v79, v66, 16, 1
	v_add3_u32 v66, v66, v79, s34
	s_waitcnt lgkmcnt(3)
	v_bfe_u32 v79, v84, 16, 1
	v_lshrrev_b32_e32 v66, 16, v66
	v_add3_u32 v79, v84, v79, s34
	ds_read2_b32 v[92:93], v77 offset0:165 offset1:173
	v_and_or_b32 v80, v79, s35, v66
	s_waitcnt lgkmcnt(3)
	v_bfe_u32 v66, v86, 16, 1
	v_add3_u32 v66, v86, v66, s34
	s_waitcnt lgkmcnt(2)
	v_bfe_u32 v79, v88, 16, 1
	ds_read2_b32 v[94:95], v77 offset0:198 offset1:206
	v_lshrrev_b32_e32 v66, 16, v66
	v_add3_u32 v79, v88, v79, s34
	ds_read2_b32 v[96:97], v77 offset0:231 offset1:239
	v_and_or_b32 v81, v79, s35, v66
	s_waitcnt lgkmcnt(3)
	v_bfe_u32 v66, v90, 16, 1
	v_add3_u32 v66, v90, v66, s34
	s_waitcnt lgkmcnt(2)
	v_bfe_u32 v79, v92, 16, 1
	v_lshrrev_b32_e32 v66, 16, v66
	v_add3_u32 v79, v92, v79, s34
	v_and_or_b32 v82, v79, s35, v66
	s_waitcnt lgkmcnt(1)
	v_bfe_u32 v66, v94, 16, 1
	v_add_u32_e32 v98, s20, v68
	v_add3_u32 v66, v94, v66, s34
	s_waitcnt lgkmcnt(0)
	v_bfe_u32 v79, v96, 16, 1
	v_ashrrev_i32_e32 v99, 31, v98
	v_lshrrev_b32_e32 v66, 16, v66
	v_add3_u32 v79, v96, v79, s34
	v_lshlrev_b64 v[98:99], 13, v[98:99]
	s_ashr_i32 s17, s16, 31
	v_and_or_b32 v83, v79, s35, v66
	v_lshl_add_u64 v[98:99], s[14:15], 0, v[98:99]
	s_lshl_b64 s[16:17], s[16:17], 1
	v_bfe_u32 v66, v67, 16, 1
	v_lshl_add_u64 v[98:99], v[98:99], 0, s[16:17]
	v_add3_u32 v66, v67, v66, s34
	v_bfe_u32 v67, v85, 16, 1
	v_lshl_add_u64 v[98:99], v[98:99], 0, v[64:65]
	v_lshrrev_b32_e32 v66, 16, v66
	v_add3_u32 v67, v85, v67, s34
	global_store_dwordx4 v[98:99], v[80:83], off nt
	ds_read2_b32 v[84:85], v77 offset0:16 offset1:24
	v_add_u32_e32 v98, s20, v71
	v_and_or_b32 v80, v67, s35, v66
	v_bfe_u32 v66, v87, 16, 1
	v_add3_u32 v66, v87, v66, s34
	v_bfe_u32 v67, v89, 16, 1
	v_lshrrev_b32_e32 v66, 16, v66
	v_add3_u32 v67, v89, v67, s34
	v_and_or_b32 v81, v67, s35, v66
	v_bfe_u32 v66, v91, 16, 1
	v_add3_u32 v66, v91, v66, s34
	v_bfe_u32 v67, v93, 16, 1
	v_lshrrev_b32_e32 v66, 16, v66
	v_add3_u32 v67, v93, v67, s34
	v_and_or_b32 v82, v67, s35, v66
	v_bfe_u32 v66, v95, 16, 1
	v_add3_u32 v66, v95, v66, s34
	v_bfe_u32 v67, v97, 16, 1
	v_lshrrev_b32_e32 v66, 16, v66
	v_add3_u32 v67, v97, v67, s34
	v_and_or_b32 v83, v67, s35, v66
	v_add_u32_e32 v66, s20, v70
	v_ashrrev_i32_e32 v67, 31, v66
	v_lshlrev_b64 v[66:67], 13, v[66:67]
	v_lshl_add_u64 v[66:67], s[14:15], 0, v[66:67]
	v_lshl_add_u64 v[66:67], v[66:67], 0, s[16:17]
	v_lshl_add_u64 v[66:67], v[66:67], 0, v[64:65]
	global_store_dwordx4 v[66:67], v[80:83], off nt
	ds_read2_b32 v[66:67], v77 offset0:49 offset1:57
	ds_read2_b32 v[86:87], v77 offset0:82 offset1:90
	ds_read2_b32 v[88:89], v77 offset0:115 offset1:123
	s_waitcnt lgkmcnt(3)
	v_bfe_u32 v79, v84, 16, 1
	v_add3_u32 v79, v84, v79, s34
	s_waitcnt lgkmcnt(2)
	v_bfe_u32 v80, v66, 16, 1
	ds_read2_b32 v[90:91], v77 offset0:148 offset1:156
	v_lshrrev_b32_e32 v79, 16, v79
	v_add3_u32 v66, v66, v80, s34
	ds_read2_b32 v[92:93], v77 offset0:181 offset1:189
	v_and_or_b32 v80, v66, s35, v79
	s_waitcnt lgkmcnt(3)
	v_bfe_u32 v66, v86, 16, 1
	v_add3_u32 v66, v86, v66, s34
	s_waitcnt lgkmcnt(2)
	v_bfe_u32 v79, v88, 16, 1
	ds_read2_b32 v[94:95], v77 offset0:214 offset1:222
	v_lshrrev_b32_e32 v66, 16, v66
	v_add3_u32 v79, v88, v79, s34
	ds_read2_b32 v[96:97], v77 offset0:247 offset1:255
	v_and_or_b32 v81, v79, s35, v66
	s_waitcnt lgkmcnt(3)
	v_bfe_u32 v66, v90, 16, 1
	v_add3_u32 v66, v90, v66, s34
	s_waitcnt lgkmcnt(2)
	v_bfe_u32 v79, v92, 16, 1
	v_lshrrev_b32_e32 v66, 16, v66
	v_add3_u32 v79, v92, v79, s34
	v_and_or_b32 v82, v79, s35, v66
	s_waitcnt lgkmcnt(1)
	v_bfe_u32 v66, v94, 16, 1
	v_add3_u32 v66, v94, v66, s34
	s_waitcnt lgkmcnt(0)
	v_bfe_u32 v79, v96, 16, 1
	v_ashrrev_i32_e32 v99, 31, v98
	v_lshrrev_b32_e32 v66, 16, v66
	v_add3_u32 v79, v96, v79, s34
	v_lshlrev_b64 v[98:99], 13, v[98:99]
	v_and_or_b32 v83, v79, s35, v66
	v_lshl_add_u64 v[98:99], s[14:15], 0, v[98:99]
	v_bfe_u32 v66, v85, 16, 1
	v_lshl_add_u64 v[98:99], v[98:99], 0, s[16:17]
	v_add3_u32 v66, v85, v66, s34
	v_bfe_u32 v79, v67, 16, 1
	v_lshl_add_u64 v[98:99], v[98:99], 0, v[64:65]
	v_lshrrev_b32_e32 v66, 16, v66
	v_add3_u32 v67, v67, v79, s34
	global_store_dwordx4 v[98:99], v[80:83], off nt
	s_add_i32 s36, s37, s10
	s_add_i32 s11, s11, s24
	v_and_or_b32 v80, v67, s35, v66
	v_bfe_u32 v66, v87, 16, 1
	v_add3_u32 v66, v87, v66, s34
	v_bfe_u32 v67, v89, 16, 1
	v_lshrrev_b32_e32 v66, 16, v66
	v_add3_u32 v67, v89, v67, s34
	v_and_or_b32 v81, v67, s35, v66
	v_bfe_u32 v66, v91, 16, 1
	v_add3_u32 v66, v91, v66, s34
	v_bfe_u32 v67, v93, 16, 1
	v_lshrrev_b32_e32 v66, 16, v66
	v_add3_u32 v67, v93, v67, s34
	v_and_or_b32 v82, v67, s35, v66
	v_bfe_u32 v66, v95, 16, 1
	v_add3_u32 v66, v95, v66, s34
	v_bfe_u32 v67, v97, 16, 1
	v_lshrrev_b32_e32 v66, 16, v66
	v_add3_u32 v67, v97, v67, s34
	v_and_or_b32 v83, v67, s35, v66
	v_add_u32_e32 v66, s20, v72
	v_ashrrev_i32_e32 v67, 31, v66
	v_lshlrev_b64 v[66:67], 13, v[66:67]
	v_lshl_add_u64 v[66:67], s[14:15], 0, v[66:67]
	v_lshl_add_u64 v[66:67], v[66:67], 0, s[16:17]
	v_lshl_add_u64 v[66:67], v[66:67], 0, v[64:65]
	global_store_dwordx4 v[66:67], v[80:83], off nt
	s_waitcnt lgkmcnt(0)
	s_cmp_gt_i32 s36, 0x139ff
	s_cselect_b64 s[14:15], -1, 0

.LBB0_2161:
	v_cmp_lt_i32_e32 vcc, -1, v66
	v_mov_b32_e32 v28, 0
	v_mov_b32_e32 v24, 0
	v_mov_b32_e32 v25, 0
	v_mov_b32_e32 v26, 0
	v_mov_b32_e32 v27, 0
	s_and_saveexec_b64 s[20:21], vcc
	s_cbranch_execz .LBB0_2163
	v_add_u32_e32 v24, s22, v68
	v_ashrrev_i32_e32 v25, 31, v24
	v_mul_lo_u32 v26, s18, v25
	v_mul_lo_u32 v27, s19, v24
	v_mad_u64_u32 v[24:25], s[38:39], s18, v24, 0
	v_add3_u32 v25, v25, v26, v27
	v_lshl_add_u64 v[24:25], v[24:25], 2, s[16:17]
	v_mov_b32_e32 v67, v65
	v_lshl_add_u64 v[24:25], v[66:67], 2, v[24:25]
	global_load_dwordx4 v[24:27], v[24:25], off nt
.LBB0_2163:
	s_or_b64 exec, exec, s[20:21]
	v_mov_b32_e32 v29, 0
	v_mov_b32_e32 v30, 0
	v_mov_b32_e32 v31, 0
	s_and_saveexec_b64 s[20:21], vcc
	s_cbranch_execz .LBB0_2165
	v_add_u32_e32 v28, s22, v70
	v_ashrrev_i32_e32 v29, 31, v28
	v_mul_lo_u32 v30, s18, v29
	v_mul_lo_u32 v31, s19, v28
	v_mad_u64_u32 v[28:29], s[38:39], s18, v28, 0
	v_add3_u32 v29, v29, v30, v31
	v_lshl_add_u64 v[28:29], v[28:29], 2, s[16:17]
	v_mov_b32_e32 v67, v65
	v_lshl_add_u64 v[28:29], v[66:67], 2, v[28:29]
	global_load_dwordx4 v[28:31], v[28:29], off nt
.LBB0_2165:
	s_or_b64 exec, exec, s[20:21]
	v_mov_b32_e32 v36, 0
	v_mov_b32_e32 v32, 0
	v_mov_b32_e32 v33, 0
	v_mov_b32_e32 v34, 0
	v_mov_b32_e32 v35, 0
	s_and_saveexec_b64 s[20:21], vcc
	s_cbranch_execz .LBB0_2167
	v_add_u32_e32 v32, s22, v71
	v_ashrrev_i32_e32 v33, 31, v32
	v_mul_lo_u32 v34, s18, v33
	v_mul_lo_u32 v35, s19, v32
	v_mad_u64_u32 v[32:33], s[38:39], s18, v32, 0
	v_add3_u32 v33, v33, v34, v35
	v_lshl_add_u64 v[32:33], v[32:33], 2, s[16:17]
	v_mov_b32_e32 v67, v65
	v_lshl_add_u64 v[32:33], v[66:67], 2, v[32:33]
	global_load_dwordx4 v[32:35], v[32:33], off nt
.LBB0_2167:
	s_or_b64 exec, exec, s[20:21]
	v_mov_b32_e32 v37, 0
	v_mov_b32_e32 v38, 0
	v_mov_b32_e32 v39, 0
	s_and_saveexec_b64 s[20:21], vcc
	s_cbranch_execz .LBB0_2169
	v_add_u32_e32 v36, s22, v72
	v_ashrrev_i32_e32 v37, 31, v36
	v_mul_lo_u32 v38, s18, v37
	v_mul_lo_u32 v39, s19, v36
	v_mad_u64_u32 v[36:37], s[38:39], s18, v36, 0
	v_add3_u32 v37, v37, v38, v39
	v_lshl_add_u64 v[36:37], v[36:37], 2, s[16:17]
	v_mov_b32_e32 v67, v65
	v_lshl_add_u64 v[36:37], v[66:67], 2, v[36:37]
	global_load_dwordx4 v[36:39], v[36:37], off nt
.LBB0_2169:
	s_or_b64 exec, exec, s[20:21]
	v_mov_b32_e32 v52, 0
	v_mov_b32_e32 v48, 0
	v_mov_b32_e32 v49, 0
	v_mov_b32_e32 v50, 0
	v_mov_b32_e32 v51, 0
	s_and_saveexec_b64 s[20:21], vcc
	s_cbranch_execz .LBB0_2171
	v_add_u32_e32 v48, s22, v74
	v_ashrrev_i32_e32 v49, 31, v48
	v_mul_lo_u32 v50, s18, v49
	v_mul_lo_u32 v51, s19, v48
	v_mad_u64_u32 v[48:49], s[38:39], s18, v48, 0
	v_add3_u32 v49, v49, v50, v51
	v_lshl_add_u64 v[48:49], v[48:49], 2, s[16:17]
	v_mov_b32_e32 v67, v65
	v_lshl_add_u64 v[48:49], v[66:67], 2, v[48:49]
	global_load_dwordx4 v[48:51], v[48:49], off nt
.LBB0_2171:
	s_or_b64 exec, exec, s[20:21]
	v_mov_b32_e32 v53, 0
	v_mov_b32_e32 v54, 0
	v_mov_b32_e32 v55, 0
	s_and_saveexec_b64 s[20:21], vcc
	s_cbranch_execz .LBB0_2173
	v_add_u32_e32 v52, s22, v75
	v_ashrrev_i32_e32 v53, 31, v52
	v_mul_lo_u32 v54, s18, v53
	v_mul_lo_u32 v55, s19, v52
	v_mad_u64_u32 v[52:53], s[38:39], s18, v52, 0
	v_add3_u32 v53, v53, v54, v55
	v_lshl_add_u64 v[52:53], v[52:53], 2, s[16:17]
	v_mov_b32_e32 v67, v65
	v_lshl_add_u64 v[52:53], v[66:67], 2, v[52:53]
	global_load_dwordx4 v[52:55], v[52:53], off nt
.LBB0_2173:
	s_or_b64 exec, exec, s[20:21]
	v_mov_b32_e32 v63, 0
	v_mov_b32_e32 v56, 0
	v_mov_b32_e32 v57, 0
	v_mov_b32_e32 v58, 0
	v_mov_b32_e32 v59, 0
	s_and_saveexec_b64 s[20:21], vcc
	s_cbranch_execz .LBB0_2175
	v_add_u32_e32 v56, s22, v76
	v_ashrrev_i32_e32 v57, 31, v56
	v_mul_lo_u32 v58, s18, v57
	v_mul_lo_u32 v59, s19, v56
	v_mad_u64_u32 v[56:57], s[38:39], s18, v56, 0
	v_add3_u32 v57, v57, v58, v59
	v_lshl_add_u64 v[56:57], v[56:57], 2, s[16:17]
	v_mov_b32_e32 v67, v65
	v_lshl_add_u64 v[56:57], v[66:67], 2, v[56:57]
	global_load_dwordx4 v[56:59], v[56:57], off nt
.LBB0_2175:
	s_or_b64 exec, exec, s[20:21]
	v_mov_b32_e32 v62, 0
	v_mov_b32_e32 v61, 0
	v_mov_b32_e32 v60, 0
	s_and_saveexec_b64 s[20:21], vcc
	s_cbranch_execz .LBB0_2177
	v_add_u32_e32 v60, s22, v69
	v_ashrrev_i32_e32 v61, 31, v60
	v_mul_lo_u32 v62, s18, v61
	v_mul_lo_u32 v63, s19, v60
	v_mad_u64_u32 v[60:61], s[18:19], s18, v60, 0
	v_add3_u32 v61, v61, v62, v63
	v_lshl_add_u64 v[60:61], v[60:61], 2, s[16:17]
	v_mov_b32_e32 v67, v65
	v_lshl_add_u64 v[60:61], v[66:67], 2, v[60:61]
	global_load_dwordx4 v[60:63], v[60:61], off nt

.LBB0_2186:
	v_add_u32_e32 v79, 0x420, v78
	v_add_u32_e32 v80, 0x428, v78
	v_add_u32_e32 v81, 0x840, v78
	v_add_u32_e32 v82, 0x848, v78
	v_add_u32_e32 v83, 0xc60, v78
	v_add_u32_e32 v84, 0xc68, v78
	v_add_u32_e32 v85, 0x1080, v78
	v_add_u32_e32 v86, 0x1088, v78
	v_add_u32_e32 v87, 0x14a0, v78
	v_add_u32_e32 v88, 0x14a8, v78
	v_add_u32_e32 v89, 0x18c0, v78
	v_add_u32_e32 v90, 0x18c8, v78
	v_add_u32_e32 v91, 0x1ce0, v78
	v_add_u32_e32 v92, 0x1ce8, v78
	s_waitcnt vmcnt(0)
	ds_write2_b32 v78, v4, v5 offset1:1
	ds_write2_b32 v78, v6, v7 offset0:2 offset1:3
	ds_write2_b32 v79, v0, v1 offset1:1
	ds_write2_b32 v80, v2, v3 offset1:1
	ds_write2_b32 v81, v12, v13 offset1:1
	ds_write2_b32 v82, v14, v15 offset1:1
	ds_write2_b32 v83, v8, v9 offset1:1
	ds_write2_b32 v84, v10, v11 offset1:1
	ds_write2_b32 v85, v20, v21 offset1:1
	ds_write2_b32 v86, v22, v23 offset1:1
	ds_write2_b32 v87, v16, v17 offset1:1
	ds_write2_b32 v88, v18, v19 offset1:1
	ds_write2_b32 v89, v44, v45 offset1:1
	ds_write2_b32 v90, v46, v47 offset1:1
	ds_write2_b32 v91, v40, v41 offset1:1
	ds_write2_b32 v92, v42, v43 offset1:1
	s_waitcnt lgkmcnt(0)
	ds_read2_b32 v[66:67], v77 offset1:8
	ds_read2_b32 v[98:99], v77 offset0:33 offset1:41
	ds_read2_b32 v[100:101], v77 offset0:66 offset1:74
	ds_read2_b32 v[102:103], v77 offset0:99 offset1:107
	ds_read2_b32 v[104:105], v77 offset0:132 offset1:140
	s_waitcnt lgkmcnt(4)
	v_bfe_u32 v93, v66, 16, 1
	v_add3_u32 v66, v66, v93, s34
	s_waitcnt lgkmcnt(3)
	v_bfe_u32 v93, v98, 16, 1
	v_lshrrev_b32_e32 v66, 16, v66
	v_add3_u32 v93, v98, v93, s34
	ds_read2_b32 v[106:107], v77 offset0:165 offset1:173
	v_and_or_b32 v94, v93, s35, v66
	s_waitcnt lgkmcnt(3)
	v_bfe_u32 v66, v100, 16, 1
	v_add3_u32 v66, v100, v66, s34
	s_waitcnt lgkmcnt(2)
	v_bfe_u32 v93, v102, 16, 1
	ds_read2_b32 v[108:109], v77 offset0:198 offset1:206
	v_lshrrev_b32_e32 v66, 16, v66
	v_add3_u32 v93, v102, v93, s34
	ds_read2_b32 v[110:111], v77 offset0:231 offset1:239
	v_and_or_b32 v95, v93, s35, v66
	s_waitcnt lgkmcnt(3)
	v_bfe_u32 v66, v104, 16, 1
	v_add3_u32 v66, v104, v66, s34
	s_waitcnt lgkmcnt(2)
	v_bfe_u32 v93, v106, 16, 1
	v_lshrrev_b32_e32 v66, 16, v66
	v_add3_u32 v93, v106, v93, s34
	v_and_or_b32 v96, v93, s35, v66
	s_waitcnt lgkmcnt(1)
	v_bfe_u32 v66, v108, 16, 1
	v_add_u32_e32 v112, s22, v68
	v_add3_u32 v66, v108, v66, s34
	s_waitcnt lgkmcnt(0)
	v_bfe_u32 v93, v110, 16, 1
	v_ashrrev_i32_e32 v113, 31, v112
	v_lshrrev_b32_e32 v66, 16, v66
	v_add3_u32 v93, v110, v93, s34
	v_lshlrev_b64 v[112:113], 13, v[112:113]
	s_ashr_i32 s19, s18, 31
	v_and_or_b32 v97, v93, s35, v66
	v_lshl_add_u64 v[112:113], s[16:17], 0, v[112:113]
	s_lshl_b64 s[18:19], s[18:19], 1
	v_bfe_u32 v66, v67, 16, 1
	v_lshl_add_u64 v[112:113], v[112:113], 0, s[18:19]
	v_add3_u32 v66, v67, v66, s34
	v_bfe_u32 v67, v99, 16, 1
	v_lshl_add_u64 v[112:113], v[112:113], 0, v[64:65]
	v_lshrrev_b32_e32 v66, 16, v66
	v_add3_u32 v67, v99, v67, s34
	global_store_dwordx4 v[112:113], v[94:97], off nt
	ds_read2_b32 v[98:99], v77 offset0:16 offset1:24
	v_add_u32_e32 v112, s22, v71
	v_and_or_b32 v94, v67, s35, v66
	v_bfe_u32 v66, v101, 16, 1
	v_add3_u32 v66, v101, v66, s34
	v_bfe_u32 v67, v103, 16, 1
	v_lshrrev_b32_e32 v66, 16, v66
	v_add3_u32 v67, v103, v67, s34
	v_and_or_b32 v95, v67, s35, v66
	v_bfe_u32 v66, v105, 16, 1
	v_add3_u32 v66, v105, v66, s34
	v_bfe_u32 v67, v107, 16, 1
	v_lshrrev_b32_e32 v66, 16, v66
	v_add3_u32 v67, v107, v67, s34
	v_and_or_b32 v96, v67, s35, v66
	v_bfe_u32 v66, v109, 16, 1
	v_add3_u32 v66, v109, v66, s34
	v_bfe_u32 v67, v111, 16, 1
	v_lshrrev_b32_e32 v66, 16, v66
	v_add3_u32 v67, v111, v67, s34
	v_and_or_b32 v97, v67, s35, v66
	v_add_u32_e32 v66, s22, v70
	v_ashrrev_i32_e32 v67, 31, v66
	v_lshlrev_b64 v[66:67], 13, v[66:67]
	v_lshl_add_u64 v[66:67], s[16:17], 0, v[66:67]
	v_lshl_add_u64 v[66:67], v[66:67], 0, s[18:19]
	v_lshl_add_u64 v[66:67], v[66:67], 0, v[64:65]
	global_store_dwordx4 v[66:67], v[94:97], off nt
	ds_read2_b32 v[66:67], v77 offset0:49 offset1:57
	ds_read2_b32 v[100:101], v77 offset0:82 offset1:90
	ds_read2_b32 v[102:103], v77 offset0:115 offset1:123
	s_waitcnt lgkmcnt(3)
	v_bfe_u32 v93, v98, 16, 1
	v_add3_u32 v93, v98, v93, s34
	s_waitcnt lgkmcnt(2)
	v_bfe_u32 v94, v66, 16, 1
	ds_read2_b32 v[104:105], v77 offset0:148 offset1:156
	v_lshrrev_b32_e32 v93, 16, v93
	v_add3_u32 v66, v66, v94, s34
	ds_read2_b32 v[106:107], v77 offset0:181 offset1:189
	v_and_or_b32 v94, v66, s35, v93
	s_waitcnt lgkmcnt(3)
	v_bfe_u32 v66, v100, 16, 1
	v_add3_u32 v66, v100, v66, s34
	s_waitcnt lgkmcnt(2)
	v_bfe_u32 v93, v102, 16, 1
	ds_read2_b32 v[108:109], v77 offset0:214 offset1:222
	v_lshrrev_b32_e32 v66, 16, v66
	v_add3_u32 v93, v102, v93, s34
	ds_read2_b32 v[110:111], v77 offset0:247 offset1:255
	v_and_or_b32 v95, v93, s35, v66
	s_waitcnt lgkmcnt(3)
	v_bfe_u32 v66, v104, 16, 1
	v_add3_u32 v66, v104, v66, s34
	s_waitcnt lgkmcnt(2)
	v_bfe_u32 v93, v106, 16, 1
	v_lshrrev_b32_e32 v66, 16, v66
	v_add3_u32 v93, v106, v93, s34
	v_and_or_b32 v96, v93, s35, v66
	s_waitcnt lgkmcnt(1)
	v_bfe_u32 v66, v108, 16, 1
	v_add3_u32 v66, v108, v66, s34
	s_waitcnt lgkmcnt(0)
	v_bfe_u32 v93, v110, 16, 1
	v_ashrrev_i32_e32 v113, 31, v112
	v_lshrrev_b32_e32 v66, 16, v66
	v_add3_u32 v93, v110, v93, s34
	v_lshlrev_b64 v[112:113], 13, v[112:113]
	v_and_or_b32 v97, v93, s35, v66
	v_lshl_add_u64 v[112:113], s[16:17], 0, v[112:113]
	v_bfe_u32 v66, v99, 16, 1
	v_lshl_add_u64 v[112:113], v[112:113], 0, s[18:19]
	v_add3_u32 v66, v99, v66, s34
	v_bfe_u32 v93, v67, 16, 1
	v_lshl_add_u64 v[112:113], v[112:113], 0, v[64:65]
	v_lshrrev_b32_e32 v66, 16, v66
	v_add3_u32 v67, v67, v93, s34
	global_store_dwordx4 v[112:113], v[94:97], off nt
	s_andn2_b64 vcc, exec, s[14:15]
	s_mov_b64 s[14:15], -1
	v_and_or_b32 v94, v67, s35, v66
	v_bfe_u32 v66, v101, 16, 1
	v_add3_u32 v66, v101, v66, s34
	v_bfe_u32 v67, v103, 16, 1
	v_lshrrev_b32_e32 v66, 16, v66
	v_add3_u32 v67, v103, v67, s34
	v_and_or_b32 v95, v67, s35, v66
	v_bfe_u32 v66, v105, 16, 1
	v_add3_u32 v66, v105, v66, s34
	v_bfe_u32 v67, v107, 16, 1
	v_lshrrev_b32_e32 v66, 16, v66
	v_add3_u32 v67, v107, v67, s34
	v_and_or_b32 v96, v67, s35, v66
	v_bfe_u32 v66, v109, 16, 1
	v_add3_u32 v66, v109, v66, s34
	v_bfe_u32 v67, v111, 16, 1
	v_lshrrev_b32_e32 v66, 16, v66
	v_add3_u32 v67, v111, v67, s34
	v_and_or_b32 v97, v67, s35, v66
	v_add_u32_e32 v66, s22, v72
	v_ashrrev_i32_e32 v67, 31, v66
	v_lshlrev_b64 v[66:67], 13, v[66:67]
	v_lshl_add_u64 v[66:67], s[16:17], 0, v[66:67]
	v_lshl_add_u64 v[66:67], v[66:67], 0, s[18:19]
	v_lshl_add_u64 v[66:67], v[66:67], 0, v[64:65]
	global_store_dwordx4 v[66:67], v[94:97], off nt
	s_waitcnt lgkmcnt(0)
	s_cbranch_vccnz .LBB0_2131
	s_add_i32 s21, s27, s36
	s_cmp_gt_i32 s21, 0x139ff
	s_cbranch_scc1 .LBB0_2233
	s_cmpk_gt_i32 s21, 0x6dff
	s_cbranch_scc0 .LBB0_2191
	s_cmpk_gt_u32 s21, 0x8dff
	s_cbranch_scc0 .LBB0_2192
	s_add_i32 s14, s21, 0x7200
	s_and_b32 s15, s14, 0xffff
	s_mul_i32 s15, s15, 0xbe83
	s_lshr_b32 s16, s15, 25
	s_mul_i32 s15, s16, 0x2b0
	s_sub_i32 s14, s14, s15
	s_and_b32 s17, s14, 0xffff
	s_lshl_b32 s18, s17, 5
	s_bitcmp0_b32 s14, 2
	s_cselect_b32 s14, s28, 0x70
	s_add_u32 s14, s2, s14
	s_addc_u32 s15, s3, 0
	s_load_dwordx2 s[14:15], s[14:15], 0x0
	s_waitcnt lgkmcnt(0)
	s_add_u32 s14, s14, 0xac00000
	s_addc_u32 s15, s15, 0
	s_lshl_b32 s17, s17, 4
	s_and_b32 s18, s18, 0x60
	s_lshl_b32 s20, s16, 6
	s_and_b32 s16, s17, 0x3f80
	s_or_b32 s16, s16, s18
	v_or_b32_e32 v66, s16, v73
	s_mov_b64 s[16:17], 0x2b00
	s_cbranch_execz .LBB0_2193
	s_branch .LBB0_2194

.LBB0_2216:
	v_cmp_lt_i32_e32 vcc, -1, v66
	v_mov_b32_e32 v0, 0
	v_mov_b32_e32 v4, 0
	v_mov_b32_e32 v5, 0
	v_mov_b32_e32 v6, 0
	v_mov_b32_e32 v7, 0
	s_and_saveexec_b64 s[18:19], vcc
	s_cbranch_execz .LBB0_2218
	v_add_u32_e32 v1, s20, v68
	v_ashrrev_i32_e32 v2, 31, v1
	v_mul_lo_u32 v4, s16, v2
	v_mul_lo_u32 v5, s17, v1
	v_mad_u64_u32 v[2:3], s[22:23], s16, v1, 0
	v_add3_u32 v3, v3, v4, v5
	v_lshl_add_u64 v[2:3], v[2:3], 2, s[14:15]
	v_mov_b32_e32 v67, v65
	v_lshl_add_u64 v[2:3], v[66:67], 2, v[2:3]
	global_load_dwordx4 v[4:7], v[2:3], off nt
.LBB0_2218:
	s_or_b64 exec, exec, s[18:19]
	v_mov_b32_e32 v1, 0
	v_mov_b32_e32 v2, 0
	v_mov_b32_e32 v3, 0
	s_and_saveexec_b64 s[18:19], vcc
	s_cbranch_execz .LBB0_2220
	v_add_u32_e32 v0, s20, v70
	v_ashrrev_i32_e32 v1, 31, v0
	v_mul_lo_u32 v2, s16, v1
	v_mul_lo_u32 v3, s17, v0
	v_mad_u64_u32 v[0:1], s[22:23], s16, v0, 0
	v_add3_u32 v1, v1, v2, v3
	v_lshl_add_u64 v[0:1], v[0:1], 2, s[14:15]
	v_mov_b32_e32 v67, v65
	v_lshl_add_u64 v[0:1], v[66:67], 2, v[0:1]
	global_load_dwordx4 v[0:3], v[0:1], off nt
.LBB0_2220:
	s_or_b64 exec, exec, s[18:19]
	v_mov_b32_e32 v8, 0
	v_mov_b32_e32 v12, 0
	v_mov_b32_e32 v13, 0
	v_mov_b32_e32 v14, 0
	v_mov_b32_e32 v15, 0
	s_and_saveexec_b64 s[18:19], vcc
	s_cbranch_execz .LBB0_2222
	v_add_u32_e32 v9, s20, v71
	v_ashrrev_i32_e32 v10, 31, v9
	v_mul_lo_u32 v12, s16, v10
	v_mul_lo_u32 v13, s17, v9
	v_mad_u64_u32 v[10:11], s[22:23], s16, v9, 0
	v_add3_u32 v11, v11, v12, v13
	v_lshl_add_u64 v[10:11], v[10:11], 2, s[14:15]
	v_mov_b32_e32 v67, v65
	v_lshl_add_u64 v[10:11], v[66:67], 2, v[10:11]
	global_load_dwordx4 v[12:15], v[10:11], off nt
.LBB0_2222:
	s_or_b64 exec, exec, s[18:19]
	v_mov_b32_e32 v9, 0
	v_mov_b32_e32 v10, 0
	v_mov_b32_e32 v11, 0
	s_and_saveexec_b64 s[18:19], vcc
	s_cbranch_execz .LBB0_2224
	v_add_u32_e32 v8, s20, v72
	v_ashrrev_i32_e32 v9, 31, v8
	v_mul_lo_u32 v10, s16, v9
	v_mul_lo_u32 v11, s17, v8
	v_mad_u64_u32 v[8:9], s[22:23], s16, v8, 0
	v_add3_u32 v9, v9, v10, v11
	v_lshl_add_u64 v[8:9], v[8:9], 2, s[14:15]
	v_mov_b32_e32 v67, v65
	v_lshl_add_u64 v[8:9], v[66:67], 2, v[8:9]
	global_load_dwordx4 v[8:11], v[8:9], off nt
.LBB0_2224:
	s_or_b64 exec, exec, s[18:19]
	v_mov_b32_e32 v16, 0
	v_mov_b32_e32 v20, 0
	v_mov_b32_e32 v21, 0
	v_mov_b32_e32 v22, 0
	v_mov_b32_e32 v23, 0
	s_and_saveexec_b64 s[18:19], vcc
	s_cbranch_execz .LBB0_2226
	v_add_u32_e32 v17, s20, v74
	v_ashrrev_i32_e32 v18, 31, v17
	v_mul_lo_u32 v20, s16, v18
	v_mul_lo_u32 v21, s17, v17
	v_mad_u64_u32 v[18:19], s[22:23], s16, v17, 0
	v_add3_u32 v19, v19, v20, v21
	v_lshl_add_u64 v[18:19], v[18:19], 2, s[14:15]
	v_mov_b32_e32 v67, v65
	v_lshl_add_u64 v[18:19], v[66:67], 2, v[18:19]
	global_load_dwordx4 v[20:23], v[18:19], off nt
.LBB0_2226:
	s_or_b64 exec, exec, s[18:19]
	v_mov_b32_e32 v17, 0
	v_mov_b32_e32 v18, 0
	v_mov_b32_e32 v19, 0
	s_and_saveexec_b64 s[18:19], vcc
	s_cbranch_execz .LBB0_2228
	v_add_u32_e32 v16, s20, v75
	v_ashrrev_i32_e32 v17, 31, v16
	v_mul_lo_u32 v18, s16, v17
	v_mul_lo_u32 v19, s17, v16
	v_mad_u64_u32 v[16:17], s[22:23], s16, v16, 0
	v_add3_u32 v17, v17, v18, v19
	v_lshl_add_u64 v[16:17], v[16:17], 2, s[14:15]
	v_mov_b32_e32 v67, v65
	v_lshl_add_u64 v[16:17], v[66:67], 2, v[16:17]
	global_load_dwordx4 v[16:19], v[16:17], off nt
.LBB0_2228:
	s_or_b64 exec, exec, s[18:19]
	v_mov_b32_e32 v43, 0
	v_mov_b32_e32 v44, 0
	v_mov_b32_e32 v45, 0
	v_mov_b32_e32 v46, 0
	v_mov_b32_e32 v47, 0
	s_and_saveexec_b64 s[18:19], vcc
	s_cbranch_execz .LBB0_2230
	v_add_u32_e32 v40, s20, v76
	v_ashrrev_i32_e32 v41, 31, v40
	v_mul_lo_u32 v42, s16, v41
	v_mul_lo_u32 v44, s17, v40
	v_mad_u64_u32 v[40:41], s[22:23], s16, v40, 0
	v_add3_u32 v41, v41, v42, v44
	v_lshl_add_u64 v[40:41], v[40:41], 2, s[14:15]
	v_mov_b32_e32 v67, v65
	v_lshl_add_u64 v[40:41], v[66:67], 2, v[40:41]
	global_load_dwordx4 v[44:47], v[40:41], off nt
.LBB0_2230:
	s_or_b64 exec, exec, s[18:19]
	v_mov_b32_e32 v42, 0
	v_mov_b32_e32 v41, 0
	v_mov_b32_e32 v40, 0
	s_and_saveexec_b64 s[18:19], vcc
	s_cbranch_execz .LBB0_2232
	v_add_u32_e32 v40, s20, v69
	v_ashrrev_i32_e32 v41, 31, v40
	v_mul_lo_u32 v42, s16, v41
	v_mul_lo_u32 v43, s17, v40
	v_mad_u64_u32 v[40:41], s[16:17], s16, v40, 0
	v_add3_u32 v41, v41, v42, v43
	v_lshl_add_u64 v[40:41], v[40:41], 2, s[14:15]
	v_mov_b32_e32 v67, v65
	v_lshl_add_u64 v[40:41], v[66:67], 2, v[40:41]
	global_load_dwordx4 v[40:43], v[40:41], off nt

.LBB0_2299:
	ds_write2_b32 v78, v24, v25 offset1:1
	ds_write2_b32 v78, v26, v27 offset0:2 offset1:3
	ds_write2_b32 v79, v28, v29 offset1:1
	ds_write2_b32 v80, v30, v31 offset1:1
	ds_write2_b32 v81, v32, v33 offset1:1
	ds_write2_b32 v82, v34, v35 offset1:1
	ds_write2_b32 v83, v36, v37 offset1:1
	ds_write2_b32 v84, v38, v39 offset1:1
	ds_write2_b32 v85, v48, v49 offset1:1
	ds_write2_b32 v86, v50, v51 offset1:1
	ds_write2_b32 v87, v52, v53 offset1:1
	ds_write2_b32 v88, v54, v55 offset1:1
	ds_write2_b32 v89, v56, v57 offset1:1
	ds_write2_b32 v90, v58, v59 offset1:1
	ds_write2_b32 v91, v60, v61 offset1:1
	ds_write2_b32 v92, v62, v63 offset1:1
	s_waitcnt lgkmcnt(0)
	ds_read2_b32 v[66:67], v77 offset1:8
	ds_read2_b32 v[84:85], v77 offset0:33 offset1:41
	ds_read2_b32 v[86:87], v77 offset0:66 offset1:74
	ds_read2_b32 v[88:89], v77 offset0:99 offset1:107
	ds_read2_b32 v[90:91], v77 offset0:132 offset1:140
	s_waitcnt lgkmcnt(4)
	v_bfe_u32 v79, v66, 16, 1
	v_add3_u32 v66, v66, v79, s36
	s_waitcnt lgkmcnt(3)
	v_bfe_u32 v79, v84, 16, 1
	v_lshrrev_b32_e32 v66, 16, v66
	v_add3_u32 v79, v84, v79, s36
	ds_read2_b32 v[92:93], v77 offset0:165 offset1:173
	v_and_or_b32 v80, v79, s37, v66
	s_waitcnt lgkmcnt(3)
	v_bfe_u32 v66, v86, 16, 1
	v_add3_u32 v66, v86, v66, s36
	s_waitcnt lgkmcnt(2)
	v_bfe_u32 v79, v88, 16, 1
	ds_read2_b32 v[94:95], v77 offset0:198 offset1:206
	v_lshrrev_b32_e32 v66, 16, v66
	v_add3_u32 v79, v88, v79, s36
	ds_read2_b32 v[96:97], v77 offset0:231 offset1:239
	v_and_or_b32 v81, v79, s37, v66
	s_waitcnt lgkmcnt(3)
	v_bfe_u32 v66, v90, 16, 1
	v_add3_u32 v66, v90, v66, s36
	s_waitcnt lgkmcnt(2)
	v_bfe_u32 v79, v92, 16, 1
	v_lshrrev_b32_e32 v66, 16, v66
	v_add3_u32 v79, v92, v79, s36
	v_and_or_b32 v82, v79, s37, v66
	s_waitcnt lgkmcnt(1)
	v_bfe_u32 v66, v94, 16, 1
	v_add3_u32 v66, v94, v66, s36
	s_waitcnt lgkmcnt(0)
	v_bfe_u32 v79, v96, 16, 1
	v_lshrrev_b32_e32 v66, 16, v66
	v_add3_u32 v79, v96, v79, s36
	v_and_or_b32 v83, v79, s37, v66
	v_add_u32_e32 v66, s24, v68
	v_ashrrev_i32_e32 v79, 31, v66
	v_mul_lo_u32 v79, s16, v79
	v_mul_lo_u32 v84, s17, v66
	v_mad_u64_u32 v[98:99], s[22:23], s16, v66, 0
	v_add3_u32 v99, v99, v79, v84
	s_ashr_i32 s21, s20, 31
	v_lshl_add_u64 v[98:99], v[98:99], 1, s[18:19]
	s_lshl_b64 s[20:21], s[20:21], 1
	v_bfe_u32 v66, v67, 16, 1
	v_lshl_add_u64 v[98:99], v[98:99], 0, s[20:21]
	v_add3_u32 v66, v67, v66, s36
	v_bfe_u32 v67, v85, 16, 1
	v_lshl_add_u64 v[98:99], v[98:99], 0, v[64:65]
	v_lshrrev_b32_e32 v66, 16, v66
	v_add3_u32 v67, v85, v67, s36
	global_store_dwordx4 v[98:99], v[80:83], off nt
	s_add_i32 s38, s39, s10
	s_add_i32 s11, s11, s27
	v_and_or_b32 v80, v67, s37, v66
	v_bfe_u32 v66, v87, 16, 1
	v_add3_u32 v66, v87, v66, s36
	v_bfe_u32 v67, v89, 16, 1
	v_lshrrev_b32_e32 v66, 16, v66
	v_add3_u32 v67, v89, v67, s36
	v_and_or_b32 v81, v67, s37, v66
	v_bfe_u32 v66, v91, 16, 1
	v_add3_u32 v66, v91, v66, s36
	v_bfe_u32 v67, v93, 16, 1
	v_lshrrev_b32_e32 v66, 16, v66
	v_add3_u32 v67, v93, v67, s36
	v_and_or_b32 v82, v67, s37, v66
	v_bfe_u32 v66, v95, 16, 1
	v_add3_u32 v66, v95, v66, s36
	v_bfe_u32 v67, v97, 16, 1
	v_lshrrev_b32_e32 v66, 16, v66
	v_add3_u32 v67, v97, v67, s36
	v_and_or_b32 v83, v67, s37, v66
	v_add_u32_e32 v66, s24, v70
	v_ashrrev_i32_e32 v67, 31, v66
	v_mul_lo_u32 v79, s16, v67
	v_mul_lo_u32 v84, s17, v66
	v_mad_u64_u32 v[66:67], s[22:23], s16, v66, 0
	v_add3_u32 v67, v67, v79, v84
	v_lshl_add_u64 v[66:67], v[66:67], 1, s[18:19]
	v_lshl_add_u64 v[66:67], v[66:67], 0, s[20:21]
	ds_read2_b32 v[84:85], v77 offset0:16 offset1:24
	v_lshl_add_u64 v[66:67], v[66:67], 0, v[64:65]
	global_store_dwordx4 v[66:67], v[80:83], off nt
	ds_read2_b32 v[66:67], v77 offset0:49 offset1:57
	ds_read2_b32 v[86:87], v77 offset0:82 offset1:90
	ds_read2_b32 v[88:89], v77 offset0:115 offset1:123
	s_waitcnt lgkmcnt(3)
	v_bfe_u32 v79, v84, 16, 1
	v_add3_u32 v79, v84, v79, s36
	s_waitcnt lgkmcnt(2)
	v_bfe_u32 v80, v66, 16, 1
	ds_read2_b32 v[90:91], v77 offset0:148 offset1:156
	v_lshrrev_b32_e32 v79, 16, v79
	v_add3_u32 v66, v66, v80, s36
	ds_read2_b32 v[92:93], v77 offset0:181 offset1:189
	v_and_or_b32 v80, v66, s37, v79
	s_waitcnt lgkmcnt(3)
	v_bfe_u32 v66, v86, 16, 1
	v_add3_u32 v66, v86, v66, s36
	s_waitcnt lgkmcnt(2)
	v_bfe_u32 v79, v88, 16, 1
	ds_read2_b32 v[94:95], v77 offset0:214 offset1:222
	v_lshrrev_b32_e32 v66, 16, v66
	v_add3_u32 v79, v88, v79, s36
	ds_read2_b32 v[96:97], v77 offset0:247 offset1:255
	v_and_or_b32 v81, v79, s37, v66
	s_waitcnt lgkmcnt(3)
	v_bfe_u32 v66, v90, 16, 1
	v_add3_u32 v66, v90, v66, s36
	s_waitcnt lgkmcnt(2)
	v_bfe_u32 v79, v92, 16, 1
	v_lshrrev_b32_e32 v66, 16, v66
	v_add3_u32 v79, v92, v79, s36
	v_and_or_b32 v82, v79, s37, v66
	s_waitcnt lgkmcnt(1)
	v_bfe_u32 v66, v94, 16, 1
	v_add3_u32 v66, v94, v66, s36
	s_waitcnt lgkmcnt(0)
	v_bfe_u32 v79, v96, 16, 1
	v_lshrrev_b32_e32 v66, 16, v66
	v_add3_u32 v79, v96, v79, s36
	v_and_or_b32 v83, v79, s37, v66
	v_add_u32_e32 v66, s24, v71
	v_ashrrev_i32_e32 v79, 31, v66
	v_mul_lo_u32 v79, s16, v79
	v_mul_lo_u32 v84, s17, v66
	v_mad_u64_u32 v[98:99], s[22:23], s16, v66, 0
	v_add3_u32 v99, v99, v79, v84
	v_lshl_add_u64 v[98:99], v[98:99], 1, s[18:19]
	v_bfe_u32 v66, v85, 16, 1
	v_lshl_add_u64 v[98:99], v[98:99], 0, s[20:21]
	v_add3_u32 v66, v85, v66, s36
	v_bfe_u32 v79, v67, 16, 1
	v_lshl_add_u64 v[98:99], v[98:99], 0, v[64:65]
	v_lshrrev_b32_e32 v66, 16, v66
	v_add3_u32 v67, v67, v79, s36
	global_store_dwordx4 v[98:99], v[80:83], off nt
	s_cmp_gt_i32 s38, 0x18fff
	s_nop 0
	v_and_or_b32 v80, v67, s37, v66
	v_bfe_u32 v66, v87, 16, 1
	v_add3_u32 v66, v87, v66, s36
	v_bfe_u32 v67, v89, 16, 1
	v_lshrrev_b32_e32 v66, 16, v66
	v_add3_u32 v67, v89, v67, s36
	v_and_or_b32 v81, v67, s37, v66
	v_bfe_u32 v66, v91, 16, 1
	v_add3_u32 v66, v91, v66, s36
	v_bfe_u32 v67, v93, 16, 1
	v_lshrrev_b32_e32 v66, 16, v66
	v_add3_u32 v67, v93, v67, s36
	v_and_or_b32 v82, v67, s37, v66
	v_bfe_u32 v66, v95, 16, 1
	v_add3_u32 v66, v95, v66, s36
	v_bfe_u32 v67, v97, 16, 1
	v_lshrrev_b32_e32 v66, 16, v66
	v_add3_u32 v67, v97, v67, s36
	v_and_or_b32 v83, v67, s37, v66
	v_add_u32_e32 v66, s24, v72
	v_ashrrev_i32_e32 v67, 31, v66
	v_mul_lo_u32 v79, s16, v67
	v_mul_lo_u32 v84, s17, v66
	v_mad_u64_u32 v[66:67], s[16:17], s16, v66, 0
	v_add3_u32 v67, v67, v79, v84
	v_lshl_add_u64 v[66:67], v[66:67], 1, s[18:19]
	v_lshl_add_u64 v[66:67], v[66:67], 0, s[20:21]
	v_lshl_add_u64 v[66:67], v[66:67], 0, v[64:65]
	global_store_dwordx4 v[66:67], v[80:83], off nt
	s_waitcnt lgkmcnt(0)
	s_cselect_b64 s[16:17], -1, 0

.LBB0_2334:
	v_cmp_lt_i32_e32 vcc, -1, v66
	v_mov_b32_e32 v28, 0
	v_mov_b32_e32 v24, 0
	v_mov_b32_e32 v25, 0
	v_mov_b32_e32 v26, 0
	v_mov_b32_e32 v27, 0
	s_and_saveexec_b64 s[22:23], vcc
	s_cbranch_execz .LBB0_2336
	v_add_u32_e32 v24, s24, v68
	v_ashrrev_i32_e32 v25, 31, v24
	v_mul_lo_u32 v26, s20, v25
	v_mul_lo_u32 v27, s21, v24
	v_mad_u64_u32 v[24:25], s[40:41], s20, v24, 0
	v_add3_u32 v25, v25, v26, v27
	v_lshl_add_u64 v[24:25], v[24:25], 2, s[18:19]
	v_mov_b32_e32 v67, v65
	v_lshl_add_u64 v[24:25], v[66:67], 2, v[24:25]
	global_load_dwordx4 v[24:27], v[24:25], off nt
.LBB0_2336:
	s_or_b64 exec, exec, s[22:23]
	v_mov_b32_e32 v29, 0
	v_mov_b32_e32 v30, 0
	v_mov_b32_e32 v31, 0
	s_and_saveexec_b64 s[22:23], vcc
	s_cbranch_execz .LBB0_2338
	v_add_u32_e32 v28, s24, v70
	v_ashrrev_i32_e32 v29, 31, v28
	v_mul_lo_u32 v30, s20, v29
	v_mul_lo_u32 v31, s21, v28
	v_mad_u64_u32 v[28:29], s[40:41], s20, v28, 0
	v_add3_u32 v29, v29, v30, v31
	v_lshl_add_u64 v[28:29], v[28:29], 2, s[18:19]
	v_mov_b32_e32 v67, v65
	v_lshl_add_u64 v[28:29], v[66:67], 2, v[28:29]
	global_load_dwordx4 v[28:31], v[28:29], off nt
.LBB0_2338:
	s_or_b64 exec, exec, s[22:23]
	v_mov_b32_e32 v36, 0
	v_mov_b32_e32 v32, 0
	v_mov_b32_e32 v33, 0
	v_mov_b32_e32 v34, 0
	v_mov_b32_e32 v35, 0
	s_and_saveexec_b64 s[22:23], vcc
	s_cbranch_execz .LBB0_2340
	v_add_u32_e32 v32, s24, v71
	v_ashrrev_i32_e32 v33, 31, v32
	v_mul_lo_u32 v34, s20, v33
	v_mul_lo_u32 v35, s21, v32
	v_mad_u64_u32 v[32:33], s[40:41], s20, v32, 0
	v_add3_u32 v33, v33, v34, v35
	v_lshl_add_u64 v[32:33], v[32:33], 2, s[18:19]
	v_mov_b32_e32 v67, v65
	v_lshl_add_u64 v[32:33], v[66:67], 2, v[32:33]
	global_load_dwordx4 v[32:35], v[32:33], off nt
.LBB0_2340:
	s_or_b64 exec, exec, s[22:23]
	v_mov_b32_e32 v37, 0
	v_mov_b32_e32 v38, 0
	v_mov_b32_e32 v39, 0
	s_and_saveexec_b64 s[22:23], vcc
	s_cbranch_execz .LBB0_2342
	v_add_u32_e32 v36, s24, v72
	v_ashrrev_i32_e32 v37, 31, v36
	v_mul_lo_u32 v38, s20, v37
	v_mul_lo_u32 v39, s21, v36
	v_mad_u64_u32 v[36:37], s[40:41], s20, v36, 0
	v_add3_u32 v37, v37, v38, v39
	v_lshl_add_u64 v[36:37], v[36:37], 2, s[18:19]
	v_mov_b32_e32 v67, v65
	v_lshl_add_u64 v[36:37], v[66:67], 2, v[36:37]
	global_load_dwordx4 v[36:39], v[36:37], off nt
.LBB0_2342:
	s_or_b64 exec, exec, s[22:23]
	v_mov_b32_e32 v52, 0
	v_mov_b32_e32 v48, 0
	v_mov_b32_e32 v49, 0
	v_mov_b32_e32 v50, 0
	v_mov_b32_e32 v51, 0
	s_and_saveexec_b64 s[22:23], vcc
	s_cbranch_execz .LBB0_2344
	v_add_u32_e32 v48, s24, v74
	v_ashrrev_i32_e32 v49, 31, v48
	v_mul_lo_u32 v50, s20, v49
	v_mul_lo_u32 v51, s21, v48
	v_mad_u64_u32 v[48:49], s[40:41], s20, v48, 0
	v_add3_u32 v49, v49, v50, v51
	v_lshl_add_u64 v[48:49], v[48:49], 2, s[18:19]
	v_mov_b32_e32 v67, v65
	v_lshl_add_u64 v[48:49], v[66:67], 2, v[48:49]
	global_load_dwordx4 v[48:51], v[48:49], off nt
.LBB0_2344:
	s_or_b64 exec, exec, s[22:23]
	v_mov_b32_e32 v53, 0
	v_mov_b32_e32 v54, 0
	v_mov_b32_e32 v55, 0
	s_and_saveexec_b64 s[22:23], vcc
	s_cbranch_execz .LBB0_2346
	v_add_u32_e32 v52, s24, v75
	v_ashrrev_i32_e32 v53, 31, v52
	v_mul_lo_u32 v54, s20, v53
	v_mul_lo_u32 v55, s21, v52
	v_mad_u64_u32 v[52:53], s[40:41], s20, v52, 0
	v_add3_u32 v53, v53, v54, v55
	v_lshl_add_u64 v[52:53], v[52:53], 2, s[18:19]
	v_mov_b32_e32 v67, v65
	v_lshl_add_u64 v[52:53], v[66:67], 2, v[52:53]
	global_load_dwordx4 v[52:55], v[52:53], off nt
.LBB0_2346:
	s_or_b64 exec, exec, s[22:23]
	v_mov_b32_e32 v63, 0
	v_mov_b32_e32 v56, 0
	v_mov_b32_e32 v57, 0
	v_mov_b32_e32 v58, 0
	v_mov_b32_e32 v59, 0
	s_and_saveexec_b64 s[22:23], vcc
	s_cbranch_execz .LBB0_2348
	v_add_u32_e32 v56, s24, v76
	v_ashrrev_i32_e32 v57, 31, v56
	v_mul_lo_u32 v58, s20, v57
	v_mul_lo_u32 v59, s21, v56
	v_mad_u64_u32 v[56:57], s[40:41], s20, v56, 0
	v_add3_u32 v57, v57, v58, v59
	v_lshl_add_u64 v[56:57], v[56:57], 2, s[18:19]
	v_mov_b32_e32 v67, v65
	v_lshl_add_u64 v[56:57], v[66:67], 2, v[56:57]
	global_load_dwordx4 v[56:59], v[56:57], off nt
.LBB0_2348:
	s_or_b64 exec, exec, s[22:23]
	v_mov_b32_e32 v62, 0
	v_mov_b32_e32 v61, 0
	v_mov_b32_e32 v60, 0
	s_and_saveexec_b64 s[22:23], vcc
	s_cbranch_execz .LBB0_2350
	v_add_u32_e32 v60, s24, v69
	v_ashrrev_i32_e32 v61, 31, v60
	v_mul_lo_u32 v62, s20, v61
	v_mul_lo_u32 v63, s21, v60
	v_mad_u64_u32 v[60:61], s[20:21], s20, v60, 0
	v_add3_u32 v61, v61, v62, v63
	v_lshl_add_u64 v[60:61], v[60:61], 2, s[18:19]
	v_mov_b32_e32 v67, v65
	v_lshl_add_u64 v[60:61], v[66:67], 2, v[60:61]
	global_load_dwordx4 v[60:63], v[60:61], off nt

.LBB0_2363:
	v_add_u32_e32 v79, 0x420, v78
	v_add_u32_e32 v80, 0x428, v78
	v_add_u32_e32 v81, 0x840, v78
	v_add_u32_e32 v82, 0x848, v78
	v_add_u32_e32 v83, 0xc60, v78
	v_add_u32_e32 v84, 0xc68, v78
	v_add_u32_e32 v85, 0x1080, v78
	v_add_u32_e32 v86, 0x1088, v78
	v_add_u32_e32 v87, 0x14a0, v78
	v_add_u32_e32 v88, 0x14a8, v78
	v_add_u32_e32 v89, 0x18c0, v78
	v_add_u32_e32 v90, 0x18c8, v78
	v_add_u32_e32 v91, 0x1ce0, v78
	v_add_u32_e32 v92, 0x1ce8, v78
	s_waitcnt vmcnt(0)
	ds_write2_b32 v78, v4, v5 offset1:1
	ds_write2_b32 v78, v6, v7 offset0:2 offset1:3
	ds_write2_b32 v79, v0, v1 offset1:1
	ds_write2_b32 v80, v2, v3 offset1:1
	ds_write2_b32 v81, v12, v13 offset1:1
	ds_write2_b32 v82, v14, v15 offset1:1
	ds_write2_b32 v83, v8, v9 offset1:1
	ds_write2_b32 v84, v10, v11 offset1:1
	ds_write2_b32 v85, v20, v21 offset1:1
	ds_write2_b32 v86, v22, v23 offset1:1
	ds_write2_b32 v87, v16, v17 offset1:1
	ds_write2_b32 v88, v18, v19 offset1:1
	ds_write2_b32 v89, v44, v45 offset1:1
	ds_write2_b32 v90, v46, v47 offset1:1
	ds_write2_b32 v91, v40, v41 offset1:1
	ds_write2_b32 v92, v42, v43 offset1:1
	s_waitcnt lgkmcnt(0)
	ds_read2_b32 v[66:67], v77 offset1:8
	ds_read2_b32 v[98:99], v77 offset0:33 offset1:41
	ds_read2_b32 v[100:101], v77 offset0:66 offset1:74
	ds_read2_b32 v[102:103], v77 offset0:99 offset1:107
	ds_read2_b32 v[104:105], v77 offset0:132 offset1:140
	s_waitcnt lgkmcnt(4)
	v_bfe_u32 v93, v66, 16, 1
	v_add3_u32 v66, v66, v93, s36
	s_waitcnt lgkmcnt(3)
	v_bfe_u32 v93, v98, 16, 1
	v_lshrrev_b32_e32 v66, 16, v66
	v_add3_u32 v93, v98, v93, s36
	ds_read2_b32 v[106:107], v77 offset0:165 offset1:173
	v_and_or_b32 v94, v93, s37, v66
	s_waitcnt lgkmcnt(3)
	v_bfe_u32 v66, v100, 16, 1
	v_add3_u32 v66, v100, v66, s36
	s_waitcnt lgkmcnt(2)
	v_bfe_u32 v93, v102, 16, 1
	ds_read2_b32 v[108:109], v77 offset0:198 offset1:206
	v_lshrrev_b32_e32 v66, 16, v66
	v_add3_u32 v93, v102, v93, s36
	ds_read2_b32 v[110:111], v77 offset0:231 offset1:239
	v_and_or_b32 v95, v93, s37, v66
	s_waitcnt lgkmcnt(3)
	v_bfe_u32 v66, v104, 16, 1
	v_add3_u32 v66, v104, v66, s36
	s_waitcnt lgkmcnt(2)
	v_bfe_u32 v93, v106, 16, 1
	v_lshrrev_b32_e32 v66, 16, v66
	v_add3_u32 v93, v106, v93, s36
	v_and_or_b32 v96, v93, s37, v66
	s_waitcnt lgkmcnt(1)
	v_bfe_u32 v66, v108, 16, 1
	v_add3_u32 v66, v108, v66, s36
	s_waitcnt lgkmcnt(0)
	v_bfe_u32 v93, v110, 16, 1
	v_lshrrev_b32_e32 v66, 16, v66
	v_add3_u32 v93, v110, v93, s36
	v_and_or_b32 v97, v93, s37, v66
	v_add_u32_e32 v66, s40, v68
	v_ashrrev_i32_e32 v93, 31, v66
	v_mul_lo_u32 v93, s18, v93
	v_mul_lo_u32 v98, s19, v66
	v_mad_u64_u32 v[112:113], s[24:25], s18, v66, 0
	v_add3_u32 v113, v113, v93, v98
	s_ashr_i32 s23, s22, 31
	v_lshl_add_u64 v[112:113], v[112:113], 1, s[20:21]
	s_lshl_b64 s[22:23], s[22:23], 1
	v_bfe_u32 v66, v67, 16, 1
	v_lshl_add_u64 v[112:113], v[112:113], 0, s[22:23]
	v_add3_u32 v66, v67, v66, s36
	v_bfe_u32 v67, v99, 16, 1
	v_lshl_add_u64 v[112:113], v[112:113], 0, v[64:65]
	v_lshrrev_b32_e32 v66, 16, v66
	v_add3_u32 v67, v99, v67, s36
	global_store_dwordx4 v[112:113], v[94:97], off nt
	s_andn2_b64 vcc, exec, s[16:17]
	s_mov_b64 s[16:17], -1
	v_and_or_b32 v94, v67, s37, v66
	v_bfe_u32 v66, v101, 16, 1
	v_add3_u32 v66, v101, v66, s36
	v_bfe_u32 v67, v103, 16, 1
	v_lshrrev_b32_e32 v66, 16, v66
	v_add3_u32 v67, v103, v67, s36
	v_and_or_b32 v95, v67, s37, v66
	v_bfe_u32 v66, v105, 16, 1
	v_add3_u32 v66, v105, v66, s36
	v_bfe_u32 v67, v107, 16, 1
	v_lshrrev_b32_e32 v66, 16, v66
	v_add3_u32 v67, v107, v67, s36
	v_and_or_b32 v96, v67, s37, v66
	v_bfe_u32 v66, v109, 16, 1
	v_add3_u32 v66, v109, v66, s36
	v_bfe_u32 v67, v111, 16, 1
	v_lshrrev_b32_e32 v66, 16, v66
	v_add3_u32 v67, v111, v67, s36
	v_and_or_b32 v97, v67, s37, v66
	v_add_u32_e32 v66, s40, v70
	v_ashrrev_i32_e32 v67, 31, v66
	v_mul_lo_u32 v93, s18, v67
	v_mul_lo_u32 v98, s19, v66
	v_mad_u64_u32 v[66:67], s[24:25], s18, v66, 0
	v_add3_u32 v67, v67, v93, v98
	v_lshl_add_u64 v[66:67], v[66:67], 1, s[20:21]
	v_lshl_add_u64 v[66:67], v[66:67], 0, s[22:23]
	ds_read2_b32 v[98:99], v77 offset0:16 offset1:24
	v_lshl_add_u64 v[66:67], v[66:67], 0, v[64:65]
	global_store_dwordx4 v[66:67], v[94:97], off nt
	ds_read2_b32 v[66:67], v77 offset0:49 offset1:57
	ds_read2_b32 v[100:101], v77 offset0:82 offset1:90
	ds_read2_b32 v[102:103], v77 offset0:115 offset1:123
	s_waitcnt lgkmcnt(3)
	v_bfe_u32 v93, v98, 16, 1
	v_add3_u32 v93, v98, v93, s36
	s_waitcnt lgkmcnt(2)
	v_bfe_u32 v94, v66, 16, 1
	ds_read2_b32 v[104:105], v77 offset0:148 offset1:156
	v_lshrrev_b32_e32 v93, 16, v93
	v_add3_u32 v66, v66, v94, s36
	ds_read2_b32 v[106:107], v77 offset0:181 offset1:189
	v_and_or_b32 v94, v66, s37, v93
	s_waitcnt lgkmcnt(3)
	v_bfe_u32 v66, v100, 16, 1
	v_add3_u32 v66, v100, v66, s36
	s_waitcnt lgkmcnt(2)
	v_bfe_u32 v93, v102, 16, 1
	ds_read2_b32 v[108:109], v77 offset0:214 offset1:222
	v_lshrrev_b32_e32 v66, 16, v66
	v_add3_u32 v93, v102, v93, s36
	ds_read2_b32 v[110:111], v77 offset0:247 offset1:255
	v_and_or_b32 v95, v93, s37, v66
	s_waitcnt lgkmcnt(3)
	v_bfe_u32 v66, v104, 16, 1
	v_add3_u32 v66, v104, v66, s36
	s_waitcnt lgkmcnt(2)
	v_bfe_u32 v93, v106, 16, 1
	v_lshrrev_b32_e32 v66, 16, v66
	v_add3_u32 v93, v106, v93, s36
	v_and_or_b32 v96, v93, s37, v66
	s_waitcnt lgkmcnt(1)
	v_bfe_u32 v66, v108, 16, 1
	v_add3_u32 v66, v108, v66, s36
	s_waitcnt lgkmcnt(0)
	v_bfe_u32 v93, v110, 16, 1
	v_lshrrev_b32_e32 v66, 16, v66
	v_add3_u32 v93, v110, v93, s36
	v_and_or_b32 v97, v93, s37, v66
	v_add_u32_e32 v66, s40, v71
	v_ashrrev_i32_e32 v93, 31, v66
	v_mul_lo_u32 v93, s18, v93
	v_mul_lo_u32 v98, s19, v66
	v_mad_u64_u32 v[112:113], s[24:25], s18, v66, 0
	v_add3_u32 v113, v113, v93, v98
	v_lshl_add_u64 v[112:113], v[112:113], 1, s[20:21]
	v_bfe_u32 v66, v99, 16, 1
	v_lshl_add_u64 v[112:113], v[112:113], 0, s[22:23]
	v_add3_u32 v66, v99, v66, s36
	v_bfe_u32 v93, v67, 16, 1
	v_lshl_add_u64 v[112:113], v[112:113], 0, v[64:65]
	v_lshrrev_b32_e32 v66, 16, v66
	v_add3_u32 v67, v67, v93, s36
	global_store_dwordx4 v[112:113], v[94:97], off nt
	s_nop 1
	v_and_or_b32 v94, v67, s37, v66
	v_bfe_u32 v66, v101, 16, 1
	v_add3_u32 v66, v101, v66, s36
	v_bfe_u32 v67, v103, 16, 1
	v_lshrrev_b32_e32 v66, 16, v66
	v_add3_u32 v67, v103, v67, s36
	v_and_or_b32 v95, v67, s37, v66
	v_bfe_u32 v66, v105, 16, 1
	v_add3_u32 v66, v105, v66, s36
	v_bfe_u32 v67, v107, 16, 1
	v_lshrrev_b32_e32 v66, 16, v66
	v_add3_u32 v67, v107, v67, s36
	v_and_or_b32 v96, v67, s37, v66
	v_bfe_u32 v66, v109, 16, 1
	v_add3_u32 v66, v109, v66, s36
	v_bfe_u32 v67, v111, 16, 1
	v_lshrrev_b32_e32 v66, 16, v66
	v_add3_u32 v67, v111, v67, s36
	v_and_or_b32 v97, v67, s37, v66
	v_add_u32_e32 v66, s40, v72
	v_ashrrev_i32_e32 v67, 31, v66
	v_mul_lo_u32 v93, s18, v67
	v_mul_lo_u32 v98, s19, v66
	v_mad_u64_u32 v[66:67], s[18:19], s18, v66, 0
	v_add3_u32 v67, v67, v93, v98
	v_lshl_add_u64 v[66:67], v[66:67], 1, s[20:21]
	v_lshl_add_u64 v[66:67], v[66:67], 0, s[22:23]
	v_lshl_add_u64 v[66:67], v[66:67], 0, v[64:65]
	global_store_dwordx4 v[66:67], v[94:97], off nt
	s_waitcnt lgkmcnt(0)
	s_cbranch_vccnz .LBB0_2300
	s_add_i32 s23, s29, s38
	s_cmp_gt_i32 s23, 0x18fff
	s_cbranch_scc1 .LBB0_2414
	s_cmpk_gt_i32 s23, 0x6dff
	s_cbranch_scc0 .LBB0_2369
	s_cmpk_gt_u32 s23, 0x8dff
	s_cbranch_scc0 .LBB0_2370
	s_cmp_gt_u32 s23, 0x139ff
	s_cbranch_scc0 .LBB0_2371
	s_load_dwordx2 s[16:17], s[2:3], 0x78
	s_add_i32 s18, s23, 0xfffec600
	s_waitcnt lgkmcnt(0)
	s_add_u32 s16, s16, 0xac00000
	s_addc_u32 s17, s17, 0
	s_add_i32 s19, s27, s11
	s_lshr_b32 s18, s18, 1
	s_and_b32 s19, s19, 0xfe0
	s_and_b32 s22, s18, 0x7fffffc0
	v_or_b32_e32 v66, s19, v73
	s_mov_b64 s[18:19], 0x1000
	s_cbranch_execz .LBB0_2372
	s_branch .LBB0_2373

.LBB0_2397:
	v_cmp_lt_i32_e32 vcc, -1, v66
	v_mov_b32_e32 v0, 0
	v_mov_b32_e32 v4, 0
	v_mov_b32_e32 v5, 0
	v_mov_b32_e32 v6, 0
	v_mov_b32_e32 v7, 0
	s_and_saveexec_b64 s[20:21], vcc
	s_cbranch_execz .LBB0_2399
	v_add_u32_e32 v1, s22, v68
	v_ashrrev_i32_e32 v2, 31, v1
	v_mul_lo_u32 v4, s18, v2
	v_mul_lo_u32 v5, s19, v1
	v_mad_u64_u32 v[2:3], s[24:25], s18, v1, 0
	v_add3_u32 v3, v3, v4, v5
	v_lshl_add_u64 v[2:3], v[2:3], 2, s[16:17]
	v_mov_b32_e32 v67, v65
	v_lshl_add_u64 v[2:3], v[66:67], 2, v[2:3]
	global_load_dwordx4 v[4:7], v[2:3], off nt
.LBB0_2399:
	s_or_b64 exec, exec, s[20:21]
	v_mov_b32_e32 v1, 0
	v_mov_b32_e32 v2, 0
	v_mov_b32_e32 v3, 0
	s_and_saveexec_b64 s[20:21], vcc
	s_cbranch_execz .LBB0_2401
	v_add_u32_e32 v0, s22, v70
	v_ashrrev_i32_e32 v1, 31, v0
	v_mul_lo_u32 v2, s18, v1
	v_mul_lo_u32 v3, s19, v0
	v_mad_u64_u32 v[0:1], s[24:25], s18, v0, 0
	v_add3_u32 v1, v1, v2, v3
	v_lshl_add_u64 v[0:1], v[0:1], 2, s[16:17]
	v_mov_b32_e32 v67, v65
	v_lshl_add_u64 v[0:1], v[66:67], 2, v[0:1]
	global_load_dwordx4 v[0:3], v[0:1], off nt
.LBB0_2401:
	s_or_b64 exec, exec, s[20:21]
	v_mov_b32_e32 v8, 0
	v_mov_b32_e32 v12, 0
	v_mov_b32_e32 v13, 0
	v_mov_b32_e32 v14, 0
	v_mov_b32_e32 v15, 0
	s_and_saveexec_b64 s[20:21], vcc
	s_cbranch_execz .LBB0_2403
	v_add_u32_e32 v9, s22, v71
	v_ashrrev_i32_e32 v10, 31, v9
	v_mul_lo_u32 v12, s18, v10
	v_mul_lo_u32 v13, s19, v9
	v_mad_u64_u32 v[10:11], s[24:25], s18, v9, 0
	v_add3_u32 v11, v11, v12, v13
	v_lshl_add_u64 v[10:11], v[10:11], 2, s[16:17]
	v_mov_b32_e32 v67, v65
	v_lshl_add_u64 v[10:11], v[66:67], 2, v[10:11]
	global_load_dwordx4 v[12:15], v[10:11], off nt
.LBB0_2403:
	s_or_b64 exec, exec, s[20:21]
	v_mov_b32_e32 v9, 0
	v_mov_b32_e32 v10, 0
	v_mov_b32_e32 v11, 0
	s_and_saveexec_b64 s[20:21], vcc
	s_cbranch_execz .LBB0_2405
	v_add_u32_e32 v8, s22, v72
	v_ashrrev_i32_e32 v9, 31, v8
	v_mul_lo_u32 v10, s18, v9
	v_mul_lo_u32 v11, s19, v8
	v_mad_u64_u32 v[8:9], s[24:25], s18, v8, 0
	v_add3_u32 v9, v9, v10, v11
	v_lshl_add_u64 v[8:9], v[8:9], 2, s[16:17]
	v_mov_b32_e32 v67, v65
	v_lshl_add_u64 v[8:9], v[66:67], 2, v[8:9]
	global_load_dwordx4 v[8:11], v[8:9], off nt
.LBB0_2405:
	s_or_b64 exec, exec, s[20:21]
	v_mov_b32_e32 v16, 0
	v_mov_b32_e32 v20, 0
	v_mov_b32_e32 v21, 0
	v_mov_b32_e32 v22, 0
	v_mov_b32_e32 v23, 0
	s_and_saveexec_b64 s[20:21], vcc
	s_cbranch_execz .LBB0_2407
	v_add_u32_e32 v17, s22, v74
	v_ashrrev_i32_e32 v18, 31, v17
	v_mul_lo_u32 v20, s18, v18
	v_mul_lo_u32 v21, s19, v17
	v_mad_u64_u32 v[18:19], s[24:25], s18, v17, 0
	v_add3_u32 v19, v19, v20, v21
	v_lshl_add_u64 v[18:19], v[18:19], 2, s[16:17]
	v_mov_b32_e32 v67, v65
	v_lshl_add_u64 v[18:19], v[66:67], 2, v[18:19]
	global_load_dwordx4 v[20:23], v[18:19], off nt
.LBB0_2407:
	s_or_b64 exec, exec, s[20:21]
	v_mov_b32_e32 v17, 0
	v_mov_b32_e32 v18, 0
	v_mov_b32_e32 v19, 0
	s_and_saveexec_b64 s[20:21], vcc
	s_cbranch_execz .LBB0_2409
	v_add_u32_e32 v16, s22, v75
	v_ashrrev_i32_e32 v17, 31, v16
	v_mul_lo_u32 v18, s18, v17
	v_mul_lo_u32 v19, s19, v16
	v_mad_u64_u32 v[16:17], s[24:25], s18, v16, 0
	v_add3_u32 v17, v17, v18, v19
	v_lshl_add_u64 v[16:17], v[16:17], 2, s[16:17]
	v_mov_b32_e32 v67, v65
	v_lshl_add_u64 v[16:17], v[66:67], 2, v[16:17]
	global_load_dwordx4 v[16:19], v[16:17], off nt
.LBB0_2409:
	s_or_b64 exec, exec, s[20:21]
	v_mov_b32_e32 v43, 0
	v_mov_b32_e32 v44, 0
	v_mov_b32_e32 v45, 0
	v_mov_b32_e32 v46, 0
	v_mov_b32_e32 v47, 0
	s_and_saveexec_b64 s[20:21], vcc
	s_cbranch_execz .LBB0_2411
	v_add_u32_e32 v40, s22, v76
	v_ashrrev_i32_e32 v41, 31, v40
	v_mul_lo_u32 v42, s18, v41
	v_mul_lo_u32 v44, s19, v40
	v_mad_u64_u32 v[40:41], s[24:25], s18, v40, 0
	v_add3_u32 v41, v41, v42, v44
	v_lshl_add_u64 v[40:41], v[40:41], 2, s[16:17]
	v_mov_b32_e32 v67, v65
	v_lshl_add_u64 v[40:41], v[66:67], 2, v[40:41]
	global_load_dwordx4 v[44:47], v[40:41], off nt
.LBB0_2411:
	s_or_b64 exec, exec, s[20:21]
	v_mov_b32_e32 v42, 0
	v_mov_b32_e32 v41, 0
	v_mov_b32_e32 v40, 0
	s_and_saveexec_b64 s[20:21], vcc
	s_cbranch_execz .LBB0_2413
	v_add_u32_e32 v40, s22, v69
	v_ashrrev_i32_e32 v41, 31, v40
	v_mul_lo_u32 v42, s18, v41
	v_mul_lo_u32 v43, s19, v40
	v_mad_u64_u32 v[40:41], s[18:19], s18, v40, 0
	v_add3_u32 v41, v41, v42, v43
	v_lshl_add_u64 v[40:41], v[40:41], 2, s[16:17]
	v_mov_b32_e32 v67, v65
	v_lshl_add_u64 v[40:41], v[66:67], 2, v[40:41]
	global_load_dwordx4 v[40:43], v[40:41], off nt

.LBB0_3749:
	v_lshl_add_u64 v[4:5], s[6:7], 0, v[112:113]
	global_load_dword v10, v[4:5], off nt
	v_lshl_add_u64 v[8:9], s[6:7], 0, v[114:115]
	v_add_co_u32_e32 v30, vcc, s17, v8
	v_lshl_add_u64 v[14:15], s[6:7], 0, v[116:117]
	s_nop 0
	v_addc_co_u32_e32 v31, vcc, 0, v9, vcc
	v_add_co_u32_e32 v16, vcc, s26, v8
	v_lshl_add_u64 v[12:13], s[4:5], 0, v[116:117]
	s_nop 0
	v_addc_co_u32_e32 v17, vcc, 0, v9, vcc
	v_add_co_u32_e32 v18, vcc, s24, v14
	global_load_dwordx4 v[0:3], v[54:55], off
	s_nop 0
	v_addc_co_u32_e32 v19, vcc, 0, v15, vcc
	v_add_co_u32_e32 v28, vcc, s25, v14
	s_add_i32 s14, s14, s16
	s_nop 0
	v_addc_co_u32_e32 v29, vcc, 0, v15, vcc
	v_add_co_u32_e32 v34, vcc, s21, v12
	v_lshl_add_u64 v[112:113], v[112:113], 0, s[8:9]
	s_nop 0
	v_addc_co_u32_e32 v35, vcc, 0, v13, vcc
	v_add_co_u32_e32 v22, vcc, s22, v12
	v_lshl_add_u64 v[114:115], v[114:115], 0, s[10:11]
	s_nop 0
	v_addc_co_u32_e32 v23, vcc, 0, v13, vcc
	v_add_co_u32_e32 v32, vcc, s27, v14
	v_lshl_add_u64 v[116:117], v[116:117], 0, s[18:19]
	s_nop 0
	v_addc_co_u32_e32 v33, vcc, 0, v15, vcc
	v_add_co_u32_e32 v120, vcc, s28, v14
	s_cmpk_gt_i32 s14, 0x3fff
	s_nop 0
	v_addc_co_u32_e32 v121, vcc, 0, v15, vcc
	v_add_co_u32_e32 v122, vcc, s23, v12
	s_nop 1
	v_addc_co_u32_e32 v123, vcc, 0, v13, vcc
	v_add_co_u32_e32 v124, vcc, s30, v8
	s_nop 1
	v_addc_co_u32_e32 v125, vcc, 0, v9, vcc
	v_add_co_u32_e32 v118, vcc, s31, v8
	s_nop 1
	v_addc_co_u32_e32 v119, vcc, 0, v9, vcc
	global_load_dwordx2 v[8:9], v[16:17], off offset:-4096 nt
	global_load_dwordx4 v[4:7], v[12:13], off nt
	s_waitcnt vmcnt(3)
	ds_bpermute_b32 v11, v129, v10
	s_waitcnt lgkmcnt(0)
	v_add_f32_e32 v10, v10, v11
	ds_bpermute_b32 v11, v138, v10
	s_waitcnt lgkmcnt(0)
	v_add_f32_e32 v10, v10, v11
	ds_bpermute_b32 v11, v139, v10
	s_waitcnt lgkmcnt(0)
	v_add_f32_e32 v10, v10, v11
	ds_bpermute_b32 v11, v140, v10
	s_waitcnt lgkmcnt(0)
	v_add_f32_e32 v10, v10, v11
	ds_bpermute_b32 v11, v141, v10
	s_waitcnt lgkmcnt(0)
	v_add_f32_e32 v10, v10, v11
	ds_bpermute_b32 v11, v142, v10
	s_waitcnt lgkmcnt(0)
	v_add_f32_e32 v10, v10, v11
	v_fmamk_f32 v10, v10, 0x39800000, v143
	v_mul_f32_e32 v11, 0x4f800000, v10
	v_cmp_gt_f32_e32 vcc, s15, v10
	s_waitcnt vmcnt(1)
	v_lshlrev_b32_e32 v14, 16, v8
	v_cndmask_b32_e32 v10, v10, v11, vcc
	v_sqrt_f32_e32 v11, v10
	v_and_b32_e32 v15, 0xffff0000, v8
	v_lshlrev_b32_e32 v8, 16, v9
	v_and_b32_e32 v9, 0xffff0000, v9
	v_add_u32_e32 v20, -1, v11
	v_add_u32_e32 v21, 1, v11
	v_fma_f32 v24, -v20, v11, v10
	v_fma_f32 v25, -v21, v11, v10
	v_cmp_ge_f32_e64 s[2:3], 0, v24
	s_nop 1
	v_cndmask_b32_e64 v11, v11, v20, s[2:3]
	v_cmp_lt_f32_e64 s[2:3], 0, v25
	s_nop 1
	v_cndmask_b32_e64 v11, v11, v21, s[2:3]
	v_mul_f32_e32 v20, 0x37800000, v11
	v_cndmask_b32_e32 v11, v11, v20, vcc
	v_cmp_class_f32_e32 vcc, v10, v144
	s_nop 1
	v_cndmask_b32_e32 v10, v11, v10, vcc
	v_div_scale_f32 v11, s[2:3], v10, v10, 1.0
	v_rcp_f32_e32 v21, v11
	v_div_scale_f32 v20, vcc, 1.0, v10, 1.0
	v_fma_f32 v24, -v11, v21, 1.0
	v_fmac_f32_e32 v21, v24, v21
	v_mul_f32_e32 v24, v20, v21
	v_fma_f32 v25, -v11, v24, v20
	v_fmac_f32_e32 v24, v25, v21
	v_fma_f32 v11, -v11, v24, v20
	v_div_fmas_f32 v11, v11, v21, v24
	v_div_fixup_f32 v128, v11, v10, 1.0
	v_pk_mul_f32 v[10:11], v[128:129], v[14:15] op_sel_hi:[0,1]
	v_pk_mul_f32 v[8:9], v[128:129], v[8:9] op_sel_hi:[0,1]
	s_waitcnt vmcnt(0)
	v_pk_fma_f32 v[0:1], v[0:1], v[10:11], v[4:5]
	v_pk_fma_f32 v[2:3], v[2:3], v[8:9], v[6:7]
	global_store_dwordx4 v[28:29], v[0:3], off offset:-4096 nt
	v_mov_b32_e32 v126, v0
	v_mov_b32_e32 v127, v2
	v_mov_b32_e32 v2, v1
	global_load_dwordx2 v[0:1], v[30:31], off offset:512 nt
	global_load_dwordx4 v[4:7], v[12:13], off offset:1024 nt
	global_load_dwordx4 v[8:11], v[56:57], off
	v_pk_mul_f32 v[14:15], v[2:3], v[2:3]
	s_nop 0
	v_pk_fma_f32 v[14:15], v[126:127], v[126:127], v[14:15]
	s_nop 0
	v_pk_add_f32 v[40:41], v[14:15], v[14:15] op_sel:[0,1] op_sel_hi:[1,0]
	s_waitcnt vmcnt(2)
	v_lshlrev_b32_e32 v14, 16, v0
	v_and_b32_e32 v15, 0xffff0000, v0
	v_lshlrev_b32_e32 v0, 16, v1
	v_and_b32_e32 v1, 0xffff0000, v1
	v_pk_mul_f32 v[14:15], v[128:129], v[14:15] op_sel_hi:[0,1]
	v_pk_mul_f32 v[0:1], v[128:129], v[0:1] op_sel_hi:[0,1]
	s_waitcnt vmcnt(0)
	v_pk_fma_f32 v[4:5], v[8:9], v[14:15], v[4:5]
	v_pk_fma_f32 v[6:7], v[10:11], v[0:1], v[6:7]
	global_store_dwordx4 v[18:19], v[4:7], off offset:1024 nt
	v_mov_b32_e32 v0, v4
	v_mov_b32_e32 v1, v6
	v_mov_b32_e32 v6, v5
	global_load_dwordx2 v[4:5], v[30:31], off offset:1024 nt
	global_load_dwordx4 v[8:11], v[12:13], off offset:2048 nt
	global_load_dwordx4 v[24:27], v[58:59], off
	v_pk_mul_f32 v[14:15], v[6:7], v[6:7]
	s_nop 0
	v_pk_fma_f32 v[14:15], v[0:1], v[0:1], v[14:15]
	s_nop 0
	v_pk_add_f32 v[42:43], v[14:15], v[14:15] op_sel:[0,1] op_sel_hi:[1,0]
	s_waitcnt vmcnt(2)
	v_lshlrev_b32_e32 v14, 16, v4
	v_and_b32_e32 v15, 0xffff0000, v4
	v_lshlrev_b32_e32 v4, 16, v5
	v_and_b32_e32 v5, 0xffff0000, v5
	v_pk_mul_f32 v[14:15], v[128:129], v[14:15] op_sel_hi:[0,1]
	v_pk_mul_f32 v[4:5], v[128:129], v[4:5] op_sel_hi:[0,1]
	s_waitcnt vmcnt(0)
	v_pk_fma_f32 v[8:9], v[24:25], v[14:15], v[8:9]
	v_pk_fma_f32 v[10:11], v[26:27], v[4:5], v[10:11]
	global_store_dwordx4 v[18:19], v[8:11], off offset:2048 nt
	global_load_dwordx2 v[44:45], v[30:31], off offset:1536 nt
	global_load_dwordx4 v[24:27], v[12:13], off offset:3072 nt
	global_load_dwordx4 v[36:39], v[60:61], off
	v_mul_f32_e32 v14, v9, v9
	v_mul_f32_e32 v20, v11, v11
	v_mov_b32_e32 v4, v8
	v_mov_b32_e32 v5, v10
	v_pk_fma_f32 v[46:47], v[8:9], v[8:9], v[14:15] op_sel_hi:[1,1,0]
	v_pk_fma_f32 v[48:49], v[10:11], v[10:11], v[20:21] op_sel_hi:[1,1,0]
	v_mov_b32_e32 v10, v9
	s_waitcnt vmcnt(2)
	v_lshlrev_b32_e32 v8, 16, v44
	v_and_b32_e32 v9, 0xffff0000, v44
	v_lshlrev_b32_e32 v12, 16, v45
	v_and_b32_e32 v13, 0xffff0000, v45
	v_pk_mul_f32 v[8:9], v[128:129], v[8:9] op_sel_hi:[0,1]
	v_pk_mul_f32 v[14:15], v[128:129], v[12:13] op_sel_hi:[0,1]
	s_waitcnt vmcnt(0)
	v_pk_fma_f32 v[12:13], v[36:37], v[8:9], v[24:25]
	v_pk_fma_f32 v[14:15], v[38:39], v[14:15], v[26:27]
	global_store_dwordx4 v[18:19], v[12:15], off offset:3072 nt
	v_pk_mul_f32 v[36:37], v[12:13], v[12:13]
	v_pk_mul_f32 v[38:39], v[14:15], v[14:15]
	v_mov_b32_e32 v8, v12
	v_mov_b32_e32 v9, v14
	v_mov_b32_e32 v14, v13
	global_load_dwordx2 v[12:13], v[30:31], off offset:2048 nt
	global_load_dwordx4 v[18:21], v[22:23], off offset:-4096 nt
	global_load_dwordx4 v[24:27], v[62:63], off
	v_mov_b32_e32 v41, v36
	v_mov_b32_e32 v43, v37
	v_mov_b32_e32 v47, v38
	v_mov_b32_e32 v49, v39
	v_pk_add_f32 v[36:37], v[40:41], v[42:43]
	v_pk_add_f32 v[38:39], v[46:47], v[48:49]
	s_nop 0
	v_pk_add_f32 v[36:37], v[36:37], v[38:39]
	s_nop 0
	v_pk_add_f32 v[46:47], v[36:37], v[36:37] op_sel:[0,1] op_sel_hi:[1,0]
	s_waitcnt vmcnt(2)
	v_lshlrev_b32_e32 v36, 16, v12
	v_and_b32_e32 v37, 0xffff0000, v12
	v_lshlrev_b32_e32 v12, 16, v13
	v_and_b32_e32 v13, 0xffff0000, v13
	v_pk_mul_f32 v[36:37], v[128:129], v[36:37] op_sel_hi:[0,1]
	v_pk_mul_f32 v[12:13], v[128:129], v[12:13] op_sel_hi:[0,1]
	s_waitcnt vmcnt(0)
	v_pk_fma_f32 v[18:19], v[24:25], v[36:37], v[18:19]
	v_pk_fma_f32 v[20:21], v[26:27], v[12:13], v[20:21]
	global_store_dwordx4 v[28:29], v[18:21], off nt
	v_mov_b32_e32 v12, v18
	v_mov_b32_e32 v13, v20
	v_mov_b32_e32 v20, v19
	global_load_dwordx2 v[18:19], v[30:31], off offset:2560 nt
	global_load_dwordx4 v[24:27], v[34:35], off offset:1024 nt
	global_load_dwordx4 v[36:39], v[64:65], off
	v_pk_mul_f32 v[40:41], v[20:21], v[20:21]
	s_nop 0
	v_pk_fma_f32 v[40:41], v[12:13], v[12:13], v[40:41]
	s_nop 0
	v_pk_add_f32 v[48:49], v[40:41], v[40:41] op_sel:[0,1] op_sel_hi:[1,0]
	s_waitcnt vmcnt(2)
	v_lshlrev_b32_e32 v40, 16, v18
	v_and_b32_e32 v41, 0xffff0000, v18
	v_lshlrev_b32_e32 v18, 16, v19
	v_and_b32_e32 v19, 0xffff0000, v19
	v_pk_mul_f32 v[40:41], v[128:129], v[40:41] op_sel_hi:[0,1]
	v_pk_mul_f32 v[18:19], v[128:129], v[18:19] op_sel_hi:[0,1]
	s_waitcnt vmcnt(0)
	v_pk_fma_f32 v[24:25], v[36:37], v[40:41], v[24:25]
	v_pk_fma_f32 v[26:27], v[38:39], v[18:19], v[26:27]
	global_store_dwordx4 v[28:29], v[24:27], off offset:1024 nt
	global_load_dwordx2 v[50:51], v[30:31], off offset:3072 nt
	global_load_dwordx4 v[36:39], v[34:35], off offset:2048 nt
	global_load_dwordx4 v[42:45], v[66:67], off
	v_mul_f32_e32 v18, v25, v25
	v_mul_f32_e32 v40, v27, v27
	v_mov_b32_e32 v130, v24
	v_mov_b32_e32 v131, v26
	v_pk_fma_f32 v[18:19], v[24:25], v[24:25], v[18:19] op_sel_hi:[1,1,0]
	v_pk_fma_f32 v[52:53], v[26:27], v[26:27], v[40:41] op_sel_hi:[1,1,0]
	v_mov_b32_e32 v26, v25
	s_waitcnt vmcnt(2)
	v_lshlrev_b32_e32 v24, 16, v50
	v_and_b32_e32 v25, 0xffff0000, v50
	v_lshlrev_b32_e32 v40, 16, v51
	v_and_b32_e32 v41, 0xffff0000, v51
	v_pk_mul_f32 v[24:25], v[128:129], v[24:25] op_sel_hi:[0,1]
	v_pk_mul_f32 v[40:41], v[128:129], v[40:41] op_sel_hi:[0,1]
	s_waitcnt vmcnt(0)
	v_pk_fma_f32 v[42:43], v[42:43], v[24:25], v[36:37]
	v_pk_fma_f32 v[44:45], v[44:45], v[40:41], v[38:39]
	global_store_dwordx4 v[28:29], v[42:45], off offset:2048 nt
	global_load_dwordx2 v[30:31], v[30:31], off offset:3584 nt
	s_nop 0
	global_load_dwordx4 v[34:37], v[34:35], off offset:3072 nt
	s_nop 0
	global_load_dwordx4 v[38:41], v[68:69], off
	v_pk_mul_f32 v[24:25], v[42:43], v[42:43]
	v_pk_mul_f32 v[50:51], v[44:45], v[44:45]
	v_mov_b32_e32 v47, v24
	v_mov_b32_e32 v49, v25
	v_mov_b32_e32 v19, v50
	v_mov_b32_e32 v53, v51
	v_pk_add_f32 v[24:25], v[46:47], v[48:49]
	v_pk_add_f32 v[18:19], v[18:19], v[52:53]
	v_mov_b32_e32 v134, v42
	v_pk_add_f32 v[18:19], v[24:25], v[18:19]
	v_mov_b32_e32 v135, v44
	v_mov_b32_e32 v44, v43
	v_pk_add_f32 v[18:19], v[18:19], v[18:19] op_sel:[0,1] op_sel_hi:[1,0]
	s_waitcnt vmcnt(2)
	v_lshlrev_b32_e32 v24, 16, v30
	v_and_b32_e32 v25, 0xffff0000, v30
	v_lshlrev_b32_e32 v30, 16, v31
	v_and_b32_e32 v31, 0xffff0000, v31
	v_pk_mul_f32 v[24:25], v[128:129], v[24:25] op_sel_hi:[0,1]
	v_pk_mul_f32 v[30:31], v[128:129], v[30:31] op_sel_hi:[0,1]
	s_waitcnt vmcnt(0)
	v_pk_fma_f32 v[46:47], v[38:39], v[24:25], v[34:35]
	v_pk_fma_f32 v[48:49], v[40:41], v[30:31], v[36:37]
	global_store_dwordx4 v[28:29], v[46:49], off offset:3072 nt
	global_load_dwordx2 v[24:25], v[16:17], off nt
	s_nop 0
	global_load_dwordx4 v[28:31], v[22:23], off nt
	global_load_dwordx4 v[34:37], v[70:71], off
	v_mov_b32_e32 v136, v46
	v_mov_b32_e32 v137, v48
	v_mov_b32_e32 v48, v47
	v_pk_mul_f32 v[38:39], v[48:49], v[48:49]
	s_waitcnt vmcnt(2)
	v_lshlrev_b32_e32 v40, 16, v24
	v_and_b32_e32 v41, 0xffff0000, v24
	v_lshlrev_b32_e32 v24, 16, v25
	v_and_b32_e32 v25, 0xffff0000, v25
	v_pk_mul_f32 v[40:41], v[128:129], v[40:41] op_sel_hi:[0,1]
	v_pk_mul_f32 v[24:25], v[128:129], v[24:25] op_sel_hi:[0,1]
	s_waitcnt vmcnt(0)
	v_pk_fma_f32 v[50:51], v[34:35], v[40:41], v[28:29]
	v_pk_fma_f32 v[52:53], v[36:37], v[24:25], v[30:31]
	global_store_dwordx4 v[120:121], v[50:53], off offset:-4096 nt
	global_load_dwordx2 v[42:43], v[16:17], off offset:512 nt
	global_load_dwordx4 v[28:31], v[22:23], off offset:1024 nt
	global_load_dwordx4 v[34:37], v[72:73], off
	v_mul_f32_e32 v40, v53, v53
	v_pk_fma_f32 v[46:47], v[52:53], v[52:53], v[40:41] op_sel_hi:[1,1,0]
	v_mul_f32_e32 v24, v51, v51
	v_mov_b32_e32 v150, v50
	v_mov_b32_e32 v151, v52
	v_pk_fma_f32 v[24:25], v[50:51], v[50:51], v[24:25] op_sel_hi:[1,1,0]
	v_mov_b32_e32 v52, v51
	v_pk_fma_f32 v[38:39], v[136:137], v[136:137], v[38:39]
	s_waitcnt vmcnt(2)
	v_lshlrev_b32_e32 v40, 16, v42
	v_and_b32_e32 v41, 0xffff0000, v42
	v_lshlrev_b32_e32 v42, 16, v43
	v_and_b32_e32 v43, 0xffff0000, v43
	v_pk_mul_f32 v[40:41], v[128:129], v[40:41] op_sel_hi:[0,1]
	v_pk_mul_f32 v[42:43], v[128:129], v[42:43] op_sel_hi:[0,1]
	s_waitcnt vmcnt(0)
	v_pk_fma_f32 v[34:35], v[34:35], v[40:41], v[28:29]
	v_pk_fma_f32 v[36:37], v[36:37], v[42:43], v[30:31]
	global_store_dwordx4 v[32:33], v[34:37], off offset:1024 nt
	v_pk_mul_f32 v[132:133], v[34:35], v[34:35]
	v_pk_mul_f32 v[146:147], v[36:37], v[36:37]
	v_mov_b32_e32 v50, v34
	v_mov_b32_e32 v51, v36
	v_mov_b32_e32 v36, v35
	global_load_dwordx2 v[34:35], v[16:17], off offset:1024 nt
	global_load_dwordx4 v[28:31], v[22:23], off offset:2048 nt
	global_load_dwordx4 v[40:43], v[74:75], off
	v_pk_add_f32 v[38:39], v[38:39], v[38:39] op_sel:[0,1] op_sel_hi:[1,0]
	v_mov_b32_e32 v19, v132
	v_mov_b32_e32 v39, v133
	v_mov_b32_e32 v25, v146
	v_mov_b32_e32 v47, v147
	v_pk_add_f32 v[18:19], v[18:19], v[38:39]
	v_pk_add_f32 v[24:25], v[24:25], v[46:47]
	s_nop 0
	v_pk_add_f32 v[18:19], v[18:19], v[24:25]
	s_waitcnt vmcnt(2)
	v_lshlrev_b32_e32 v24, 16, v34
	v_and_b32_e32 v25, 0xffff0000, v34
	v_lshlrev_b32_e32 v34, 16, v35
	v_and_b32_e32 v35, 0xffff0000, v35
	v_pk_mul_f32 v[24:25], v[128:129], v[24:25] op_sel_hi:[0,1]
	v_pk_mul_f32 v[34:35], v[128:129], v[34:35] op_sel_hi:[0,1]
	s_waitcnt vmcnt(0)
	v_pk_fma_f32 v[40:41], v[40:41], v[24:25], v[28:29]
	v_pk_fma_f32 v[42:43], v[42:43], v[34:35], v[30:31]
	global_store_dwordx4 v[32:33], v[40:43], off offset:2048 nt
	global_load_dwordx2 v[34:35], v[16:17], off offset:1536 nt
	s_nop 0
	global_load_dwordx4 v[22:25], v[22:23], off offset:3072 nt
	s_nop 0
	global_load_dwordx4 v[28:31], v[76:77], off
	v_mov_b32_e32 v133, v42
	v_mov_b32_e32 v42, v41
	v_mov_b32_e32 v132, v40
	v_pk_mul_f32 v[38:39], v[42:43], v[42:43]
	v_pk_add_f32 v[18:19], v[18:19], v[18:19] op_sel:[0,1] op_sel_hi:[1,0]
	v_pk_fma_f32 v[38:39], v[132:133], v[132:133], v[38:39]
	s_nop 0
	v_pk_add_f32 v[46:47], v[38:39], v[38:39] op_sel:[0,1] op_sel_hi:[1,0]
	s_waitcnt vmcnt(2)
	v_lshlrev_b32_e32 v38, 16, v34
	v_and_b32_e32 v39, 0xffff0000, v34
	v_lshlrev_b32_e32 v34, 16, v35
	v_and_b32_e32 v35, 0xffff0000, v35
	v_pk_mul_f32 v[38:39], v[128:129], v[38:39] op_sel_hi:[0,1]
	v_pk_mul_f32 v[34:35], v[128:129], v[34:35] op_sel_hi:[0,1]
	s_waitcnt vmcnt(0)
	v_pk_fma_f32 v[38:39], v[28:29], v[38:39], v[22:23]
	v_pk_fma_f32 v[40:41], v[30:31], v[34:35], v[24:25]
	global_store_dwordx4 v[32:33], v[38:41], off offset:3072 nt
	global_load_dwordx2 v[146:147], v[16:17], off offset:2048 nt
	global_load_dwordx4 v[22:25], v[122:123], off nt
	global_load_dwordx4 v[28:31], v[78:79], off
	v_mul_f32_e32 v32, v39, v39
	v_mul_f32_e32 v34, v41, v41
	v_pk_fma_f32 v[148:149], v[38:39], v[38:39], v[32:33] op_sel_hi:[1,1,0]
	v_pk_fma_f32 v[152:153], v[40:41], v[40:41], v[34:35] op_sel_hi:[1,1,0]
	s_waitcnt vmcnt(2)
	v_lshlrev_b32_e32 v32, 16, v146
	v_and_b32_e32 v33, 0xffff0000, v146
	v_lshlrev_b32_e32 v34, 16, v147
	v_and_b32_e32 v35, 0xffff0000, v147
	v_pk_mul_f32 v[32:33], v[128:129], v[32:33] op_sel_hi:[0,1]
	v_pk_mul_f32 v[34:35], v[128:129], v[34:35] op_sel_hi:[0,1]
	s_waitcnt vmcnt(0)
	v_pk_fma_f32 v[32:33], v[28:29], v[32:33], v[22:23]
	v_pk_fma_f32 v[34:35], v[30:31], v[34:35], v[24:25]
	global_store_dwordx4 v[120:121], v[32:35], off nt
	global_load_dwordx2 v[156:157], v[16:17], off offset:2560 nt
	global_load_dwordx4 v[22:25], v[122:123], off offset:1024 nt
	global_load_dwordx4 v[28:31], v[80:81], off
	v_pk_mul_f32 v[146:147], v[32:33], v[32:33]
	v_pk_mul_f32 v[154:155], v[34:35], v[34:35]
	v_mov_b32_e32 v19, v146
	v_mov_b32_e32 v47, v147
	v_mov_b32_e32 v149, v154
	v_mov_b32_e32 v153, v155
	v_pk_add_f32 v[18:19], v[18:19], v[46:47]
	v_pk_add_f32 v[46:47], v[148:149], v[152:153]
	s_nop 0
	v_pk_add_f32 v[18:19], v[18:19], v[46:47]
	s_waitcnt vmcnt(2)
	v_lshlrev_b32_e32 v46, 16, v157
	v_pk_add_f32 v[152:153], v[18:19], v[18:19] op_sel:[0,1] op_sel_hi:[1,0]
	v_lshlrev_b32_e32 v18, 16, v156
	v_and_b32_e32 v19, 0xffff0000, v156
	v_and_b32_e32 v47, 0xffff0000, v157
	v_pk_mul_f32 v[18:19], v[128:129], v[18:19] op_sel_hi:[0,1]
	v_pk_mul_f32 v[46:47], v[128:129], v[46:47] op_sel_hi:[0,1]
	s_waitcnt vmcnt(0)
	v_pk_fma_f32 v[28:29], v[28:29], v[18:19], v[22:23]
	v_pk_fma_f32 v[30:31], v[30:31], v[46:47], v[24:25]
	global_store_dwordx4 v[120:121], v[28:31], off offset:1024 nt
	global_load_dwordx2 v[18:19], v[16:17], off offset:3072 nt
	global_load_dwordx4 v[22:25], v[122:123], off offset:2048 nt
	global_load_dwordx4 v[146:149], v[82:83], off
	v_mov_b32_e32 v47, v30
	v_mov_b32_e32 v30, v29
	v_mov_b32_e32 v46, v28
	v_pk_mul_f32 v[28:29], v[30:31], v[30:31]
	s_waitcnt vmcnt(2)
	v_lshlrev_b32_e32 v154, 16, v18
	v_and_b32_e32 v155, 0xffff0000, v18
	v_lshlrev_b32_e32 v18, 16, v19
	v_and_b32_e32 v19, 0xffff0000, v19
	v_pk_mul_f32 v[154:155], v[128:129], v[154:155] op_sel_hi:[0,1]
	v_pk_mul_f32 v[18:19], v[128:129], v[18:19] op_sel_hi:[0,1]
	s_waitcnt vmcnt(0)
	v_pk_fma_f32 v[22:23], v[146:147], v[154:155], v[22:23]
	v_pk_fma_f32 v[24:25], v[148:149], v[18:19], v[24:25]
	global_store_dwordx4 v[120:121], v[22:25], off offset:2048 nt
	global_load_dwordx2 v[158:159], v[16:17], off offset:3584 nt
	s_nop 0
	global_load_dwordx4 v[16:19], v[122:123], off offset:3072 nt
	global_load_dwordx4 v[146:149], v[84:85], off
	v_pk_fma_f32 v[28:29], v[46:47], v[46:47], v[28:29]
	v_mul_f32_e32 v154, v23, v23
	v_mul_f32_e32 v156, v25, v25
	v_pk_add_f32 v[28:29], v[28:29], v[28:29] op_sel:[0,1] op_sel_hi:[1,0]
	v_pk_fma_f32 v[154:155], v[22:23], v[22:23], v[154:155] op_sel_hi:[1,1,0]
	v_pk_fma_f32 v[156:157], v[24:25], v[24:25], v[156:157] op_sel_hi:[1,1,0]
	s_waitcnt vmcnt(2)
	v_lshlrev_b32_e32 v122, 16, v158
	v_and_b32_e32 v123, 0xffff0000, v158
	v_lshlrev_b32_e32 v158, 16, v159
	v_and_b32_e32 v159, 0xffff0000, v159
	v_pk_mul_f32 v[122:123], v[128:129], v[122:123] op_sel_hi:[0,1]
	v_pk_mul_f32 v[158:159], v[128:129], v[158:159] op_sel_hi:[0,1]
	s_waitcnt vmcnt(0)
	v_pk_fma_f32 v[16:17], v[146:147], v[122:123], v[16:17]
	v_pk_fma_f32 v[18:19], v[148:149], v[158:159], v[18:19]
	global_store_dwordx4 v[120:121], v[16:19], off offset:3072 nt
	v_pk_mul_f32 v[120:121], v[16:17], v[16:17]
	v_pk_mul_f32 v[122:123], v[18:19], v[18:19]
	v_mov_b32_e32 v153, v120
	v_mov_b32_e32 v29, v121
	v_mov_b32_e32 v155, v122
	v_mov_b32_e32 v157, v123
	global_load_dwordx4 v[120:123], v[86:87], off
	v_pk_add_f32 v[28:29], v[152:153], v[28:29]
	v_pk_add_f32 v[146:147], v[154:155], v[156:157]
	s_nop 0
	v_pk_add_f32 v[28:29], v[28:29], v[146:147]
	s_nop 0
	v_add_f32_e32 v28, v28, v29
	ds_bpermute_b32 v29, v129, v28
	s_waitcnt lgkmcnt(0)
	v_add_f32_e32 v28, v28, v29
	ds_bpermute_b32 v29, v138, v28
	s_waitcnt lgkmcnt(0)
	v_add_f32_e32 v28, v28, v29
	ds_bpermute_b32 v29, v139, v28
	s_waitcnt lgkmcnt(0)
	v_add_f32_e32 v28, v28, v29
	ds_bpermute_b32 v29, v140, v28
	s_waitcnt lgkmcnt(0)
	v_add_f32_e32 v28, v28, v29
	ds_bpermute_b32 v29, v141, v28
	s_waitcnt lgkmcnt(0)
	v_add_f32_e32 v28, v28, v29
	ds_bpermute_b32 v29, v142, v28
	s_waitcnt lgkmcnt(0)
	v_add_f32_e32 v28, v28, v29
	v_fmamk_f32 v28, v28, 0x39800000, v143
	v_mul_f32_e32 v29, 0x4f800000, v28
	v_cmp_gt_f32_e32 vcc, s15, v28
	s_nop 1
	v_cndmask_b32_e32 v28, v28, v29, vcc
	v_sqrt_f32_e32 v29, v28
	s_nop 0
	v_add_u32_e32 v128, -1, v29
	v_add_u32_e32 v146, 1, v29
	v_fma_f32 v147, -v128, v29, v28
	v_fma_f32 v148, -v146, v29, v28
	v_cmp_ge_f32_e64 s[2:3], 0, v147
	s_nop 1
	v_cndmask_b32_e64 v29, v29, v128, s[2:3]
	v_cmp_lt_f32_e64 s[2:3], 0, v148
	s_nop 1
	v_cndmask_b32_e64 v29, v29, v146, s[2:3]
	v_mul_f32_e32 v128, 0x37800000, v29
	v_cndmask_b32_e32 v29, v29, v128, vcc
	v_cmp_class_f32_e32 vcc, v28, v144
	s_nop 1
	v_cndmask_b32_e32 v28, v29, v28, vcc
	v_div_scale_f32 v29, s[2:3], v28, v28, 1.0
	v_rcp_f32_e32 v146, v29
	v_div_scale_f32 v128, vcc, 1.0, v28, 1.0
	v_fma_f32 v147, -v29, v146, 1.0
	v_fmac_f32_e32 v146, v147, v146
	v_mul_f32_e32 v147, v128, v146
	v_fma_f32 v148, -v29, v147, v128
	v_fmac_f32_e32 v147, v148, v146
	v_fma_f32 v29, -v29, v147, v128
	v_div_fmas_f32 v29, v29, v146, v147
	v_div_fixup_f32 v28, v29, v28, 1.0
	v_pk_mul_f32 v[2:3], v[2:3], v[28:29] op_sel_hi:[1,0]
	v_pk_mul_f32 v[146:147], v[0:1], v[28:29] op_sel_hi:[1,0]
	s_waitcnt vmcnt(0)
	v_mov_b32_e32 v1, v122
	v_mov_b32_e32 v122, v121
	v_pk_mul_f32 v[126:127], v[126:127], v[28:29] op_sel_hi:[1,0]
	v_mov_b32_e32 v0, v120
	v_pk_mul_f32 v[2:3], v[122:123], v[2:3]
	v_pk_mul_f32 v[0:1], v[0:1], v[126:127]
	v_and_b32_sdwa v121, v3, v145 dst_sel:DWORD dst_unused:UNUSED_PAD src0_sel:WORD_1 src1_sel:DWORD
	v_and_b32_sdwa v122, v2, v145 dst_sel:DWORD dst_unused:UNUSED_PAD src0_sel:WORD_1 src1_sel:DWORD
	v_pk_mul_f32 v[6:7], v[6:7], v[28:29] op_sel_hi:[1,0]
	v_pk_mul_f32 v[4:5], v[4:5], v[28:29] op_sel_hi:[1,0]
	v_pk_mul_f32 v[10:11], v[10:11], v[28:29] op_sel_hi:[1,0]
	v_pk_mul_f32 v[8:9], v[8:9], v[28:29] op_sel_hi:[1,0]
	v_pk_mul_f32 v[14:15], v[14:15], v[28:29] op_sel_hi:[1,0]
	v_pk_mul_f32 v[12:13], v[12:13], v[28:29] op_sel_hi:[1,0]
	v_pk_mul_f32 v[20:21], v[20:21], v[28:29] op_sel_hi:[1,0]
	v_pk_mul_f32 v[130:131], v[130:131], v[28:29] op_sel_hi:[1,0]
	v_pk_mul_f32 v[26:27], v[26:27], v[28:29] op_sel_hi:[1,0]
	v_pk_mul_f32 v[134:135], v[134:135], v[28:29] op_sel_hi:[1,0]
	v_pk_mul_f32 v[44:45], v[44:45], v[28:29] op_sel_hi:[1,0]
	v_pk_mul_f32 v[136:137], v[136:137], v[28:29] op_sel_hi:[1,0]
	v_pk_mul_f32 v[48:49], v[48:49], v[28:29] op_sel_hi:[1,0]
	v_pk_mul_f32 v[148:149], v[150:151], v[28:29] op_sel_hi:[1,0]
	v_pk_mul_f32 v[52:53], v[52:53], v[28:29] op_sel_hi:[1,0]
	v_and_b32_sdwa v29, v1, v145 dst_sel:DWORD dst_unused:UNUSED_PAD src0_sel:WORD_1 src1_sel:DWORD
	v_and_b32_sdwa v120, v0, v145 dst_sel:DWORD dst_unused:UNUSED_PAD src0_sel:WORD_1 src1_sel:DWORD
	v_add3_u32 v3, v3, v121, s29
	v_add3_u32 v2, v2, v122, s29
	v_add3_u32 v0, v0, v120, s29
	v_add3_u32 v1, v1, v29, s29
	v_and_b32_e32 v3, 0xffff0000, v3
	v_and_b32_e32 v2, 0xffff0000, v2
	v_or_b32_sdwa v1, v3, v1 dst_sel:DWORD dst_unused:UNUSED_PAD src0_sel:DWORD src1_sel:WORD_1
	v_or_b32_sdwa v0, v2, v0 dst_sel:DWORD dst_unused:UNUSED_PAD src0_sel:DWORD src1_sel:WORD_1
	global_store_dwordx2 v[118:119], v[0:1], off offset:-4096 nt
	global_load_dwordx4 v[0:3], v[86:87], off offset:1024
	s_waitcnt vmcnt(0)
	v_mov_b32_e32 v121, v2
	v_mov_b32_e32 v2, v1
	v_mov_b32_e32 v120, v0
	v_pk_mul_f32 v[2:3], v[2:3], v[6:7]
	v_pk_mul_f32 v[0:1], v[120:121], v[146:147]
	v_and_b32_sdwa v29, v3, v145 dst_sel:DWORD dst_unused:UNUSED_PAD src0_sel:WORD_1 src1_sel:DWORD
	v_and_b32_sdwa v120, v2, v145 dst_sel:DWORD dst_unused:UNUSED_PAD src0_sel:WORD_1 src1_sel:DWORD
	v_and_b32_sdwa v6, v1, v145 dst_sel:DWORD dst_unused:UNUSED_PAD src0_sel:WORD_1 src1_sel:DWORD
	v_and_b32_sdwa v7, v0, v145 dst_sel:DWORD dst_unused:UNUSED_PAD src0_sel:WORD_1 src1_sel:DWORD
	v_add3_u32 v3, v3, v29, s29
	v_add3_u32 v2, v2, v120, s29
	v_add3_u32 v0, v0, v7, s29
	v_add3_u32 v1, v1, v6, s29
	v_and_b32_e32 v3, 0xffff0000, v3
	v_and_b32_e32 v2, 0xffff0000, v2
	v_or_b32_sdwa v1, v3, v1 dst_sel:DWORD dst_unused:UNUSED_PAD src0_sel:DWORD src1_sel:WORD_1
	v_or_b32_sdwa v0, v2, v0 dst_sel:DWORD dst_unused:UNUSED_PAD src0_sel:DWORD src1_sel:WORD_1
	global_store_dwordx2 v[124:125], v[0:1], off offset:512 nt
	global_load_dwordx4 v[0:3], v[86:87], off offset:2048
	s_waitcnt vmcnt(0)
	v_mov_b32_e32 v7, v2
	v_mov_b32_e32 v2, v1
	v_mov_b32_e32 v6, v0
	v_pk_mul_f32 v[2:3], v[2:3], v[10:11]
	v_pk_mul_f32 v[0:1], v[6:7], v[4:5]
	v_and_b32_sdwa v6, v3, v145 dst_sel:DWORD dst_unused:UNUSED_PAD src0_sel:WORD_1 src1_sel:DWORD
	v_and_b32_sdwa v7, v2, v145 dst_sel:DWORD dst_unused:UNUSED_PAD src0_sel:WORD_1 src1_sel:DWORD
	v_and_b32_sdwa v4, v1, v145 dst_sel:DWORD dst_unused:UNUSED_PAD src0_sel:WORD_1 src1_sel:DWORD
	v_and_b32_sdwa v5, v0, v145 dst_sel:DWORD dst_unused:UNUSED_PAD src0_sel:WORD_1 src1_sel:DWORD
	v_add3_u32 v3, v3, v6, s29
	v_add3_u32 v2, v2, v7, s29
	v_add3_u32 v0, v0, v5, s29
	v_add3_u32 v1, v1, v4, s29
	v_and_b32_e32 v3, 0xffff0000, v3
	v_and_b32_e32 v2, 0xffff0000, v2
	v_or_b32_sdwa v1, v3, v1 dst_sel:DWORD dst_unused:UNUSED_PAD src0_sel:DWORD src1_sel:WORD_1
	v_or_b32_sdwa v0, v2, v0 dst_sel:DWORD dst_unused:UNUSED_PAD src0_sel:DWORD src1_sel:WORD_1
	global_store_dwordx2 v[124:125], v[0:1], off offset:1024 nt
	global_load_dwordx4 v[0:3], v[86:87], off offset:3072
	s_waitcnt vmcnt(0)
	v_mov_b32_e32 v5, v2
	v_mov_b32_e32 v2, v1
	v_mov_b32_e32 v4, v0
	v_pk_mul_f32 v[2:3], v[2:3], v[14:15]
	v_pk_mul_f32 v[0:1], v[4:5], v[8:9]
	v_and_b32_sdwa v6, v3, v145 dst_sel:DWORD dst_unused:UNUSED_PAD src0_sel:WORD_1 src1_sel:DWORD
	v_and_b32_sdwa v7, v2, v145 dst_sel:DWORD dst_unused:UNUSED_PAD src0_sel:WORD_1 src1_sel:DWORD
	v_and_b32_sdwa v4, v1, v145 dst_sel:DWORD dst_unused:UNUSED_PAD src0_sel:WORD_1 src1_sel:DWORD
	v_and_b32_sdwa v5, v0, v145 dst_sel:DWORD dst_unused:UNUSED_PAD src0_sel:WORD_1 src1_sel:DWORD
	v_add3_u32 v3, v3, v6, s29
	v_add3_u32 v2, v2, v7, s29
	v_add3_u32 v0, v0, v5, s29
	v_add3_u32 v1, v1, v4, s29
	v_and_b32_e32 v3, 0xffff0000, v3
	v_and_b32_e32 v2, 0xffff0000, v2
	v_or_b32_sdwa v1, v3, v1 dst_sel:DWORD dst_unused:UNUSED_PAD src0_sel:DWORD src1_sel:WORD_1
	v_or_b32_sdwa v0, v2, v0 dst_sel:DWORD dst_unused:UNUSED_PAD src0_sel:DWORD src1_sel:WORD_1
	global_store_dwordx2 v[124:125], v[0:1], off offset:1536 nt
	global_load_dwordx4 v[0:3], v[88:89], off
	s_waitcnt vmcnt(0)
	v_mov_b32_e32 v5, v2
	v_mov_b32_e32 v2, v1
	v_mov_b32_e32 v4, v0
	v_pk_mul_f32 v[2:3], v[2:3], v[20:21]
	v_pk_mul_f32 v[0:1], v[4:5], v[12:13]
	v_and_b32_sdwa v6, v3, v145 dst_sel:DWORD dst_unused:UNUSED_PAD src0_sel:WORD_1 src1_sel:DWORD
	v_and_b32_sdwa v7, v2, v145 dst_sel:DWORD dst_unused:UNUSED_PAD src0_sel:WORD_1 src1_sel:DWORD
	v_and_b32_sdwa v4, v1, v145 dst_sel:DWORD dst_unused:UNUSED_PAD src0_sel:WORD_1 src1_sel:DWORD
	v_and_b32_sdwa v5, v0, v145 dst_sel:DWORD dst_unused:UNUSED_PAD src0_sel:WORD_1 src1_sel:DWORD
	v_add3_u32 v3, v3, v6, s29
	v_add3_u32 v2, v2, v7, s29
	v_add3_u32 v0, v0, v5, s29
	v_add3_u32 v1, v1, v4, s29
	v_and_b32_e32 v3, 0xffff0000, v3
	v_and_b32_e32 v2, 0xffff0000, v2
	v_or_b32_sdwa v1, v3, v1 dst_sel:DWORD dst_unused:UNUSED_PAD src0_sel:DWORD src1_sel:WORD_1
	v_or_b32_sdwa v0, v2, v0 dst_sel:DWORD dst_unused:UNUSED_PAD src0_sel:DWORD src1_sel:WORD_1
	global_store_dwordx2 v[124:125], v[0:1], off offset:2048 nt
	global_load_dwordx4 v[0:3], v[90:91], off
	s_waitcnt vmcnt(0)
	v_mov_b32_e32 v5, v2
	v_mov_b32_e32 v2, v1
	v_mov_b32_e32 v4, v0
	v_pk_mul_f32 v[2:3], v[2:3], v[26:27]
	v_pk_mul_f32 v[0:1], v[4:5], v[130:131]
	v_and_b32_sdwa v6, v3, v145 dst_sel:DWORD dst_unused:UNUSED_PAD src0_sel:WORD_1 src1_sel:DWORD
	v_and_b32_sdwa v7, v2, v145 dst_sel:DWORD dst_unused:UNUSED_PAD src0_sel:WORD_1 src1_sel:DWORD
	v_and_b32_sdwa v4, v1, v145 dst_sel:DWORD dst_unused:UNUSED_PAD src0_sel:WORD_1 src1_sel:DWORD
	v_and_b32_sdwa v5, v0, v145 dst_sel:DWORD dst_unused:UNUSED_PAD src0_sel:WORD_1 src1_sel:DWORD
	v_add3_u32 v3, v3, v6, s29
	v_add3_u32 v2, v2, v7, s29
	v_add3_u32 v0, v0, v5, s29
	v_add3_u32 v1, v1, v4, s29
	v_and_b32_e32 v3, 0xffff0000, v3
	v_and_b32_e32 v2, 0xffff0000, v2
	v_or_b32_sdwa v1, v3, v1 dst_sel:DWORD dst_unused:UNUSED_PAD src0_sel:DWORD src1_sel:WORD_1
	v_or_b32_sdwa v0, v2, v0 dst_sel:DWORD dst_unused:UNUSED_PAD src0_sel:DWORD src1_sel:WORD_1
	global_store_dwordx2 v[124:125], v[0:1], off offset:2560 nt
	global_load_dwordx4 v[0:3], v[92:93], off
	s_waitcnt vmcnt(0)
	v_mov_b32_e32 v5, v2
	v_mov_b32_e32 v2, v1
	v_mov_b32_e32 v4, v0
	v_pk_mul_f32 v[2:3], v[44:45], v[2:3]
	v_pk_mul_f32 v[0:1], v[134:135], v[4:5]
	v_and_b32_sdwa v6, v3, v145 dst_sel:DWORD dst_unused:UNUSED_PAD src0_sel:WORD_1 src1_sel:DWORD
	v_and_b32_sdwa v7, v2, v145 dst_sel:DWORD dst_unused:UNUSED_PAD src0_sel:WORD_1 src1_sel:DWORD
	v_and_b32_sdwa v4, v1, v145 dst_sel:DWORD dst_unused:UNUSED_PAD src0_sel:WORD_1 src1_sel:DWORD
	v_and_b32_sdwa v5, v0, v145 dst_sel:DWORD dst_unused:UNUSED_PAD src0_sel:WORD_1 src1_sel:DWORD
	v_add3_u32 v3, v3, v6, s29
	v_add3_u32 v2, v2, v7, s29
	v_add3_u32 v0, v0, v5, s29
	v_add3_u32 v1, v1, v4, s29
	v_and_b32_e32 v3, 0xffff0000, v3
	v_and_b32_e32 v2, 0xffff0000, v2
	v_or_b32_sdwa v1, v3, v1 dst_sel:DWORD dst_unused:UNUSED_PAD src0_sel:DWORD src1_sel:WORD_1
	v_or_b32_sdwa v0, v2, v0 dst_sel:DWORD dst_unused:UNUSED_PAD src0_sel:DWORD src1_sel:WORD_1
	global_store_dwordx2 v[124:125], v[0:1], off offset:3072 nt
	global_load_dwordx4 v[0:3], v[94:95], off
	s_waitcnt vmcnt(0)
	v_mov_b32_e32 v5, v2
	v_mov_b32_e32 v2, v1
	v_mov_b32_e32 v4, v0
	v_pk_mul_f32 v[2:3], v[48:49], v[2:3]
	v_pk_mul_f32 v[0:1], v[136:137], v[4:5]
	v_and_b32_sdwa v6, v3, v145 dst_sel:DWORD dst_unused:UNUSED_PAD src0_sel:WORD_1 src1_sel:DWORD
	v_and_b32_sdwa v7, v2, v145 dst_sel:DWORD dst_unused:UNUSED_PAD src0_sel:WORD_1 src1_sel:DWORD
	v_and_b32_sdwa v4, v1, v145 dst_sel:DWORD dst_unused:UNUSED_PAD src0_sel:WORD_1 src1_sel:DWORD
	v_and_b32_sdwa v5, v0, v145 dst_sel:DWORD dst_unused:UNUSED_PAD src0_sel:WORD_1 src1_sel:DWORD
	v_add3_u32 v3, v3, v6, s29
	v_add3_u32 v2, v2, v7, s29
	v_add3_u32 v0, v0, v5, s29
	v_add3_u32 v1, v1, v4, s29
	v_and_b32_e32 v3, 0xffff0000, v3
	v_and_b32_e32 v2, 0xffff0000, v2
	v_or_b32_sdwa v1, v3, v1 dst_sel:DWORD dst_unused:UNUSED_PAD src0_sel:DWORD src1_sel:WORD_1
	v_or_b32_sdwa v0, v2, v0 dst_sel:DWORD dst_unused:UNUSED_PAD src0_sel:DWORD src1_sel:WORD_1
	global_store_dwordx2 v[124:125], v[0:1], off offset:3584 nt
	global_load_dwordx4 v[0:3], v[96:97], off
	s_waitcnt vmcnt(0)
	v_mov_b32_e32 v5, v2
	v_mov_b32_e32 v2, v1
	v_mov_b32_e32 v4, v0
	v_pk_mul_f32 v[2:3], v[52:53], v[2:3]
	v_pk_mul_f32 v[0:1], v[148:149], v[4:5]
	v_and_b32_sdwa v6, v3, v145 dst_sel:DWORD dst_unused:UNUSED_PAD src0_sel:WORD_1 src1_sel:DWORD
	v_and_b32_sdwa v7, v2, v145 dst_sel:DWORD dst_unused:UNUSED_PAD src0_sel:WORD_1 src1_sel:DWORD
	v_and_b32_sdwa v4, v1, v145 dst_sel:DWORD dst_unused:UNUSED_PAD src0_sel:WORD_1 src1_sel:DWORD
	v_and_b32_sdwa v5, v0, v145 dst_sel:DWORD dst_unused:UNUSED_PAD src0_sel:WORD_1 src1_sel:DWORD
	v_add3_u32 v3, v3, v6, s29
	v_add3_u32 v2, v2, v7, s29
	v_add3_u32 v0, v0, v5, s29
	v_add3_u32 v1, v1, v4, s29
	v_and_b32_e32 v3, 0xffff0000, v3
	v_and_b32_e32 v2, 0xffff0000, v2
	v_or_b32_sdwa v1, v3, v1 dst_sel:DWORD dst_unused:UNUSED_PAD src0_sel:DWORD src1_sel:WORD_1
	v_or_b32_sdwa v0, v2, v0 dst_sel:DWORD dst_unused:UNUSED_PAD src0_sel:DWORD src1_sel:WORD_1
	global_store_dwordx2 v[118:119], v[0:1], off nt
	global_load_dwordx4 v[0:3], v[98:99], off
	v_pk_mul_f32 v[6:7], v[36:37], v[28:29] op_sel_hi:[1,0]
	v_pk_mul_f32 v[4:5], v[50:51], v[28:29] op_sel_hi:[1,0]
	s_waitcnt vmcnt(0)
	v_mov_b32_e32 v9, v2
	v_mov_b32_e32 v2, v1
	v_mov_b32_e32 v8, v0
	v_pk_mul_f32 v[2:3], v[6:7], v[2:3]
	v_pk_mul_f32 v[0:1], v[4:5], v[8:9]
	v_and_b32_sdwa v6, v3, v145 dst_sel:DWORD dst_unused:UNUSED_PAD src0_sel:WORD_1 src1_sel:DWORD
	v_and_b32_sdwa v7, v2, v145 dst_sel:DWORD dst_unused:UNUSED_PAD src0_sel:WORD_1 src1_sel:DWORD
	v_and_b32_sdwa v4, v1, v145 dst_sel:DWORD dst_unused:UNUSED_PAD src0_sel:WORD_1 src1_sel:DWORD
	v_and_b32_sdwa v5, v0, v145 dst_sel:DWORD dst_unused:UNUSED_PAD src0_sel:WORD_1 src1_sel:DWORD
	v_add3_u32 v3, v3, v6, s29
	v_add3_u32 v2, v2, v7, s29
	v_add3_u32 v0, v0, v5, s29
	v_add3_u32 v1, v1, v4, s29
	v_and_b32_e32 v3, 0xffff0000, v3
	v_and_b32_e32 v2, 0xffff0000, v2
	v_or_b32_sdwa v1, v3, v1 dst_sel:DWORD dst_unused:UNUSED_PAD src0_sel:DWORD src1_sel:WORD_1
	v_or_b32_sdwa v0, v2, v0 dst_sel:DWORD dst_unused:UNUSED_PAD src0_sel:DWORD src1_sel:WORD_1
	global_store_dwordx2 v[118:119], v[0:1], off offset:512 nt
	global_load_dwordx4 v[0:3], v[100:101], off
	v_pk_mul_f32 v[6:7], v[42:43], v[28:29] op_sel_hi:[1,0]
	v_pk_mul_f32 v[4:5], v[132:133], v[28:29] op_sel_hi:[1,0]
	s_waitcnt vmcnt(0)
	v_mov_b32_e32 v9, v2
	v_mov_b32_e32 v2, v1
	v_mov_b32_e32 v8, v0
	v_pk_mul_f32 v[2:3], v[6:7], v[2:3]
	v_pk_mul_f32 v[0:1], v[4:5], v[8:9]
	v_and_b32_sdwa v6, v3, v145 dst_sel:DWORD dst_unused:UNUSED_PAD src0_sel:WORD_1 src1_sel:DWORD
	v_and_b32_sdwa v7, v2, v145 dst_sel:DWORD dst_unused:UNUSED_PAD src0_sel:WORD_1 src1_sel:DWORD
	v_and_b32_sdwa v4, v1, v145 dst_sel:DWORD dst_unused:UNUSED_PAD src0_sel:WORD_1 src1_sel:DWORD
	v_and_b32_sdwa v5, v0, v145 dst_sel:DWORD dst_unused:UNUSED_PAD src0_sel:WORD_1 src1_sel:DWORD
	v_add3_u32 v3, v3, v6, s29
	v_add3_u32 v2, v2, v7, s29
	v_add3_u32 v0, v0, v5, s29
	v_add3_u32 v1, v1, v4, s29
	v_and_b32_e32 v3, 0xffff0000, v3
	v_and_b32_e32 v2, 0xffff0000, v2
	v_or_b32_sdwa v1, v3, v1 dst_sel:DWORD dst_unused:UNUSED_PAD src0_sel:DWORD src1_sel:WORD_1
	v_or_b32_sdwa v0, v2, v0 dst_sel:DWORD dst_unused:UNUSED_PAD src0_sel:DWORD src1_sel:WORD_1
	global_store_dwordx2 v[118:119], v[0:1], off offset:1024 nt
	global_load_dwordx4 v[0:3], v[102:103], off
	v_mov_b32_e32 v5, v40
	v_mov_b32_e32 v40, v39
	v_mov_b32_e32 v4, v38
	v_pk_mul_f32 v[6:7], v[40:41], v[28:29] op_sel_hi:[1,0]
	v_pk_mul_f32 v[4:5], v[4:5], v[28:29] op_sel_hi:[1,0]
	s_waitcnt vmcnt(0)
	v_mov_b32_e32 v9, v2
	v_mov_b32_e32 v2, v1
	v_mov_b32_e32 v8, v0
	v_pk_mul_f32 v[2:3], v[6:7], v[2:3]
	v_pk_mul_f32 v[0:1], v[4:5], v[8:9]
	v_and_b32_sdwa v6, v3, v145 dst_sel:DWORD dst_unused:UNUSED_PAD src0_sel:WORD_1 src1_sel:DWORD
	v_and_b32_sdwa v7, v2, v145 dst_sel:DWORD dst_unused:UNUSED_PAD src0_sel:WORD_1 src1_sel:DWORD
	v_and_b32_sdwa v4, v1, v145 dst_sel:DWORD dst_unused:UNUSED_PAD src0_sel:WORD_1 src1_sel:DWORD
	v_and_b32_sdwa v5, v0, v145 dst_sel:DWORD dst_unused:UNUSED_PAD src0_sel:WORD_1 src1_sel:DWORD
	v_add3_u32 v3, v3, v6, s29
	v_add3_u32 v2, v2, v7, s29
	v_add3_u32 v0, v0, v5, s29
	v_add3_u32 v1, v1, v4, s29
	v_and_b32_e32 v3, 0xffff0000, v3
	v_and_b32_e32 v2, 0xffff0000, v2
	v_or_b32_sdwa v1, v3, v1 dst_sel:DWORD dst_unused:UNUSED_PAD src0_sel:DWORD src1_sel:WORD_1
	v_or_b32_sdwa v0, v2, v0 dst_sel:DWORD dst_unused:UNUSED_PAD src0_sel:DWORD src1_sel:WORD_1
	global_store_dwordx2 v[118:119], v[0:1], off offset:1536 nt
	global_load_dwordx4 v[0:3], v[104:105], off
	v_mov_b32_e32 v5, v34
	v_mov_b32_e32 v34, v33
	v_mov_b32_e32 v4, v32
	v_pk_mul_f32 v[6:7], v[34:35], v[28:29] op_sel_hi:[1,0]
	v_pk_mul_f32 v[4:5], v[4:5], v[28:29] op_sel_hi:[1,0]
	s_waitcnt vmcnt(0)
	v_mov_b32_e32 v9, v2
	v_mov_b32_e32 v2, v1
	v_mov_b32_e32 v8, v0
	v_pk_mul_f32 v[2:3], v[6:7], v[2:3]
	v_pk_mul_f32 v[0:1], v[4:5], v[8:9]
	v_and_b32_sdwa v6, v3, v145 dst_sel:DWORD dst_unused:UNUSED_PAD src0_sel:WORD_1 src1_sel:DWORD
	v_and_b32_sdwa v7, v2, v145 dst_sel:DWORD dst_unused:UNUSED_PAD src0_sel:WORD_1 src1_sel:DWORD
	v_and_b32_sdwa v4, v1, v145 dst_sel:DWORD dst_unused:UNUSED_PAD src0_sel:WORD_1 src1_sel:DWORD
	v_and_b32_sdwa v5, v0, v145 dst_sel:DWORD dst_unused:UNUSED_PAD src0_sel:WORD_1 src1_sel:DWORD
	v_add3_u32 v3, v3, v6, s29
	v_add3_u32 v2, v2, v7, s29
	v_add3_u32 v0, v0, v5, s29
	v_add3_u32 v1, v1, v4, s29
	v_and_b32_e32 v3, 0xffff0000, v3
	v_and_b32_e32 v2, 0xffff0000, v2
	v_or_b32_sdwa v1, v3, v1 dst_sel:DWORD dst_unused:UNUSED_PAD src0_sel:DWORD src1_sel:WORD_1
	v_or_b32_sdwa v0, v2, v0 dst_sel:DWORD dst_unused:UNUSED_PAD src0_sel:DWORD src1_sel:WORD_1
	global_store_dwordx2 v[118:119], v[0:1], off offset:2048 nt
	global_load_dwordx4 v[0:3], v[106:107], off
	v_pk_mul_f32 v[6:7], v[30:31], v[28:29] op_sel_hi:[1,0]
	v_pk_mul_f32 v[4:5], v[46:47], v[28:29] op_sel_hi:[1,0]
	s_waitcnt vmcnt(0)
	v_mov_b32_e32 v9, v2
	v_mov_b32_e32 v2, v1
	v_mov_b32_e32 v8, v0
	v_pk_mul_f32 v[2:3], v[6:7], v[2:3]
	v_pk_mul_f32 v[0:1], v[4:5], v[8:9]
	v_and_b32_sdwa v6, v3, v145 dst_sel:DWORD dst_unused:UNUSED_PAD src0_sel:WORD_1 src1_sel:DWORD
	v_and_b32_sdwa v7, v2, v145 dst_sel:DWORD dst_unused:UNUSED_PAD src0_sel:WORD_1 src1_sel:DWORD
	v_and_b32_sdwa v4, v1, v145 dst_sel:DWORD dst_unused:UNUSED_PAD src0_sel:WORD_1 src1_sel:DWORD
	v_and_b32_sdwa v5, v0, v145 dst_sel:DWORD dst_unused:UNUSED_PAD src0_sel:WORD_1 src1_sel:DWORD
	v_add3_u32 v3, v3, v6, s29
	v_add3_u32 v2, v2, v7, s29
	v_add3_u32 v0, v0, v5, s29
	v_add3_u32 v1, v1, v4, s29
	v_and_b32_e32 v3, 0xffff0000, v3
	v_and_b32_e32 v2, 0xffff0000, v2
	v_or_b32_sdwa v1, v3, v1 dst_sel:DWORD dst_unused:UNUSED_PAD src0_sel:DWORD src1_sel:WORD_1
	v_or_b32_sdwa v0, v2, v0 dst_sel:DWORD dst_unused:UNUSED_PAD src0_sel:DWORD src1_sel:WORD_1
	global_store_dwordx2 v[118:119], v[0:1], off offset:2560 nt
	global_load_dwordx4 v[0:3], v[108:109], off
	v_mov_b32_e32 v5, v24
	v_mov_b32_e32 v24, v23
	v_mov_b32_e32 v4, v22
	v_pk_mul_f32 v[6:7], v[24:25], v[28:29] op_sel_hi:[1,0]
	v_pk_mul_f32 v[4:5], v[4:5], v[28:29] op_sel_hi:[1,0]
	s_waitcnt vmcnt(0)
	v_mov_b32_e32 v9, v2
	v_mov_b32_e32 v2, v1
	v_mov_b32_e32 v8, v0
	v_pk_mul_f32 v[2:3], v[6:7], v[2:3]
	v_pk_mul_f32 v[0:1], v[4:5], v[8:9]
	v_and_b32_sdwa v6, v3, v145 dst_sel:DWORD dst_unused:UNUSED_PAD src0_sel:WORD_1 src1_sel:DWORD
	v_and_b32_sdwa v7, v2, v145 dst_sel:DWORD dst_unused:UNUSED_PAD src0_sel:WORD_1 src1_sel:DWORD
	v_and_b32_sdwa v4, v1, v145 dst_sel:DWORD dst_unused:UNUSED_PAD src0_sel:WORD_1 src1_sel:DWORD
	v_and_b32_sdwa v5, v0, v145 dst_sel:DWORD dst_unused:UNUSED_PAD src0_sel:WORD_1 src1_sel:DWORD
	v_add3_u32 v3, v3, v6, s29
	v_add3_u32 v2, v2, v7, s29
	v_add3_u32 v0, v0, v5, s29
	v_add3_u32 v1, v1, v4, s29
	v_and_b32_e32 v3, 0xffff0000, v3
	v_and_b32_e32 v2, 0xffff0000, v2
	v_or_b32_sdwa v1, v3, v1 dst_sel:DWORD dst_unused:UNUSED_PAD src0_sel:DWORD src1_sel:WORD_1
	v_or_b32_sdwa v0, v2, v0 dst_sel:DWORD dst_unused:UNUSED_PAD src0_sel:DWORD src1_sel:WORD_1
	global_store_dwordx2 v[118:119], v[0:1], off offset:3072 nt
	global_load_dwordx4 v[0:3], v[110:111], off
	v_mov_b32_e32 v5, v18
	v_mov_b32_e32 v18, v17
	v_mov_b32_e32 v4, v16
	v_pk_mul_f32 v[6:7], v[18:19], v[28:29] op_sel_hi:[1,0]
	v_pk_mul_f32 v[4:5], v[4:5], v[28:29] op_sel_hi:[1,0]
	s_waitcnt vmcnt(0)
	v_mov_b32_e32 v9, v2
	v_mov_b32_e32 v2, v1
	v_mov_b32_e32 v8, v0
	v_pk_mul_f32 v[2:3], v[6:7], v[2:3]
	v_pk_mul_f32 v[0:1], v[4:5], v[8:9]
	v_and_b32_sdwa v6, v3, v145 dst_sel:DWORD dst_unused:UNUSED_PAD src0_sel:WORD_1 src1_sel:DWORD
	v_and_b32_sdwa v7, v2, v145 dst_sel:DWORD dst_unused:UNUSED_PAD src0_sel:WORD_1 src1_sel:DWORD
	v_and_b32_sdwa v4, v1, v145 dst_sel:DWORD dst_unused:UNUSED_PAD src0_sel:WORD_1 src1_sel:DWORD
	v_and_b32_sdwa v5, v0, v145 dst_sel:DWORD dst_unused:UNUSED_PAD src0_sel:WORD_1 src1_sel:DWORD
	v_add3_u32 v3, v3, v6, s29
	v_add3_u32 v2, v2, v7, s29
	v_add3_u32 v0, v0, v5, s29
	v_add3_u32 v1, v1, v4, s29
	v_and_b32_e32 v3, 0xffff0000, v3
	v_and_b32_e32 v2, 0xffff0000, v2
	v_or_b32_sdwa v1, v3, v1 dst_sel:DWORD dst_unused:UNUSED_PAD src0_sel:DWORD src1_sel:WORD_1
	v_or_b32_sdwa v0, v2, v0 dst_sel:DWORD dst_unused:UNUSED_PAD src0_sel:DWORD src1_sel:WORD_1
	global_store_dwordx2 v[118:119], v[0:1], off offset:3584 nt
	s_cbranch_scc0 .LBB0_3749

.LBB0_4009:
	v_lshl_add_u64 v[38:39], s[14:15], 0, v[36:37]
	v_add_co_u32_e32 v64, vcc, s13, v38
	v_lshl_add_u64 v[44:45], s[14:15], 0, v[34:35]
	s_nop 0
	v_addc_co_u32_e32 v65, vcc, 0, v39, vcc
	v_add_co_u32_e32 v38, vcc, s26, v38
	v_lshl_add_u64 v[62:63], s[14:15], 0, v[32:33]
	s_nop 0
	v_addc_co_u32_e32 v39, vcc, 0, v39, vcc
	v_add_co_u32_e32 v66, vcc, s24, v44
	global_load_dwordx4 v[54:57], v[0:1], off
	s_nop 0
	v_addc_co_u32_e32 v67, vcc, 0, v45, vcc
	v_add_co_u32_e32 v68, vcc, s25, v44
	v_lshl_add_u64 v[42:43], s[6:7], 0, v[34:35]
	s_nop 0
	v_addc_co_u32_e32 v69, vcc, 0, v45, vcc
	global_load_dword v40, v[62:63], off nt
	global_load_dwordx2 v[70:71], v[38:39], off offset:-4096 nt
	global_load_dwordx4 v[58:61], v[68:69], off offset:-4096 nt
	s_add_i32 s10, s10, s12
	v_lshl_add_u64 v[32:33], v[32:33], 0, s[4:5]
	v_lshl_add_u64 v[34:35], v[34:35], 0, s[16:17]
	v_lshl_add_u64 v[36:37], v[36:37], 0, s[18:19]
	s_cmpk_gt_i32 s10, 0x3fff
	s_waitcnt vmcnt(2)
	ds_bpermute_b32 v53, v41, v40
	s_waitcnt vmcnt(1)
	v_lshlrev_b32_e32 v62, 16, v70
	v_and_b32_e32 v63, 0xffff0000, v70
	v_lshlrev_b32_e32 v70, 16, v71
	v_and_b32_e32 v71, 0xffff0000, v71
	s_waitcnt lgkmcnt(0)
	v_add_f32_e32 v40, v40, v53
	ds_bpermute_b32 v53, v46, v40
	s_waitcnt lgkmcnt(0)
	v_add_f32_e32 v40, v40, v53
	ds_bpermute_b32 v53, v47, v40
	s_waitcnt lgkmcnt(0)
	v_add_f32_e32 v40, v40, v53
	ds_bpermute_b32 v53, v48, v40
	s_waitcnt lgkmcnt(0)
	v_add_f32_e32 v40, v40, v53
	ds_bpermute_b32 v53, v49, v40
	s_waitcnt lgkmcnt(0)
	v_add_f32_e32 v40, v40, v53
	ds_bpermute_b32 v53, v50, v40
	s_waitcnt lgkmcnt(0)
	v_add_f32_e32 v40, v40, v53
	v_fmamk_f32 v40, v40, 0x39800000, v51
	v_mul_f32_e32 v53, 0x4f800000, v40
	v_cmp_gt_f32_e32 vcc, s11, v40
	s_nop 1
	v_cndmask_b32_e32 v40, v40, v53, vcc
	v_sqrt_f32_e32 v53, v40
	s_nop 0
	v_add_u32_e32 v72, -1, v53
	v_add_u32_e32 v73, 1, v53
	v_fma_f32 v74, -v72, v53, v40
	v_fma_f32 v75, -v73, v53, v40
	v_cmp_ge_f32_e64 s[2:3], 0, v74
	s_nop 1
	v_cndmask_b32_e64 v53, v53, v72, s[2:3]
	v_cmp_lt_f32_e64 s[2:3], 0, v75
	s_nop 1
	v_cndmask_b32_e64 v53, v53, v73, s[2:3]
	v_mul_f32_e32 v72, 0x37800000, v53
	v_cndmask_b32_e32 v53, v53, v72, vcc
	v_cmp_class_f32_e32 vcc, v40, v52
	s_nop 1
	v_cndmask_b32_e32 v40, v53, v40, vcc
	v_div_scale_f32 v53, s[2:3], v40, v40, 1.0
	v_rcp_f32_e32 v73, v53
	v_div_scale_f32 v72, vcc, 1.0, v40, 1.0
	v_fma_f32 v74, -v53, v73, 1.0
	v_fmac_f32_e32 v73, v74, v73
	v_mul_f32_e32 v74, v72, v73
	v_fma_f32 v75, -v53, v74, v72
	v_fmac_f32_e32 v74, v75, v73
	v_fma_f32 v53, -v53, v74, v72
	v_div_fmas_f32 v53, v53, v73, v74
	v_div_fixup_f32 v40, v53, v40, 1.0
	v_pk_mul_f32 v[62:63], v[40:41], v[62:63] op_sel_hi:[0,1]
	v_pk_mul_f32 v[70:71], v[40:41], v[70:71] op_sel_hi:[0,1]
	s_waitcnt vmcnt(0)
	v_pk_fma_f32 v[54:55], v[54:55], v[62:63], v[58:59]
	v_pk_fma_f32 v[56:57], v[56:57], v[70:71], v[60:61]
	global_store_dwordx4 v[42:43], v[54:57], off nt
	global_load_dwordx2 v[62:63], v[64:65], off offset:512 nt
	s_nop 0
	global_load_dwordx4 v[54:57], v[66:67], off offset:1024 nt
	global_load_dwordx4 v[58:61], v[2:3], off
	s_waitcnt vmcnt(2)
	v_lshlrev_b32_e32 v70, 16, v62
	v_and_b32_e32 v71, 0xffff0000, v62
	v_lshlrev_b32_e32 v62, 16, v63
	v_and_b32_e32 v63, 0xffff0000, v63
	v_pk_mul_f32 v[70:71], v[40:41], v[70:71] op_sel_hi:[0,1]
	v_pk_mul_f32 v[62:63], v[40:41], v[62:63] op_sel_hi:[0,1]
	s_waitcnt vmcnt(0)
	v_pk_fma_f32 v[54:55], v[58:59], v[70:71], v[54:55]
	v_pk_fma_f32 v[56:57], v[60:61], v[62:63], v[56:57]
	global_store_dwordx4 v[42:43], v[54:57], off offset:1024 nt
	global_load_dwordx2 v[62:63], v[64:65], off offset:1024 nt
	s_nop 0
	global_load_dwordx4 v[54:57], v[66:67], off offset:2048 nt
	global_load_dwordx4 v[58:61], v[4:5], off
	s_waitcnt vmcnt(2)
	v_lshlrev_b32_e32 v70, 16, v62
	v_and_b32_e32 v71, 0xffff0000, v62
	v_lshlrev_b32_e32 v62, 16, v63
	v_and_b32_e32 v63, 0xffff0000, v63
	v_pk_mul_f32 v[70:71], v[40:41], v[70:71] op_sel_hi:[0,1]
	v_pk_mul_f32 v[62:63], v[40:41], v[62:63] op_sel_hi:[0,1]
	s_waitcnt vmcnt(0)
	v_pk_fma_f32 v[54:55], v[58:59], v[70:71], v[54:55]
	v_pk_fma_f32 v[56:57], v[60:61], v[62:63], v[56:57]
	global_store_dwordx4 v[42:43], v[54:57], off offset:2048 nt
	global_load_dwordx2 v[62:63], v[64:65], off offset:1536 nt
	s_nop 0
	global_load_dwordx4 v[54:57], v[66:67], off offset:3072 nt
	global_load_dwordx4 v[58:61], v[6:7], off
	s_waitcnt vmcnt(2)
	v_lshlrev_b32_e32 v66, 16, v62
	v_and_b32_e32 v67, 0xffff0000, v62
	v_lshlrev_b32_e32 v62, 16, v63
	v_and_b32_e32 v63, 0xffff0000, v63
	v_pk_mul_f32 v[66:67], v[40:41], v[66:67] op_sel_hi:[0,1]
	v_pk_mul_f32 v[62:63], v[40:41], v[62:63] op_sel_hi:[0,1]
	s_waitcnt vmcnt(0)
	v_pk_fma_f32 v[54:55], v[58:59], v[66:67], v[54:55]
	v_pk_fma_f32 v[56:57], v[60:61], v[62:63], v[56:57]
	global_store_dwordx4 v[42:43], v[54:57], off offset:3072 nt
	global_load_dwordx2 v[62:63], v[64:65], off offset:2048 nt
	s_nop 0
	global_load_dwordx4 v[54:57], v[68:69], off nt
	global_load_dwordx4 v[58:61], v[8:9], off
	v_add_co_u32_e32 v66, vcc, s22, v42
	s_waitcnt vmcnt(2)
	v_lshlrev_b32_e32 v70, 16, v62
	v_and_b32_e32 v71, 0xffff0000, v62
	v_lshlrev_b32_e32 v62, 16, v63
	v_and_b32_e32 v63, 0xffff0000, v63
	v_pk_mul_f32 v[70:71], v[40:41], v[70:71] op_sel_hi:[0,1]
	v_pk_mul_f32 v[62:63], v[40:41], v[62:63] op_sel_hi:[0,1]
	v_addc_co_u32_e32 v67, vcc, 0, v43, vcc
	s_waitcnt vmcnt(0)
	v_pk_fma_f32 v[54:55], v[58:59], v[70:71], v[54:55]
	v_pk_fma_f32 v[56:57], v[60:61], v[62:63], v[56:57]
	global_store_dwordx4 v[66:67], v[54:57], off offset:-4096 nt
	global_load_dwordx2 v[62:63], v[64:65], off offset:2560 nt
	s_nop 0
	global_load_dwordx4 v[54:57], v[68:69], off offset:1024 nt
	global_load_dwordx4 v[58:61], v[10:11], off
	v_add_co_u32_e32 v70, vcc, s21, v42
	s_waitcnt vmcnt(2)
	v_lshlrev_b32_e32 v72, 16, v62
	v_and_b32_e32 v73, 0xffff0000, v62
	v_lshlrev_b32_e32 v62, 16, v63
	v_and_b32_e32 v63, 0xffff0000, v63
	v_pk_mul_f32 v[72:73], v[40:41], v[72:73] op_sel_hi:[0,1]
	v_pk_mul_f32 v[62:63], v[40:41], v[62:63] op_sel_hi:[0,1]
	v_addc_co_u32_e32 v71, vcc, 0, v43, vcc
	s_waitcnt vmcnt(0)
	v_pk_fma_f32 v[54:55], v[58:59], v[72:73], v[54:55]
	v_pk_fma_f32 v[56:57], v[60:61], v[62:63], v[56:57]
	global_store_dwordx4 v[70:71], v[54:57], off offset:1024 nt
	global_load_dwordx2 v[62:63], v[64:65], off offset:3072 nt
	s_nop 0
	global_load_dwordx4 v[54:57], v[68:69], off offset:2048 nt
	global_load_dwordx4 v[58:61], v[12:13], off
	s_waitcnt vmcnt(2)
	v_lshlrev_b32_e32 v72, 16, v62
	v_and_b32_e32 v73, 0xffff0000, v62
	v_lshlrev_b32_e32 v62, 16, v63
	v_and_b32_e32 v63, 0xffff0000, v63
	v_pk_mul_f32 v[72:73], v[40:41], v[72:73] op_sel_hi:[0,1]
	v_pk_mul_f32 v[62:63], v[40:41], v[62:63] op_sel_hi:[0,1]
	s_waitcnt vmcnt(0)
	v_pk_fma_f32 v[54:55], v[58:59], v[72:73], v[54:55]
	v_pk_fma_f32 v[56:57], v[60:61], v[62:63], v[56:57]
	global_store_dwordx4 v[70:71], v[54:57], off offset:2048 nt
	global_load_dwordx2 v[62:63], v[64:65], off offset:3584 nt
	s_nop 0
	global_load_dwordx4 v[54:57], v[68:69], off offset:3072 nt
	global_load_dwordx4 v[58:61], v[14:15], off
	v_add_co_u32_e32 v64, vcc, s28, v44
	s_waitcnt vmcnt(2)
	v_lshlrev_b32_e32 v68, 16, v62
	v_and_b32_e32 v69, 0xffff0000, v62
	v_lshlrev_b32_e32 v62, 16, v63
	v_and_b32_e32 v63, 0xffff0000, v63
	v_pk_mul_f32 v[68:69], v[40:41], v[68:69] op_sel_hi:[0,1]
	v_pk_mul_f32 v[62:63], v[40:41], v[62:63] op_sel_hi:[0,1]
	s_waitcnt vmcnt(0)
	v_pk_fma_f32 v[54:55], v[58:59], v[68:69], v[54:55]
	v_pk_fma_f32 v[56:57], v[60:61], v[62:63], v[56:57]
	global_store_dwordx4 v[70:71], v[54:57], off offset:3072 nt
	v_addc_co_u32_e32 v65, vcc, 0, v45, vcc
	global_load_dwordx2 v[62:63], v[38:39], off nt
	global_load_dwordx4 v[54:57], v[64:65], off offset:-4096 nt
	global_load_dwordx4 v[58:61], v[16:17], off
	v_add_co_u32_e32 v44, vcc, s27, v44
	s_waitcnt vmcnt(2)
	v_lshlrev_b32_e32 v68, 16, v62
	v_and_b32_e32 v69, 0xffff0000, v62
	v_lshlrev_b32_e32 v62, 16, v63
	v_and_b32_e32 v63, 0xffff0000, v63
	v_pk_mul_f32 v[68:69], v[40:41], v[68:69] op_sel_hi:[0,1]
	v_pk_mul_f32 v[62:63], v[40:41], v[62:63] op_sel_hi:[0,1]
	s_waitcnt vmcnt(0)
	v_pk_fma_f32 v[54:55], v[58:59], v[68:69], v[54:55]
	v_pk_fma_f32 v[56:57], v[60:61], v[62:63], v[56:57]
	global_store_dwordx4 v[66:67], v[54:57], off nt
	v_addc_co_u32_e32 v45, vcc, 0, v45, vcc
	global_load_dwordx2 v[62:63], v[38:39], off offset:512 nt
	global_load_dwordx4 v[54:57], v[44:45], off offset:1024 nt
	global_load_dwordx4 v[58:61], v[18:19], off
	s_waitcnt vmcnt(2)
	v_lshlrev_b32_e32 v68, 16, v62
	v_and_b32_e32 v69, 0xffff0000, v62
	v_lshlrev_b32_e32 v62, 16, v63
	v_and_b32_e32 v63, 0xffff0000, v63
	v_pk_mul_f32 v[68:69], v[40:41], v[68:69] op_sel_hi:[0,1]
	v_pk_mul_f32 v[62:63], v[40:41], v[62:63] op_sel_hi:[0,1]
	s_waitcnt vmcnt(0)
	v_pk_fma_f32 v[54:55], v[58:59], v[68:69], v[54:55]
	v_pk_fma_f32 v[56:57], v[60:61], v[62:63], v[56:57]
	global_store_dwordx4 v[66:67], v[54:57], off offset:1024 nt
	global_load_dwordx2 v[62:63], v[38:39], off offset:1024 nt
	s_nop 0
	global_load_dwordx4 v[54:57], v[44:45], off offset:2048 nt
	global_load_dwordx4 v[58:61], v[20:21], off
	s_waitcnt vmcnt(2)
	v_lshlrev_b32_e32 v68, 16, v62
	v_and_b32_e32 v69, 0xffff0000, v62
	v_lshlrev_b32_e32 v62, 16, v63
	v_and_b32_e32 v63, 0xffff0000, v63
	v_pk_mul_f32 v[68:69], v[40:41], v[68:69] op_sel_hi:[0,1]
	v_pk_mul_f32 v[62:63], v[40:41], v[62:63] op_sel_hi:[0,1]
	s_waitcnt vmcnt(0)
	v_pk_fma_f32 v[54:55], v[58:59], v[68:69], v[54:55]
	v_pk_fma_f32 v[56:57], v[60:61], v[62:63], v[56:57]
	global_store_dwordx4 v[66:67], v[54:57], off offset:2048 nt
	global_load_dwordx2 v[62:63], v[38:39], off offset:1536 nt
	s_nop 0
	global_load_dwordx4 v[54:57], v[44:45], off offset:3072 nt
	global_load_dwordx4 v[58:61], v[22:23], off
	s_waitcnt vmcnt(2)
	v_lshlrev_b32_e32 v44, 16, v62
	v_and_b32_e32 v45, 0xffff0000, v62
	v_lshlrev_b32_e32 v62, 16, v63
	v_and_b32_e32 v63, 0xffff0000, v63
	v_pk_mul_f32 v[44:45], v[40:41], v[44:45] op_sel_hi:[0,1]
	v_pk_mul_f32 v[62:63], v[40:41], v[62:63] op_sel_hi:[0,1]
	s_waitcnt vmcnt(0)
	v_pk_fma_f32 v[54:55], v[58:59], v[44:45], v[54:55]
	v_pk_fma_f32 v[56:57], v[60:61], v[62:63], v[56:57]
	global_store_dwordx4 v[66:67], v[54:57], off offset:3072 nt
	global_load_dwordx2 v[44:45], v[38:39], off offset:2048 nt
	s_nop 0
	global_load_dwordx4 v[54:57], v[64:65], off nt
	global_load_dwordx4 v[58:61], v[24:25], off
	v_add_co_u32_e32 v62, vcc, s23, v42
	s_waitcnt vmcnt(2)
	v_lshlrev_b32_e32 v42, 16, v44
	v_addc_co_u32_e32 v63, vcc, 0, v43, vcc
	v_and_b32_e32 v43, 0xffff0000, v44
	v_lshlrev_b32_e32 v44, 16, v45
	v_and_b32_e32 v45, 0xffff0000, v45
	v_pk_mul_f32 v[42:43], v[40:41], v[42:43] op_sel_hi:[0,1]
	v_pk_mul_f32 v[44:45], v[40:41], v[44:45] op_sel_hi:[0,1]
	s_waitcnt vmcnt(0)
	v_pk_fma_f32 v[42:43], v[58:59], v[42:43], v[54:55]
	v_pk_fma_f32 v[44:45], v[60:61], v[44:45], v[56:57]
	global_store_dwordx4 v[62:63], v[42:45], off nt
	global_load_dwordx2 v[58:59], v[38:39], off offset:2560 nt
	s_nop 0
	global_load_dwordx4 v[42:45], v[64:65], off offset:1024 nt
	global_load_dwordx4 v[54:57], v[26:27], off
	s_waitcnt vmcnt(2)
	v_lshlrev_b32_e32 v60, 16, v58
	v_and_b32_e32 v61, 0xffff0000, v58
	v_lshlrev_b32_e32 v58, 16, v59
	v_and_b32_e32 v59, 0xffff0000, v59
	v_pk_mul_f32 v[60:61], v[40:41], v[60:61] op_sel_hi:[0,1]
	v_pk_mul_f32 v[58:59], v[40:41], v[58:59] op_sel_hi:[0,1]
	s_waitcnt vmcnt(0)
	v_pk_fma_f32 v[42:43], v[54:55], v[60:61], v[42:43]
	v_pk_fma_f32 v[44:45], v[56:57], v[58:59], v[44:45]
	global_store_dwordx4 v[62:63], v[42:45], off offset:1024 nt
	global_load_dwordx2 v[58:59], v[38:39], off offset:3072 nt
	s_nop 0
	global_load_dwordx4 v[42:45], v[64:65], off offset:2048 nt
	global_load_dwordx4 v[54:57], v[28:29], off
	s_waitcnt vmcnt(2)
	v_lshlrev_b32_e32 v60, 16, v58
	v_and_b32_e32 v61, 0xffff0000, v58
	v_lshlrev_b32_e32 v58, 16, v59
	v_and_b32_e32 v59, 0xffff0000, v59
	v_pk_mul_f32 v[60:61], v[40:41], v[60:61] op_sel_hi:[0,1]
	v_pk_mul_f32 v[58:59], v[40:41], v[58:59] op_sel_hi:[0,1]
	s_waitcnt vmcnt(0)
	v_pk_fma_f32 v[42:43], v[54:55], v[60:61], v[42:43]
	v_pk_fma_f32 v[44:45], v[56:57], v[58:59], v[44:45]
	global_store_dwordx4 v[62:63], v[42:45], off offset:2048 nt
	global_load_dwordx2 v[58:59], v[38:39], off offset:3584 nt
	s_nop 0
	global_load_dwordx4 v[42:45], v[64:65], off offset:3072 nt
	global_load_dwordx4 v[54:57], v[30:31], off
	s_waitcnt vmcnt(2)
	v_lshlrev_b32_e32 v38, 16, v58
	v_and_b32_e32 v39, 0xffff0000, v58
	v_lshlrev_b32_e32 v58, 16, v59
	v_and_b32_e32 v59, 0xffff0000, v59
	v_pk_mul_f32 v[38:39], v[40:41], v[38:39] op_sel_hi:[0,1]
	v_pk_mul_f32 v[58:59], v[40:41], v[58:59] op_sel_hi:[0,1]
	s_waitcnt vmcnt(0)
	v_pk_fma_f32 v[42:43], v[54:55], v[38:39], v[42:43]
	v_pk_fma_f32 v[44:45], v[56:57], v[58:59], v[44:45]
	global_store_dwordx4 v[62:63], v[42:45], off offset:3072 nt
	s_cbranch_scc0 .LBB0_4009
